# GEMM compute segment: no lgkmcnt wait after the release (already waited before the barrier) and the priority drop moved after the post-MMA barrier, so the barrier is signalled right after the last MFM
# speedup vs baseline: 1.0111x; 1.0040x over previous
.Lpk354_peel:
	ds_read_b128 v[166:169], v139
	ds_read_b128 v[170:173], v139 offset:1024
	ds_read_b128 v[178:181], v139 offset:2048
	ds_read_b128 v[182:185], v139 offset:3072
	ds_read_b128 v[186:189], v164
	ds_read_b128 v[190:193], v164 offset:1024
	ds_read_b128 v[194:197], v164 offset:2048
	ds_read_b128 v[198:201], v164 offset:3072
	s_add_u32 s2, s26, 0xfffc0080
	s_addc_u32 s3, s27, -1
	s_cmp_eq_u32 s52, 12
	s_cselect_b32 s3, s11, s3
	s_cselect_b32 s2, s13, s2
	s_cselect_b32 s29, s44, s47
	s_cselect_b32 s28, s45, s46
	v_lshl_add_u64 v[148:149], s[26:27], 0, v[142:143]
	s_add_i32 m0, s34, 0xc000
	ds_read_b128 v[202:205], v165
	ds_read_b128 v[206:209], v165 offset:1024
	ds_read_b128 v[210:213], v165 offset:2048
	ds_read_b128 v[214:217], v165 offset:3072
	ds_read_b128 v[218:221], v165 offset:4096
	ds_read_b128 v[222:225], v165 offset:5120
	ds_read_b128 v[226:229], v165 offset:6144
	ds_read_b128 v[230:233], v165 offset:7168
	global_load_lds_dwordx4 v[148:149], off
	v_lshl_add_u64 v[148:149], s[26:27], 0, v[144:145]
	s_add_i32 m0, s34, 0xe000
	s_nop 0
	global_load_lds_dwordx4 v[148:149], off
	s_waitcnt vmcnt(8)
	s_waitcnt lgkmcnt(0)
	s_setprio 1
	s_barrier
	v_mfma_f32_16x16x32_bf16 v[126:129], v[166:169], v[202:205], 0
	v_mfma_f32_16x16x32_bf16 v[122:125], v[178:181], v[202:205], 0
	v_mfma_f32_16x16x32_bf16 v[110:113], v[166:169], v[210:213], 0
	v_mfma_f32_16x16x32_bf16 v[106:109], v[178:181], v[210:213], 0
	v_mfma_f32_16x16x32_bf16 v[94:97], v[166:169], v[218:221], 0
	v_mfma_f32_16x16x32_bf16 v[90:93], v[178:181], v[218:221], 0
	v_mfma_f32_16x16x32_bf16 v[78:81], v[166:169], v[226:229], 0
	v_mfma_f32_16x16x32_bf16 v[74:77], v[178:181], v[226:229], 0
	v_mfma_f32_16x16x32_bf16 v[126:129], v[170:173], v[206:209], v[126:129]
	v_mfma_f32_16x16x32_bf16 v[122:125], v[182:185], v[206:209], v[122:125]
	v_mfma_f32_16x16x32_bf16 v[110:113], v[170:173], v[214:217], v[110:113]
	v_mfma_f32_16x16x32_bf16 v[106:109], v[182:185], v[214:217], v[106:109]
	v_mfma_f32_16x16x32_bf16 v[94:97], v[170:173], v[222:225], v[94:97]
	v_mfma_f32_16x16x32_bf16 v[90:93], v[182:185], v[222:225], v[90:93]
	v_mfma_f32_16x16x32_bf16 v[78:81], v[170:173], v[230:233], v[78:81]
	v_mfma_f32_16x16x32_bf16 v[74:77], v[182:185], v[230:233], v[74:77]
	s_setprio 0
	s_setprio 1
	v_mfma_f32_16x16x32_bf16 v[118:121], v[186:189], v[202:205], 0
	v_mfma_f32_16x16x32_bf16 v[114:117], v[194:197], v[202:205], 0
	v_mfma_f32_16x16x32_bf16 v[102:105], v[186:189], v[210:213], 0
	v_mfma_f32_16x16x32_bf16 v[98:101], v[194:197], v[210:213], 0
	v_mfma_f32_16x16x32_bf16 v[86:89], v[186:189], v[218:221], 0
	v_mfma_f32_16x16x32_bf16 v[82:85], v[194:197], v[218:221], 0
	v_mfma_f32_16x16x32_bf16 v[70:73], v[186:189], v[226:229], 0
	v_mfma_f32_16x16x32_bf16 v[66:69], v[194:197], v[226:229], 0
	v_mfma_f32_16x16x32_bf16 v[118:121], v[190:193], v[206:209], v[118:121]
	v_mfma_f32_16x16x32_bf16 v[114:117], v[198:201], v[206:209], v[114:117]
	v_mfma_f32_16x16x32_bf16 v[102:105], v[190:193], v[214:217], v[102:105]
	v_mfma_f32_16x16x32_bf16 v[98:101], v[198:201], v[214:217], v[98:101]
	v_mfma_f32_16x16x32_bf16 v[86:89], v[190:193], v[222:225], v[86:89]
	v_mfma_f32_16x16x32_bf16 v[82:85], v[198:201], v[222:225], v[82:85]
	v_mfma_f32_16x16x32_bf16 v[70:73], v[190:193], v[230:233], v[70:73]
	v_mfma_f32_16x16x32_bf16 v[66:69], v[198:201], v[230:233], v[66:69]
	s_barrier
	s_setprio 0
	s_add_i32 s53, s41, s30
	v_lshl_add_u64 v[148:149], s[28:29], 0, v[132:133]
	s_mov_b32 m0, s53
	ds_read_b128 v[202:205], v165 offset:16384
	ds_read_b128 v[206:209], v165 offset:17408
	ds_read_b128 v[210:213], v165 offset:18432
	ds_read_b128 v[214:217], v165 offset:19456
	ds_read_b128 v[218:221], v165 offset:20480
	ds_read_b128 v[222:225], v165 offset:21504
	ds_read_b128 v[226:229], v165 offset:22528
	ds_read_b128 v[230:233], v165 offset:23552
	global_load_lds_dwordx4 v[148:149], off
	s_add_i32 m0, s53, 0x2000
	s_add_u32 s54, s28, 0x40000
	v_lshl_add_u64 v[174:175], s[28:29], 0, v[136:137]
	s_addc_u32 s55, s29, 0
	s_add_i32 s53, s42, s30
	global_load_lds_dwordx4 v[174:175], off
	v_lshl_add_u64 v[234:235], s[54:55], 0, v[132:133]
	s_mov_b32 m0, s53
	v_lshl_add_u64 v[236:237], s[2:3], 0, v[134:135]
	global_load_lds_dwordx4 v[234:235], off
	v_lshl_add_u64 v[234:235], s[54:55], 0, v[136:137]
	s_add_i32 m0, s53, 0x2000
	s_nop 0
	global_load_lds_dwordx4 v[234:235], off
	v_lshl_add_u64 v[234:235], s[2:3], 0, v[130:131]
	s_mov_b32 m0, s34
	s_nop 0
	global_load_lds_dwordx4 v[234:235], off
	s_mov_b32 m0, s25
	s_nop 0
	global_load_lds_dwordx4 v[236:237], off
	s_waitcnt vmcnt(8)
	s_waitcnt lgkmcnt(0)
	s_setprio 1
	s_barrier
	v_mfma_f32_16x16x32_bf16 v[62:65], v[166:169], v[202:205], 0
	v_mfma_f32_16x16x32_bf16 v[58:61], v[178:181], v[202:205], 0
	v_mfma_f32_16x16x32_bf16 v[46:49], v[166:169], v[210:213], 0
	v_mfma_f32_16x16x32_bf16 v[42:45], v[178:181], v[210:213], 0
	v_mfma_f32_16x16x32_bf16 v[30:33], v[166:169], v[218:221], 0
	v_mfma_f32_16x16x32_bf16 v[26:29], v[178:181], v[218:221], 0
	v_mfma_f32_16x16x32_bf16 v[14:17], v[166:169], v[226:229], 0
	v_mfma_f32_16x16x32_bf16 v[10:13], v[178:181], v[226:229], 0
	v_mfma_f32_16x16x32_bf16 v[62:65], v[170:173], v[206:209], v[62:65]
	v_mfma_f32_16x16x32_bf16 v[58:61], v[182:185], v[206:209], v[58:61]
	v_mfma_f32_16x16x32_bf16 v[46:49], v[170:173], v[214:217], v[46:49]
	v_mfma_f32_16x16x32_bf16 v[42:45], v[182:185], v[214:217], v[42:45]
	v_mfma_f32_16x16x32_bf16 v[30:33], v[170:173], v[222:225], v[30:33]
	v_mfma_f32_16x16x32_bf16 v[26:29], v[182:185], v[222:225], v[26:29]
	v_mfma_f32_16x16x32_bf16 v[14:17], v[170:173], v[230:233], v[14:17]
	v_mfma_f32_16x16x32_bf16 v[10:13], v[182:185], v[230:233], v[10:13]
	s_setprio 0
	s_setprio 1
	v_mfma_f32_16x16x32_bf16 v[54:57], v[186:189], v[202:205], 0
	v_mfma_f32_16x16x32_bf16 v[50:53], v[194:197], v[202:205], 0
	v_mfma_f32_16x16x32_bf16 v[38:41], v[186:189], v[210:213], 0
	v_mfma_f32_16x16x32_bf16 v[34:37], v[194:197], v[210:213], 0
	v_mfma_f32_16x16x32_bf16 v[22:25], v[186:189], v[218:221], 0
	v_mfma_f32_16x16x32_bf16 v[18:21], v[194:197], v[218:221], 0
	v_mfma_f32_16x16x32_bf16 v[6:9], v[186:189], v[226:229], 0
	v_mfma_f32_16x16x32_bf16 v[2:5], v[194:197], v[226:229], 0
	v_mfma_f32_16x16x32_bf16 v[54:57], v[190:193], v[206:209], v[54:57]
	v_mfma_f32_16x16x32_bf16 v[50:53], v[198:201], v[206:209], v[50:53]
	v_mfma_f32_16x16x32_bf16 v[38:41], v[190:193], v[214:217], v[38:41]
	v_mfma_f32_16x16x32_bf16 v[34:37], v[198:201], v[214:217], v[34:37]
	v_mfma_f32_16x16x32_bf16 v[22:25], v[190:193], v[222:225], v[22:25]
	v_mfma_f32_16x16x32_bf16 v[18:21], v[198:201], v[222:225], v[18:21]
	v_mfma_f32_16x16x32_bf16 v[6:9], v[190:193], v[230:233], v[6:9]
	v_mfma_f32_16x16x32_bf16 v[2:5], v[198:201], v[230:233], v[2:5]
	s_barrier
	s_setprio 0
	s_add_i32 s53, 0, 0x18000
	v_add_u32_e32 v176, s53, v163
	s_add_i32 s54, 0, 0x1c000
	ds_read_b128 v[166:169], v176
	ds_read_b128 v[170:173], v176 offset:1024
	ds_read_b128 v[178:181], v176 offset:2048
	ds_read_b128 v[182:185], v176 offset:3072
	v_add_u32_e32 v176, s54, v163
	ds_read_b128 v[186:189], v176
	ds_read_b128 v[190:193], v176 offset:1024
	ds_read_b128 v[194:197], v176 offset:2048
	ds_read_b128 v[198:201], v176 offset:3072
	s_add_u32 s2, s2, 0x40000
	s_addc_u32 s3, s3, 0
	s_mov_b32 m0, s35
	v_lshl_add_u64 v[238:239], s[2:3], 0, v[130:131]
	ds_read_b128 v[202:205], v165 offset:32768
	ds_read_b128 v[206:209], v165 offset:33792
	ds_read_b128 v[210:213], v165 offset:34816
	ds_read_b128 v[214:217], v165 offset:35840
	ds_read_b128 v[218:221], v165 offset:36864
	ds_read_b128 v[222:225], v165 offset:37888
	ds_read_b128 v[226:229], v165 offset:38912
	ds_read_b128 v[230:233], v165 offset:39936
	global_load_lds_dwordx4 v[238:239], off
	v_lshl_add_u64 v[238:239], s[2:3], 0, v[134:135]
	s_mov_b32 m0, s36
	s_nop 0
	global_load_lds_dwordx4 v[238:239], off
	s_waitcnt vmcnt(8)
	s_waitcnt lgkmcnt(0)
	s_setprio 1
	s_barrier
	v_mfma_f32_16x16x32_bf16 v[126:129], v[166:169], v[202:205], v[126:129]
	v_mfma_f32_16x16x32_bf16 v[122:125], v[178:181], v[202:205], v[122:125]
	v_mfma_f32_16x16x32_bf16 v[110:113], v[166:169], v[210:213], v[110:113]
	v_mfma_f32_16x16x32_bf16 v[106:109], v[178:181], v[210:213], v[106:109]
	v_mfma_f32_16x16x32_bf16 v[94:97], v[166:169], v[218:221], v[94:97]
	v_mfma_f32_16x16x32_bf16 v[90:93], v[178:181], v[218:221], v[90:93]
	v_mfma_f32_16x16x32_bf16 v[78:81], v[166:169], v[226:229], v[78:81]
	v_mfma_f32_16x16x32_bf16 v[74:77], v[178:181], v[226:229], v[74:77]
	v_mfma_f32_16x16x32_bf16 v[126:129], v[170:173], v[206:209], v[126:129]
	v_mfma_f32_16x16x32_bf16 v[122:125], v[182:185], v[206:209], v[122:125]
	v_mfma_f32_16x16x32_bf16 v[110:113], v[170:173], v[214:217], v[110:113]
	v_mfma_f32_16x16x32_bf16 v[106:109], v[182:185], v[214:217], v[106:109]
	v_mfma_f32_16x16x32_bf16 v[94:97], v[170:173], v[222:225], v[94:97]
	v_mfma_f32_16x16x32_bf16 v[90:93], v[182:185], v[222:225], v[90:93]
	v_mfma_f32_16x16x32_bf16 v[78:81], v[170:173], v[230:233], v[78:81]
	v_mfma_f32_16x16x32_bf16 v[74:77], v[182:185], v[230:233], v[74:77]
	s_setprio 0
	s_setprio 1
	v_mfma_f32_16x16x32_bf16 v[118:121], v[186:189], v[202:205], v[118:121]
	v_mfma_f32_16x16x32_bf16 v[114:117], v[194:197], v[202:205], v[114:117]
	v_mfma_f32_16x16x32_bf16 v[102:105], v[186:189], v[210:213], v[102:105]
	v_mfma_f32_16x16x32_bf16 v[98:101], v[194:197], v[210:213], v[98:101]
	v_mfma_f32_16x16x32_bf16 v[86:89], v[186:189], v[218:221], v[86:89]
	v_mfma_f32_16x16x32_bf16 v[82:85], v[194:197], v[218:221], v[82:85]
	v_mfma_f32_16x16x32_bf16 v[70:73], v[186:189], v[226:229], v[70:73]
	v_mfma_f32_16x16x32_bf16 v[66:69], v[194:197], v[226:229], v[66:69]
	v_mfma_f32_16x16x32_bf16 v[118:121], v[190:193], v[206:209], v[118:121]
	v_mfma_f32_16x16x32_bf16 v[114:117], v[198:201], v[206:209], v[114:117]
	v_mfma_f32_16x16x32_bf16 v[102:105], v[190:193], v[214:217], v[102:105]
	v_mfma_f32_16x16x32_bf16 v[98:101], v[198:201], v[214:217], v[98:101]
	v_mfma_f32_16x16x32_bf16 v[86:89], v[190:193], v[222:225], v[86:89]
	v_mfma_f32_16x16x32_bf16 v[82:85], v[198:201], v[222:225], v[82:85]
	v_mfma_f32_16x16x32_bf16 v[70:73], v[190:193], v[230:233], v[70:73]
	v_mfma_f32_16x16x32_bf16 v[66:69], v[198:201], v[230:233], v[66:69]
	s_barrier
	s_setprio 0
	s_add_i32 s2, s53, s30
	v_lshl_add_u64 v[148:149], v[148:149], 0, s[6:7]
	s_mov_b32 m0, s2
	ds_read_b128 v[202:205], v165 offset:49152
	ds_read_b128 v[206:209], v165 offset:50176
	ds_read_b128 v[210:213], v165 offset:51200
	ds_read_b128 v[214:217], v165 offset:52224
	ds_read_b128 v[218:221], v165 offset:53248
	ds_read_b128 v[222:225], v165 offset:54272
	ds_read_b128 v[226:229], v165 offset:55296
	ds_read_b128 v[230:233], v165 offset:56320
	global_load_lds_dwordx4 v[148:149], off
	s_add_i32 m0, s2, 0x2000
	s_add_u32 s2, s28, 0x40080
	v_lshl_add_u64 v[148:149], v[174:175], 0, s[6:7]
	s_addc_u32 s3, s29, 0
	s_add_i32 s28, s54, s30
	global_load_lds_dwordx4 v[148:149], off
	v_lshl_add_u64 v[148:149], s[2:3], 0, v[132:133]
	s_mov_b32 m0, s28
	s_nop 0
	global_load_lds_dwordx4 v[148:149], off
	v_lshl_add_u64 v[148:149], s[2:3], 0, v[136:137]
	s_add_i32 m0, s28, 0x2000
	s_nop 0
	global_load_lds_dwordx4 v[148:149], off
	v_lshl_add_u64 v[148:149], v[234:235], 0, s[6:7]
	s_mov_b32 m0, s38
	s_nop 0
	global_load_lds_dwordx4 v[148:149], off
	v_lshl_add_u64 v[148:149], v[236:237], 0, s[6:7]
	s_mov_b32 m0, s39
	s_nop 0
	global_load_lds_dwordx4 v[148:149], off
	s_waitcnt vmcnt(8)
	s_waitcnt lgkmcnt(0)
	s_setprio 1
	s_barrier
	v_mfma_f32_16x16x32_bf16 v[62:65], v[166:169], v[202:205], v[62:65]
	v_mfma_f32_16x16x32_bf16 v[58:61], v[178:181], v[202:205], v[58:61]
	v_mfma_f32_16x16x32_bf16 v[46:49], v[166:169], v[210:213], v[46:49]
	v_mfma_f32_16x16x32_bf16 v[42:45], v[178:181], v[210:213], v[42:45]
	v_mfma_f32_16x16x32_bf16 v[30:33], v[166:169], v[218:221], v[30:33]
	v_mfma_f32_16x16x32_bf16 v[26:29], v[178:181], v[218:221], v[26:29]
	v_mfma_f32_16x16x32_bf16 v[14:17], v[166:169], v[226:229], v[14:17]
	v_mfma_f32_16x16x32_bf16 v[10:13], v[178:181], v[226:229], v[10:13]
	v_mfma_f32_16x16x32_bf16 v[62:65], v[170:173], v[206:209], v[62:65]
	v_mfma_f32_16x16x32_bf16 v[58:61], v[182:185], v[206:209], v[58:61]
	v_mfma_f32_16x16x32_bf16 v[46:49], v[170:173], v[214:217], v[46:49]
	v_mfma_f32_16x16x32_bf16 v[42:45], v[182:185], v[214:217], v[42:45]
	v_mfma_f32_16x16x32_bf16 v[30:33], v[170:173], v[222:225], v[30:33]
	v_mfma_f32_16x16x32_bf16 v[26:29], v[182:185], v[222:225], v[26:29]
	v_mfma_f32_16x16x32_bf16 v[14:17], v[170:173], v[230:233], v[14:17]
	v_mfma_f32_16x16x32_bf16 v[10:13], v[182:185], v[230:233], v[10:13]
	s_setprio 0
	s_setprio 1
	v_mfma_f32_16x16x32_bf16 v[54:57], v[186:189], v[202:205], v[54:57]
	v_mfma_f32_16x16x32_bf16 v[50:53], v[194:197], v[202:205], v[50:53]
	v_mfma_f32_16x16x32_bf16 v[38:41], v[186:189], v[210:213], v[38:41]
	v_mfma_f32_16x16x32_bf16 v[34:37], v[194:197], v[210:213], v[34:37]
	v_mfma_f32_16x16x32_bf16 v[22:25], v[186:189], v[218:221], v[22:25]
	v_mfma_f32_16x16x32_bf16 v[18:21], v[194:197], v[218:221], v[18:21]
	v_mfma_f32_16x16x32_bf16 v[6:9], v[186:189], v[226:229], v[6:9]
	v_mfma_f32_16x16x32_bf16 v[2:5], v[194:197], v[226:229], v[2:5]
	v_mfma_f32_16x16x32_bf16 v[54:57], v[190:193], v[206:209], v[54:57]
	v_mfma_f32_16x16x32_bf16 v[50:53], v[198:201], v[206:209], v[50:53]
	v_mfma_f32_16x16x32_bf16 v[38:41], v[190:193], v[214:217], v[38:41]
	v_mfma_f32_16x16x32_bf16 v[34:37], v[198:201], v[214:217], v[34:37]
	v_mfma_f32_16x16x32_bf16 v[22:25], v[190:193], v[222:225], v[22:25]
	v_mfma_f32_16x16x32_bf16 v[18:21], v[198:201], v[222:225], v[18:21]
	v_mfma_f32_16x16x32_bf16 v[6:9], v[190:193], v[230:233], v[6:9]
	v_mfma_f32_16x16x32_bf16 v[2:5], v[198:201], v[230:233], v[2:5]
	s_barrier
	s_setprio 0
	s_add_i32 s52, s52, 2
	s_add_u32 s26, s26, 0x100
	s_addc_u32 s27, s27, 0
	s_add_u32 s46, s46, 0x100
	s_addc_u32 s47, s47, 0
	s_cmp_gt_u32 s52, 13
	s_cbranch_scc0 .LBB0_354
	s_branch .Lpk354_exit
.LBB0_354:
	ds_read_b128 v[166:169], v139
	ds_read_b128 v[170:173], v139 offset:1024
	ds_read_b128 v[178:181], v139 offset:2048
	ds_read_b128 v[182:185], v139 offset:3072
	ds_read_b128 v[186:189], v164
	ds_read_b128 v[190:193], v164 offset:1024
	ds_read_b128 v[194:197], v164 offset:2048
	ds_read_b128 v[198:201], v164 offset:3072
	s_add_u32 s2, s26, 0xfffc0080
	s_addc_u32 s3, s27, -1
	s_cmp_eq_u32 s52, 12
	s_cselect_b32 s3, s11, s3
	s_cselect_b32 s2, s13, s2
	s_cselect_b32 s29, s44, s47
	s_cselect_b32 s28, s45, s46
	v_lshl_add_u64 v[148:149], s[26:27], 0, v[142:143]
	s_add_i32 m0, s34, 0xc000
	ds_read_b128 v[202:205], v165
	ds_read_b128 v[206:209], v165 offset:1024
	ds_read_b128 v[210:213], v165 offset:2048
	ds_read_b128 v[214:217], v165 offset:3072
	ds_read_b128 v[218:221], v165 offset:4096
	ds_read_b128 v[222:225], v165 offset:5120
	ds_read_b128 v[226:229], v165 offset:6144
	ds_read_b128 v[230:233], v165 offset:7168
	global_load_lds_dwordx4 v[148:149], off
	v_lshl_add_u64 v[148:149], s[26:27], 0, v[144:145]
	s_add_i32 m0, s34, 0xe000
	s_nop 0
	global_load_lds_dwordx4 v[148:149], off
	s_waitcnt vmcnt(8)
	s_waitcnt lgkmcnt(0)
	s_setprio 1
	s_barrier
	v_mfma_f32_16x16x32_bf16 v[126:129], v[166:169], v[202:205], v[126:129]
	v_mfma_f32_16x16x32_bf16 v[122:125], v[178:181], v[202:205], v[122:125]
	v_mfma_f32_16x16x32_bf16 v[110:113], v[166:169], v[210:213], v[110:113]
	v_mfma_f32_16x16x32_bf16 v[106:109], v[178:181], v[210:213], v[106:109]
	v_mfma_f32_16x16x32_bf16 v[94:97], v[166:169], v[218:221], v[94:97]
	v_mfma_f32_16x16x32_bf16 v[90:93], v[178:181], v[218:221], v[90:93]
	v_mfma_f32_16x16x32_bf16 v[78:81], v[166:169], v[226:229], v[78:81]
	v_mfma_f32_16x16x32_bf16 v[74:77], v[178:181], v[226:229], v[74:77]
	v_mfma_f32_16x16x32_bf16 v[126:129], v[170:173], v[206:209], v[126:129]
	v_mfma_f32_16x16x32_bf16 v[122:125], v[182:185], v[206:209], v[122:125]
	v_mfma_f32_16x16x32_bf16 v[110:113], v[170:173], v[214:217], v[110:113]
	v_mfma_f32_16x16x32_bf16 v[106:109], v[182:185], v[214:217], v[106:109]
	v_mfma_f32_16x16x32_bf16 v[94:97], v[170:173], v[222:225], v[94:97]
	v_mfma_f32_16x16x32_bf16 v[90:93], v[182:185], v[222:225], v[90:93]
	v_mfma_f32_16x16x32_bf16 v[78:81], v[170:173], v[230:233], v[78:81]
	v_mfma_f32_16x16x32_bf16 v[74:77], v[182:185], v[230:233], v[74:77]
	s_setprio 0
	s_setprio 1
	v_mfma_f32_16x16x32_bf16 v[118:121], v[186:189], v[202:205], v[118:121]
	v_mfma_f32_16x16x32_bf16 v[114:117], v[194:197], v[202:205], v[114:117]
	v_mfma_f32_16x16x32_bf16 v[102:105], v[186:189], v[210:213], v[102:105]
	v_mfma_f32_16x16x32_bf16 v[98:101], v[194:197], v[210:213], v[98:101]
	v_mfma_f32_16x16x32_bf16 v[86:89], v[186:189], v[218:221], v[86:89]
	v_mfma_f32_16x16x32_bf16 v[82:85], v[194:197], v[218:221], v[82:85]
	v_mfma_f32_16x16x32_bf16 v[70:73], v[186:189], v[226:229], v[70:73]
	v_mfma_f32_16x16x32_bf16 v[66:69], v[194:197], v[226:229], v[66:69]
	v_mfma_f32_16x16x32_bf16 v[118:121], v[190:193], v[206:209], v[118:121]
	v_mfma_f32_16x16x32_bf16 v[114:117], v[198:201], v[206:209], v[114:117]
	v_mfma_f32_16x16x32_bf16 v[102:105], v[190:193], v[214:217], v[102:105]
	v_mfma_f32_16x16x32_bf16 v[98:101], v[198:201], v[214:217], v[98:101]
	v_mfma_f32_16x16x32_bf16 v[86:89], v[190:193], v[222:225], v[86:89]
	v_mfma_f32_16x16x32_bf16 v[82:85], v[198:201], v[222:225], v[82:85]
	v_mfma_f32_16x16x32_bf16 v[70:73], v[190:193], v[230:233], v[70:73]
	v_mfma_f32_16x16x32_bf16 v[66:69], v[198:201], v[230:233], v[66:69]
	s_barrier
	s_setprio 0
	s_add_i32 s53, s41, s30
	v_lshl_add_u64 v[148:149], s[28:29], 0, v[132:133]
	s_mov_b32 m0, s53
	ds_read_b128 v[202:205], v165 offset:16384
	ds_read_b128 v[206:209], v165 offset:17408
	ds_read_b128 v[210:213], v165 offset:18432
	ds_read_b128 v[214:217], v165 offset:19456
	ds_read_b128 v[218:221], v165 offset:20480
	ds_read_b128 v[222:225], v165 offset:21504
	ds_read_b128 v[226:229], v165 offset:22528
	ds_read_b128 v[230:233], v165 offset:23552
	global_load_lds_dwordx4 v[148:149], off
	s_add_i32 m0, s53, 0x2000
	s_add_u32 s54, s28, 0x40000
	v_lshl_add_u64 v[174:175], s[28:29], 0, v[136:137]
	s_addc_u32 s55, s29, 0
	s_add_i32 s53, s42, s30
	global_load_lds_dwordx4 v[174:175], off
	v_lshl_add_u64 v[234:235], s[54:55], 0, v[132:133]
	s_mov_b32 m0, s53
	v_lshl_add_u64 v[236:237], s[2:3], 0, v[134:135]
	global_load_lds_dwordx4 v[234:235], off
	v_lshl_add_u64 v[234:235], s[54:55], 0, v[136:137]
	s_add_i32 m0, s53, 0x2000
	s_nop 0
	global_load_lds_dwordx4 v[234:235], off
	v_lshl_add_u64 v[234:235], s[2:3], 0, v[130:131]
	s_mov_b32 m0, s34
	s_nop 0
	global_load_lds_dwordx4 v[234:235], off
	s_mov_b32 m0, s25
	s_nop 0
	global_load_lds_dwordx4 v[236:237], off
	s_waitcnt vmcnt(8)
	s_waitcnt lgkmcnt(0)
	s_setprio 1
	s_barrier
	v_mfma_f32_16x16x32_bf16 v[62:65], v[166:169], v[202:205], v[62:65]
	v_mfma_f32_16x16x32_bf16 v[58:61], v[178:181], v[202:205], v[58:61]
	v_mfma_f32_16x16x32_bf16 v[46:49], v[166:169], v[210:213], v[46:49]
	v_mfma_f32_16x16x32_bf16 v[42:45], v[178:181], v[210:213], v[42:45]
	v_mfma_f32_16x16x32_bf16 v[30:33], v[166:169], v[218:221], v[30:33]
	v_mfma_f32_16x16x32_bf16 v[26:29], v[178:181], v[218:221], v[26:29]
	v_mfma_f32_16x16x32_bf16 v[14:17], v[166:169], v[226:229], v[14:17]
	v_mfma_f32_16x16x32_bf16 v[10:13], v[178:181], v[226:229], v[10:13]
	v_mfma_f32_16x16x32_bf16 v[62:65], v[170:173], v[206:209], v[62:65]
	v_mfma_f32_16x16x32_bf16 v[58:61], v[182:185], v[206:209], v[58:61]
	v_mfma_f32_16x16x32_bf16 v[46:49], v[170:173], v[214:217], v[46:49]
	v_mfma_f32_16x16x32_bf16 v[42:45], v[182:185], v[214:217], v[42:45]
	v_mfma_f32_16x16x32_bf16 v[30:33], v[170:173], v[222:225], v[30:33]
	v_mfma_f32_16x16x32_bf16 v[26:29], v[182:185], v[222:225], v[26:29]
	v_mfma_f32_16x16x32_bf16 v[14:17], v[170:173], v[230:233], v[14:17]
	v_mfma_f32_16x16x32_bf16 v[10:13], v[182:185], v[230:233], v[10:13]
	s_setprio 0
	s_setprio 1
	v_mfma_f32_16x16x32_bf16 v[54:57], v[186:189], v[202:205], v[54:57]
	v_mfma_f32_16x16x32_bf16 v[50:53], v[194:197], v[202:205], v[50:53]
	v_mfma_f32_16x16x32_bf16 v[38:41], v[186:189], v[210:213], v[38:41]
	v_mfma_f32_16x16x32_bf16 v[34:37], v[194:197], v[210:213], v[34:37]
	v_mfma_f32_16x16x32_bf16 v[22:25], v[186:189], v[218:221], v[22:25]
	v_mfma_f32_16x16x32_bf16 v[18:21], v[194:197], v[218:221], v[18:21]
	v_mfma_f32_16x16x32_bf16 v[6:9], v[186:189], v[226:229], v[6:9]
	v_mfma_f32_16x16x32_bf16 v[2:5], v[194:197], v[226:229], v[2:5]
	v_mfma_f32_16x16x32_bf16 v[54:57], v[190:193], v[206:209], v[54:57]
	v_mfma_f32_16x16x32_bf16 v[50:53], v[198:201], v[206:209], v[50:53]
	v_mfma_f32_16x16x32_bf16 v[38:41], v[190:193], v[214:217], v[38:41]
	v_mfma_f32_16x16x32_bf16 v[34:37], v[198:201], v[214:217], v[34:37]
	v_mfma_f32_16x16x32_bf16 v[22:25], v[190:193], v[222:225], v[22:25]
	v_mfma_f32_16x16x32_bf16 v[18:21], v[198:201], v[222:225], v[18:21]
	v_mfma_f32_16x16x32_bf16 v[6:9], v[190:193], v[230:233], v[6:9]
	v_mfma_f32_16x16x32_bf16 v[2:5], v[198:201], v[230:233], v[2:5]
	s_barrier
	s_setprio 0
	s_add_i32 s53, 0, 0x18000
	v_add_u32_e32 v176, s53, v163
	s_add_i32 s54, 0, 0x1c000
	ds_read_b128 v[166:169], v176
	ds_read_b128 v[170:173], v176 offset:1024
	ds_read_b128 v[178:181], v176 offset:2048
	ds_read_b128 v[182:185], v176 offset:3072
	v_add_u32_e32 v176, s54, v163
	ds_read_b128 v[186:189], v176
	ds_read_b128 v[190:193], v176 offset:1024
	ds_read_b128 v[194:197], v176 offset:2048
	ds_read_b128 v[198:201], v176 offset:3072
	s_add_u32 s2, s2, 0x40000
	s_addc_u32 s3, s3, 0
	s_mov_b32 m0, s35
	v_lshl_add_u64 v[238:239], s[2:3], 0, v[130:131]
	ds_read_b128 v[202:205], v165 offset:32768
	ds_read_b128 v[206:209], v165 offset:33792
	ds_read_b128 v[210:213], v165 offset:34816
	ds_read_b128 v[214:217], v165 offset:35840
	ds_read_b128 v[218:221], v165 offset:36864
	ds_read_b128 v[222:225], v165 offset:37888
	ds_read_b128 v[226:229], v165 offset:38912
	ds_read_b128 v[230:233], v165 offset:39936
	global_load_lds_dwordx4 v[238:239], off
	v_lshl_add_u64 v[238:239], s[2:3], 0, v[134:135]
	s_mov_b32 m0, s36
	s_nop 0
	global_load_lds_dwordx4 v[238:239], off
	s_waitcnt vmcnt(8)
	s_waitcnt lgkmcnt(0)
	s_setprio 1
	s_barrier
	v_mfma_f32_16x16x32_bf16 v[126:129], v[166:169], v[202:205], v[126:129]
	v_mfma_f32_16x16x32_bf16 v[122:125], v[178:181], v[202:205], v[122:125]
	v_mfma_f32_16x16x32_bf16 v[110:113], v[166:169], v[210:213], v[110:113]
	v_mfma_f32_16x16x32_bf16 v[106:109], v[178:181], v[210:213], v[106:109]
	v_mfma_f32_16x16x32_bf16 v[94:97], v[166:169], v[218:221], v[94:97]
	v_mfma_f32_16x16x32_bf16 v[90:93], v[178:181], v[218:221], v[90:93]
	v_mfma_f32_16x16x32_bf16 v[78:81], v[166:169], v[226:229], v[78:81]
	v_mfma_f32_16x16x32_bf16 v[74:77], v[178:181], v[226:229], v[74:77]
	v_mfma_f32_16x16x32_bf16 v[126:129], v[170:173], v[206:209], v[126:129]
	v_mfma_f32_16x16x32_bf16 v[122:125], v[182:185], v[206:209], v[122:125]
	v_mfma_f32_16x16x32_bf16 v[110:113], v[170:173], v[214:217], v[110:113]
	v_mfma_f32_16x16x32_bf16 v[106:109], v[182:185], v[214:217], v[106:109]
	v_mfma_f32_16x16x32_bf16 v[94:97], v[170:173], v[222:225], v[94:97]
	v_mfma_f32_16x16x32_bf16 v[90:93], v[182:185], v[222:225], v[90:93]
	v_mfma_f32_16x16x32_bf16 v[78:81], v[170:173], v[230:233], v[78:81]
	v_mfma_f32_16x16x32_bf16 v[74:77], v[182:185], v[230:233], v[74:77]
	s_setprio 0
	s_setprio 1
	v_mfma_f32_16x16x32_bf16 v[118:121], v[186:189], v[202:205], v[118:121]
	v_mfma_f32_16x16x32_bf16 v[114:117], v[194:197], v[202:205], v[114:117]
	v_mfma_f32_16x16x32_bf16 v[102:105], v[186:189], v[210:213], v[102:105]
	v_mfma_f32_16x16x32_bf16 v[98:101], v[194:197], v[210:213], v[98:101]
	v_mfma_f32_16x16x32_bf16 v[86:89], v[186:189], v[218:221], v[86:89]
	v_mfma_f32_16x16x32_bf16 v[82:85], v[194:197], v[218:221], v[82:85]
	v_mfma_f32_16x16x32_bf16 v[70:73], v[186:189], v[226:229], v[70:73]
	v_mfma_f32_16x16x32_bf16 v[66:69], v[194:197], v[226:229], v[66:69]
	v_mfma_f32_16x16x32_bf16 v[118:121], v[190:193], v[206:209], v[118:121]
	v_mfma_f32_16x16x32_bf16 v[114:117], v[198:201], v[206:209], v[114:117]
	v_mfma_f32_16x16x32_bf16 v[102:105], v[190:193], v[214:217], v[102:105]
	v_mfma_f32_16x16x32_bf16 v[98:101], v[198:201], v[214:217], v[98:101]
	v_mfma_f32_16x16x32_bf16 v[86:89], v[190:193], v[222:225], v[86:89]
	v_mfma_f32_16x16x32_bf16 v[82:85], v[198:201], v[222:225], v[82:85]
	v_mfma_f32_16x16x32_bf16 v[70:73], v[190:193], v[230:233], v[70:73]
	v_mfma_f32_16x16x32_bf16 v[66:69], v[198:201], v[230:233], v[66:69]
	s_barrier
	s_setprio 0
	s_add_i32 s2, s53, s30
	v_lshl_add_u64 v[148:149], v[148:149], 0, s[6:7]
	s_mov_b32 m0, s2
	ds_read_b128 v[202:205], v165 offset:49152
	ds_read_b128 v[206:209], v165 offset:50176
	ds_read_b128 v[210:213], v165 offset:51200
	ds_read_b128 v[214:217], v165 offset:52224
	ds_read_b128 v[218:221], v165 offset:53248
	ds_read_b128 v[222:225], v165 offset:54272
	ds_read_b128 v[226:229], v165 offset:55296
	ds_read_b128 v[230:233], v165 offset:56320
	global_load_lds_dwordx4 v[148:149], off
	s_add_i32 m0, s2, 0x2000
	s_add_u32 s2, s28, 0x40080
	v_lshl_add_u64 v[148:149], v[174:175], 0, s[6:7]
	s_addc_u32 s3, s29, 0
	s_add_i32 s28, s54, s30
	global_load_lds_dwordx4 v[148:149], off
	v_lshl_add_u64 v[148:149], s[2:3], 0, v[132:133]
	s_mov_b32 m0, s28
	s_nop 0
	global_load_lds_dwordx4 v[148:149], off
	v_lshl_add_u64 v[148:149], s[2:3], 0, v[136:137]
	s_add_i32 m0, s28, 0x2000
	s_nop 0
	global_load_lds_dwordx4 v[148:149], off
	v_lshl_add_u64 v[148:149], v[234:235], 0, s[6:7]
	s_mov_b32 m0, s38
	s_nop 0
	global_load_lds_dwordx4 v[148:149], off
	v_lshl_add_u64 v[148:149], v[236:237], 0, s[6:7]
	s_mov_b32 m0, s39
	s_nop 0
	global_load_lds_dwordx4 v[148:149], off
	s_waitcnt vmcnt(8)
	s_waitcnt lgkmcnt(0)
	s_setprio 1
	s_barrier
	v_mfma_f32_16x16x32_bf16 v[62:65], v[166:169], v[202:205], v[62:65]
	v_mfma_f32_16x16x32_bf16 v[58:61], v[178:181], v[202:205], v[58:61]
	v_mfma_f32_16x16x32_bf16 v[46:49], v[166:169], v[210:213], v[46:49]
	v_mfma_f32_16x16x32_bf16 v[42:45], v[178:181], v[210:213], v[42:45]
	v_mfma_f32_16x16x32_bf16 v[30:33], v[166:169], v[218:221], v[30:33]
	v_mfma_f32_16x16x32_bf16 v[26:29], v[178:181], v[218:221], v[26:29]
	v_mfma_f32_16x16x32_bf16 v[14:17], v[166:169], v[226:229], v[14:17]
	v_mfma_f32_16x16x32_bf16 v[10:13], v[178:181], v[226:229], v[10:13]
	v_mfma_f32_16x16x32_bf16 v[62:65], v[170:173], v[206:209], v[62:65]
	v_mfma_f32_16x16x32_bf16 v[58:61], v[182:185], v[206:209], v[58:61]
	v_mfma_f32_16x16x32_bf16 v[46:49], v[170:173], v[214:217], v[46:49]
	v_mfma_f32_16x16x32_bf16 v[42:45], v[182:185], v[214:217], v[42:45]
	v_mfma_f32_16x16x32_bf16 v[30:33], v[170:173], v[222:225], v[30:33]
	v_mfma_f32_16x16x32_bf16 v[26:29], v[182:185], v[222:225], v[26:29]
	v_mfma_f32_16x16x32_bf16 v[14:17], v[170:173], v[230:233], v[14:17]
	v_mfma_f32_16x16x32_bf16 v[10:13], v[182:185], v[230:233], v[10:13]
	s_setprio 0
	s_setprio 1
	v_mfma_f32_16x16x32_bf16 v[54:57], v[186:189], v[202:205], v[54:57]
	v_mfma_f32_16x16x32_bf16 v[50:53], v[194:197], v[202:205], v[50:53]
	v_mfma_f32_16x16x32_bf16 v[38:41], v[186:189], v[210:213], v[38:41]
	v_mfma_f32_16x16x32_bf16 v[34:37], v[194:197], v[210:213], v[34:37]
	v_mfma_f32_16x16x32_bf16 v[22:25], v[186:189], v[218:221], v[22:25]
	v_mfma_f32_16x16x32_bf16 v[18:21], v[194:197], v[218:221], v[18:21]
	v_mfma_f32_16x16x32_bf16 v[6:9], v[186:189], v[226:229], v[6:9]
	v_mfma_f32_16x16x32_bf16 v[2:5], v[194:197], v[226:229], v[2:5]
	v_mfma_f32_16x16x32_bf16 v[54:57], v[190:193], v[206:209], v[54:57]
	v_mfma_f32_16x16x32_bf16 v[50:53], v[198:201], v[206:209], v[50:53]
	v_mfma_f32_16x16x32_bf16 v[38:41], v[190:193], v[214:217], v[38:41]
	v_mfma_f32_16x16x32_bf16 v[34:37], v[198:201], v[214:217], v[34:37]
	v_mfma_f32_16x16x32_bf16 v[22:25], v[190:193], v[222:225], v[22:25]
	v_mfma_f32_16x16x32_bf16 v[18:21], v[198:201], v[222:225], v[18:21]
	v_mfma_f32_16x16x32_bf16 v[6:9], v[190:193], v[230:233], v[6:9]
	v_mfma_f32_16x16x32_bf16 v[2:5], v[198:201], v[230:233], v[2:5]
	s_barrier
	s_setprio 0
	s_add_i32 s52, s52, 2
	s_add_u32 s26, s26, 0x100
	s_addc_u32 s27, s27, 0
	s_add_u32 s46, s46, 0x100
	s_addc_u32 s47, s47, 0
	s_cmp_gt_u32 s52, 13
	s_cbranch_scc0 .LBB0_354

.LBB0_437:
	ds_read_b128 v[160:163], v133
	ds_read_b128 v[164:167], v133 offset:1024
	ds_read_b128 v[168:171], v133 offset:2048
	ds_read_b128 v[172:175], v133 offset:3072
	ds_read_b128 v[178:181], v135
	ds_read_b128 v[182:185], v135 offset:1024
	ds_read_b128 v[186:189], v135 offset:2048
	ds_read_b128 v[190:193], v135 offset:3072
	s_cmp_lg_u32 s8, 0x160000
	s_cselect_b32 s13, s8, 0
	s_cselect_b32 s12, s9, 0
	s_add_u32 s2, s6, s13
	s_addc_u32 s3, s7, s12
	s_add_u32 s14, s0, s13
	s_addc_u32 s15, s1, s12
	s_add_u32 s12, s2, 0x8000
	s_addc_u32 s13, s3, 0
	v_lshl_add_u64 v[226:227], v[148:149], 0, s[8:9]
	s_mov_b32 m0, s27
	v_lshl_add_u64 v[226:227], v[226:227], 0, s[10:11]
	ds_read_b128 v[194:197], v137
	ds_read_b128 v[198:201], v137 offset:1024
	ds_read_b128 v[202:205], v137 offset:2048
	ds_read_b128 v[206:209], v137 offset:3072
	ds_read_b128 v[210:213], v137 offset:4096
	ds_read_b128 v[214:217], v137 offset:5120
	ds_read_b128 v[218:221], v137 offset:6144
	ds_read_b128 v[222:225], v137 offset:7168
	global_load_lds_dwordx4 v[226:227], off
	v_lshl_add_u64 v[226:227], v[150:151], 0, s[8:9]
	v_lshl_add_u64 v[226:227], v[226:227], 0, s[10:11]
	s_mov_b32 m0, s28
	s_nop 0
	global_load_lds_dwordx4 v[226:227], off
	s_waitcnt vmcnt(8)
	s_waitcnt lgkmcnt(0)
	s_setprio 1
	s_barrier
	v_mfma_f32_16x16x32_bf16 v[126:129], v[160:163], v[194:197], v[126:129]
	v_mfma_f32_16x16x32_bf16 v[122:125], v[168:171], v[194:197], v[122:125]
	v_mfma_f32_16x16x32_bf16 v[114:117], v[160:163], v[202:205], v[114:117]
	v_mfma_f32_16x16x32_bf16 v[106:109], v[168:171], v[202:205], v[106:109]
	v_mfma_f32_16x16x32_bf16 v[98:101], v[160:163], v[210:213], v[98:101]
	v_mfma_f32_16x16x32_bf16 v[90:93], v[168:171], v[210:213], v[90:93]
	v_mfma_f32_16x16x32_bf16 v[82:85], v[160:163], v[218:221], v[82:85]
	v_mfma_f32_16x16x32_bf16 v[74:77], v[168:171], v[218:221], v[74:77]
	v_mfma_f32_16x16x32_bf16 v[126:129], v[164:167], v[198:201], v[126:129]
	v_mfma_f32_16x16x32_bf16 v[122:125], v[172:175], v[198:201], v[122:125]
	v_mfma_f32_16x16x32_bf16 v[114:117], v[164:167], v[206:209], v[114:117]
	v_mfma_f32_16x16x32_bf16 v[106:109], v[172:175], v[206:209], v[106:109]
	v_mfma_f32_16x16x32_bf16 v[98:101], v[164:167], v[214:217], v[98:101]
	v_mfma_f32_16x16x32_bf16 v[90:93], v[172:175], v[214:217], v[90:93]
	v_mfma_f32_16x16x32_bf16 v[82:85], v[164:167], v[222:225], v[82:85]
	v_mfma_f32_16x16x32_bf16 v[74:77], v[172:175], v[222:225], v[74:77]
	s_setprio 0
	s_setprio 1
	v_mfma_f32_16x16x32_bf16 v[118:121], v[178:181], v[194:197], v[118:121]
	v_mfma_f32_16x16x32_bf16 v[110:113], v[186:189], v[194:197], v[110:113]
	v_mfma_f32_16x16x32_bf16 v[102:105], v[178:181], v[202:205], v[102:105]
	v_mfma_f32_16x16x32_bf16 v[94:97], v[186:189], v[202:205], v[94:97]
	v_mfma_f32_16x16x32_bf16 v[86:89], v[178:181], v[210:213], v[86:89]
	v_mfma_f32_16x16x32_bf16 v[78:81], v[186:189], v[210:213], v[78:81]
	v_mfma_f32_16x16x32_bf16 v[70:73], v[178:181], v[218:221], v[70:73]
	v_mfma_f32_16x16x32_bf16 v[66:69], v[186:189], v[218:221], v[66:69]
	v_mfma_f32_16x16x32_bf16 v[118:121], v[182:185], v[198:201], v[118:121]
	v_mfma_f32_16x16x32_bf16 v[110:113], v[190:193], v[198:201], v[110:113]
	v_mfma_f32_16x16x32_bf16 v[102:105], v[182:185], v[206:209], v[102:105]
	v_mfma_f32_16x16x32_bf16 v[94:97], v[190:193], v[206:209], v[94:97]
	v_mfma_f32_16x16x32_bf16 v[86:89], v[182:185], v[214:217], v[86:89]
	v_mfma_f32_16x16x32_bf16 v[78:81], v[190:193], v[214:217], v[78:81]
	v_mfma_f32_16x16x32_bf16 v[70:73], v[182:185], v[222:225], v[70:73]
	v_mfma_f32_16x16x32_bf16 v[66:69], v[190:193], v[222:225], v[66:69]
	s_barrier
	s_setprio 0
	s_mov_b32 m0, s29
	v_lshl_add_u64 v[226:227], s[14:15], 0, v[142:143]
	s_add_u32 s40, s14, 0x4000
	ds_read_b128 v[194:197], v137 offset:16384
	ds_read_b128 v[198:201], v137 offset:17408
	ds_read_b128 v[202:205], v137 offset:18432
	ds_read_b128 v[206:209], v137 offset:19456
	ds_read_b128 v[210:213], v137 offset:20480
	ds_read_b128 v[214:217], v137 offset:21504
	ds_read_b128 v[218:221], v137 offset:22528
	ds_read_b128 v[222:225], v137 offset:23552
	global_load_lds_dwordx4 v[226:227], off
	v_lshl_add_u64 v[226:227], s[14:15], 0, v[146:147]
	s_mov_b32 m0, s30
	s_addc_u32 s41, s15, 0
	global_load_lds_dwordx4 v[226:227], off
	v_lshl_add_u64 v[226:227], s[40:41], 0, v[142:143]
	s_mov_b32 m0, s31
	s_nop 0
	global_load_lds_dwordx4 v[226:227], off
	v_lshl_add_u64 v[226:227], s[40:41], 0, v[146:147]
	s_mov_b32 m0, s34
	s_nop 0
	global_load_lds_dwordx4 v[226:227], off
	v_lshl_add_u64 v[226:227], s[2:3], 0, v[140:141]
	s_mov_b32 m0, s19
	s_nop 0
	global_load_lds_dwordx4 v[226:227], off
	v_lshl_add_u64 v[226:227], s[2:3], 0, v[144:145]
	s_mov_b32 m0, s20
	s_nop 0
	global_load_lds_dwordx4 v[226:227], off
	s_waitcnt vmcnt(8)
	s_waitcnt lgkmcnt(0)
	s_setprio 1
	s_barrier
	v_mfma_f32_16x16x32_bf16 v[62:65], v[160:163], v[194:197], v[62:65]
	v_mfma_f32_16x16x32_bf16 v[58:61], v[168:171], v[194:197], v[58:61]
	v_mfma_f32_16x16x32_bf16 v[50:53], v[160:163], v[202:205], v[50:53]
	v_mfma_f32_16x16x32_bf16 v[42:45], v[168:171], v[202:205], v[42:45]
	v_mfma_f32_16x16x32_bf16 v[34:37], v[160:163], v[210:213], v[34:37]
	v_mfma_f32_16x16x32_bf16 v[26:29], v[168:171], v[210:213], v[26:29]
	v_mfma_f32_16x16x32_bf16 v[18:21], v[160:163], v[218:221], v[18:21]
	v_mfma_f32_16x16x32_bf16 v[10:13], v[168:171], v[218:221], v[10:13]
	v_mfma_f32_16x16x32_bf16 v[62:65], v[164:167], v[198:201], v[62:65]
	v_mfma_f32_16x16x32_bf16 v[58:61], v[172:175], v[198:201], v[58:61]
	v_mfma_f32_16x16x32_bf16 v[50:53], v[164:167], v[206:209], v[50:53]
	v_mfma_f32_16x16x32_bf16 v[42:45], v[172:175], v[206:209], v[42:45]
	v_mfma_f32_16x16x32_bf16 v[34:37], v[164:167], v[214:217], v[34:37]
	v_mfma_f32_16x16x32_bf16 v[26:29], v[172:175], v[214:217], v[26:29]
	v_mfma_f32_16x16x32_bf16 v[18:21], v[164:167], v[222:225], v[18:21]
	v_mfma_f32_16x16x32_bf16 v[10:13], v[172:175], v[222:225], v[10:13]
	s_setprio 0
	s_setprio 1
	v_mfma_f32_16x16x32_bf16 v[54:57], v[178:181], v[194:197], v[54:57]
	v_mfma_f32_16x16x32_bf16 v[46:49], v[186:189], v[194:197], v[46:49]
	v_mfma_f32_16x16x32_bf16 v[38:41], v[178:181], v[202:205], v[38:41]
	v_mfma_f32_16x16x32_bf16 v[30:33], v[186:189], v[202:205], v[30:33]
	v_mfma_f32_16x16x32_bf16 v[22:25], v[178:181], v[210:213], v[22:25]
	v_mfma_f32_16x16x32_bf16 v[14:17], v[186:189], v[210:213], v[14:17]
	v_mfma_f32_16x16x32_bf16 v[6:9], v[178:181], v[218:221], v[6:9]
	v_mfma_f32_16x16x32_bf16 v[2:5], v[186:189], v[218:221], v[2:5]
	v_mfma_f32_16x16x32_bf16 v[54:57], v[182:185], v[198:201], v[54:57]
	v_mfma_f32_16x16x32_bf16 v[46:49], v[190:193], v[198:201], v[46:49]
	v_mfma_f32_16x16x32_bf16 v[38:41], v[182:185], v[206:209], v[38:41]
	v_mfma_f32_16x16x32_bf16 v[30:33], v[190:193], v[206:209], v[30:33]
	v_mfma_f32_16x16x32_bf16 v[22:25], v[182:185], v[214:217], v[22:25]
	v_mfma_f32_16x16x32_bf16 v[14:17], v[190:193], v[214:217], v[14:17]
	v_mfma_f32_16x16x32_bf16 v[6:9], v[182:185], v[222:225], v[6:9]
	v_mfma_f32_16x16x32_bf16 v[2:5], v[190:193], v[222:225], v[2:5]
	s_barrier
	s_setprio 0
	ds_read_b128 v[160:163], v139
	ds_read_b128 v[164:167], v139 offset:1024
	ds_read_b128 v[168:171], v139 offset:2048
	ds_read_b128 v[172:175], v139 offset:3072
	ds_read_b128 v[178:181], v159
	ds_read_b128 v[182:185], v159 offset:1024
	ds_read_b128 v[186:189], v159 offset:2048
	ds_read_b128 v[190:193], v159 offset:3072
	s_add_u32 s2, s2, 0x4000
	s_addc_u32 s3, s3, 0
	s_mov_b32 m0, s21
	v_lshl_add_u64 v[226:227], s[2:3], 0, v[140:141]
	ds_read_b128 v[194:197], v137 offset:32768
	ds_read_b128 v[198:201], v137 offset:33792
	ds_read_b128 v[202:205], v137 offset:34816
	ds_read_b128 v[206:209], v137 offset:35840
	ds_read_b128 v[210:213], v137 offset:36864
	ds_read_b128 v[214:217], v137 offset:37888
	ds_read_b128 v[218:221], v137 offset:38912
	ds_read_b128 v[222:225], v137 offset:39936
	global_load_lds_dwordx4 v[226:227], off
	v_lshl_add_u64 v[226:227], s[2:3], 0, v[144:145]
	s_mov_b32 m0, s22
	s_nop 0
	global_load_lds_dwordx4 v[226:227], off
	s_waitcnt vmcnt(8)
	s_waitcnt lgkmcnt(0)
	s_setprio 1
	s_barrier
	v_mfma_f32_16x16x32_bf16 v[126:129], v[160:163], v[194:197], v[126:129]
	v_mfma_f32_16x16x32_bf16 v[122:125], v[168:171], v[194:197], v[122:125]
	v_mfma_f32_16x16x32_bf16 v[114:117], v[160:163], v[202:205], v[114:117]
	v_mfma_f32_16x16x32_bf16 v[106:109], v[168:171], v[202:205], v[106:109]
	v_mfma_f32_16x16x32_bf16 v[98:101], v[160:163], v[210:213], v[98:101]
	v_mfma_f32_16x16x32_bf16 v[90:93], v[168:171], v[210:213], v[90:93]
	v_mfma_f32_16x16x32_bf16 v[82:85], v[160:163], v[218:221], v[82:85]
	v_mfma_f32_16x16x32_bf16 v[74:77], v[168:171], v[218:221], v[74:77]
	v_mfma_f32_16x16x32_bf16 v[126:129], v[164:167], v[198:201], v[126:129]
	v_mfma_f32_16x16x32_bf16 v[122:125], v[172:175], v[198:201], v[122:125]
	v_mfma_f32_16x16x32_bf16 v[114:117], v[164:167], v[206:209], v[114:117]
	v_mfma_f32_16x16x32_bf16 v[106:109], v[172:175], v[206:209], v[106:109]
	v_mfma_f32_16x16x32_bf16 v[98:101], v[164:167], v[214:217], v[98:101]
	v_mfma_f32_16x16x32_bf16 v[90:93], v[172:175], v[214:217], v[90:93]
	v_mfma_f32_16x16x32_bf16 v[82:85], v[164:167], v[222:225], v[82:85]
	v_mfma_f32_16x16x32_bf16 v[74:77], v[172:175], v[222:225], v[74:77]
	s_setprio 0
	s_setprio 1
	v_mfma_f32_16x16x32_bf16 v[118:121], v[178:181], v[194:197], v[118:121]
	v_mfma_f32_16x16x32_bf16 v[110:113], v[186:189], v[194:197], v[110:113]
	v_mfma_f32_16x16x32_bf16 v[102:105], v[178:181], v[202:205], v[102:105]
	v_mfma_f32_16x16x32_bf16 v[94:97], v[186:189], v[202:205], v[94:97]
	v_mfma_f32_16x16x32_bf16 v[86:89], v[178:181], v[210:213], v[86:89]
	v_mfma_f32_16x16x32_bf16 v[78:81], v[186:189], v[210:213], v[78:81]
	v_mfma_f32_16x16x32_bf16 v[70:73], v[178:181], v[218:221], v[70:73]
	v_mfma_f32_16x16x32_bf16 v[66:69], v[186:189], v[218:221], v[66:69]
	v_mfma_f32_16x16x32_bf16 v[118:121], v[182:185], v[198:201], v[118:121]
	v_mfma_f32_16x16x32_bf16 v[110:113], v[190:193], v[198:201], v[110:113]
	v_mfma_f32_16x16x32_bf16 v[102:105], v[182:185], v[206:209], v[102:105]
	v_mfma_f32_16x16x32_bf16 v[94:97], v[190:193], v[206:209], v[94:97]
	v_mfma_f32_16x16x32_bf16 v[86:89], v[182:185], v[214:217], v[86:89]
	v_mfma_f32_16x16x32_bf16 v[78:81], v[190:193], v[214:217], v[78:81]
	v_mfma_f32_16x16x32_bf16 v[70:73], v[182:185], v[222:225], v[70:73]
	v_mfma_f32_16x16x32_bf16 v[66:69], v[190:193], v[222:225], v[66:69]
	s_barrier
	s_setprio 0
	s_add_u32 s2, s14, 0x8000
	s_addc_u32 s3, s15, 0
	s_mov_b32 m0, s35
	v_lshl_add_u64 v[226:227], s[2:3], 0, v[142:143]
	ds_read_b128 v[194:197], v137 offset:49152
	ds_read_b128 v[198:201], v137 offset:50176
	ds_read_b128 v[202:205], v137 offset:51200
	ds_read_b128 v[206:209], v137 offset:52224
	ds_read_b128 v[210:213], v137 offset:53248
	ds_read_b128 v[214:217], v137 offset:54272
	ds_read_b128 v[218:221], v137 offset:55296
	ds_read_b128 v[222:225], v137 offset:56320
	global_load_lds_dwordx4 v[226:227], off
	v_lshl_add_u64 v[226:227], s[2:3], 0, v[146:147]
	s_add_u32 s2, s14, 0xc000
	s_mov_b32 m0, s36
	s_addc_u32 s3, s15, 0
	global_load_lds_dwordx4 v[226:227], off
	v_lshl_add_u64 v[226:227], s[2:3], 0, v[142:143]
	s_mov_b32 m0, s37
	s_nop 0
	global_load_lds_dwordx4 v[226:227], off
	v_lshl_add_u64 v[226:227], s[2:3], 0, v[146:147]
	s_mov_b32 m0, s38
	s_nop 0
	global_load_lds_dwordx4 v[226:227], off
	v_lshl_add_u64 v[226:227], s[12:13], 0, v[140:141]
	s_mov_b32 m0, s24
	s_nop 0
	global_load_lds_dwordx4 v[226:227], off
	v_lshl_add_u64 v[226:227], s[12:13], 0, v[144:145]
	s_mov_b32 m0, s25
	s_nop 0
	global_load_lds_dwordx4 v[226:227], off
	s_waitcnt vmcnt(8)
	s_waitcnt lgkmcnt(0)
	s_setprio 1
	s_barrier
	v_mfma_f32_16x16x32_bf16 v[62:65], v[160:163], v[194:197], v[62:65]
	v_mfma_f32_16x16x32_bf16 v[58:61], v[168:171], v[194:197], v[58:61]
	v_mfma_f32_16x16x32_bf16 v[50:53], v[160:163], v[202:205], v[50:53]
	v_mfma_f32_16x16x32_bf16 v[42:45], v[168:171], v[202:205], v[42:45]
	v_mfma_f32_16x16x32_bf16 v[34:37], v[160:163], v[210:213], v[34:37]
	v_mfma_f32_16x16x32_bf16 v[26:29], v[168:171], v[210:213], v[26:29]
	v_mfma_f32_16x16x32_bf16 v[18:21], v[160:163], v[218:221], v[18:21]
	v_mfma_f32_16x16x32_bf16 v[10:13], v[168:171], v[218:221], v[10:13]
	v_mfma_f32_16x16x32_bf16 v[62:65], v[164:167], v[198:201], v[62:65]
	v_mfma_f32_16x16x32_bf16 v[58:61], v[172:175], v[198:201], v[58:61]
	v_mfma_f32_16x16x32_bf16 v[50:53], v[164:167], v[206:209], v[50:53]
	v_mfma_f32_16x16x32_bf16 v[42:45], v[172:175], v[206:209], v[42:45]
	v_mfma_f32_16x16x32_bf16 v[34:37], v[164:167], v[214:217], v[34:37]
	v_mfma_f32_16x16x32_bf16 v[26:29], v[172:175], v[214:217], v[26:29]
	v_mfma_f32_16x16x32_bf16 v[18:21], v[164:167], v[222:225], v[18:21]
	v_mfma_f32_16x16x32_bf16 v[10:13], v[172:175], v[222:225], v[10:13]
	s_setprio 0
	s_setprio 1
	v_mfma_f32_16x16x32_bf16 v[54:57], v[178:181], v[194:197], v[54:57]
	v_mfma_f32_16x16x32_bf16 v[46:49], v[186:189], v[194:197], v[46:49]
	v_mfma_f32_16x16x32_bf16 v[38:41], v[178:181], v[202:205], v[38:41]
	v_mfma_f32_16x16x32_bf16 v[30:33], v[186:189], v[202:205], v[30:33]
	v_mfma_f32_16x16x32_bf16 v[22:25], v[178:181], v[210:213], v[22:25]
	v_mfma_f32_16x16x32_bf16 v[14:17], v[186:189], v[210:213], v[14:17]
	v_mfma_f32_16x16x32_bf16 v[6:9], v[178:181], v[218:221], v[6:9]
	v_mfma_f32_16x16x32_bf16 v[2:5], v[186:189], v[218:221], v[2:5]
	v_mfma_f32_16x16x32_bf16 v[54:57], v[182:185], v[198:201], v[54:57]
	v_mfma_f32_16x16x32_bf16 v[46:49], v[190:193], v[198:201], v[46:49]
	v_mfma_f32_16x16x32_bf16 v[38:41], v[182:185], v[206:209], v[38:41]
	v_mfma_f32_16x16x32_bf16 v[30:33], v[190:193], v[206:209], v[30:33]
	v_mfma_f32_16x16x32_bf16 v[22:25], v[182:185], v[214:217], v[22:25]
	v_mfma_f32_16x16x32_bf16 v[14:17], v[190:193], v[214:217], v[14:17]
	v_mfma_f32_16x16x32_bf16 v[6:9], v[182:185], v[222:225], v[6:9]
	v_mfma_f32_16x16x32_bf16 v[2:5], v[190:193], v[222:225], v[2:5]
	s_barrier
	s_setprio 0
	s_add_i32 s26, s26, 2
	s_add_u32 s8, s8, 0x10000
	s_addc_u32 s9, s9, 0
	s_cmp_gt_u32 s26, 41
	s_cbranch_scc0 .LBB0_437
	s_cmpk_lt_u32 s16, 0x100
	s_cbranch_scc0 .LBB0_440
	s_barrier

.Lpk451_peel:
	ds_read_b128 v[152:155], v149
	ds_read_b128 v[156:159], v149 offset:1024
	ds_read_b128 v[160:163], v149 offset:2048
	ds_read_b128 v[164:167], v149 offset:3072
	ds_read_b128 v[168:171], v150
	ds_read_b128 v[172:175], v150 offset:1024
	ds_read_b128 v[178:181], v150 offset:2048
	ds_read_b128 v[182:185], v150 offset:3072
	s_add_u32 s2, s28, 0xfffc0080
	s_addc_u32 s3, s29, -1
	s_cmp_eq_u32 s52, 12
	s_cselect_b32 s3, s11, s3
	s_cselect_b32 s2, s13, s2
	s_cselect_b32 s31, s44, s47
	s_cselect_b32 s30, s45, s46
	v_lshl_add_u64 v[146:147], s[28:29], 0, v[140:141]
	s_add_i32 m0, s25, 0xc000
	ds_read_b128 v[186:189], v151
	ds_read_b128 v[190:193], v151 offset:1024
	ds_read_b128 v[194:197], v151 offset:2048
	ds_read_b128 v[198:201], v151 offset:3072
	ds_read_b128 v[202:205], v151 offset:4096
	ds_read_b128 v[206:209], v151 offset:5120
	ds_read_b128 v[210:213], v151 offset:6144
	ds_read_b128 v[214:217], v151 offset:7168
	global_load_lds_dwordx4 v[146:147], off
	v_lshl_add_u64 v[146:147], s[28:29], 0, v[142:143]
	s_add_i32 m0, s25, 0xe000
	s_nop 0
	global_load_lds_dwordx4 v[146:147], off
	s_waitcnt vmcnt(8)
	s_waitcnt lgkmcnt(0)
	s_setprio 1
	s_barrier
	v_mfma_f32_16x16x32_bf16 v[126:129], v[152:155], v[186:189], 0
	v_mfma_f32_16x16x32_bf16 v[122:125], v[160:163], v[186:189], 0
	v_mfma_f32_16x16x32_bf16 v[110:113], v[152:155], v[194:197], 0
	v_mfma_f32_16x16x32_bf16 v[106:109], v[160:163], v[194:197], 0
	v_mfma_f32_16x16x32_bf16 v[94:97], v[152:155], v[202:205], 0
	v_mfma_f32_16x16x32_bf16 v[90:93], v[160:163], v[202:205], 0
	v_mfma_f32_16x16x32_bf16 v[78:81], v[152:155], v[210:213], 0
	v_mfma_f32_16x16x32_bf16 v[74:77], v[160:163], v[210:213], 0
	v_mfma_f32_16x16x32_bf16 v[126:129], v[156:159], v[190:193], v[126:129]
	v_mfma_f32_16x16x32_bf16 v[122:125], v[164:167], v[190:193], v[122:125]
	v_mfma_f32_16x16x32_bf16 v[110:113], v[156:159], v[198:201], v[110:113]
	v_mfma_f32_16x16x32_bf16 v[106:109], v[164:167], v[198:201], v[106:109]
	v_mfma_f32_16x16x32_bf16 v[94:97], v[156:159], v[206:209], v[94:97]
	v_mfma_f32_16x16x32_bf16 v[90:93], v[164:167], v[206:209], v[90:93]
	v_mfma_f32_16x16x32_bf16 v[78:81], v[156:159], v[214:217], v[78:81]
	v_mfma_f32_16x16x32_bf16 v[74:77], v[164:167], v[214:217], v[74:77]
	s_setprio 0
	s_setprio 1
	v_mfma_f32_16x16x32_bf16 v[118:121], v[168:171], v[186:189], 0
	v_mfma_f32_16x16x32_bf16 v[114:117], v[178:181], v[186:189], 0
	v_mfma_f32_16x16x32_bf16 v[102:105], v[168:171], v[194:197], 0
	v_mfma_f32_16x16x32_bf16 v[98:101], v[178:181], v[194:197], 0
	v_mfma_f32_16x16x32_bf16 v[86:89], v[168:171], v[202:205], 0
	v_mfma_f32_16x16x32_bf16 v[82:85], v[178:181], v[202:205], 0
	v_mfma_f32_16x16x32_bf16 v[70:73], v[168:171], v[210:213], 0
	v_mfma_f32_16x16x32_bf16 v[66:69], v[178:181], v[210:213], 0
	v_mfma_f32_16x16x32_bf16 v[118:121], v[172:175], v[190:193], v[118:121]
	v_mfma_f32_16x16x32_bf16 v[114:117], v[182:185], v[190:193], v[114:117]
	v_mfma_f32_16x16x32_bf16 v[102:105], v[172:175], v[198:201], v[102:105]
	v_mfma_f32_16x16x32_bf16 v[98:101], v[182:185], v[198:201], v[98:101]
	v_mfma_f32_16x16x32_bf16 v[86:89], v[172:175], v[206:209], v[86:89]
	v_mfma_f32_16x16x32_bf16 v[82:85], v[182:185], v[206:209], v[82:85]
	v_mfma_f32_16x16x32_bf16 v[70:73], v[172:175], v[214:217], v[70:73]
	v_mfma_f32_16x16x32_bf16 v[66:69], v[182:185], v[214:217], v[66:69]
	s_barrier
	s_setprio 0
	s_add_i32 s53, s42, s34
	v_lshl_add_u64 v[146:147], s[30:31], 0, v[132:133]
	s_mov_b32 m0, s53
	ds_read_b128 v[186:189], v151 offset:16384
	ds_read_b128 v[190:193], v151 offset:17408
	ds_read_b128 v[194:197], v151 offset:18432
	ds_read_b128 v[198:201], v151 offset:19456
	ds_read_b128 v[202:205], v151 offset:20480
	ds_read_b128 v[206:209], v151 offset:21504
	ds_read_b128 v[210:213], v151 offset:22528
	ds_read_b128 v[214:217], v151 offset:23552
	global_load_lds_dwordx4 v[146:147], off
	s_add_i32 m0, s53, 0x2000
	s_add_u32 s54, s30, 0x40000
	v_lshl_add_u64 v[218:219], s[30:31], 0, v[136:137]
	s_addc_u32 s55, s31, 0
	s_add_i32 s53, s43, s34
	global_load_lds_dwordx4 v[218:219], off
	v_lshl_add_u64 v[220:221], s[54:55], 0, v[132:133]
	s_mov_b32 m0, s53
	v_lshl_add_u64 v[222:223], s[2:3], 0, v[134:135]
	global_load_lds_dwordx4 v[220:221], off
	v_lshl_add_u64 v[220:221], s[54:55], 0, v[136:137]
	s_add_i32 m0, s53, 0x2000
	s_nop 0
	global_load_lds_dwordx4 v[220:221], off
	v_lshl_add_u64 v[220:221], s[2:3], 0, v[130:131]
	s_mov_b32 m0, s25
	s_nop 0
	global_load_lds_dwordx4 v[220:221], off
	s_mov_b32 m0, s27
	s_nop 0
	global_load_lds_dwordx4 v[222:223], off
	s_waitcnt vmcnt(8)
	s_waitcnt lgkmcnt(0)
	s_setprio 1
	s_barrier
	v_mfma_f32_16x16x32_bf16 v[62:65], v[152:155], v[186:189], 0
	v_mfma_f32_16x16x32_bf16 v[58:61], v[160:163], v[186:189], 0
	v_mfma_f32_16x16x32_bf16 v[46:49], v[152:155], v[194:197], 0
	v_mfma_f32_16x16x32_bf16 v[42:45], v[160:163], v[194:197], 0
	v_mfma_f32_16x16x32_bf16 v[30:33], v[152:155], v[202:205], 0
	v_mfma_f32_16x16x32_bf16 v[26:29], v[160:163], v[202:205], 0
	v_mfma_f32_16x16x32_bf16 v[14:17], v[152:155], v[210:213], 0
	v_mfma_f32_16x16x32_bf16 v[10:13], v[160:163], v[210:213], 0
	v_mfma_f32_16x16x32_bf16 v[62:65], v[156:159], v[190:193], v[62:65]
	v_mfma_f32_16x16x32_bf16 v[58:61], v[164:167], v[190:193], v[58:61]
	v_mfma_f32_16x16x32_bf16 v[46:49], v[156:159], v[198:201], v[46:49]
	v_mfma_f32_16x16x32_bf16 v[42:45], v[164:167], v[198:201], v[42:45]
	v_mfma_f32_16x16x32_bf16 v[30:33], v[156:159], v[206:209], v[30:33]
	v_mfma_f32_16x16x32_bf16 v[26:29], v[164:167], v[206:209], v[26:29]
	v_mfma_f32_16x16x32_bf16 v[14:17], v[156:159], v[214:217], v[14:17]
	v_mfma_f32_16x16x32_bf16 v[10:13], v[164:167], v[214:217], v[10:13]
	s_setprio 0
	s_setprio 1
	v_mfma_f32_16x16x32_bf16 v[54:57], v[168:171], v[186:189], 0
	v_mfma_f32_16x16x32_bf16 v[50:53], v[178:181], v[186:189], 0
	v_mfma_f32_16x16x32_bf16 v[38:41], v[168:171], v[194:197], 0
	v_mfma_f32_16x16x32_bf16 v[34:37], v[178:181], v[194:197], 0
	v_mfma_f32_16x16x32_bf16 v[22:25], v[168:171], v[202:205], 0
	v_mfma_f32_16x16x32_bf16 v[18:21], v[178:181], v[202:205], 0
	v_mfma_f32_16x16x32_bf16 v[6:9], v[168:171], v[210:213], 0
	v_mfma_f32_16x16x32_bf16 v[2:5], v[178:181], v[210:213], 0
	v_mfma_f32_16x16x32_bf16 v[54:57], v[172:175], v[190:193], v[54:57]
	v_mfma_f32_16x16x32_bf16 v[50:53], v[182:185], v[190:193], v[50:53]
	v_mfma_f32_16x16x32_bf16 v[38:41], v[172:175], v[198:201], v[38:41]
	v_mfma_f32_16x16x32_bf16 v[34:37], v[182:185], v[198:201], v[34:37]
	v_mfma_f32_16x16x32_bf16 v[22:25], v[172:175], v[206:209], v[22:25]
	v_mfma_f32_16x16x32_bf16 v[18:21], v[182:185], v[206:209], v[18:21]
	v_mfma_f32_16x16x32_bf16 v[6:9], v[172:175], v[214:217], v[6:9]
	v_mfma_f32_16x16x32_bf16 v[2:5], v[182:185], v[214:217], v[2:5]
	s_barrier
	s_setprio 0
	s_add_i32 s53, 0, 0x18000
	s_add_i32 s54, 0, 0x1c000
	v_add_u32_e32 v164, s53, v148
	v_add_u32_e32 v176, s54, v148
	ds_read_b128 v[152:155], v164
	ds_read_b128 v[156:159], v164 offset:1024
	ds_read_b128 v[160:163], v164 offset:2048
	ds_read_b128 v[164:167], v164 offset:3072
	ds_read_b128 v[168:171], v176
	ds_read_b128 v[172:175], v176 offset:1024
	ds_read_b128 v[178:181], v176 offset:2048
	ds_read_b128 v[182:185], v176 offset:3072
	s_add_u32 s2, s2, 0x40000
	s_addc_u32 s3, s3, 0
	s_mov_b32 m0, s36
	v_lshl_add_u64 v[224:225], s[2:3], 0, v[130:131]
	ds_read_b128 v[186:189], v151 offset:32768
	ds_read_b128 v[190:193], v151 offset:33792
	ds_read_b128 v[194:197], v151 offset:34816
	ds_read_b128 v[198:201], v151 offset:35840
	ds_read_b128 v[202:205], v151 offset:36864
	ds_read_b128 v[206:209], v151 offset:37888
	ds_read_b128 v[210:213], v151 offset:38912
	ds_read_b128 v[214:217], v151 offset:39936
	global_load_lds_dwordx4 v[224:225], off
	v_lshl_add_u64 v[224:225], s[2:3], 0, v[134:135]
	s_mov_b32 m0, s37
	s_nop 0
	global_load_lds_dwordx4 v[224:225], off
	s_waitcnt vmcnt(8)
	s_waitcnt lgkmcnt(0)
	s_setprio 1
	s_barrier
	v_mfma_f32_16x16x32_bf16 v[126:129], v[152:155], v[186:189], v[126:129]
	v_mfma_f32_16x16x32_bf16 v[122:125], v[160:163], v[186:189], v[122:125]
	v_mfma_f32_16x16x32_bf16 v[110:113], v[152:155], v[194:197], v[110:113]
	v_mfma_f32_16x16x32_bf16 v[106:109], v[160:163], v[194:197], v[106:109]
	v_mfma_f32_16x16x32_bf16 v[94:97], v[152:155], v[202:205], v[94:97]
	v_mfma_f32_16x16x32_bf16 v[90:93], v[160:163], v[202:205], v[90:93]
	v_mfma_f32_16x16x32_bf16 v[78:81], v[152:155], v[210:213], v[78:81]
	v_mfma_f32_16x16x32_bf16 v[74:77], v[160:163], v[210:213], v[74:77]
	v_mfma_f32_16x16x32_bf16 v[126:129], v[156:159], v[190:193], v[126:129]
	v_mfma_f32_16x16x32_bf16 v[122:125], v[164:167], v[190:193], v[122:125]
	v_mfma_f32_16x16x32_bf16 v[110:113], v[156:159], v[198:201], v[110:113]
	v_mfma_f32_16x16x32_bf16 v[106:109], v[164:167], v[198:201], v[106:109]
	v_mfma_f32_16x16x32_bf16 v[94:97], v[156:159], v[206:209], v[94:97]
	v_mfma_f32_16x16x32_bf16 v[90:93], v[164:167], v[206:209], v[90:93]
	v_mfma_f32_16x16x32_bf16 v[78:81], v[156:159], v[214:217], v[78:81]
	v_mfma_f32_16x16x32_bf16 v[74:77], v[164:167], v[214:217], v[74:77]
	s_setprio 0
	s_setprio 1
	v_mfma_f32_16x16x32_bf16 v[118:121], v[168:171], v[186:189], v[118:121]
	v_mfma_f32_16x16x32_bf16 v[114:117], v[178:181], v[186:189], v[114:117]
	v_mfma_f32_16x16x32_bf16 v[102:105], v[168:171], v[194:197], v[102:105]
	v_mfma_f32_16x16x32_bf16 v[98:101], v[178:181], v[194:197], v[98:101]
	v_mfma_f32_16x16x32_bf16 v[86:89], v[168:171], v[202:205], v[86:89]
	v_mfma_f32_16x16x32_bf16 v[82:85], v[178:181], v[202:205], v[82:85]
	v_mfma_f32_16x16x32_bf16 v[70:73], v[168:171], v[210:213], v[70:73]
	v_mfma_f32_16x16x32_bf16 v[66:69], v[178:181], v[210:213], v[66:69]
	v_mfma_f32_16x16x32_bf16 v[118:121], v[172:175], v[190:193], v[118:121]
	v_mfma_f32_16x16x32_bf16 v[114:117], v[182:185], v[190:193], v[114:117]
	v_mfma_f32_16x16x32_bf16 v[102:105], v[172:175], v[198:201], v[102:105]
	v_mfma_f32_16x16x32_bf16 v[98:101], v[182:185], v[198:201], v[98:101]
	v_mfma_f32_16x16x32_bf16 v[86:89], v[172:175], v[206:209], v[86:89]
	v_mfma_f32_16x16x32_bf16 v[82:85], v[182:185], v[206:209], v[82:85]
	v_mfma_f32_16x16x32_bf16 v[70:73], v[172:175], v[214:217], v[70:73]
	v_mfma_f32_16x16x32_bf16 v[66:69], v[182:185], v[214:217], v[66:69]
	s_barrier
	s_setprio 0
	s_add_i32 s2, s53, s34
	v_lshl_add_u64 v[146:147], v[146:147], 0, s[6:7]
	s_mov_b32 m0, s2
	ds_read_b128 v[186:189], v151 offset:49152
	ds_read_b128 v[190:193], v151 offset:50176
	ds_read_b128 v[194:197], v151 offset:51200
	ds_read_b128 v[198:201], v151 offset:52224
	ds_read_b128 v[202:205], v151 offset:53248
	ds_read_b128 v[206:209], v151 offset:54272
	ds_read_b128 v[210:213], v151 offset:55296
	ds_read_b128 v[214:217], v151 offset:56320
	global_load_lds_dwordx4 v[146:147], off
	s_add_i32 m0, s2, 0x2000
	s_add_u32 s2, s30, 0x40080
	v_lshl_add_u64 v[146:147], v[218:219], 0, s[6:7]
	s_addc_u32 s3, s31, 0
	s_add_i32 s30, s54, s34
	global_load_lds_dwordx4 v[146:147], off
	v_lshl_add_u64 v[146:147], s[2:3], 0, v[132:133]
	s_mov_b32 m0, s30
	s_nop 0
	global_load_lds_dwordx4 v[146:147], off
	v_lshl_add_u64 v[146:147], s[2:3], 0, v[136:137]
	s_add_i32 m0, s30, 0x2000
	s_nop 0
	global_load_lds_dwordx4 v[146:147], off
	v_lshl_add_u64 v[146:147], v[220:221], 0, s[6:7]
	s_mov_b32 m0, s39
	s_nop 0
	global_load_lds_dwordx4 v[146:147], off
	v_lshl_add_u64 v[146:147], v[222:223], 0, s[6:7]
	s_mov_b32 m0, s40
	s_nop 0
	global_load_lds_dwordx4 v[146:147], off
	s_waitcnt vmcnt(8)
	s_waitcnt lgkmcnt(0)
	s_setprio 1
	s_barrier
	v_mfma_f32_16x16x32_bf16 v[62:65], v[152:155], v[186:189], v[62:65]
	v_mfma_f32_16x16x32_bf16 v[58:61], v[160:163], v[186:189], v[58:61]
	v_mfma_f32_16x16x32_bf16 v[46:49], v[152:155], v[194:197], v[46:49]
	v_mfma_f32_16x16x32_bf16 v[42:45], v[160:163], v[194:197], v[42:45]
	v_mfma_f32_16x16x32_bf16 v[30:33], v[152:155], v[202:205], v[30:33]
	v_mfma_f32_16x16x32_bf16 v[26:29], v[160:163], v[202:205], v[26:29]
	v_mfma_f32_16x16x32_bf16 v[14:17], v[152:155], v[210:213], v[14:17]
	v_mfma_f32_16x16x32_bf16 v[10:13], v[160:163], v[210:213], v[10:13]
	v_mfma_f32_16x16x32_bf16 v[62:65], v[156:159], v[190:193], v[62:65]
	v_mfma_f32_16x16x32_bf16 v[58:61], v[164:167], v[190:193], v[58:61]
	v_mfma_f32_16x16x32_bf16 v[46:49], v[156:159], v[198:201], v[46:49]
	v_mfma_f32_16x16x32_bf16 v[42:45], v[164:167], v[198:201], v[42:45]
	v_mfma_f32_16x16x32_bf16 v[30:33], v[156:159], v[206:209], v[30:33]
	v_mfma_f32_16x16x32_bf16 v[26:29], v[164:167], v[206:209], v[26:29]
	v_mfma_f32_16x16x32_bf16 v[14:17], v[156:159], v[214:217], v[14:17]
	v_mfma_f32_16x16x32_bf16 v[10:13], v[164:167], v[214:217], v[10:13]
	s_setprio 0
	s_setprio 1
	v_mfma_f32_16x16x32_bf16 v[54:57], v[168:171], v[186:189], v[54:57]
	v_mfma_f32_16x16x32_bf16 v[50:53], v[178:181], v[186:189], v[50:53]
	v_mfma_f32_16x16x32_bf16 v[38:41], v[168:171], v[194:197], v[38:41]
	v_mfma_f32_16x16x32_bf16 v[34:37], v[178:181], v[194:197], v[34:37]
	v_mfma_f32_16x16x32_bf16 v[22:25], v[168:171], v[202:205], v[22:25]
	v_mfma_f32_16x16x32_bf16 v[18:21], v[178:181], v[202:205], v[18:21]
	v_mfma_f32_16x16x32_bf16 v[6:9], v[168:171], v[210:213], v[6:9]
	v_mfma_f32_16x16x32_bf16 v[2:5], v[178:181], v[210:213], v[2:5]
	v_mfma_f32_16x16x32_bf16 v[54:57], v[172:175], v[190:193], v[54:57]
	v_mfma_f32_16x16x32_bf16 v[50:53], v[182:185], v[190:193], v[50:53]
	v_mfma_f32_16x16x32_bf16 v[38:41], v[172:175], v[198:201], v[38:41]
	v_mfma_f32_16x16x32_bf16 v[34:37], v[182:185], v[198:201], v[34:37]
	v_mfma_f32_16x16x32_bf16 v[22:25], v[172:175], v[206:209], v[22:25]
	v_mfma_f32_16x16x32_bf16 v[18:21], v[182:185], v[206:209], v[18:21]
	v_mfma_f32_16x16x32_bf16 v[6:9], v[172:175], v[214:217], v[6:9]
	v_mfma_f32_16x16x32_bf16 v[2:5], v[182:185], v[214:217], v[2:5]
	s_barrier
	s_setprio 0
	s_add_i32 s52, s52, 2
	s_add_u32 s28, s28, 0x100
	s_addc_u32 s29, s29, 0
	s_add_u32 s46, s46, 0x100
	s_addc_u32 s47, s47, 0
	s_cmp_gt_u32 s52, 13
	s_cbranch_scc0 .LBB0_451
	s_branch .Lpk451_exit
.LBB0_451:
	ds_read_b128 v[152:155], v149
	ds_read_b128 v[156:159], v149 offset:1024
	ds_read_b128 v[160:163], v149 offset:2048
	ds_read_b128 v[164:167], v149 offset:3072
	ds_read_b128 v[168:171], v150
	ds_read_b128 v[172:175], v150 offset:1024
	ds_read_b128 v[178:181], v150 offset:2048
	ds_read_b128 v[182:185], v150 offset:3072
	s_add_u32 s2, s28, 0xfffc0080
	s_addc_u32 s3, s29, -1
	s_cmp_eq_u32 s52, 12
	s_cselect_b32 s3, s11, s3
	s_cselect_b32 s2, s13, s2
	s_cselect_b32 s31, s44, s47
	s_cselect_b32 s30, s45, s46
	v_lshl_add_u64 v[146:147], s[28:29], 0, v[140:141]
	s_add_i32 m0, s25, 0xc000
	ds_read_b128 v[186:189], v151
	ds_read_b128 v[190:193], v151 offset:1024
	ds_read_b128 v[194:197], v151 offset:2048
	ds_read_b128 v[198:201], v151 offset:3072
	ds_read_b128 v[202:205], v151 offset:4096
	ds_read_b128 v[206:209], v151 offset:5120
	ds_read_b128 v[210:213], v151 offset:6144
	ds_read_b128 v[214:217], v151 offset:7168
	global_load_lds_dwordx4 v[146:147], off
	v_lshl_add_u64 v[146:147], s[28:29], 0, v[142:143]
	s_add_i32 m0, s25, 0xe000
	s_nop 0
	global_load_lds_dwordx4 v[146:147], off
	s_waitcnt vmcnt(8)
	s_waitcnt lgkmcnt(0)
	s_setprio 1
	s_barrier
	v_mfma_f32_16x16x32_bf16 v[126:129], v[152:155], v[186:189], v[126:129]
	v_mfma_f32_16x16x32_bf16 v[122:125], v[160:163], v[186:189], v[122:125]
	v_mfma_f32_16x16x32_bf16 v[110:113], v[152:155], v[194:197], v[110:113]
	v_mfma_f32_16x16x32_bf16 v[106:109], v[160:163], v[194:197], v[106:109]
	v_mfma_f32_16x16x32_bf16 v[94:97], v[152:155], v[202:205], v[94:97]
	v_mfma_f32_16x16x32_bf16 v[90:93], v[160:163], v[202:205], v[90:93]
	v_mfma_f32_16x16x32_bf16 v[78:81], v[152:155], v[210:213], v[78:81]
	v_mfma_f32_16x16x32_bf16 v[74:77], v[160:163], v[210:213], v[74:77]
	v_mfma_f32_16x16x32_bf16 v[126:129], v[156:159], v[190:193], v[126:129]
	v_mfma_f32_16x16x32_bf16 v[122:125], v[164:167], v[190:193], v[122:125]
	v_mfma_f32_16x16x32_bf16 v[110:113], v[156:159], v[198:201], v[110:113]
	v_mfma_f32_16x16x32_bf16 v[106:109], v[164:167], v[198:201], v[106:109]
	v_mfma_f32_16x16x32_bf16 v[94:97], v[156:159], v[206:209], v[94:97]
	v_mfma_f32_16x16x32_bf16 v[90:93], v[164:167], v[206:209], v[90:93]
	v_mfma_f32_16x16x32_bf16 v[78:81], v[156:159], v[214:217], v[78:81]
	v_mfma_f32_16x16x32_bf16 v[74:77], v[164:167], v[214:217], v[74:77]
	s_setprio 0
	s_setprio 1
	v_mfma_f32_16x16x32_bf16 v[118:121], v[168:171], v[186:189], v[118:121]
	v_mfma_f32_16x16x32_bf16 v[114:117], v[178:181], v[186:189], v[114:117]
	v_mfma_f32_16x16x32_bf16 v[102:105], v[168:171], v[194:197], v[102:105]
	v_mfma_f32_16x16x32_bf16 v[98:101], v[178:181], v[194:197], v[98:101]
	v_mfma_f32_16x16x32_bf16 v[86:89], v[168:171], v[202:205], v[86:89]
	v_mfma_f32_16x16x32_bf16 v[82:85], v[178:181], v[202:205], v[82:85]
	v_mfma_f32_16x16x32_bf16 v[70:73], v[168:171], v[210:213], v[70:73]
	v_mfma_f32_16x16x32_bf16 v[66:69], v[178:181], v[210:213], v[66:69]
	v_mfma_f32_16x16x32_bf16 v[118:121], v[172:175], v[190:193], v[118:121]
	v_mfma_f32_16x16x32_bf16 v[114:117], v[182:185], v[190:193], v[114:117]
	v_mfma_f32_16x16x32_bf16 v[102:105], v[172:175], v[198:201], v[102:105]
	v_mfma_f32_16x16x32_bf16 v[98:101], v[182:185], v[198:201], v[98:101]
	v_mfma_f32_16x16x32_bf16 v[86:89], v[172:175], v[206:209], v[86:89]
	v_mfma_f32_16x16x32_bf16 v[82:85], v[182:185], v[206:209], v[82:85]
	v_mfma_f32_16x16x32_bf16 v[70:73], v[172:175], v[214:217], v[70:73]
	v_mfma_f32_16x16x32_bf16 v[66:69], v[182:185], v[214:217], v[66:69]
	s_barrier
	s_setprio 0
	s_add_i32 s53, s42, s34
	v_lshl_add_u64 v[146:147], s[30:31], 0, v[132:133]
	s_mov_b32 m0, s53
	ds_read_b128 v[186:189], v151 offset:16384
	ds_read_b128 v[190:193], v151 offset:17408
	ds_read_b128 v[194:197], v151 offset:18432
	ds_read_b128 v[198:201], v151 offset:19456
	ds_read_b128 v[202:205], v151 offset:20480
	ds_read_b128 v[206:209], v151 offset:21504
	ds_read_b128 v[210:213], v151 offset:22528
	ds_read_b128 v[214:217], v151 offset:23552
	global_load_lds_dwordx4 v[146:147], off
	s_add_i32 m0, s53, 0x2000
	s_add_u32 s54, s30, 0x40000
	v_lshl_add_u64 v[218:219], s[30:31], 0, v[136:137]
	s_addc_u32 s55, s31, 0
	s_add_i32 s53, s43, s34
	global_load_lds_dwordx4 v[218:219], off
	v_lshl_add_u64 v[220:221], s[54:55], 0, v[132:133]
	s_mov_b32 m0, s53
	v_lshl_add_u64 v[222:223], s[2:3], 0, v[134:135]
	global_load_lds_dwordx4 v[220:221], off
	v_lshl_add_u64 v[220:221], s[54:55], 0, v[136:137]
	s_add_i32 m0, s53, 0x2000
	s_nop 0
	global_load_lds_dwordx4 v[220:221], off
	v_lshl_add_u64 v[220:221], s[2:3], 0, v[130:131]
	s_mov_b32 m0, s25
	s_nop 0
	global_load_lds_dwordx4 v[220:221], off
	s_mov_b32 m0, s27
	s_nop 0
	global_load_lds_dwordx4 v[222:223], off
	s_waitcnt vmcnt(8)
	s_waitcnt lgkmcnt(0)
	s_setprio 1
	s_barrier
	v_mfma_f32_16x16x32_bf16 v[62:65], v[152:155], v[186:189], v[62:65]
	v_mfma_f32_16x16x32_bf16 v[58:61], v[160:163], v[186:189], v[58:61]
	v_mfma_f32_16x16x32_bf16 v[46:49], v[152:155], v[194:197], v[46:49]
	v_mfma_f32_16x16x32_bf16 v[42:45], v[160:163], v[194:197], v[42:45]
	v_mfma_f32_16x16x32_bf16 v[30:33], v[152:155], v[202:205], v[30:33]
	v_mfma_f32_16x16x32_bf16 v[26:29], v[160:163], v[202:205], v[26:29]
	v_mfma_f32_16x16x32_bf16 v[14:17], v[152:155], v[210:213], v[14:17]
	v_mfma_f32_16x16x32_bf16 v[10:13], v[160:163], v[210:213], v[10:13]
	v_mfma_f32_16x16x32_bf16 v[62:65], v[156:159], v[190:193], v[62:65]
	v_mfma_f32_16x16x32_bf16 v[58:61], v[164:167], v[190:193], v[58:61]
	v_mfma_f32_16x16x32_bf16 v[46:49], v[156:159], v[198:201], v[46:49]
	v_mfma_f32_16x16x32_bf16 v[42:45], v[164:167], v[198:201], v[42:45]
	v_mfma_f32_16x16x32_bf16 v[30:33], v[156:159], v[206:209], v[30:33]
	v_mfma_f32_16x16x32_bf16 v[26:29], v[164:167], v[206:209], v[26:29]
	v_mfma_f32_16x16x32_bf16 v[14:17], v[156:159], v[214:217], v[14:17]
	v_mfma_f32_16x16x32_bf16 v[10:13], v[164:167], v[214:217], v[10:13]
	s_setprio 0
	s_setprio 1
	v_mfma_f32_16x16x32_bf16 v[54:57], v[168:171], v[186:189], v[54:57]
	v_mfma_f32_16x16x32_bf16 v[50:53], v[178:181], v[186:189], v[50:53]
	v_mfma_f32_16x16x32_bf16 v[38:41], v[168:171], v[194:197], v[38:41]
	v_mfma_f32_16x16x32_bf16 v[34:37], v[178:181], v[194:197], v[34:37]
	v_mfma_f32_16x16x32_bf16 v[22:25], v[168:171], v[202:205], v[22:25]
	v_mfma_f32_16x16x32_bf16 v[18:21], v[178:181], v[202:205], v[18:21]
	v_mfma_f32_16x16x32_bf16 v[6:9], v[168:171], v[210:213], v[6:9]
	v_mfma_f32_16x16x32_bf16 v[2:5], v[178:181], v[210:213], v[2:5]
	v_mfma_f32_16x16x32_bf16 v[54:57], v[172:175], v[190:193], v[54:57]
	v_mfma_f32_16x16x32_bf16 v[50:53], v[182:185], v[190:193], v[50:53]
	v_mfma_f32_16x16x32_bf16 v[38:41], v[172:175], v[198:201], v[38:41]
	v_mfma_f32_16x16x32_bf16 v[34:37], v[182:185], v[198:201], v[34:37]
	v_mfma_f32_16x16x32_bf16 v[22:25], v[172:175], v[206:209], v[22:25]
	v_mfma_f32_16x16x32_bf16 v[18:21], v[182:185], v[206:209], v[18:21]
	v_mfma_f32_16x16x32_bf16 v[6:9], v[172:175], v[214:217], v[6:9]
	v_mfma_f32_16x16x32_bf16 v[2:5], v[182:185], v[214:217], v[2:5]
	s_barrier
	s_setprio 0
	s_add_i32 s53, 0, 0x18000
	s_add_i32 s54, 0, 0x1c000
	v_add_u32_e32 v164, s53, v148
	v_add_u32_e32 v176, s54, v148
	ds_read_b128 v[152:155], v164
	ds_read_b128 v[156:159], v164 offset:1024
	ds_read_b128 v[160:163], v164 offset:2048
	ds_read_b128 v[164:167], v164 offset:3072
	ds_read_b128 v[168:171], v176
	ds_read_b128 v[172:175], v176 offset:1024
	ds_read_b128 v[178:181], v176 offset:2048
	ds_read_b128 v[182:185], v176 offset:3072
	s_add_u32 s2, s2, 0x40000
	s_addc_u32 s3, s3, 0
	s_mov_b32 m0, s36
	v_lshl_add_u64 v[224:225], s[2:3], 0, v[130:131]
	ds_read_b128 v[186:189], v151 offset:32768
	ds_read_b128 v[190:193], v151 offset:33792
	ds_read_b128 v[194:197], v151 offset:34816
	ds_read_b128 v[198:201], v151 offset:35840
	ds_read_b128 v[202:205], v151 offset:36864
	ds_read_b128 v[206:209], v151 offset:37888
	ds_read_b128 v[210:213], v151 offset:38912
	ds_read_b128 v[214:217], v151 offset:39936
	global_load_lds_dwordx4 v[224:225], off
	v_lshl_add_u64 v[224:225], s[2:3], 0, v[134:135]
	s_mov_b32 m0, s37
	s_nop 0
	global_load_lds_dwordx4 v[224:225], off
	s_waitcnt vmcnt(8)
	s_waitcnt lgkmcnt(0)
	s_setprio 1
	s_barrier
	v_mfma_f32_16x16x32_bf16 v[126:129], v[152:155], v[186:189], v[126:129]
	v_mfma_f32_16x16x32_bf16 v[122:125], v[160:163], v[186:189], v[122:125]
	v_mfma_f32_16x16x32_bf16 v[110:113], v[152:155], v[194:197], v[110:113]
	v_mfma_f32_16x16x32_bf16 v[106:109], v[160:163], v[194:197], v[106:109]
	v_mfma_f32_16x16x32_bf16 v[94:97], v[152:155], v[202:205], v[94:97]
	v_mfma_f32_16x16x32_bf16 v[90:93], v[160:163], v[202:205], v[90:93]
	v_mfma_f32_16x16x32_bf16 v[78:81], v[152:155], v[210:213], v[78:81]
	v_mfma_f32_16x16x32_bf16 v[74:77], v[160:163], v[210:213], v[74:77]
	v_mfma_f32_16x16x32_bf16 v[126:129], v[156:159], v[190:193], v[126:129]
	v_mfma_f32_16x16x32_bf16 v[122:125], v[164:167], v[190:193], v[122:125]
	v_mfma_f32_16x16x32_bf16 v[110:113], v[156:159], v[198:201], v[110:113]
	v_mfma_f32_16x16x32_bf16 v[106:109], v[164:167], v[198:201], v[106:109]
	v_mfma_f32_16x16x32_bf16 v[94:97], v[156:159], v[206:209], v[94:97]
	v_mfma_f32_16x16x32_bf16 v[90:93], v[164:167], v[206:209], v[90:93]
	v_mfma_f32_16x16x32_bf16 v[78:81], v[156:159], v[214:217], v[78:81]
	v_mfma_f32_16x16x32_bf16 v[74:77], v[164:167], v[214:217], v[74:77]
	s_setprio 0
	s_setprio 1
	v_mfma_f32_16x16x32_bf16 v[118:121], v[168:171], v[186:189], v[118:121]
	v_mfma_f32_16x16x32_bf16 v[114:117], v[178:181], v[186:189], v[114:117]
	v_mfma_f32_16x16x32_bf16 v[102:105], v[168:171], v[194:197], v[102:105]
	v_mfma_f32_16x16x32_bf16 v[98:101], v[178:181], v[194:197], v[98:101]
	v_mfma_f32_16x16x32_bf16 v[86:89], v[168:171], v[202:205], v[86:89]
	v_mfma_f32_16x16x32_bf16 v[82:85], v[178:181], v[202:205], v[82:85]
	v_mfma_f32_16x16x32_bf16 v[70:73], v[168:171], v[210:213], v[70:73]
	v_mfma_f32_16x16x32_bf16 v[66:69], v[178:181], v[210:213], v[66:69]
	v_mfma_f32_16x16x32_bf16 v[118:121], v[172:175], v[190:193], v[118:121]
	v_mfma_f32_16x16x32_bf16 v[114:117], v[182:185], v[190:193], v[114:117]
	v_mfma_f32_16x16x32_bf16 v[102:105], v[172:175], v[198:201], v[102:105]
	v_mfma_f32_16x16x32_bf16 v[98:101], v[182:185], v[198:201], v[98:101]
	v_mfma_f32_16x16x32_bf16 v[86:89], v[172:175], v[206:209], v[86:89]
	v_mfma_f32_16x16x32_bf16 v[82:85], v[182:185], v[206:209], v[82:85]
	v_mfma_f32_16x16x32_bf16 v[70:73], v[172:175], v[214:217], v[70:73]
	v_mfma_f32_16x16x32_bf16 v[66:69], v[182:185], v[214:217], v[66:69]
	s_barrier
	s_setprio 0
	s_add_i32 s2, s53, s34
	v_lshl_add_u64 v[146:147], v[146:147], 0, s[6:7]
	s_mov_b32 m0, s2
	ds_read_b128 v[186:189], v151 offset:49152
	ds_read_b128 v[190:193], v151 offset:50176
	ds_read_b128 v[194:197], v151 offset:51200
	ds_read_b128 v[198:201], v151 offset:52224
	ds_read_b128 v[202:205], v151 offset:53248
	ds_read_b128 v[206:209], v151 offset:54272
	ds_read_b128 v[210:213], v151 offset:55296
	ds_read_b128 v[214:217], v151 offset:56320
	global_load_lds_dwordx4 v[146:147], off
	s_add_i32 m0, s2, 0x2000
	s_add_u32 s2, s30, 0x40080
	v_lshl_add_u64 v[146:147], v[218:219], 0, s[6:7]
	s_addc_u32 s3, s31, 0
	s_add_i32 s30, s54, s34
	global_load_lds_dwordx4 v[146:147], off
	v_lshl_add_u64 v[146:147], s[2:3], 0, v[132:133]
	s_mov_b32 m0, s30
	s_nop 0
	global_load_lds_dwordx4 v[146:147], off
	v_lshl_add_u64 v[146:147], s[2:3], 0, v[136:137]
	s_add_i32 m0, s30, 0x2000
	s_nop 0
	global_load_lds_dwordx4 v[146:147], off
	v_lshl_add_u64 v[146:147], v[220:221], 0, s[6:7]
	s_mov_b32 m0, s39
	s_nop 0
	global_load_lds_dwordx4 v[146:147], off
	v_lshl_add_u64 v[146:147], v[222:223], 0, s[6:7]
	s_mov_b32 m0, s40
	s_nop 0
	global_load_lds_dwordx4 v[146:147], off
	s_waitcnt vmcnt(8)
	s_waitcnt lgkmcnt(0)
	s_setprio 1
	s_barrier
	v_mfma_f32_16x16x32_bf16 v[62:65], v[152:155], v[186:189], v[62:65]
	v_mfma_f32_16x16x32_bf16 v[58:61], v[160:163], v[186:189], v[58:61]
	v_mfma_f32_16x16x32_bf16 v[46:49], v[152:155], v[194:197], v[46:49]
	v_mfma_f32_16x16x32_bf16 v[42:45], v[160:163], v[194:197], v[42:45]
	v_mfma_f32_16x16x32_bf16 v[30:33], v[152:155], v[202:205], v[30:33]
	v_mfma_f32_16x16x32_bf16 v[26:29], v[160:163], v[202:205], v[26:29]
	v_mfma_f32_16x16x32_bf16 v[14:17], v[152:155], v[210:213], v[14:17]
	v_mfma_f32_16x16x32_bf16 v[10:13], v[160:163], v[210:213], v[10:13]
	v_mfma_f32_16x16x32_bf16 v[62:65], v[156:159], v[190:193], v[62:65]
	v_mfma_f32_16x16x32_bf16 v[58:61], v[164:167], v[190:193], v[58:61]
	v_mfma_f32_16x16x32_bf16 v[46:49], v[156:159], v[198:201], v[46:49]
	v_mfma_f32_16x16x32_bf16 v[42:45], v[164:167], v[198:201], v[42:45]
	v_mfma_f32_16x16x32_bf16 v[30:33], v[156:159], v[206:209], v[30:33]
	v_mfma_f32_16x16x32_bf16 v[26:29], v[164:167], v[206:209], v[26:29]
	v_mfma_f32_16x16x32_bf16 v[14:17], v[156:159], v[214:217], v[14:17]
	v_mfma_f32_16x16x32_bf16 v[10:13], v[164:167], v[214:217], v[10:13]
	s_setprio 0
	s_setprio 1
	v_mfma_f32_16x16x32_bf16 v[54:57], v[168:171], v[186:189], v[54:57]
	v_mfma_f32_16x16x32_bf16 v[50:53], v[178:181], v[186:189], v[50:53]
	v_mfma_f32_16x16x32_bf16 v[38:41], v[168:171], v[194:197], v[38:41]
	v_mfma_f32_16x16x32_bf16 v[34:37], v[178:181], v[194:197], v[34:37]
	v_mfma_f32_16x16x32_bf16 v[22:25], v[168:171], v[202:205], v[22:25]
	v_mfma_f32_16x16x32_bf16 v[18:21], v[178:181], v[202:205], v[18:21]
	v_mfma_f32_16x16x32_bf16 v[6:9], v[168:171], v[210:213], v[6:9]
	v_mfma_f32_16x16x32_bf16 v[2:5], v[178:181], v[210:213], v[2:5]
	v_mfma_f32_16x16x32_bf16 v[54:57], v[172:175], v[190:193], v[54:57]
	v_mfma_f32_16x16x32_bf16 v[50:53], v[182:185], v[190:193], v[50:53]
	v_mfma_f32_16x16x32_bf16 v[38:41], v[172:175], v[198:201], v[38:41]
	v_mfma_f32_16x16x32_bf16 v[34:37], v[182:185], v[198:201], v[34:37]
	v_mfma_f32_16x16x32_bf16 v[22:25], v[172:175], v[206:209], v[22:25]
	v_mfma_f32_16x16x32_bf16 v[18:21], v[182:185], v[206:209], v[18:21]
	v_mfma_f32_16x16x32_bf16 v[6:9], v[172:175], v[214:217], v[6:9]
	v_mfma_f32_16x16x32_bf16 v[2:5], v[182:185], v[214:217], v[2:5]
	s_barrier
	s_setprio 0
	s_add_i32 s52, s52, 2
	s_add_u32 s28, s28, 0x100
	s_addc_u32 s29, s29, 0
	s_add_u32 s46, s46, 0x100
	s_addc_u32 s47, s47, 0
	s_cmp_gt_u32 s52, 13
	s_cbranch_scc0 .LBB0_451

.Lpk495_peel:
	ds_read_b128 v[152:155], v149
	ds_read_b128 v[156:159], v149 offset:1024
	ds_read_b128 v[160:163], v149 offset:2048
	ds_read_b128 v[164:167], v149 offset:3072
	ds_read_b128 v[168:171], v150
	ds_read_b128 v[172:175], v150 offset:1024
	ds_read_b128 v[178:181], v150 offset:2048
	ds_read_b128 v[182:185], v150 offset:3072
	s_add_u32 s2, s18, 0x4000
	s_addc_u32 s3, s19, 0
	s_cmp_eq_u32 s50, 40
	s_cselect_b32 s2, s45, s2
	s_cselect_b32 s3, s44, s3
	s_cselect_b32 s23, s46, s49
	s_cselect_b32 s22, s47, s48
	s_add_u32 s20, s2, 0x8000
	s_addc_u32 s21, s3, 0
	v_lshl_add_u64 v[144:145], s[18:19], 0, v[138:139]
	s_add_i32 m0, s29, 0xc000
	ds_read_b128 v[186:189], v151
	ds_read_b128 v[190:193], v151 offset:1024
	ds_read_b128 v[194:197], v151 offset:2048
	ds_read_b128 v[198:201], v151 offset:3072
	ds_read_b128 v[202:205], v151 offset:4096
	ds_read_b128 v[206:209], v151 offset:5120
	ds_read_b128 v[210:213], v151 offset:6144
	ds_read_b128 v[214:217], v151 offset:7168
	global_load_lds_dwordx4 v[144:145], off
	v_lshl_add_u64 v[144:145], s[18:19], 0, v[140:141]
	s_add_i32 m0, s29, 0xe000
	s_nop 0
	global_load_lds_dwordx4 v[144:145], off
	s_waitcnt vmcnt(8)
	s_waitcnt lgkmcnt(0)
	s_setprio 1
	s_barrier
	v_mfma_f32_16x16x32_bf16 v[126:129], v[152:155], v[186:189], 0
	v_mfma_f32_16x16x32_bf16 v[122:125], v[160:163], v[186:189], 0
	v_mfma_f32_16x16x32_bf16 v[114:117], v[152:155], v[194:197], 0
	v_mfma_f32_16x16x32_bf16 v[106:109], v[160:163], v[194:197], 0
	v_mfma_f32_16x16x32_bf16 v[98:101], v[152:155], v[202:205], 0
	v_mfma_f32_16x16x32_bf16 v[90:93], v[160:163], v[202:205], 0
	v_mfma_f32_16x16x32_bf16 v[82:85], v[152:155], v[210:213], 0
	v_mfma_f32_16x16x32_bf16 v[74:77], v[160:163], v[210:213], 0
	v_mfma_f32_16x16x32_bf16 v[126:129], v[156:159], v[190:193], v[126:129]
	v_mfma_f32_16x16x32_bf16 v[122:125], v[164:167], v[190:193], v[122:125]
	v_mfma_f32_16x16x32_bf16 v[114:117], v[156:159], v[198:201], v[114:117]
	v_mfma_f32_16x16x32_bf16 v[106:109], v[164:167], v[198:201], v[106:109]
	v_mfma_f32_16x16x32_bf16 v[98:101], v[156:159], v[206:209], v[98:101]
	v_mfma_f32_16x16x32_bf16 v[90:93], v[164:167], v[206:209], v[90:93]
	v_mfma_f32_16x16x32_bf16 v[82:85], v[156:159], v[214:217], v[82:85]
	v_mfma_f32_16x16x32_bf16 v[74:77], v[164:167], v[214:217], v[74:77]
	s_setprio 0
	s_setprio 1
	v_mfma_f32_16x16x32_bf16 v[118:121], v[168:171], v[186:189], 0
	v_mfma_f32_16x16x32_bf16 v[110:113], v[178:181], v[186:189], 0
	v_mfma_f32_16x16x32_bf16 v[102:105], v[168:171], v[194:197], 0
	v_mfma_f32_16x16x32_bf16 v[94:97], v[178:181], v[194:197], 0
	v_mfma_f32_16x16x32_bf16 v[86:89], v[168:171], v[202:205], 0
	v_mfma_f32_16x16x32_bf16 v[78:81], v[178:181], v[202:205], 0
	v_mfma_f32_16x16x32_bf16 v[70:73], v[168:171], v[210:213], 0
	v_mfma_f32_16x16x32_bf16 v[66:69], v[178:181], v[210:213], 0
	v_mfma_f32_16x16x32_bf16 v[118:121], v[172:175], v[190:193], v[118:121]
	v_mfma_f32_16x16x32_bf16 v[110:113], v[182:185], v[190:193], v[110:113]
	v_mfma_f32_16x16x32_bf16 v[102:105], v[172:175], v[198:201], v[102:105]
	v_mfma_f32_16x16x32_bf16 v[94:97], v[182:185], v[198:201], v[94:97]
	v_mfma_f32_16x16x32_bf16 v[86:89], v[172:175], v[206:209], v[86:89]
	v_mfma_f32_16x16x32_bf16 v[78:81], v[182:185], v[206:209], v[78:81]
	v_mfma_f32_16x16x32_bf16 v[70:73], v[172:175], v[214:217], v[70:73]
	v_mfma_f32_16x16x32_bf16 v[66:69], v[182:185], v[214:217], v[66:69]
	s_barrier
	s_setprio 0
	s_add_i32 s51, s38, s28
	v_lshl_add_u64 v[144:145], s[22:23], 0, v[132:133]
	s_mov_b32 m0, s51
	ds_read_b128 v[186:189], v151 offset:16384
	ds_read_b128 v[190:193], v151 offset:17408
	ds_read_b128 v[194:197], v151 offset:18432
	ds_read_b128 v[198:201], v151 offset:19456
	ds_read_b128 v[202:205], v151 offset:20480
	ds_read_b128 v[206:209], v151 offset:21504
	ds_read_b128 v[210:213], v151 offset:22528
	ds_read_b128 v[214:217], v151 offset:23552
	global_load_lds_dwordx4 v[144:145], off
	s_add_i32 m0, s51, 0x2000
	s_add_u32 s52, s22, 0x4000
	v_lshl_add_u64 v[144:145], s[22:23], 0, v[136:137]
	s_addc_u32 s53, s23, 0
	s_add_i32 s51, s39, s28
	global_load_lds_dwordx4 v[144:145], off
	v_lshl_add_u64 v[144:145], s[52:53], 0, v[132:133]
	s_mov_b32 m0, s51
	s_nop 0
	global_load_lds_dwordx4 v[144:145], off
	v_lshl_add_u64 v[144:145], s[52:53], 0, v[136:137]
	s_add_i32 m0, s51, 0x2000
	s_nop 0
	global_load_lds_dwordx4 v[144:145], off
	v_lshl_add_u64 v[144:145], s[2:3], 0, v[130:131]
	s_mov_b32 m0, s29
	s_nop 0
	global_load_lds_dwordx4 v[144:145], off
	v_lshl_add_u64 v[144:145], s[2:3], 0, v[134:135]
	s_mov_b32 m0, s30
	s_nop 0
	global_load_lds_dwordx4 v[144:145], off
	s_waitcnt vmcnt(8)
	s_waitcnt lgkmcnt(0)
	s_setprio 1
	s_barrier
	v_mfma_f32_16x16x32_bf16 v[62:65], v[152:155], v[186:189], 0
	v_mfma_f32_16x16x32_bf16 v[58:61], v[160:163], v[186:189], 0
	v_mfma_f32_16x16x32_bf16 v[50:53], v[152:155], v[194:197], 0
	v_mfma_f32_16x16x32_bf16 v[42:45], v[160:163], v[194:197], 0
	v_mfma_f32_16x16x32_bf16 v[34:37], v[152:155], v[202:205], 0
	v_mfma_f32_16x16x32_bf16 v[26:29], v[160:163], v[202:205], 0
	v_mfma_f32_16x16x32_bf16 v[18:21], v[152:155], v[210:213], 0
	v_mfma_f32_16x16x32_bf16 v[10:13], v[160:163], v[210:213], 0
	v_mfma_f32_16x16x32_bf16 v[62:65], v[156:159], v[190:193], v[62:65]
	v_mfma_f32_16x16x32_bf16 v[58:61], v[164:167], v[190:193], v[58:61]
	v_mfma_f32_16x16x32_bf16 v[50:53], v[156:159], v[198:201], v[50:53]
	v_mfma_f32_16x16x32_bf16 v[42:45], v[164:167], v[198:201], v[42:45]
	v_mfma_f32_16x16x32_bf16 v[34:37], v[156:159], v[206:209], v[34:37]
	v_mfma_f32_16x16x32_bf16 v[26:29], v[164:167], v[206:209], v[26:29]
	v_mfma_f32_16x16x32_bf16 v[18:21], v[156:159], v[214:217], v[18:21]
	v_mfma_f32_16x16x32_bf16 v[10:13], v[164:167], v[214:217], v[10:13]
	s_setprio 0
	s_setprio 1
	v_mfma_f32_16x16x32_bf16 v[54:57], v[168:171], v[186:189], 0
	v_mfma_f32_16x16x32_bf16 v[46:49], v[178:181], v[186:189], 0
	v_mfma_f32_16x16x32_bf16 v[38:41], v[168:171], v[194:197], 0
	v_mfma_f32_16x16x32_bf16 v[30:33], v[178:181], v[194:197], 0
	v_mfma_f32_16x16x32_bf16 v[22:25], v[168:171], v[202:205], 0
	v_mfma_f32_16x16x32_bf16 v[14:17], v[178:181], v[202:205], 0
	v_mfma_f32_16x16x32_bf16 v[6:9], v[168:171], v[210:213], 0
	v_mfma_f32_16x16x32_bf16 v[2:5], v[178:181], v[210:213], 0
	v_mfma_f32_16x16x32_bf16 v[54:57], v[172:175], v[190:193], v[54:57]
	v_mfma_f32_16x16x32_bf16 v[46:49], v[182:185], v[190:193], v[46:49]
	v_mfma_f32_16x16x32_bf16 v[38:41], v[172:175], v[198:201], v[38:41]
	v_mfma_f32_16x16x32_bf16 v[30:33], v[182:185], v[198:201], v[30:33]
	v_mfma_f32_16x16x32_bf16 v[22:25], v[172:175], v[206:209], v[22:25]
	v_mfma_f32_16x16x32_bf16 v[14:17], v[182:185], v[206:209], v[14:17]
	v_mfma_f32_16x16x32_bf16 v[6:9], v[172:175], v[214:217], v[6:9]
	v_mfma_f32_16x16x32_bf16 v[2:5], v[182:185], v[214:217], v[2:5]
	s_barrier
	s_setprio 0
	s_add_i32 s51, 0, 0x18000
	v_add_u32_e32 v144, s51, v147
	s_add_i32 s52, 0, 0x1c000
	ds_read_b128 v[152:155], v144
	ds_read_b128 v[156:159], v144 offset:1024
	ds_read_b128 v[160:163], v144 offset:2048
	ds_read_b128 v[164:167], v144 offset:3072
	v_add_u32_e32 v144, s52, v147
	ds_read_b128 v[168:171], v144
	ds_read_b128 v[172:175], v144 offset:1024
	ds_read_b128 v[178:181], v144 offset:2048
	ds_read_b128 v[182:185], v144 offset:3072
	s_add_u32 s2, s2, 0x4000
	s_addc_u32 s3, s3, 0
	s_mov_b32 m0, s31
	v_lshl_add_u64 v[144:145], s[2:3], 0, v[130:131]
	ds_read_b128 v[186:189], v151 offset:32768
	ds_read_b128 v[190:193], v151 offset:33792
	ds_read_b128 v[194:197], v151 offset:34816
	ds_read_b128 v[198:201], v151 offset:35840
	ds_read_b128 v[202:205], v151 offset:36864
	ds_read_b128 v[206:209], v151 offset:37888
	ds_read_b128 v[210:213], v151 offset:38912
	ds_read_b128 v[214:217], v151 offset:39936
	global_load_lds_dwordx4 v[144:145], off
	v_lshl_add_u64 v[144:145], s[2:3], 0, v[134:135]
	s_mov_b32 m0, s34
	s_nop 0
	global_load_lds_dwordx4 v[144:145], off
	s_waitcnt vmcnt(8)
	s_waitcnt lgkmcnt(0)
	s_setprio 1
	s_barrier
	v_mfma_f32_16x16x32_bf16 v[126:129], v[152:155], v[186:189], v[126:129]
	v_mfma_f32_16x16x32_bf16 v[122:125], v[160:163], v[186:189], v[122:125]
	v_mfma_f32_16x16x32_bf16 v[114:117], v[152:155], v[194:197], v[114:117]
	v_mfma_f32_16x16x32_bf16 v[106:109], v[160:163], v[194:197], v[106:109]
	v_mfma_f32_16x16x32_bf16 v[98:101], v[152:155], v[202:205], v[98:101]
	v_mfma_f32_16x16x32_bf16 v[90:93], v[160:163], v[202:205], v[90:93]
	v_mfma_f32_16x16x32_bf16 v[82:85], v[152:155], v[210:213], v[82:85]
	v_mfma_f32_16x16x32_bf16 v[74:77], v[160:163], v[210:213], v[74:77]
	v_mfma_f32_16x16x32_bf16 v[126:129], v[156:159], v[190:193], v[126:129]
	v_mfma_f32_16x16x32_bf16 v[122:125], v[164:167], v[190:193], v[122:125]
	v_mfma_f32_16x16x32_bf16 v[114:117], v[156:159], v[198:201], v[114:117]
	v_mfma_f32_16x16x32_bf16 v[106:109], v[164:167], v[198:201], v[106:109]
	v_mfma_f32_16x16x32_bf16 v[98:101], v[156:159], v[206:209], v[98:101]
	v_mfma_f32_16x16x32_bf16 v[90:93], v[164:167], v[206:209], v[90:93]
	v_mfma_f32_16x16x32_bf16 v[82:85], v[156:159], v[214:217], v[82:85]
	v_mfma_f32_16x16x32_bf16 v[74:77], v[164:167], v[214:217], v[74:77]
	s_setprio 0
	s_setprio 1
	v_mfma_f32_16x16x32_bf16 v[118:121], v[168:171], v[186:189], v[118:121]
	v_mfma_f32_16x16x32_bf16 v[110:113], v[178:181], v[186:189], v[110:113]
	v_mfma_f32_16x16x32_bf16 v[102:105], v[168:171], v[194:197], v[102:105]
	v_mfma_f32_16x16x32_bf16 v[94:97], v[178:181], v[194:197], v[94:97]
	v_mfma_f32_16x16x32_bf16 v[86:89], v[168:171], v[202:205], v[86:89]
	v_mfma_f32_16x16x32_bf16 v[78:81], v[178:181], v[202:205], v[78:81]
	v_mfma_f32_16x16x32_bf16 v[70:73], v[168:171], v[210:213], v[70:73]
	v_mfma_f32_16x16x32_bf16 v[66:69], v[178:181], v[210:213], v[66:69]
	v_mfma_f32_16x16x32_bf16 v[118:121], v[172:175], v[190:193], v[118:121]
	v_mfma_f32_16x16x32_bf16 v[110:113], v[182:185], v[190:193], v[110:113]
	v_mfma_f32_16x16x32_bf16 v[102:105], v[172:175], v[198:201], v[102:105]
	v_mfma_f32_16x16x32_bf16 v[94:97], v[182:185], v[198:201], v[94:97]
	v_mfma_f32_16x16x32_bf16 v[86:89], v[172:175], v[206:209], v[86:89]
	v_mfma_f32_16x16x32_bf16 v[78:81], v[182:185], v[206:209], v[78:81]
	v_mfma_f32_16x16x32_bf16 v[70:73], v[172:175], v[214:217], v[70:73]
	v_mfma_f32_16x16x32_bf16 v[66:69], v[182:185], v[214:217], v[66:69]
	s_barrier
	s_setprio 0
	s_add_u32 s2, s22, 0x8000
	s_addc_u32 s3, s23, 0
	s_add_i32 s51, s51, s28
	v_lshl_add_u64 v[144:145], s[2:3], 0, v[132:133]
	s_mov_b32 m0, s51
	ds_read_b128 v[186:189], v151 offset:49152
	ds_read_b128 v[190:193], v151 offset:50176
	ds_read_b128 v[194:197], v151 offset:51200
	ds_read_b128 v[198:201], v151 offset:52224
	ds_read_b128 v[202:205], v151 offset:53248
	ds_read_b128 v[206:209], v151 offset:54272
	ds_read_b128 v[210:213], v151 offset:55296
	ds_read_b128 v[214:217], v151 offset:56320
	global_load_lds_dwordx4 v[144:145], off
	s_add_i32 m0, s51, 0x2000
	v_lshl_add_u64 v[144:145], s[2:3], 0, v[136:137]
	s_add_u32 s2, s22, 0xc000
	s_addc_u32 s3, s23, 0
	s_add_i32 s22, s52, s28
	global_load_lds_dwordx4 v[144:145], off
	v_lshl_add_u64 v[144:145], s[2:3], 0, v[132:133]
	s_mov_b32 m0, s22
	s_nop 0
	global_load_lds_dwordx4 v[144:145], off
	v_lshl_add_u64 v[144:145], s[2:3], 0, v[136:137]
	s_add_i32 m0, s22, 0x2000
	s_nop 0
	global_load_lds_dwordx4 v[144:145], off
	v_lshl_add_u64 v[144:145], s[20:21], 0, v[130:131]
	s_mov_b32 m0, s36
	s_nop 0
	global_load_lds_dwordx4 v[144:145], off
	v_lshl_add_u64 v[144:145], s[20:21], 0, v[134:135]
	s_mov_b32 m0, s37
	s_nop 0
	global_load_lds_dwordx4 v[144:145], off
	s_waitcnt vmcnt(8)
	s_waitcnt lgkmcnt(0)
	s_setprio 1
	s_barrier
	v_mfma_f32_16x16x32_bf16 v[62:65], v[152:155], v[186:189], v[62:65]
	v_mfma_f32_16x16x32_bf16 v[58:61], v[160:163], v[186:189], v[58:61]
	v_mfma_f32_16x16x32_bf16 v[50:53], v[152:155], v[194:197], v[50:53]
	v_mfma_f32_16x16x32_bf16 v[42:45], v[160:163], v[194:197], v[42:45]
	v_mfma_f32_16x16x32_bf16 v[34:37], v[152:155], v[202:205], v[34:37]
	v_mfma_f32_16x16x32_bf16 v[26:29], v[160:163], v[202:205], v[26:29]
	v_mfma_f32_16x16x32_bf16 v[18:21], v[152:155], v[210:213], v[18:21]
	v_mfma_f32_16x16x32_bf16 v[10:13], v[160:163], v[210:213], v[10:13]
	v_mfma_f32_16x16x32_bf16 v[62:65], v[156:159], v[190:193], v[62:65]
	v_mfma_f32_16x16x32_bf16 v[58:61], v[164:167], v[190:193], v[58:61]
	v_mfma_f32_16x16x32_bf16 v[50:53], v[156:159], v[198:201], v[50:53]
	v_mfma_f32_16x16x32_bf16 v[42:45], v[164:167], v[198:201], v[42:45]
	v_mfma_f32_16x16x32_bf16 v[34:37], v[156:159], v[206:209], v[34:37]
	v_mfma_f32_16x16x32_bf16 v[26:29], v[164:167], v[206:209], v[26:29]
	v_mfma_f32_16x16x32_bf16 v[18:21], v[156:159], v[214:217], v[18:21]
	v_mfma_f32_16x16x32_bf16 v[10:13], v[164:167], v[214:217], v[10:13]
	s_setprio 0
	s_setprio 1
	v_mfma_f32_16x16x32_bf16 v[54:57], v[168:171], v[186:189], v[54:57]
	v_mfma_f32_16x16x32_bf16 v[46:49], v[178:181], v[186:189], v[46:49]
	v_mfma_f32_16x16x32_bf16 v[38:41], v[168:171], v[194:197], v[38:41]
	v_mfma_f32_16x16x32_bf16 v[30:33], v[178:181], v[194:197], v[30:33]
	v_mfma_f32_16x16x32_bf16 v[22:25], v[168:171], v[202:205], v[22:25]
	v_mfma_f32_16x16x32_bf16 v[14:17], v[178:181], v[202:205], v[14:17]
	v_mfma_f32_16x16x32_bf16 v[6:9], v[168:171], v[210:213], v[6:9]
	v_mfma_f32_16x16x32_bf16 v[2:5], v[178:181], v[210:213], v[2:5]
	v_mfma_f32_16x16x32_bf16 v[54:57], v[172:175], v[190:193], v[54:57]
	v_mfma_f32_16x16x32_bf16 v[46:49], v[182:185], v[190:193], v[46:49]
	v_mfma_f32_16x16x32_bf16 v[38:41], v[172:175], v[198:201], v[38:41]
	v_mfma_f32_16x16x32_bf16 v[30:33], v[182:185], v[198:201], v[30:33]
	v_mfma_f32_16x16x32_bf16 v[22:25], v[172:175], v[206:209], v[22:25]
	v_mfma_f32_16x16x32_bf16 v[14:17], v[182:185], v[206:209], v[14:17]
	v_mfma_f32_16x16x32_bf16 v[6:9], v[172:175], v[214:217], v[6:9]
	v_mfma_f32_16x16x32_bf16 v[2:5], v[182:185], v[214:217], v[2:5]
	s_barrier
	s_setprio 0
	s_add_i32 s50, s50, 2
	s_add_u32 s18, s18, 0x10000
	s_addc_u32 s19, s19, 0
	s_add_u32 s48, s48, 0x10000
	s_addc_u32 s49, s49, 0
	s_cmp_gt_u32 s50, 41
	s_cbranch_scc0 .LBB0_495
	s_branch .Lpk495_exit
.LBB0_495:
	ds_read_b128 v[152:155], v149
	ds_read_b128 v[156:159], v149 offset:1024
	ds_read_b128 v[160:163], v149 offset:2048
	ds_read_b128 v[164:167], v149 offset:3072
	ds_read_b128 v[168:171], v150
	ds_read_b128 v[172:175], v150 offset:1024
	ds_read_b128 v[178:181], v150 offset:2048
	ds_read_b128 v[182:185], v150 offset:3072
	s_add_u32 s2, s18, 0x4000
	s_addc_u32 s3, s19, 0
	s_cmp_eq_u32 s50, 40
	s_cselect_b32 s2, s45, s2
	s_cselect_b32 s3, s44, s3
	s_cselect_b32 s23, s46, s49
	s_cselect_b32 s22, s47, s48
	s_add_u32 s20, s2, 0x8000
	s_addc_u32 s21, s3, 0
	v_lshl_add_u64 v[144:145], s[18:19], 0, v[138:139]
	s_add_i32 m0, s29, 0xc000
	ds_read_b128 v[186:189], v151
	ds_read_b128 v[190:193], v151 offset:1024
	ds_read_b128 v[194:197], v151 offset:2048
	ds_read_b128 v[198:201], v151 offset:3072
	ds_read_b128 v[202:205], v151 offset:4096
	ds_read_b128 v[206:209], v151 offset:5120
	ds_read_b128 v[210:213], v151 offset:6144
	ds_read_b128 v[214:217], v151 offset:7168
	global_load_lds_dwordx4 v[144:145], off
	v_lshl_add_u64 v[144:145], s[18:19], 0, v[140:141]
	s_add_i32 m0, s29, 0xe000
	s_nop 0
	global_load_lds_dwordx4 v[144:145], off
	s_waitcnt vmcnt(8)
	s_waitcnt lgkmcnt(0)
	s_setprio 1
	s_barrier
	v_mfma_f32_16x16x32_bf16 v[126:129], v[152:155], v[186:189], v[126:129]
	v_mfma_f32_16x16x32_bf16 v[122:125], v[160:163], v[186:189], v[122:125]
	v_mfma_f32_16x16x32_bf16 v[114:117], v[152:155], v[194:197], v[114:117]
	v_mfma_f32_16x16x32_bf16 v[106:109], v[160:163], v[194:197], v[106:109]
	v_mfma_f32_16x16x32_bf16 v[98:101], v[152:155], v[202:205], v[98:101]
	v_mfma_f32_16x16x32_bf16 v[90:93], v[160:163], v[202:205], v[90:93]
	v_mfma_f32_16x16x32_bf16 v[82:85], v[152:155], v[210:213], v[82:85]
	v_mfma_f32_16x16x32_bf16 v[74:77], v[160:163], v[210:213], v[74:77]
	v_mfma_f32_16x16x32_bf16 v[126:129], v[156:159], v[190:193], v[126:129]
	v_mfma_f32_16x16x32_bf16 v[122:125], v[164:167], v[190:193], v[122:125]
	v_mfma_f32_16x16x32_bf16 v[114:117], v[156:159], v[198:201], v[114:117]
	v_mfma_f32_16x16x32_bf16 v[106:109], v[164:167], v[198:201], v[106:109]
	v_mfma_f32_16x16x32_bf16 v[98:101], v[156:159], v[206:209], v[98:101]
	v_mfma_f32_16x16x32_bf16 v[90:93], v[164:167], v[206:209], v[90:93]
	v_mfma_f32_16x16x32_bf16 v[82:85], v[156:159], v[214:217], v[82:85]
	v_mfma_f32_16x16x32_bf16 v[74:77], v[164:167], v[214:217], v[74:77]
	s_setprio 0
	s_setprio 1
	v_mfma_f32_16x16x32_bf16 v[118:121], v[168:171], v[186:189], v[118:121]
	v_mfma_f32_16x16x32_bf16 v[110:113], v[178:181], v[186:189], v[110:113]
	v_mfma_f32_16x16x32_bf16 v[102:105], v[168:171], v[194:197], v[102:105]
	v_mfma_f32_16x16x32_bf16 v[94:97], v[178:181], v[194:197], v[94:97]
	v_mfma_f32_16x16x32_bf16 v[86:89], v[168:171], v[202:205], v[86:89]
	v_mfma_f32_16x16x32_bf16 v[78:81], v[178:181], v[202:205], v[78:81]
	v_mfma_f32_16x16x32_bf16 v[70:73], v[168:171], v[210:213], v[70:73]
	v_mfma_f32_16x16x32_bf16 v[66:69], v[178:181], v[210:213], v[66:69]
	v_mfma_f32_16x16x32_bf16 v[118:121], v[172:175], v[190:193], v[118:121]
	v_mfma_f32_16x16x32_bf16 v[110:113], v[182:185], v[190:193], v[110:113]
	v_mfma_f32_16x16x32_bf16 v[102:105], v[172:175], v[198:201], v[102:105]
	v_mfma_f32_16x16x32_bf16 v[94:97], v[182:185], v[198:201], v[94:97]
	v_mfma_f32_16x16x32_bf16 v[86:89], v[172:175], v[206:209], v[86:89]
	v_mfma_f32_16x16x32_bf16 v[78:81], v[182:185], v[206:209], v[78:81]
	v_mfma_f32_16x16x32_bf16 v[70:73], v[172:175], v[214:217], v[70:73]
	v_mfma_f32_16x16x32_bf16 v[66:69], v[182:185], v[214:217], v[66:69]
	s_barrier
	s_setprio 0
	s_add_i32 s51, s38, s28
	v_lshl_add_u64 v[144:145], s[22:23], 0, v[132:133]
	s_mov_b32 m0, s51
	ds_read_b128 v[186:189], v151 offset:16384
	ds_read_b128 v[190:193], v151 offset:17408
	ds_read_b128 v[194:197], v151 offset:18432
	ds_read_b128 v[198:201], v151 offset:19456
	ds_read_b128 v[202:205], v151 offset:20480
	ds_read_b128 v[206:209], v151 offset:21504
	ds_read_b128 v[210:213], v151 offset:22528
	ds_read_b128 v[214:217], v151 offset:23552
	global_load_lds_dwordx4 v[144:145], off
	s_add_i32 m0, s51, 0x2000
	s_add_u32 s52, s22, 0x4000
	v_lshl_add_u64 v[144:145], s[22:23], 0, v[136:137]
	s_addc_u32 s53, s23, 0
	s_add_i32 s51, s39, s28
	global_load_lds_dwordx4 v[144:145], off
	v_lshl_add_u64 v[144:145], s[52:53], 0, v[132:133]
	s_mov_b32 m0, s51
	s_nop 0
	global_load_lds_dwordx4 v[144:145], off
	v_lshl_add_u64 v[144:145], s[52:53], 0, v[136:137]
	s_add_i32 m0, s51, 0x2000
	s_nop 0
	global_load_lds_dwordx4 v[144:145], off
	v_lshl_add_u64 v[144:145], s[2:3], 0, v[130:131]
	s_mov_b32 m0, s29
	s_nop 0
	global_load_lds_dwordx4 v[144:145], off
	v_lshl_add_u64 v[144:145], s[2:3], 0, v[134:135]
	s_mov_b32 m0, s30
	s_nop 0
	global_load_lds_dwordx4 v[144:145], off
	s_waitcnt vmcnt(8)
	s_waitcnt lgkmcnt(0)
	s_setprio 1
	s_barrier
	v_mfma_f32_16x16x32_bf16 v[62:65], v[152:155], v[186:189], v[62:65]
	v_mfma_f32_16x16x32_bf16 v[58:61], v[160:163], v[186:189], v[58:61]
	v_mfma_f32_16x16x32_bf16 v[50:53], v[152:155], v[194:197], v[50:53]
	v_mfma_f32_16x16x32_bf16 v[42:45], v[160:163], v[194:197], v[42:45]
	v_mfma_f32_16x16x32_bf16 v[34:37], v[152:155], v[202:205], v[34:37]
	v_mfma_f32_16x16x32_bf16 v[26:29], v[160:163], v[202:205], v[26:29]
	v_mfma_f32_16x16x32_bf16 v[18:21], v[152:155], v[210:213], v[18:21]
	v_mfma_f32_16x16x32_bf16 v[10:13], v[160:163], v[210:213], v[10:13]
	v_mfma_f32_16x16x32_bf16 v[62:65], v[156:159], v[190:193], v[62:65]
	v_mfma_f32_16x16x32_bf16 v[58:61], v[164:167], v[190:193], v[58:61]
	v_mfma_f32_16x16x32_bf16 v[50:53], v[156:159], v[198:201], v[50:53]
	v_mfma_f32_16x16x32_bf16 v[42:45], v[164:167], v[198:201], v[42:45]
	v_mfma_f32_16x16x32_bf16 v[34:37], v[156:159], v[206:209], v[34:37]
	v_mfma_f32_16x16x32_bf16 v[26:29], v[164:167], v[206:209], v[26:29]
	v_mfma_f32_16x16x32_bf16 v[18:21], v[156:159], v[214:217], v[18:21]
	v_mfma_f32_16x16x32_bf16 v[10:13], v[164:167], v[214:217], v[10:13]
	s_setprio 0
	s_setprio 1
	v_mfma_f32_16x16x32_bf16 v[54:57], v[168:171], v[186:189], v[54:57]
	v_mfma_f32_16x16x32_bf16 v[46:49], v[178:181], v[186:189], v[46:49]
	v_mfma_f32_16x16x32_bf16 v[38:41], v[168:171], v[194:197], v[38:41]
	v_mfma_f32_16x16x32_bf16 v[30:33], v[178:181], v[194:197], v[30:33]
	v_mfma_f32_16x16x32_bf16 v[22:25], v[168:171], v[202:205], v[22:25]
	v_mfma_f32_16x16x32_bf16 v[14:17], v[178:181], v[202:205], v[14:17]
	v_mfma_f32_16x16x32_bf16 v[6:9], v[168:171], v[210:213], v[6:9]
	v_mfma_f32_16x16x32_bf16 v[2:5], v[178:181], v[210:213], v[2:5]
	v_mfma_f32_16x16x32_bf16 v[54:57], v[172:175], v[190:193], v[54:57]
	v_mfma_f32_16x16x32_bf16 v[46:49], v[182:185], v[190:193], v[46:49]
	v_mfma_f32_16x16x32_bf16 v[38:41], v[172:175], v[198:201], v[38:41]
	v_mfma_f32_16x16x32_bf16 v[30:33], v[182:185], v[198:201], v[30:33]
	v_mfma_f32_16x16x32_bf16 v[22:25], v[172:175], v[206:209], v[22:25]
	v_mfma_f32_16x16x32_bf16 v[14:17], v[182:185], v[206:209], v[14:17]
	v_mfma_f32_16x16x32_bf16 v[6:9], v[172:175], v[214:217], v[6:9]
	v_mfma_f32_16x16x32_bf16 v[2:5], v[182:185], v[214:217], v[2:5]
	s_barrier
	s_setprio 0
	s_add_i32 s51, 0, 0x18000
	v_add_u32_e32 v144, s51, v147
	s_add_i32 s52, 0, 0x1c000
	ds_read_b128 v[152:155], v144
	ds_read_b128 v[156:159], v144 offset:1024
	ds_read_b128 v[160:163], v144 offset:2048
	ds_read_b128 v[164:167], v144 offset:3072
	v_add_u32_e32 v144, s52, v147
	ds_read_b128 v[168:171], v144
	ds_read_b128 v[172:175], v144 offset:1024
	ds_read_b128 v[178:181], v144 offset:2048
	ds_read_b128 v[182:185], v144 offset:3072
	s_add_u32 s2, s2, 0x4000
	s_addc_u32 s3, s3, 0
	s_mov_b32 m0, s31
	v_lshl_add_u64 v[144:145], s[2:3], 0, v[130:131]
	ds_read_b128 v[186:189], v151 offset:32768
	ds_read_b128 v[190:193], v151 offset:33792
	ds_read_b128 v[194:197], v151 offset:34816
	ds_read_b128 v[198:201], v151 offset:35840
	ds_read_b128 v[202:205], v151 offset:36864
	ds_read_b128 v[206:209], v151 offset:37888
	ds_read_b128 v[210:213], v151 offset:38912
	ds_read_b128 v[214:217], v151 offset:39936
	global_load_lds_dwordx4 v[144:145], off
	v_lshl_add_u64 v[144:145], s[2:3], 0, v[134:135]
	s_mov_b32 m0, s34
	s_nop 0
	global_load_lds_dwordx4 v[144:145], off
	s_waitcnt vmcnt(8)
	s_waitcnt lgkmcnt(0)
	s_setprio 1
	s_barrier
	v_mfma_f32_16x16x32_bf16 v[126:129], v[152:155], v[186:189], v[126:129]
	v_mfma_f32_16x16x32_bf16 v[122:125], v[160:163], v[186:189], v[122:125]
	v_mfma_f32_16x16x32_bf16 v[114:117], v[152:155], v[194:197], v[114:117]
	v_mfma_f32_16x16x32_bf16 v[106:109], v[160:163], v[194:197], v[106:109]
	v_mfma_f32_16x16x32_bf16 v[98:101], v[152:155], v[202:205], v[98:101]
	v_mfma_f32_16x16x32_bf16 v[90:93], v[160:163], v[202:205], v[90:93]
	v_mfma_f32_16x16x32_bf16 v[82:85], v[152:155], v[210:213], v[82:85]
	v_mfma_f32_16x16x32_bf16 v[74:77], v[160:163], v[210:213], v[74:77]
	v_mfma_f32_16x16x32_bf16 v[126:129], v[156:159], v[190:193], v[126:129]
	v_mfma_f32_16x16x32_bf16 v[122:125], v[164:167], v[190:193], v[122:125]
	v_mfma_f32_16x16x32_bf16 v[114:117], v[156:159], v[198:201], v[114:117]
	v_mfma_f32_16x16x32_bf16 v[106:109], v[164:167], v[198:201], v[106:109]
	v_mfma_f32_16x16x32_bf16 v[98:101], v[156:159], v[206:209], v[98:101]
	v_mfma_f32_16x16x32_bf16 v[90:93], v[164:167], v[206:209], v[90:93]
	v_mfma_f32_16x16x32_bf16 v[82:85], v[156:159], v[214:217], v[82:85]
	v_mfma_f32_16x16x32_bf16 v[74:77], v[164:167], v[214:217], v[74:77]
	s_setprio 0
	s_setprio 1
	v_mfma_f32_16x16x32_bf16 v[118:121], v[168:171], v[186:189], v[118:121]
	v_mfma_f32_16x16x32_bf16 v[110:113], v[178:181], v[186:189], v[110:113]
	v_mfma_f32_16x16x32_bf16 v[102:105], v[168:171], v[194:197], v[102:105]
	v_mfma_f32_16x16x32_bf16 v[94:97], v[178:181], v[194:197], v[94:97]
	v_mfma_f32_16x16x32_bf16 v[86:89], v[168:171], v[202:205], v[86:89]
	v_mfma_f32_16x16x32_bf16 v[78:81], v[178:181], v[202:205], v[78:81]
	v_mfma_f32_16x16x32_bf16 v[70:73], v[168:171], v[210:213], v[70:73]
	v_mfma_f32_16x16x32_bf16 v[66:69], v[178:181], v[210:213], v[66:69]
	v_mfma_f32_16x16x32_bf16 v[118:121], v[172:175], v[190:193], v[118:121]
	v_mfma_f32_16x16x32_bf16 v[110:113], v[182:185], v[190:193], v[110:113]
	v_mfma_f32_16x16x32_bf16 v[102:105], v[172:175], v[198:201], v[102:105]
	v_mfma_f32_16x16x32_bf16 v[94:97], v[182:185], v[198:201], v[94:97]
	v_mfma_f32_16x16x32_bf16 v[86:89], v[172:175], v[206:209], v[86:89]
	v_mfma_f32_16x16x32_bf16 v[78:81], v[182:185], v[206:209], v[78:81]
	v_mfma_f32_16x16x32_bf16 v[70:73], v[172:175], v[214:217], v[70:73]
	v_mfma_f32_16x16x32_bf16 v[66:69], v[182:185], v[214:217], v[66:69]
	s_barrier
	s_setprio 0
	s_add_u32 s2, s22, 0x8000
	s_addc_u32 s3, s23, 0
	s_add_i32 s51, s51, s28
	v_lshl_add_u64 v[144:145], s[2:3], 0, v[132:133]
	s_mov_b32 m0, s51
	ds_read_b128 v[186:189], v151 offset:49152
	ds_read_b128 v[190:193], v151 offset:50176
	ds_read_b128 v[194:197], v151 offset:51200
	ds_read_b128 v[198:201], v151 offset:52224
	ds_read_b128 v[202:205], v151 offset:53248
	ds_read_b128 v[206:209], v151 offset:54272
	ds_read_b128 v[210:213], v151 offset:55296
	ds_read_b128 v[214:217], v151 offset:56320
	global_load_lds_dwordx4 v[144:145], off
	s_add_i32 m0, s51, 0x2000
	v_lshl_add_u64 v[144:145], s[2:3], 0, v[136:137]
	s_add_u32 s2, s22, 0xc000
	s_addc_u32 s3, s23, 0
	s_add_i32 s22, s52, s28
	global_load_lds_dwordx4 v[144:145], off
	v_lshl_add_u64 v[144:145], s[2:3], 0, v[132:133]
	s_mov_b32 m0, s22
	s_nop 0
	global_load_lds_dwordx4 v[144:145], off
	v_lshl_add_u64 v[144:145], s[2:3], 0, v[136:137]
	s_add_i32 m0, s22, 0x2000
	s_nop 0
	global_load_lds_dwordx4 v[144:145], off
	v_lshl_add_u64 v[144:145], s[20:21], 0, v[130:131]
	s_mov_b32 m0, s36
	s_nop 0
	global_load_lds_dwordx4 v[144:145], off
	v_lshl_add_u64 v[144:145], s[20:21], 0, v[134:135]
	s_mov_b32 m0, s37
	s_nop 0
	global_load_lds_dwordx4 v[144:145], off
	s_waitcnt vmcnt(8)
	s_waitcnt lgkmcnt(0)
	s_setprio 1
	s_barrier
	v_mfma_f32_16x16x32_bf16 v[62:65], v[152:155], v[186:189], v[62:65]
	v_mfma_f32_16x16x32_bf16 v[58:61], v[160:163], v[186:189], v[58:61]
	v_mfma_f32_16x16x32_bf16 v[50:53], v[152:155], v[194:197], v[50:53]
	v_mfma_f32_16x16x32_bf16 v[42:45], v[160:163], v[194:197], v[42:45]
	v_mfma_f32_16x16x32_bf16 v[34:37], v[152:155], v[202:205], v[34:37]
	v_mfma_f32_16x16x32_bf16 v[26:29], v[160:163], v[202:205], v[26:29]
	v_mfma_f32_16x16x32_bf16 v[18:21], v[152:155], v[210:213], v[18:21]
	v_mfma_f32_16x16x32_bf16 v[10:13], v[160:163], v[210:213], v[10:13]
	v_mfma_f32_16x16x32_bf16 v[62:65], v[156:159], v[190:193], v[62:65]
	v_mfma_f32_16x16x32_bf16 v[58:61], v[164:167], v[190:193], v[58:61]
	v_mfma_f32_16x16x32_bf16 v[50:53], v[156:159], v[198:201], v[50:53]
	v_mfma_f32_16x16x32_bf16 v[42:45], v[164:167], v[198:201], v[42:45]
	v_mfma_f32_16x16x32_bf16 v[34:37], v[156:159], v[206:209], v[34:37]
	v_mfma_f32_16x16x32_bf16 v[26:29], v[164:167], v[206:209], v[26:29]
	v_mfma_f32_16x16x32_bf16 v[18:21], v[156:159], v[214:217], v[18:21]
	v_mfma_f32_16x16x32_bf16 v[10:13], v[164:167], v[214:217], v[10:13]
	s_setprio 0
	s_setprio 1
	v_mfma_f32_16x16x32_bf16 v[54:57], v[168:171], v[186:189], v[54:57]
	v_mfma_f32_16x16x32_bf16 v[46:49], v[178:181], v[186:189], v[46:49]
	v_mfma_f32_16x16x32_bf16 v[38:41], v[168:171], v[194:197], v[38:41]
	v_mfma_f32_16x16x32_bf16 v[30:33], v[178:181], v[194:197], v[30:33]
	v_mfma_f32_16x16x32_bf16 v[22:25], v[168:171], v[202:205], v[22:25]
	v_mfma_f32_16x16x32_bf16 v[14:17], v[178:181], v[202:205], v[14:17]
	v_mfma_f32_16x16x32_bf16 v[6:9], v[168:171], v[210:213], v[6:9]
	v_mfma_f32_16x16x32_bf16 v[2:5], v[178:181], v[210:213], v[2:5]
	v_mfma_f32_16x16x32_bf16 v[54:57], v[172:175], v[190:193], v[54:57]
	v_mfma_f32_16x16x32_bf16 v[46:49], v[182:185], v[190:193], v[46:49]
	v_mfma_f32_16x16x32_bf16 v[38:41], v[172:175], v[198:201], v[38:41]
	v_mfma_f32_16x16x32_bf16 v[30:33], v[182:185], v[198:201], v[30:33]
	v_mfma_f32_16x16x32_bf16 v[22:25], v[172:175], v[206:209], v[22:25]
	v_mfma_f32_16x16x32_bf16 v[14:17], v[182:185], v[206:209], v[14:17]
	v_mfma_f32_16x16x32_bf16 v[6:9], v[172:175], v[214:217], v[6:9]
	v_mfma_f32_16x16x32_bf16 v[2:5], v[182:185], v[214:217], v[2:5]
	s_barrier
	s_setprio 0
	s_add_i32 s50, s50, 2
	s_add_u32 s18, s18, 0x10000
	s_addc_u32 s19, s19, 0
	s_add_u32 s48, s48, 0x10000
	s_addc_u32 s49, s49, 0
	s_cmp_gt_u32 s50, 41
	s_cbranch_scc0 .LBB0_495

.Lpk555_peel:
	ds_read_b128 v[154:157], v151
	ds_read_b128 v[158:161], v151 offset:1024
	ds_read_b128 v[162:165], v151 offset:2048
	ds_read_b128 v[166:169], v151 offset:3072
	ds_read_b128 v[170:173], v152
	ds_read_b128 v[178:181], v152 offset:1024
	ds_read_b128 v[182:185], v152 offset:2048
	ds_read_b128 v[186:189], v152 offset:3072
	s_add_u32 s2, s26, 0xfffc0080
	s_addc_u32 s3, s27, -1
	s_cmp_eq_u32 s52, 12
	s_cselect_b32 s3, s11, s3
	s_cselect_b32 s2, s13, s2
	s_cselect_b32 s29, s48, s51
	s_cselect_b32 s28, s49, s50
	v_lshl_add_u64 v[144:145], s[26:27], 0, v[138:139]
	s_add_i32 m0, s37, 0xc000
	ds_read_b128 v[190:193], v153
	ds_read_b128 v[194:197], v153 offset:1024
	ds_read_b128 v[198:201], v153 offset:2048
	ds_read_b128 v[202:205], v153 offset:3072
	ds_read_b128 v[206:209], v153 offset:4096
	ds_read_b128 v[210:213], v153 offset:5120
	ds_read_b128 v[214:217], v153 offset:6144
	ds_read_b128 v[218:221], v153 offset:7168
	global_load_lds_dwordx4 v[144:145], off
	v_lshl_add_u64 v[144:145], s[26:27], 0, v[140:141]
	s_add_i32 m0, s37, 0xe000
	s_nop 0
	global_load_lds_dwordx4 v[144:145], off
	s_waitcnt vmcnt(8)
	s_waitcnt lgkmcnt(0)
	s_setprio 1
	s_barrier
	v_mfma_f32_16x16x32_bf16 v[126:129], v[154:157], v[190:193], 0
	v_mfma_f32_16x16x32_bf16 v[122:125], v[162:165], v[190:193], 0
	v_mfma_f32_16x16x32_bf16 v[114:117], v[154:157], v[198:201], 0
	v_mfma_f32_16x16x32_bf16 v[106:109], v[162:165], v[198:201], 0
	v_mfma_f32_16x16x32_bf16 v[98:101], v[154:157], v[206:209], 0
	v_mfma_f32_16x16x32_bf16 v[90:93], v[162:165], v[206:209], 0
	v_mfma_f32_16x16x32_bf16 v[82:85], v[154:157], v[214:217], 0
	v_mfma_f32_16x16x32_bf16 v[74:77], v[162:165], v[214:217], 0
	v_mfma_f32_16x16x32_bf16 v[126:129], v[158:161], v[194:197], v[126:129]
	v_mfma_f32_16x16x32_bf16 v[122:125], v[166:169], v[194:197], v[122:125]
	v_mfma_f32_16x16x32_bf16 v[114:117], v[158:161], v[202:205], v[114:117]
	v_mfma_f32_16x16x32_bf16 v[106:109], v[166:169], v[202:205], v[106:109]
	v_mfma_f32_16x16x32_bf16 v[98:101], v[158:161], v[210:213], v[98:101]
	v_mfma_f32_16x16x32_bf16 v[90:93], v[166:169], v[210:213], v[90:93]
	v_mfma_f32_16x16x32_bf16 v[82:85], v[158:161], v[218:221], v[82:85]
	v_mfma_f32_16x16x32_bf16 v[74:77], v[166:169], v[218:221], v[74:77]
	s_setprio 0
	s_setprio 1
	v_mfma_f32_16x16x32_bf16 v[118:121], v[170:173], v[190:193], 0
	v_mfma_f32_16x16x32_bf16 v[110:113], v[182:185], v[190:193], 0
	v_mfma_f32_16x16x32_bf16 v[102:105], v[170:173], v[198:201], 0
	v_mfma_f32_16x16x32_bf16 v[94:97], v[182:185], v[198:201], 0
	v_mfma_f32_16x16x32_bf16 v[86:89], v[170:173], v[206:209], 0
	v_mfma_f32_16x16x32_bf16 v[78:81], v[182:185], v[206:209], 0
	v_mfma_f32_16x16x32_bf16 v[70:73], v[170:173], v[214:217], 0
	v_mfma_f32_16x16x32_bf16 v[66:69], v[182:185], v[214:217], 0
	v_mfma_f32_16x16x32_bf16 v[118:121], v[178:181], v[194:197], v[118:121]
	v_mfma_f32_16x16x32_bf16 v[110:113], v[186:189], v[194:197], v[110:113]
	v_mfma_f32_16x16x32_bf16 v[102:105], v[178:181], v[202:205], v[102:105]
	v_mfma_f32_16x16x32_bf16 v[94:97], v[186:189], v[202:205], v[94:97]
	v_mfma_f32_16x16x32_bf16 v[86:89], v[178:181], v[210:213], v[86:89]
	v_mfma_f32_16x16x32_bf16 v[78:81], v[186:189], v[210:213], v[78:81]
	v_mfma_f32_16x16x32_bf16 v[70:73], v[178:181], v[218:221], v[70:73]
	v_mfma_f32_16x16x32_bf16 v[66:69], v[186:189], v[218:221], v[66:69]
	s_barrier
	s_setprio 0
	s_add_i32 s53, s44, s34
	v_lshl_add_u64 v[144:145], s[28:29], 0, v[134:135]
	s_mov_b32 m0, s53
	ds_read_b128 v[190:193], v153 offset:16384
	ds_read_b128 v[194:197], v153 offset:17408
	ds_read_b128 v[198:201], v153 offset:18432
	ds_read_b128 v[202:205], v153 offset:19456
	ds_read_b128 v[206:209], v153 offset:20480
	ds_read_b128 v[210:213], v153 offset:21504
	ds_read_b128 v[214:217], v153 offset:22528
	ds_read_b128 v[218:221], v153 offset:23552
	global_load_lds_dwordx4 v[144:145], off
	s_add_i32 m0, s53, 0x2000
	s_add_u32 s54, s28, 0x40000
	v_lshl_add_u64 v[174:175], s[28:29], 0, v[130:131]
	s_addc_u32 s55, s29, 0
	s_add_i32 s53, s45, s34
	global_load_lds_dwordx4 v[174:175], off
	v_lshl_add_u64 v[222:223], s[54:55], 0, v[134:135]
	s_mov_b32 m0, s53
	v_lshl_add_u64 v[224:225], s[2:3], 0, v[132:133]
	global_load_lds_dwordx4 v[222:223], off
	v_lshl_add_u64 v[222:223], s[54:55], 0, v[130:131]
	s_add_i32 m0, s53, 0x2000
	s_nop 0
	global_load_lds_dwordx4 v[222:223], off
	v_lshl_add_u64 v[222:223], s[2:3], 0, v[136:137]
	s_mov_b32 m0, s37
	s_nop 0
	global_load_lds_dwordx4 v[222:223], off
	s_mov_b32 m0, s25
	s_nop 0
	global_load_lds_dwordx4 v[224:225], off
	s_waitcnt vmcnt(8)
	s_waitcnt lgkmcnt(0)
	s_setprio 1
	s_barrier
	v_mfma_f32_16x16x32_bf16 v[62:65], v[154:157], v[190:193], 0
	v_mfma_f32_16x16x32_bf16 v[58:61], v[162:165], v[190:193], 0
	v_mfma_f32_16x16x32_bf16 v[50:53], v[154:157], v[198:201], 0
	v_mfma_f32_16x16x32_bf16 v[42:45], v[162:165], v[198:201], 0
	v_mfma_f32_16x16x32_bf16 v[34:37], v[154:157], v[206:209], 0
	v_mfma_f32_16x16x32_bf16 v[26:29], v[162:165], v[206:209], 0
	v_mfma_f32_16x16x32_bf16 v[18:21], v[154:157], v[214:217], 0
	v_mfma_f32_16x16x32_bf16 v[10:13], v[162:165], v[214:217], 0
	v_mfma_f32_16x16x32_bf16 v[62:65], v[158:161], v[194:197], v[62:65]
	v_mfma_f32_16x16x32_bf16 v[58:61], v[166:169], v[194:197], v[58:61]
	v_mfma_f32_16x16x32_bf16 v[50:53], v[158:161], v[202:205], v[50:53]
	v_mfma_f32_16x16x32_bf16 v[42:45], v[166:169], v[202:205], v[42:45]
	v_mfma_f32_16x16x32_bf16 v[34:37], v[158:161], v[210:213], v[34:37]
	v_mfma_f32_16x16x32_bf16 v[26:29], v[166:169], v[210:213], v[26:29]
	v_mfma_f32_16x16x32_bf16 v[18:21], v[158:161], v[218:221], v[18:21]
	v_mfma_f32_16x16x32_bf16 v[10:13], v[166:169], v[218:221], v[10:13]
	s_setprio 0
	s_setprio 1
	v_mfma_f32_16x16x32_bf16 v[54:57], v[170:173], v[190:193], 0
	v_mfma_f32_16x16x32_bf16 v[46:49], v[182:185], v[190:193], 0
	v_mfma_f32_16x16x32_bf16 v[38:41], v[170:173], v[198:201], 0
	v_mfma_f32_16x16x32_bf16 v[30:33], v[182:185], v[198:201], 0
	v_mfma_f32_16x16x32_bf16 v[22:25], v[170:173], v[206:209], 0
	v_mfma_f32_16x16x32_bf16 v[14:17], v[182:185], v[206:209], 0
	v_mfma_f32_16x16x32_bf16 v[6:9], v[170:173], v[214:217], 0
	v_mfma_f32_16x16x32_bf16 v[2:5], v[182:185], v[214:217], 0
	v_mfma_f32_16x16x32_bf16 v[54:57], v[178:181], v[194:197], v[54:57]
	v_mfma_f32_16x16x32_bf16 v[46:49], v[186:189], v[194:197], v[46:49]
	v_mfma_f32_16x16x32_bf16 v[38:41], v[178:181], v[202:205], v[38:41]
	v_mfma_f32_16x16x32_bf16 v[30:33], v[186:189], v[202:205], v[30:33]
	v_mfma_f32_16x16x32_bf16 v[22:25], v[178:181], v[210:213], v[22:25]
	v_mfma_f32_16x16x32_bf16 v[14:17], v[186:189], v[210:213], v[14:17]
	v_mfma_f32_16x16x32_bf16 v[6:9], v[178:181], v[218:221], v[6:9]
	v_mfma_f32_16x16x32_bf16 v[2:5], v[186:189], v[218:221], v[2:5]
	s_barrier
	s_setprio 0
	s_add_i32 s53, 0, 0x18000
	s_add_i32 s54, 0, 0x1c000
	v_add_u32_e32 v166, s53, v149
	v_add_u32_e32 v176, s54, v149
	ds_read_b128 v[154:157], v166
	ds_read_b128 v[158:161], v166 offset:1024
	ds_read_b128 v[162:165], v166 offset:2048
	ds_read_b128 v[166:169], v166 offset:3072
	ds_read_b128 v[170:173], v176
	ds_read_b128 v[178:181], v176 offset:1024
	ds_read_b128 v[182:185], v176 offset:2048
	ds_read_b128 v[186:189], v176 offset:3072
	s_add_u32 s2, s2, 0x40000
	s_addc_u32 s3, s3, 0
	s_mov_b32 m0, s38
	v_lshl_add_u64 v[226:227], s[2:3], 0, v[136:137]
	ds_read_b128 v[190:193], v153 offset:32768
	ds_read_b128 v[194:197], v153 offset:33792
	ds_read_b128 v[198:201], v153 offset:34816
	ds_read_b128 v[202:205], v153 offset:35840
	ds_read_b128 v[206:209], v153 offset:36864
	ds_read_b128 v[210:213], v153 offset:37888
	ds_read_b128 v[214:217], v153 offset:38912
	ds_read_b128 v[218:221], v153 offset:39936
	global_load_lds_dwordx4 v[226:227], off
	v_lshl_add_u64 v[226:227], s[2:3], 0, v[132:133]
	s_mov_b32 m0, s39
	s_nop 0
	global_load_lds_dwordx4 v[226:227], off
	s_waitcnt vmcnt(8)
	s_waitcnt lgkmcnt(0)
	s_setprio 1
	s_barrier
	v_mfma_f32_16x16x32_bf16 v[126:129], v[154:157], v[190:193], v[126:129]
	v_mfma_f32_16x16x32_bf16 v[122:125], v[162:165], v[190:193], v[122:125]
	v_mfma_f32_16x16x32_bf16 v[114:117], v[154:157], v[198:201], v[114:117]
	v_mfma_f32_16x16x32_bf16 v[106:109], v[162:165], v[198:201], v[106:109]
	v_mfma_f32_16x16x32_bf16 v[98:101], v[154:157], v[206:209], v[98:101]
	v_mfma_f32_16x16x32_bf16 v[90:93], v[162:165], v[206:209], v[90:93]
	v_mfma_f32_16x16x32_bf16 v[82:85], v[154:157], v[214:217], v[82:85]
	v_mfma_f32_16x16x32_bf16 v[74:77], v[162:165], v[214:217], v[74:77]
	v_mfma_f32_16x16x32_bf16 v[126:129], v[158:161], v[194:197], v[126:129]
	v_mfma_f32_16x16x32_bf16 v[122:125], v[166:169], v[194:197], v[122:125]
	v_mfma_f32_16x16x32_bf16 v[114:117], v[158:161], v[202:205], v[114:117]
	v_mfma_f32_16x16x32_bf16 v[106:109], v[166:169], v[202:205], v[106:109]
	v_mfma_f32_16x16x32_bf16 v[98:101], v[158:161], v[210:213], v[98:101]
	v_mfma_f32_16x16x32_bf16 v[90:93], v[166:169], v[210:213], v[90:93]
	v_mfma_f32_16x16x32_bf16 v[82:85], v[158:161], v[218:221], v[82:85]
	v_mfma_f32_16x16x32_bf16 v[74:77], v[166:169], v[218:221], v[74:77]
	s_setprio 0
	s_setprio 1
	v_mfma_f32_16x16x32_bf16 v[118:121], v[170:173], v[190:193], v[118:121]
	v_mfma_f32_16x16x32_bf16 v[110:113], v[182:185], v[190:193], v[110:113]
	v_mfma_f32_16x16x32_bf16 v[102:105], v[170:173], v[198:201], v[102:105]
	v_mfma_f32_16x16x32_bf16 v[94:97], v[182:185], v[198:201], v[94:97]
	v_mfma_f32_16x16x32_bf16 v[86:89], v[170:173], v[206:209], v[86:89]
	v_mfma_f32_16x16x32_bf16 v[78:81], v[182:185], v[206:209], v[78:81]
	v_mfma_f32_16x16x32_bf16 v[70:73], v[170:173], v[214:217], v[70:73]
	v_mfma_f32_16x16x32_bf16 v[66:69], v[182:185], v[214:217], v[66:69]
	v_mfma_f32_16x16x32_bf16 v[118:121], v[178:181], v[194:197], v[118:121]
	v_mfma_f32_16x16x32_bf16 v[110:113], v[186:189], v[194:197], v[110:113]
	v_mfma_f32_16x16x32_bf16 v[102:105], v[178:181], v[202:205], v[102:105]
	v_mfma_f32_16x16x32_bf16 v[94:97], v[186:189], v[202:205], v[94:97]
	v_mfma_f32_16x16x32_bf16 v[86:89], v[178:181], v[210:213], v[86:89]
	v_mfma_f32_16x16x32_bf16 v[78:81], v[186:189], v[210:213], v[78:81]
	v_mfma_f32_16x16x32_bf16 v[70:73], v[178:181], v[218:221], v[70:73]
	v_mfma_f32_16x16x32_bf16 v[66:69], v[186:189], v[218:221], v[66:69]
	s_barrier
	s_setprio 0
	s_add_i32 s2, s53, s34
	v_lshl_add_u64 v[144:145], v[144:145], 0, s[6:7]
	s_mov_b32 m0, s2
	ds_read_b128 v[190:193], v153 offset:49152
	ds_read_b128 v[194:197], v153 offset:50176
	ds_read_b128 v[198:201], v153 offset:51200
	ds_read_b128 v[202:205], v153 offset:52224
	ds_read_b128 v[206:209], v153 offset:53248
	ds_read_b128 v[210:213], v153 offset:54272
	ds_read_b128 v[214:217], v153 offset:55296
	ds_read_b128 v[218:221], v153 offset:56320
	global_load_lds_dwordx4 v[144:145], off
	s_add_i32 m0, s2, 0x2000
	s_add_u32 s2, s28, 0x40080
	v_lshl_add_u64 v[144:145], v[174:175], 0, s[6:7]
	s_addc_u32 s3, s29, 0
	s_add_i32 s28, s54, s34
	global_load_lds_dwordx4 v[144:145], off
	v_lshl_add_u64 v[144:145], s[2:3], 0, v[134:135]
	s_mov_b32 m0, s28
	s_nop 0
	global_load_lds_dwordx4 v[144:145], off
	v_lshl_add_u64 v[144:145], s[2:3], 0, v[130:131]
	s_add_i32 m0, s28, 0x2000
	s_nop 0
	global_load_lds_dwordx4 v[144:145], off
	v_lshl_add_u64 v[144:145], v[222:223], 0, s[6:7]
	s_mov_b32 m0, s41
	s_nop 0
	global_load_lds_dwordx4 v[144:145], off
	v_lshl_add_u64 v[144:145], v[224:225], 0, s[6:7]
	s_mov_b32 m0, s42
	s_nop 0
	global_load_lds_dwordx4 v[144:145], off
	s_waitcnt vmcnt(8)
	s_waitcnt lgkmcnt(0)
	s_setprio 1
	s_barrier
	v_mfma_f32_16x16x32_bf16 v[62:65], v[154:157], v[190:193], v[62:65]
	v_mfma_f32_16x16x32_bf16 v[58:61], v[162:165], v[190:193], v[58:61]
	v_mfma_f32_16x16x32_bf16 v[50:53], v[154:157], v[198:201], v[50:53]
	v_mfma_f32_16x16x32_bf16 v[42:45], v[162:165], v[198:201], v[42:45]
	v_mfma_f32_16x16x32_bf16 v[34:37], v[154:157], v[206:209], v[34:37]
	v_mfma_f32_16x16x32_bf16 v[26:29], v[162:165], v[206:209], v[26:29]
	v_mfma_f32_16x16x32_bf16 v[18:21], v[154:157], v[214:217], v[18:21]
	v_mfma_f32_16x16x32_bf16 v[10:13], v[162:165], v[214:217], v[10:13]
	v_mfma_f32_16x16x32_bf16 v[62:65], v[158:161], v[194:197], v[62:65]
	v_mfma_f32_16x16x32_bf16 v[58:61], v[166:169], v[194:197], v[58:61]
	v_mfma_f32_16x16x32_bf16 v[50:53], v[158:161], v[202:205], v[50:53]
	v_mfma_f32_16x16x32_bf16 v[42:45], v[166:169], v[202:205], v[42:45]
	v_mfma_f32_16x16x32_bf16 v[34:37], v[158:161], v[210:213], v[34:37]
	v_mfma_f32_16x16x32_bf16 v[26:29], v[166:169], v[210:213], v[26:29]
	v_mfma_f32_16x16x32_bf16 v[18:21], v[158:161], v[218:221], v[18:21]
	v_mfma_f32_16x16x32_bf16 v[10:13], v[166:169], v[218:221], v[10:13]
	s_setprio 0
	s_setprio 1
	v_mfma_f32_16x16x32_bf16 v[54:57], v[170:173], v[190:193], v[54:57]
	v_mfma_f32_16x16x32_bf16 v[46:49], v[182:185], v[190:193], v[46:49]
	v_mfma_f32_16x16x32_bf16 v[38:41], v[170:173], v[198:201], v[38:41]
	v_mfma_f32_16x16x32_bf16 v[30:33], v[182:185], v[198:201], v[30:33]
	v_mfma_f32_16x16x32_bf16 v[22:25], v[170:173], v[206:209], v[22:25]
	v_mfma_f32_16x16x32_bf16 v[14:17], v[182:185], v[206:209], v[14:17]
	v_mfma_f32_16x16x32_bf16 v[6:9], v[170:173], v[214:217], v[6:9]
	v_mfma_f32_16x16x32_bf16 v[2:5], v[182:185], v[214:217], v[2:5]
	v_mfma_f32_16x16x32_bf16 v[54:57], v[178:181], v[194:197], v[54:57]
	v_mfma_f32_16x16x32_bf16 v[46:49], v[186:189], v[194:197], v[46:49]
	v_mfma_f32_16x16x32_bf16 v[38:41], v[178:181], v[202:205], v[38:41]
	v_mfma_f32_16x16x32_bf16 v[30:33], v[186:189], v[202:205], v[30:33]
	v_mfma_f32_16x16x32_bf16 v[22:25], v[178:181], v[210:213], v[22:25]
	v_mfma_f32_16x16x32_bf16 v[14:17], v[186:189], v[210:213], v[14:17]
	v_mfma_f32_16x16x32_bf16 v[6:9], v[178:181], v[218:221], v[6:9]
	v_mfma_f32_16x16x32_bf16 v[2:5], v[186:189], v[218:221], v[2:5]
	s_barrier
	s_setprio 0
	s_add_i32 s52, s52, 2
	s_add_u32 s26, s26, 0x100
	s_addc_u32 s27, s27, 0
	s_add_u32 s50, s50, 0x100
	s_addc_u32 s51, s51, 0
	s_cmp_gt_u32 s52, 13
	s_cbranch_scc0 .LBB0_555
	s_branch .Lpk555_exit
.LBB0_555:
	ds_read_b128 v[154:157], v151
	ds_read_b128 v[158:161], v151 offset:1024
	ds_read_b128 v[162:165], v151 offset:2048
	ds_read_b128 v[166:169], v151 offset:3072
	ds_read_b128 v[170:173], v152
	ds_read_b128 v[178:181], v152 offset:1024
	ds_read_b128 v[182:185], v152 offset:2048
	ds_read_b128 v[186:189], v152 offset:3072
	s_add_u32 s2, s26, 0xfffc0080
	s_addc_u32 s3, s27, -1
	s_cmp_eq_u32 s52, 12
	s_cselect_b32 s3, s11, s3
	s_cselect_b32 s2, s13, s2
	s_cselect_b32 s29, s48, s51
	s_cselect_b32 s28, s49, s50
	v_lshl_add_u64 v[144:145], s[26:27], 0, v[138:139]
	s_add_i32 m0, s37, 0xc000
	ds_read_b128 v[190:193], v153
	ds_read_b128 v[194:197], v153 offset:1024
	ds_read_b128 v[198:201], v153 offset:2048
	ds_read_b128 v[202:205], v153 offset:3072
	ds_read_b128 v[206:209], v153 offset:4096
	ds_read_b128 v[210:213], v153 offset:5120
	ds_read_b128 v[214:217], v153 offset:6144
	ds_read_b128 v[218:221], v153 offset:7168
	global_load_lds_dwordx4 v[144:145], off
	v_lshl_add_u64 v[144:145], s[26:27], 0, v[140:141]
	s_add_i32 m0, s37, 0xe000
	s_nop 0
	global_load_lds_dwordx4 v[144:145], off
	s_waitcnt vmcnt(8)
	s_waitcnt lgkmcnt(0)
	s_setprio 1
	s_barrier
	v_mfma_f32_16x16x32_bf16 v[126:129], v[154:157], v[190:193], v[126:129]
	v_mfma_f32_16x16x32_bf16 v[122:125], v[162:165], v[190:193], v[122:125]
	v_mfma_f32_16x16x32_bf16 v[114:117], v[154:157], v[198:201], v[114:117]
	v_mfma_f32_16x16x32_bf16 v[106:109], v[162:165], v[198:201], v[106:109]
	v_mfma_f32_16x16x32_bf16 v[98:101], v[154:157], v[206:209], v[98:101]
	v_mfma_f32_16x16x32_bf16 v[90:93], v[162:165], v[206:209], v[90:93]
	v_mfma_f32_16x16x32_bf16 v[82:85], v[154:157], v[214:217], v[82:85]
	v_mfma_f32_16x16x32_bf16 v[74:77], v[162:165], v[214:217], v[74:77]
	v_mfma_f32_16x16x32_bf16 v[126:129], v[158:161], v[194:197], v[126:129]
	v_mfma_f32_16x16x32_bf16 v[122:125], v[166:169], v[194:197], v[122:125]
	v_mfma_f32_16x16x32_bf16 v[114:117], v[158:161], v[202:205], v[114:117]
	v_mfma_f32_16x16x32_bf16 v[106:109], v[166:169], v[202:205], v[106:109]
	v_mfma_f32_16x16x32_bf16 v[98:101], v[158:161], v[210:213], v[98:101]
	v_mfma_f32_16x16x32_bf16 v[90:93], v[166:169], v[210:213], v[90:93]
	v_mfma_f32_16x16x32_bf16 v[82:85], v[158:161], v[218:221], v[82:85]
	v_mfma_f32_16x16x32_bf16 v[74:77], v[166:169], v[218:221], v[74:77]
	s_setprio 0
	s_setprio 1
	v_mfma_f32_16x16x32_bf16 v[118:121], v[170:173], v[190:193], v[118:121]
	v_mfma_f32_16x16x32_bf16 v[110:113], v[182:185], v[190:193], v[110:113]
	v_mfma_f32_16x16x32_bf16 v[102:105], v[170:173], v[198:201], v[102:105]
	v_mfma_f32_16x16x32_bf16 v[94:97], v[182:185], v[198:201], v[94:97]
	v_mfma_f32_16x16x32_bf16 v[86:89], v[170:173], v[206:209], v[86:89]
	v_mfma_f32_16x16x32_bf16 v[78:81], v[182:185], v[206:209], v[78:81]
	v_mfma_f32_16x16x32_bf16 v[70:73], v[170:173], v[214:217], v[70:73]
	v_mfma_f32_16x16x32_bf16 v[66:69], v[182:185], v[214:217], v[66:69]
	v_mfma_f32_16x16x32_bf16 v[118:121], v[178:181], v[194:197], v[118:121]
	v_mfma_f32_16x16x32_bf16 v[110:113], v[186:189], v[194:197], v[110:113]
	v_mfma_f32_16x16x32_bf16 v[102:105], v[178:181], v[202:205], v[102:105]
	v_mfma_f32_16x16x32_bf16 v[94:97], v[186:189], v[202:205], v[94:97]
	v_mfma_f32_16x16x32_bf16 v[86:89], v[178:181], v[210:213], v[86:89]
	v_mfma_f32_16x16x32_bf16 v[78:81], v[186:189], v[210:213], v[78:81]
	v_mfma_f32_16x16x32_bf16 v[70:73], v[178:181], v[218:221], v[70:73]
	v_mfma_f32_16x16x32_bf16 v[66:69], v[186:189], v[218:221], v[66:69]
	s_barrier
	s_setprio 0
	s_add_i32 s53, s44, s34
	v_lshl_add_u64 v[144:145], s[28:29], 0, v[134:135]
	s_mov_b32 m0, s53
	ds_read_b128 v[190:193], v153 offset:16384
	ds_read_b128 v[194:197], v153 offset:17408
	ds_read_b128 v[198:201], v153 offset:18432
	ds_read_b128 v[202:205], v153 offset:19456
	ds_read_b128 v[206:209], v153 offset:20480
	ds_read_b128 v[210:213], v153 offset:21504
	ds_read_b128 v[214:217], v153 offset:22528
	ds_read_b128 v[218:221], v153 offset:23552
	global_load_lds_dwordx4 v[144:145], off
	s_add_i32 m0, s53, 0x2000
	s_add_u32 s54, s28, 0x40000
	v_lshl_add_u64 v[174:175], s[28:29], 0, v[130:131]
	s_addc_u32 s55, s29, 0
	s_add_i32 s53, s45, s34
	global_load_lds_dwordx4 v[174:175], off
	v_lshl_add_u64 v[222:223], s[54:55], 0, v[134:135]
	s_mov_b32 m0, s53
	v_lshl_add_u64 v[224:225], s[2:3], 0, v[132:133]
	global_load_lds_dwordx4 v[222:223], off
	v_lshl_add_u64 v[222:223], s[54:55], 0, v[130:131]
	s_add_i32 m0, s53, 0x2000
	s_nop 0
	global_load_lds_dwordx4 v[222:223], off
	v_lshl_add_u64 v[222:223], s[2:3], 0, v[136:137]
	s_mov_b32 m0, s37
	s_nop 0
	global_load_lds_dwordx4 v[222:223], off
	s_mov_b32 m0, s25
	s_nop 0
	global_load_lds_dwordx4 v[224:225], off
	s_waitcnt vmcnt(8)
	s_waitcnt lgkmcnt(0)
	s_setprio 1
	s_barrier
	v_mfma_f32_16x16x32_bf16 v[62:65], v[154:157], v[190:193], v[62:65]
	v_mfma_f32_16x16x32_bf16 v[58:61], v[162:165], v[190:193], v[58:61]
	v_mfma_f32_16x16x32_bf16 v[50:53], v[154:157], v[198:201], v[50:53]
	v_mfma_f32_16x16x32_bf16 v[42:45], v[162:165], v[198:201], v[42:45]
	v_mfma_f32_16x16x32_bf16 v[34:37], v[154:157], v[206:209], v[34:37]
	v_mfma_f32_16x16x32_bf16 v[26:29], v[162:165], v[206:209], v[26:29]
	v_mfma_f32_16x16x32_bf16 v[18:21], v[154:157], v[214:217], v[18:21]
	v_mfma_f32_16x16x32_bf16 v[10:13], v[162:165], v[214:217], v[10:13]
	v_mfma_f32_16x16x32_bf16 v[62:65], v[158:161], v[194:197], v[62:65]
	v_mfma_f32_16x16x32_bf16 v[58:61], v[166:169], v[194:197], v[58:61]
	v_mfma_f32_16x16x32_bf16 v[50:53], v[158:161], v[202:205], v[50:53]
	v_mfma_f32_16x16x32_bf16 v[42:45], v[166:169], v[202:205], v[42:45]
	v_mfma_f32_16x16x32_bf16 v[34:37], v[158:161], v[210:213], v[34:37]
	v_mfma_f32_16x16x32_bf16 v[26:29], v[166:169], v[210:213], v[26:29]
	v_mfma_f32_16x16x32_bf16 v[18:21], v[158:161], v[218:221], v[18:21]
	v_mfma_f32_16x16x32_bf16 v[10:13], v[166:169], v[218:221], v[10:13]
	s_setprio 0
	s_setprio 1
	v_mfma_f32_16x16x32_bf16 v[54:57], v[170:173], v[190:193], v[54:57]
	v_mfma_f32_16x16x32_bf16 v[46:49], v[182:185], v[190:193], v[46:49]
	v_mfma_f32_16x16x32_bf16 v[38:41], v[170:173], v[198:201], v[38:41]
	v_mfma_f32_16x16x32_bf16 v[30:33], v[182:185], v[198:201], v[30:33]
	v_mfma_f32_16x16x32_bf16 v[22:25], v[170:173], v[206:209], v[22:25]
	v_mfma_f32_16x16x32_bf16 v[14:17], v[182:185], v[206:209], v[14:17]
	v_mfma_f32_16x16x32_bf16 v[6:9], v[170:173], v[214:217], v[6:9]
	v_mfma_f32_16x16x32_bf16 v[2:5], v[182:185], v[214:217], v[2:5]
	v_mfma_f32_16x16x32_bf16 v[54:57], v[178:181], v[194:197], v[54:57]
	v_mfma_f32_16x16x32_bf16 v[46:49], v[186:189], v[194:197], v[46:49]
	v_mfma_f32_16x16x32_bf16 v[38:41], v[178:181], v[202:205], v[38:41]
	v_mfma_f32_16x16x32_bf16 v[30:33], v[186:189], v[202:205], v[30:33]
	v_mfma_f32_16x16x32_bf16 v[22:25], v[178:181], v[210:213], v[22:25]
	v_mfma_f32_16x16x32_bf16 v[14:17], v[186:189], v[210:213], v[14:17]
	v_mfma_f32_16x16x32_bf16 v[6:9], v[178:181], v[218:221], v[6:9]
	v_mfma_f32_16x16x32_bf16 v[2:5], v[186:189], v[218:221], v[2:5]
	s_barrier
	s_setprio 0
	s_add_i32 s53, 0, 0x18000
	s_add_i32 s54, 0, 0x1c000
	v_add_u32_e32 v166, s53, v149
	v_add_u32_e32 v176, s54, v149
	ds_read_b128 v[154:157], v166
	ds_read_b128 v[158:161], v166 offset:1024
	ds_read_b128 v[162:165], v166 offset:2048
	ds_read_b128 v[166:169], v166 offset:3072
	ds_read_b128 v[170:173], v176
	ds_read_b128 v[178:181], v176 offset:1024
	ds_read_b128 v[182:185], v176 offset:2048
	ds_read_b128 v[186:189], v176 offset:3072
	s_add_u32 s2, s2, 0x40000
	s_addc_u32 s3, s3, 0
	s_mov_b32 m0, s38
	v_lshl_add_u64 v[226:227], s[2:3], 0, v[136:137]
	ds_read_b128 v[190:193], v153 offset:32768
	ds_read_b128 v[194:197], v153 offset:33792
	ds_read_b128 v[198:201], v153 offset:34816
	ds_read_b128 v[202:205], v153 offset:35840
	ds_read_b128 v[206:209], v153 offset:36864
	ds_read_b128 v[210:213], v153 offset:37888
	ds_read_b128 v[214:217], v153 offset:38912
	ds_read_b128 v[218:221], v153 offset:39936
	global_load_lds_dwordx4 v[226:227], off
	v_lshl_add_u64 v[226:227], s[2:3], 0, v[132:133]
	s_mov_b32 m0, s39
	s_nop 0
	global_load_lds_dwordx4 v[226:227], off
	s_waitcnt vmcnt(8)
	s_waitcnt lgkmcnt(0)
	s_setprio 1
	s_barrier
	v_mfma_f32_16x16x32_bf16 v[126:129], v[154:157], v[190:193], v[126:129]
	v_mfma_f32_16x16x32_bf16 v[122:125], v[162:165], v[190:193], v[122:125]
	v_mfma_f32_16x16x32_bf16 v[114:117], v[154:157], v[198:201], v[114:117]
	v_mfma_f32_16x16x32_bf16 v[106:109], v[162:165], v[198:201], v[106:109]
	v_mfma_f32_16x16x32_bf16 v[98:101], v[154:157], v[206:209], v[98:101]
	v_mfma_f32_16x16x32_bf16 v[90:93], v[162:165], v[206:209], v[90:93]
	v_mfma_f32_16x16x32_bf16 v[82:85], v[154:157], v[214:217], v[82:85]
	v_mfma_f32_16x16x32_bf16 v[74:77], v[162:165], v[214:217], v[74:77]
	v_mfma_f32_16x16x32_bf16 v[126:129], v[158:161], v[194:197], v[126:129]
	v_mfma_f32_16x16x32_bf16 v[122:125], v[166:169], v[194:197], v[122:125]
	v_mfma_f32_16x16x32_bf16 v[114:117], v[158:161], v[202:205], v[114:117]
	v_mfma_f32_16x16x32_bf16 v[106:109], v[166:169], v[202:205], v[106:109]
	v_mfma_f32_16x16x32_bf16 v[98:101], v[158:161], v[210:213], v[98:101]
	v_mfma_f32_16x16x32_bf16 v[90:93], v[166:169], v[210:213], v[90:93]
	v_mfma_f32_16x16x32_bf16 v[82:85], v[158:161], v[218:221], v[82:85]
	v_mfma_f32_16x16x32_bf16 v[74:77], v[166:169], v[218:221], v[74:77]
	s_setprio 0
	s_setprio 1
	v_mfma_f32_16x16x32_bf16 v[118:121], v[170:173], v[190:193], v[118:121]
	v_mfma_f32_16x16x32_bf16 v[110:113], v[182:185], v[190:193], v[110:113]
	v_mfma_f32_16x16x32_bf16 v[102:105], v[170:173], v[198:201], v[102:105]
	v_mfma_f32_16x16x32_bf16 v[94:97], v[182:185], v[198:201], v[94:97]
	v_mfma_f32_16x16x32_bf16 v[86:89], v[170:173], v[206:209], v[86:89]
	v_mfma_f32_16x16x32_bf16 v[78:81], v[182:185], v[206:209], v[78:81]
	v_mfma_f32_16x16x32_bf16 v[70:73], v[170:173], v[214:217], v[70:73]
	v_mfma_f32_16x16x32_bf16 v[66:69], v[182:185], v[214:217], v[66:69]
	v_mfma_f32_16x16x32_bf16 v[118:121], v[178:181], v[194:197], v[118:121]
	v_mfma_f32_16x16x32_bf16 v[110:113], v[186:189], v[194:197], v[110:113]
	v_mfma_f32_16x16x32_bf16 v[102:105], v[178:181], v[202:205], v[102:105]
	v_mfma_f32_16x16x32_bf16 v[94:97], v[186:189], v[202:205], v[94:97]
	v_mfma_f32_16x16x32_bf16 v[86:89], v[178:181], v[210:213], v[86:89]
	v_mfma_f32_16x16x32_bf16 v[78:81], v[186:189], v[210:213], v[78:81]
	v_mfma_f32_16x16x32_bf16 v[70:73], v[178:181], v[218:221], v[70:73]
	v_mfma_f32_16x16x32_bf16 v[66:69], v[186:189], v[218:221], v[66:69]
	s_barrier
	s_setprio 0
	s_add_i32 s2, s53, s34
	v_lshl_add_u64 v[144:145], v[144:145], 0, s[6:7]
	s_mov_b32 m0, s2
	ds_read_b128 v[190:193], v153 offset:49152
	ds_read_b128 v[194:197], v153 offset:50176
	ds_read_b128 v[198:201], v153 offset:51200
	ds_read_b128 v[202:205], v153 offset:52224
	ds_read_b128 v[206:209], v153 offset:53248
	ds_read_b128 v[210:213], v153 offset:54272
	ds_read_b128 v[214:217], v153 offset:55296
	ds_read_b128 v[218:221], v153 offset:56320
	global_load_lds_dwordx4 v[144:145], off
	s_add_i32 m0, s2, 0x2000
	s_add_u32 s2, s28, 0x40080
	v_lshl_add_u64 v[144:145], v[174:175], 0, s[6:7]
	s_addc_u32 s3, s29, 0
	s_add_i32 s28, s54, s34
	global_load_lds_dwordx4 v[144:145], off
	v_lshl_add_u64 v[144:145], s[2:3], 0, v[134:135]
	s_mov_b32 m0, s28
	s_nop 0
	global_load_lds_dwordx4 v[144:145], off
	v_lshl_add_u64 v[144:145], s[2:3], 0, v[130:131]
	s_add_i32 m0, s28, 0x2000
	s_nop 0
	global_load_lds_dwordx4 v[144:145], off
	v_lshl_add_u64 v[144:145], v[222:223], 0, s[6:7]
	s_mov_b32 m0, s41
	s_nop 0
	global_load_lds_dwordx4 v[144:145], off
	v_lshl_add_u64 v[144:145], v[224:225], 0, s[6:7]
	s_mov_b32 m0, s42
	s_nop 0
	global_load_lds_dwordx4 v[144:145], off
	s_waitcnt vmcnt(8)
	s_waitcnt lgkmcnt(0)
	s_setprio 1
	s_barrier
	v_mfma_f32_16x16x32_bf16 v[62:65], v[154:157], v[190:193], v[62:65]
	v_mfma_f32_16x16x32_bf16 v[58:61], v[162:165], v[190:193], v[58:61]
	v_mfma_f32_16x16x32_bf16 v[50:53], v[154:157], v[198:201], v[50:53]
	v_mfma_f32_16x16x32_bf16 v[42:45], v[162:165], v[198:201], v[42:45]
	v_mfma_f32_16x16x32_bf16 v[34:37], v[154:157], v[206:209], v[34:37]
	v_mfma_f32_16x16x32_bf16 v[26:29], v[162:165], v[206:209], v[26:29]
	v_mfma_f32_16x16x32_bf16 v[18:21], v[154:157], v[214:217], v[18:21]
	v_mfma_f32_16x16x32_bf16 v[10:13], v[162:165], v[214:217], v[10:13]
	v_mfma_f32_16x16x32_bf16 v[62:65], v[158:161], v[194:197], v[62:65]
	v_mfma_f32_16x16x32_bf16 v[58:61], v[166:169], v[194:197], v[58:61]
	v_mfma_f32_16x16x32_bf16 v[50:53], v[158:161], v[202:205], v[50:53]
	v_mfma_f32_16x16x32_bf16 v[42:45], v[166:169], v[202:205], v[42:45]
	v_mfma_f32_16x16x32_bf16 v[34:37], v[158:161], v[210:213], v[34:37]
	v_mfma_f32_16x16x32_bf16 v[26:29], v[166:169], v[210:213], v[26:29]
	v_mfma_f32_16x16x32_bf16 v[18:21], v[158:161], v[218:221], v[18:21]
	v_mfma_f32_16x16x32_bf16 v[10:13], v[166:169], v[218:221], v[10:13]
	s_setprio 0
	s_setprio 1
	v_mfma_f32_16x16x32_bf16 v[54:57], v[170:173], v[190:193], v[54:57]
	v_mfma_f32_16x16x32_bf16 v[46:49], v[182:185], v[190:193], v[46:49]
	v_mfma_f32_16x16x32_bf16 v[38:41], v[170:173], v[198:201], v[38:41]
	v_mfma_f32_16x16x32_bf16 v[30:33], v[182:185], v[198:201], v[30:33]
	v_mfma_f32_16x16x32_bf16 v[22:25], v[170:173], v[206:209], v[22:25]
	v_mfma_f32_16x16x32_bf16 v[14:17], v[182:185], v[206:209], v[14:17]
	v_mfma_f32_16x16x32_bf16 v[6:9], v[170:173], v[214:217], v[6:9]
	v_mfma_f32_16x16x32_bf16 v[2:5], v[182:185], v[214:217], v[2:5]
	v_mfma_f32_16x16x32_bf16 v[54:57], v[178:181], v[194:197], v[54:57]
	v_mfma_f32_16x16x32_bf16 v[46:49], v[186:189], v[194:197], v[46:49]
	v_mfma_f32_16x16x32_bf16 v[38:41], v[178:181], v[202:205], v[38:41]
	v_mfma_f32_16x16x32_bf16 v[30:33], v[186:189], v[202:205], v[30:33]
	v_mfma_f32_16x16x32_bf16 v[22:25], v[178:181], v[210:213], v[22:25]
	v_mfma_f32_16x16x32_bf16 v[14:17], v[186:189], v[210:213], v[14:17]
	v_mfma_f32_16x16x32_bf16 v[6:9], v[178:181], v[218:221], v[6:9]
	v_mfma_f32_16x16x32_bf16 v[2:5], v[186:189], v[218:221], v[2:5]
	s_barrier
	s_setprio 0
	s_add_i32 s52, s52, 2
	s_add_u32 s26, s26, 0x100
	s_addc_u32 s27, s27, 0
	s_add_u32 s50, s50, 0x100
	s_addc_u32 s51, s51, 0
	s_cmp_gt_u32 s52, 13
	s_cbranch_scc0 .LBB0_555

.LBB0_646:
	ds_read_b128 v[152:155], v146
	ds_read_b128 v[156:159], v146 offset:1024
	ds_read_b128 v[160:163], v146 offset:2048
	ds_read_b128 v[164:167], v146 offset:3072
	ds_read_b128 v[168:171], v147
	ds_read_b128 v[172:175], v147 offset:1024
	ds_read_b128 v[178:181], v147 offset:2048
	ds_read_b128 v[182:185], v147 offset:3072
	s_add_u32 s2, s10, s12
	s_addc_u32 s3, s11, s13
	s_add_u32 s2, s2, 0x3400100
	s_addc_u32 s3, s3, 0
	s_add_u32 s14, s24, s12
	s_addc_u32 s15, s25, s13
	s_cmpk_eq_i32 s12, 0x700
	s_cselect_b32 s3, s7, s3
	s_cselect_b32 s2, s6, s2
	s_cselect_b32 s15, s5, s15
	s_cselect_b32 s14, s4, s14
	s_mov_b32 m0, s27
	v_lshl_add_u64 v[218:219], v[138:139], 0, s[12:13]
	ds_read_b128 v[186:189], v148
	ds_read_b128 v[190:193], v148 offset:1024
	ds_read_b128 v[194:197], v148 offset:2048
	ds_read_b128 v[198:201], v148 offset:3072
	ds_read_b128 v[202:205], v148 offset:4096
	ds_read_b128 v[206:209], v148 offset:5120
	ds_read_b128 v[210:213], v148 offset:6144
	ds_read_b128 v[214:217], v148 offset:7168
	global_load_lds_dwordx4 v[218:219], off
	v_lshl_add_u64 v[218:219], v[140:141], 0, s[12:13]
	s_mov_b32 m0, s28
	s_nop 0
	global_load_lds_dwordx4 v[218:219], off
	s_waitcnt vmcnt(8)
	s_waitcnt lgkmcnt(0)
	s_setprio 1
	s_barrier
	v_mfma_f32_16x16x32_bf16 v[126:129], v[152:155], v[186:189], v[126:129]
	v_mfma_f32_16x16x32_bf16 v[122:125], v[160:163], v[186:189], v[122:125]
	v_mfma_f32_16x16x32_bf16 v[114:117], v[152:155], v[194:197], v[114:117]
	v_mfma_f32_16x16x32_bf16 v[106:109], v[160:163], v[194:197], v[106:109]
	v_mfma_f32_16x16x32_bf16 v[98:101], v[152:155], v[202:205], v[98:101]
	v_mfma_f32_16x16x32_bf16 v[90:93], v[160:163], v[202:205], v[90:93]
	v_mfma_f32_16x16x32_bf16 v[82:85], v[152:155], v[210:213], v[82:85]
	v_mfma_f32_16x16x32_bf16 v[74:77], v[160:163], v[210:213], v[74:77]
	v_mfma_f32_16x16x32_bf16 v[126:129], v[156:159], v[190:193], v[126:129]
	v_mfma_f32_16x16x32_bf16 v[122:125], v[164:167], v[190:193], v[122:125]
	v_mfma_f32_16x16x32_bf16 v[114:117], v[156:159], v[198:201], v[114:117]
	v_mfma_f32_16x16x32_bf16 v[106:109], v[164:167], v[198:201], v[106:109]
	v_mfma_f32_16x16x32_bf16 v[98:101], v[156:159], v[206:209], v[98:101]
	v_mfma_f32_16x16x32_bf16 v[90:93], v[164:167], v[206:209], v[90:93]
	v_mfma_f32_16x16x32_bf16 v[82:85], v[156:159], v[214:217], v[82:85]
	v_mfma_f32_16x16x32_bf16 v[74:77], v[164:167], v[214:217], v[74:77]
	s_setprio 0
	s_setprio 1
	v_mfma_f32_16x16x32_bf16 v[118:121], v[168:171], v[186:189], v[118:121]
	v_mfma_f32_16x16x32_bf16 v[110:113], v[178:181], v[186:189], v[110:113]
	v_mfma_f32_16x16x32_bf16 v[102:105], v[168:171], v[194:197], v[102:105]
	v_mfma_f32_16x16x32_bf16 v[94:97], v[178:181], v[194:197], v[94:97]
	v_mfma_f32_16x16x32_bf16 v[86:89], v[168:171], v[202:205], v[86:89]
	v_mfma_f32_16x16x32_bf16 v[78:81], v[178:181], v[202:205], v[78:81]
	v_mfma_f32_16x16x32_bf16 v[70:73], v[168:171], v[210:213], v[70:73]
	v_mfma_f32_16x16x32_bf16 v[66:69], v[178:181], v[210:213], v[66:69]
	v_mfma_f32_16x16x32_bf16 v[118:121], v[172:175], v[190:193], v[118:121]
	v_mfma_f32_16x16x32_bf16 v[110:113], v[182:185], v[190:193], v[110:113]
	v_mfma_f32_16x16x32_bf16 v[102:105], v[172:175], v[198:201], v[102:105]
	v_mfma_f32_16x16x32_bf16 v[94:97], v[182:185], v[198:201], v[94:97]
	v_mfma_f32_16x16x32_bf16 v[86:89], v[172:175], v[206:209], v[86:89]
	v_mfma_f32_16x16x32_bf16 v[78:81], v[182:185], v[206:209], v[78:81]
	v_mfma_f32_16x16x32_bf16 v[70:73], v[172:175], v[214:217], v[70:73]
	v_mfma_f32_16x16x32_bf16 v[66:69], v[182:185], v[214:217], v[66:69]
	s_barrier
	s_setprio 0
	s_mov_b32 m0, s29
	v_lshl_add_u64 v[218:219], s[14:15], 0, v[134:135]
	s_add_u32 s40, s14, 0x40000
	ds_read_b128 v[186:189], v148 offset:16384
	ds_read_b128 v[190:193], v148 offset:17408
	ds_read_b128 v[194:197], v148 offset:18432
	ds_read_b128 v[198:201], v148 offset:19456
	ds_read_b128 v[202:205], v148 offset:20480
	ds_read_b128 v[206:209], v148 offset:21504
	ds_read_b128 v[210:213], v148 offset:22528
	ds_read_b128 v[214:217], v148 offset:23552
	global_load_lds_dwordx4 v[218:219], off
	v_lshl_add_u64 v[220:221], s[14:15], 0, v[130:131]
	s_mov_b32 m0, s30
	s_addc_u32 s41, s15, 0
	global_load_lds_dwordx4 v[220:221], off
	v_lshl_add_u64 v[222:223], s[40:41], 0, v[134:135]
	s_mov_b32 m0, s31
	v_lshl_add_u64 v[224:225], s[2:3], 0, v[132:133]
	global_load_lds_dwordx4 v[222:223], off
	v_lshl_add_u64 v[222:223], s[40:41], 0, v[130:131]
	s_mov_b32 m0, s34
	s_nop 0
	global_load_lds_dwordx4 v[222:223], off
	v_lshl_add_u64 v[222:223], s[2:3], 0, v[136:137]
	s_mov_b32 m0, s18
	s_nop 0
	global_load_lds_dwordx4 v[222:223], off
	s_mov_b32 m0, s1
	s_nop 0
	global_load_lds_dwordx4 v[224:225], off
	s_waitcnt vmcnt(8)
	s_waitcnt lgkmcnt(0)
	s_setprio 1
	s_barrier
	v_mfma_f32_16x16x32_bf16 v[62:65], v[152:155], v[186:189], v[62:65]
	v_mfma_f32_16x16x32_bf16 v[58:61], v[160:163], v[186:189], v[58:61]
	v_mfma_f32_16x16x32_bf16 v[50:53], v[152:155], v[194:197], v[50:53]
	v_mfma_f32_16x16x32_bf16 v[42:45], v[160:163], v[194:197], v[42:45]
	v_mfma_f32_16x16x32_bf16 v[34:37], v[152:155], v[202:205], v[34:37]
	v_mfma_f32_16x16x32_bf16 v[26:29], v[160:163], v[202:205], v[26:29]
	v_mfma_f32_16x16x32_bf16 v[18:21], v[152:155], v[210:213], v[18:21]
	v_mfma_f32_16x16x32_bf16 v[10:13], v[160:163], v[210:213], v[10:13]
	v_mfma_f32_16x16x32_bf16 v[62:65], v[156:159], v[190:193], v[62:65]
	v_mfma_f32_16x16x32_bf16 v[58:61], v[164:167], v[190:193], v[58:61]
	v_mfma_f32_16x16x32_bf16 v[50:53], v[156:159], v[198:201], v[50:53]
	v_mfma_f32_16x16x32_bf16 v[42:45], v[164:167], v[198:201], v[42:45]
	v_mfma_f32_16x16x32_bf16 v[34:37], v[156:159], v[206:209], v[34:37]
	v_mfma_f32_16x16x32_bf16 v[26:29], v[164:167], v[206:209], v[26:29]
	v_mfma_f32_16x16x32_bf16 v[18:21], v[156:159], v[214:217], v[18:21]
	v_mfma_f32_16x16x32_bf16 v[10:13], v[164:167], v[214:217], v[10:13]
	s_setprio 0
	s_setprio 1
	v_mfma_f32_16x16x32_bf16 v[54:57], v[168:171], v[186:189], v[54:57]
	v_mfma_f32_16x16x32_bf16 v[46:49], v[178:181], v[186:189], v[46:49]
	v_mfma_f32_16x16x32_bf16 v[38:41], v[168:171], v[194:197], v[38:41]
	v_mfma_f32_16x16x32_bf16 v[30:33], v[178:181], v[194:197], v[30:33]
	v_mfma_f32_16x16x32_bf16 v[22:25], v[168:171], v[202:205], v[22:25]
	v_mfma_f32_16x16x32_bf16 v[14:17], v[178:181], v[202:205], v[14:17]
	v_mfma_f32_16x16x32_bf16 v[6:9], v[168:171], v[210:213], v[6:9]
	v_mfma_f32_16x16x32_bf16 v[2:5], v[178:181], v[210:213], v[2:5]
	v_mfma_f32_16x16x32_bf16 v[54:57], v[172:175], v[190:193], v[54:57]
	v_mfma_f32_16x16x32_bf16 v[46:49], v[182:185], v[190:193], v[46:49]
	v_mfma_f32_16x16x32_bf16 v[38:41], v[172:175], v[198:201], v[38:41]
	v_mfma_f32_16x16x32_bf16 v[30:33], v[182:185], v[198:201], v[30:33]
	v_mfma_f32_16x16x32_bf16 v[22:25], v[172:175], v[206:209], v[22:25]
	v_mfma_f32_16x16x32_bf16 v[14:17], v[182:185], v[206:209], v[14:17]
	v_mfma_f32_16x16x32_bf16 v[6:9], v[172:175], v[214:217], v[6:9]
	v_mfma_f32_16x16x32_bf16 v[2:5], v[182:185], v[214:217], v[2:5]
	s_barrier
	s_setprio 0
	ds_read_b128 v[152:155], v149
	ds_read_b128 v[156:159], v149 offset:1024
	ds_read_b128 v[160:163], v149 offset:2048
	ds_read_b128 v[164:167], v149 offset:3072
	ds_read_b128 v[168:171], v150
	ds_read_b128 v[172:175], v150 offset:1024
	ds_read_b128 v[178:181], v150 offset:2048
	ds_read_b128 v[182:185], v150 offset:3072
	s_add_u32 s2, s2, 0x40000
	s_addc_u32 s3, s3, 0
	s_mov_b32 m0, s19
	v_lshl_add_u64 v[226:227], s[2:3], 0, v[136:137]
	ds_read_b128 v[186:189], v148 offset:32768
	ds_read_b128 v[190:193], v148 offset:33792
	ds_read_b128 v[194:197], v148 offset:34816
	ds_read_b128 v[198:201], v148 offset:35840
	ds_read_b128 v[202:205], v148 offset:36864
	ds_read_b128 v[206:209], v148 offset:37888
	ds_read_b128 v[210:213], v148 offset:38912
	ds_read_b128 v[214:217], v148 offset:39936
	global_load_lds_dwordx4 v[226:227], off
	v_lshl_add_u64 v[226:227], s[2:3], 0, v[132:133]
	s_mov_b32 m0, s20
	s_nop 0
	global_load_lds_dwordx4 v[226:227], off
	s_waitcnt vmcnt(8)
	s_waitcnt lgkmcnt(0)
	s_setprio 1
	s_barrier
	v_mfma_f32_16x16x32_bf16 v[126:129], v[152:155], v[186:189], v[126:129]
	v_mfma_f32_16x16x32_bf16 v[122:125], v[160:163], v[186:189], v[122:125]
	v_mfma_f32_16x16x32_bf16 v[114:117], v[152:155], v[194:197], v[114:117]
	v_mfma_f32_16x16x32_bf16 v[106:109], v[160:163], v[194:197], v[106:109]
	v_mfma_f32_16x16x32_bf16 v[98:101], v[152:155], v[202:205], v[98:101]
	v_mfma_f32_16x16x32_bf16 v[90:93], v[160:163], v[202:205], v[90:93]
	v_mfma_f32_16x16x32_bf16 v[82:85], v[152:155], v[210:213], v[82:85]
	v_mfma_f32_16x16x32_bf16 v[74:77], v[160:163], v[210:213], v[74:77]
	v_mfma_f32_16x16x32_bf16 v[126:129], v[156:159], v[190:193], v[126:129]
	v_mfma_f32_16x16x32_bf16 v[122:125], v[164:167], v[190:193], v[122:125]
	v_mfma_f32_16x16x32_bf16 v[114:117], v[156:159], v[198:201], v[114:117]
	v_mfma_f32_16x16x32_bf16 v[106:109], v[164:167], v[198:201], v[106:109]
	v_mfma_f32_16x16x32_bf16 v[98:101], v[156:159], v[206:209], v[98:101]
	v_mfma_f32_16x16x32_bf16 v[90:93], v[164:167], v[206:209], v[90:93]
	v_mfma_f32_16x16x32_bf16 v[82:85], v[156:159], v[214:217], v[82:85]
	v_mfma_f32_16x16x32_bf16 v[74:77], v[164:167], v[214:217], v[74:77]
	s_setprio 0
	s_setprio 1
	v_mfma_f32_16x16x32_bf16 v[118:121], v[168:171], v[186:189], v[118:121]
	v_mfma_f32_16x16x32_bf16 v[110:113], v[178:181], v[186:189], v[110:113]
	v_mfma_f32_16x16x32_bf16 v[102:105], v[168:171], v[194:197], v[102:105]
	v_mfma_f32_16x16x32_bf16 v[94:97], v[178:181], v[194:197], v[94:97]
	v_mfma_f32_16x16x32_bf16 v[86:89], v[168:171], v[202:205], v[86:89]
	v_mfma_f32_16x16x32_bf16 v[78:81], v[178:181], v[202:205], v[78:81]
	v_mfma_f32_16x16x32_bf16 v[70:73], v[168:171], v[210:213], v[70:73]
	v_mfma_f32_16x16x32_bf16 v[66:69], v[178:181], v[210:213], v[66:69]
	v_mfma_f32_16x16x32_bf16 v[118:121], v[172:175], v[190:193], v[118:121]
	v_mfma_f32_16x16x32_bf16 v[110:113], v[182:185], v[190:193], v[110:113]
	v_mfma_f32_16x16x32_bf16 v[102:105], v[172:175], v[198:201], v[102:105]
	v_mfma_f32_16x16x32_bf16 v[94:97], v[182:185], v[198:201], v[94:97]
	v_mfma_f32_16x16x32_bf16 v[86:89], v[172:175], v[206:209], v[86:89]
	v_mfma_f32_16x16x32_bf16 v[78:81], v[182:185], v[206:209], v[78:81]
	v_mfma_f32_16x16x32_bf16 v[70:73], v[172:175], v[214:217], v[70:73]
	v_mfma_f32_16x16x32_bf16 v[66:69], v[182:185], v[214:217], v[66:69]
	s_barrier
	s_setprio 0
	s_mov_b32 m0, s35
	v_lshl_add_u64 v[218:219], v[218:219], 0, s[8:9]
	s_add_u32 s2, s14, 0x40080
	ds_read_b128 v[186:189], v148 offset:49152
	ds_read_b128 v[190:193], v148 offset:50176
	ds_read_b128 v[194:197], v148 offset:51200
	ds_read_b128 v[198:201], v148 offset:52224
	ds_read_b128 v[202:205], v148 offset:53248
	ds_read_b128 v[206:209], v148 offset:54272
	ds_read_b128 v[210:213], v148 offset:55296
	ds_read_b128 v[214:217], v148 offset:56320
	global_load_lds_dwordx4 v[218:219], off
	v_lshl_add_u64 v[218:219], v[220:221], 0, s[8:9]
	s_mov_b32 m0, s36
	s_addc_u32 s3, s15, 0
	global_load_lds_dwordx4 v[218:219], off
	v_lshl_add_u64 v[218:219], s[2:3], 0, v[134:135]
	s_mov_b32 m0, s37
	s_nop 0
	global_load_lds_dwordx4 v[218:219], off
	v_lshl_add_u64 v[218:219], s[2:3], 0, v[130:131]
	s_mov_b32 m0, s38
	s_nop 0
	global_load_lds_dwordx4 v[218:219], off
	v_lshl_add_u64 v[218:219], v[222:223], 0, s[8:9]
	s_mov_b32 m0, s22
	s_nop 0
	global_load_lds_dwordx4 v[218:219], off
	v_lshl_add_u64 v[218:219], v[224:225], 0, s[8:9]
	s_mov_b32 m0, s23
	s_nop 0
	global_load_lds_dwordx4 v[218:219], off
	s_waitcnt vmcnt(8)
	s_waitcnt lgkmcnt(0)
	s_setprio 1
	s_barrier
	v_mfma_f32_16x16x32_bf16 v[62:65], v[152:155], v[186:189], v[62:65]
	v_mfma_f32_16x16x32_bf16 v[58:61], v[160:163], v[186:189], v[58:61]
	v_mfma_f32_16x16x32_bf16 v[50:53], v[152:155], v[194:197], v[50:53]
	v_mfma_f32_16x16x32_bf16 v[42:45], v[160:163], v[194:197], v[42:45]
	v_mfma_f32_16x16x32_bf16 v[34:37], v[152:155], v[202:205], v[34:37]
	v_mfma_f32_16x16x32_bf16 v[26:29], v[160:163], v[202:205], v[26:29]
	v_mfma_f32_16x16x32_bf16 v[18:21], v[152:155], v[210:213], v[18:21]
	v_mfma_f32_16x16x32_bf16 v[10:13], v[160:163], v[210:213], v[10:13]
	v_mfma_f32_16x16x32_bf16 v[62:65], v[156:159], v[190:193], v[62:65]
	v_mfma_f32_16x16x32_bf16 v[58:61], v[164:167], v[190:193], v[58:61]
	v_mfma_f32_16x16x32_bf16 v[50:53], v[156:159], v[198:201], v[50:53]
	v_mfma_f32_16x16x32_bf16 v[42:45], v[164:167], v[198:201], v[42:45]
	v_mfma_f32_16x16x32_bf16 v[34:37], v[156:159], v[206:209], v[34:37]
	v_mfma_f32_16x16x32_bf16 v[26:29], v[164:167], v[206:209], v[26:29]
	v_mfma_f32_16x16x32_bf16 v[18:21], v[156:159], v[214:217], v[18:21]
	v_mfma_f32_16x16x32_bf16 v[10:13], v[164:167], v[214:217], v[10:13]
	s_setprio 0
	s_setprio 1
	v_mfma_f32_16x16x32_bf16 v[54:57], v[168:171], v[186:189], v[54:57]
	v_mfma_f32_16x16x32_bf16 v[46:49], v[178:181], v[186:189], v[46:49]
	v_mfma_f32_16x16x32_bf16 v[38:41], v[168:171], v[194:197], v[38:41]
	v_mfma_f32_16x16x32_bf16 v[30:33], v[178:181], v[194:197], v[30:33]
	v_mfma_f32_16x16x32_bf16 v[22:25], v[168:171], v[202:205], v[22:25]
	v_mfma_f32_16x16x32_bf16 v[14:17], v[178:181], v[202:205], v[14:17]
	v_mfma_f32_16x16x32_bf16 v[6:9], v[168:171], v[210:213], v[6:9]
	v_mfma_f32_16x16x32_bf16 v[2:5], v[178:181], v[210:213], v[2:5]
	v_mfma_f32_16x16x32_bf16 v[54:57], v[172:175], v[190:193], v[54:57]
	v_mfma_f32_16x16x32_bf16 v[46:49], v[182:185], v[190:193], v[46:49]
	v_mfma_f32_16x16x32_bf16 v[38:41], v[172:175], v[198:201], v[38:41]
	v_mfma_f32_16x16x32_bf16 v[30:33], v[182:185], v[198:201], v[30:33]
	v_mfma_f32_16x16x32_bf16 v[22:25], v[172:175], v[206:209], v[22:25]
	v_mfma_f32_16x16x32_bf16 v[14:17], v[182:185], v[206:209], v[14:17]
	v_mfma_f32_16x16x32_bf16 v[6:9], v[172:175], v[214:217], v[6:9]
	v_mfma_f32_16x16x32_bf16 v[2:5], v[182:185], v[214:217], v[2:5]
	s_barrier
	s_setprio 0
	s_add_i32 s26, s26, 2
	s_add_u32 s12, s12, 0x100
	s_addc_u32 s13, s13, 0
	s_cmp_gt_u32 s26, 13
	s_cbranch_scc0 .LBB0_646
	s_cmpk_lt_u32 s16, 0x100
	s_mov_b32 s28, s33
	v_readlane_b32 s30, v253, 58
	s_cbranch_scc0 .LBB0_649
	s_barrier

.Lpk1098_peel:
	ds_read_b128 v[152:155], v148
	ds_read_b128 v[156:159], v148 offset:1024
	ds_read_b128 v[160:163], v148 offset:2048
	ds_read_b128 v[164:167], v148 offset:3072
	ds_read_b128 v[168:171], v149
	ds_read_b128 v[172:175], v149 offset:1024
	ds_read_b128 v[178:181], v149 offset:2048
	ds_read_b128 v[182:185], v149 offset:3072
	s_add_u32 s2, s30, 0xfffc0080
	s_addc_u32 s3, s31, -1
	s_cmp_eq_u32 s56, 12
	s_cselect_b32 s3, s15, s3
	s_cselect_b32 s2, s17, s2
	s_cselect_b32 s35, s52, s55
	s_cselect_b32 s34, s53, s54
	v_lshl_add_u64 v[144:145], s[30:31], 0, v[138:139]
	s_add_i32 m0, s40, 0xc000
	ds_read_b128 v[186:189], v150
	ds_read_b128 v[190:193], v150 offset:1024
	ds_read_b128 v[194:197], v150 offset:2048
	ds_read_b128 v[198:201], v150 offset:3072
	ds_read_b128 v[202:205], v150 offset:4096
	ds_read_b128 v[206:209], v150 offset:5120
	ds_read_b128 v[210:213], v150 offset:6144
	ds_read_b128 v[214:217], v150 offset:7168
	global_load_lds_dwordx4 v[144:145], off
	v_lshl_add_u64 v[144:145], s[30:31], 0, v[140:141]
	s_add_i32 m0, s40, 0xe000
	s_nop 0
	global_load_lds_dwordx4 v[144:145], off
	s_waitcnt vmcnt(8)
	s_waitcnt lgkmcnt(0)
	s_setprio 1
	s_barrier
	v_mfma_f32_16x16x32_bf16 v[126:129], v[152:155], v[186:189], 0
	v_mfma_f32_16x16x32_bf16 v[122:125], v[160:163], v[186:189], 0
	v_mfma_f32_16x16x32_bf16 v[114:117], v[152:155], v[194:197], 0
	v_mfma_f32_16x16x32_bf16 v[106:109], v[160:163], v[194:197], 0
	v_mfma_f32_16x16x32_bf16 v[98:101], v[152:155], v[202:205], 0
	v_mfma_f32_16x16x32_bf16 v[90:93], v[160:163], v[202:205], 0
	v_mfma_f32_16x16x32_bf16 v[82:85], v[152:155], v[210:213], 0
	v_mfma_f32_16x16x32_bf16 v[74:77], v[160:163], v[210:213], 0
	v_mfma_f32_16x16x32_bf16 v[126:129], v[156:159], v[190:193], v[126:129]
	v_mfma_f32_16x16x32_bf16 v[122:125], v[164:167], v[190:193], v[122:125]
	v_mfma_f32_16x16x32_bf16 v[114:117], v[156:159], v[198:201], v[114:117]
	v_mfma_f32_16x16x32_bf16 v[106:109], v[164:167], v[198:201], v[106:109]
	v_mfma_f32_16x16x32_bf16 v[98:101], v[156:159], v[206:209], v[98:101]
	v_mfma_f32_16x16x32_bf16 v[90:93], v[164:167], v[206:209], v[90:93]
	v_mfma_f32_16x16x32_bf16 v[82:85], v[156:159], v[214:217], v[82:85]
	v_mfma_f32_16x16x32_bf16 v[74:77], v[164:167], v[214:217], v[74:77]
	s_setprio 0
	s_setprio 1
	v_mfma_f32_16x16x32_bf16 v[118:121], v[168:171], v[186:189], 0
	v_mfma_f32_16x16x32_bf16 v[110:113], v[178:181], v[186:189], 0
	v_mfma_f32_16x16x32_bf16 v[102:105], v[168:171], v[194:197], 0
	v_mfma_f32_16x16x32_bf16 v[94:97], v[178:181], v[194:197], 0
	v_mfma_f32_16x16x32_bf16 v[86:89], v[168:171], v[202:205], 0
	v_mfma_f32_16x16x32_bf16 v[78:81], v[178:181], v[202:205], 0
	v_mfma_f32_16x16x32_bf16 v[70:73], v[168:171], v[210:213], 0
	v_mfma_f32_16x16x32_bf16 v[66:69], v[178:181], v[210:213], 0
	v_mfma_f32_16x16x32_bf16 v[118:121], v[172:175], v[190:193], v[118:121]
	v_mfma_f32_16x16x32_bf16 v[110:113], v[182:185], v[190:193], v[110:113]
	v_mfma_f32_16x16x32_bf16 v[102:105], v[172:175], v[198:201], v[102:105]
	v_mfma_f32_16x16x32_bf16 v[94:97], v[182:185], v[198:201], v[94:97]
	v_mfma_f32_16x16x32_bf16 v[86:89], v[172:175], v[206:209], v[86:89]
	v_mfma_f32_16x16x32_bf16 v[78:81], v[182:185], v[206:209], v[78:81]
	v_mfma_f32_16x16x32_bf16 v[70:73], v[172:175], v[214:217], v[70:73]
	v_mfma_f32_16x16x32_bf16 v[66:69], v[182:185], v[214:217], v[66:69]
	s_barrier
	s_setprio 0
	s_add_i32 s57, s47, s39
	v_lshl_add_u64 v[144:145], s[34:35], 0, v[132:133]
	s_mov_b32 m0, s57
	ds_read_b128 v[186:189], v150 offset:16384
	ds_read_b128 v[190:193], v150 offset:17408
	ds_read_b128 v[194:197], v150 offset:18432
	ds_read_b128 v[198:201], v150 offset:19456
	ds_read_b128 v[202:205], v150 offset:20480
	ds_read_b128 v[206:209], v150 offset:21504
	ds_read_b128 v[210:213], v150 offset:22528
	ds_read_b128 v[214:217], v150 offset:23552
	global_load_lds_dwordx4 v[144:145], off
	s_add_i32 m0, s57, 0x2000
	s_add_u32 s58, s34, 0x40000
	v_lshl_add_u64 v[218:219], s[34:35], 0, v[136:137]
	s_addc_u32 s59, s35, 0
	s_add_i32 s57, s48, s39
	global_load_lds_dwordx4 v[218:219], off
	v_lshl_add_u64 v[220:221], s[58:59], 0, v[132:133]
	s_mov_b32 m0, s57
	v_lshl_add_u64 v[222:223], s[2:3], 0, v[134:135]
	global_load_lds_dwordx4 v[220:221], off
	v_lshl_add_u64 v[220:221], s[58:59], 0, v[136:137]
	s_add_i32 m0, s57, 0x2000
	s_nop 0
	global_load_lds_dwordx4 v[220:221], off
	v_lshl_add_u64 v[220:221], s[2:3], 0, v[130:131]
	s_mov_b32 m0, s40
	s_nop 0
	global_load_lds_dwordx4 v[220:221], off
	s_mov_b32 m0, s29
	s_nop 0
	global_load_lds_dwordx4 v[222:223], off
	s_waitcnt vmcnt(8)
	s_waitcnt lgkmcnt(0)
	s_setprio 1
	s_barrier
	v_mfma_f32_16x16x32_bf16 v[62:65], v[152:155], v[186:189], 0
	v_mfma_f32_16x16x32_bf16 v[58:61], v[160:163], v[186:189], 0
	v_mfma_f32_16x16x32_bf16 v[50:53], v[152:155], v[194:197], 0
	v_mfma_f32_16x16x32_bf16 v[42:45], v[160:163], v[194:197], 0
	v_mfma_f32_16x16x32_bf16 v[34:37], v[152:155], v[202:205], 0
	v_mfma_f32_16x16x32_bf16 v[26:29], v[160:163], v[202:205], 0
	v_mfma_f32_16x16x32_bf16 v[18:21], v[152:155], v[210:213], 0
	v_mfma_f32_16x16x32_bf16 v[10:13], v[160:163], v[210:213], 0
	v_mfma_f32_16x16x32_bf16 v[62:65], v[156:159], v[190:193], v[62:65]
	v_mfma_f32_16x16x32_bf16 v[58:61], v[164:167], v[190:193], v[58:61]
	v_mfma_f32_16x16x32_bf16 v[50:53], v[156:159], v[198:201], v[50:53]
	v_mfma_f32_16x16x32_bf16 v[42:45], v[164:167], v[198:201], v[42:45]
	v_mfma_f32_16x16x32_bf16 v[34:37], v[156:159], v[206:209], v[34:37]
	v_mfma_f32_16x16x32_bf16 v[26:29], v[164:167], v[206:209], v[26:29]
	v_mfma_f32_16x16x32_bf16 v[18:21], v[156:159], v[214:217], v[18:21]
	v_mfma_f32_16x16x32_bf16 v[10:13], v[164:167], v[214:217], v[10:13]
	s_setprio 0
	s_setprio 1
	v_mfma_f32_16x16x32_bf16 v[54:57], v[168:171], v[186:189], 0
	v_mfma_f32_16x16x32_bf16 v[46:49], v[178:181], v[186:189], 0
	v_mfma_f32_16x16x32_bf16 v[38:41], v[168:171], v[194:197], 0
	v_mfma_f32_16x16x32_bf16 v[30:33], v[178:181], v[194:197], 0
	v_mfma_f32_16x16x32_bf16 v[22:25], v[168:171], v[202:205], 0
	v_mfma_f32_16x16x32_bf16 v[14:17], v[178:181], v[202:205], 0
	v_mfma_f32_16x16x32_bf16 v[6:9], v[168:171], v[210:213], 0
	v_mfma_f32_16x16x32_bf16 v[2:5], v[178:181], v[210:213], 0
	v_mfma_f32_16x16x32_bf16 v[54:57], v[172:175], v[190:193], v[54:57]
	v_mfma_f32_16x16x32_bf16 v[46:49], v[182:185], v[190:193], v[46:49]
	v_mfma_f32_16x16x32_bf16 v[38:41], v[172:175], v[198:201], v[38:41]
	v_mfma_f32_16x16x32_bf16 v[30:33], v[182:185], v[198:201], v[30:33]
	v_mfma_f32_16x16x32_bf16 v[22:25], v[172:175], v[206:209], v[22:25]
	v_mfma_f32_16x16x32_bf16 v[14:17], v[182:185], v[206:209], v[14:17]
	v_mfma_f32_16x16x32_bf16 v[6:9], v[172:175], v[214:217], v[6:9]
	v_mfma_f32_16x16x32_bf16 v[2:5], v[182:185], v[214:217], v[2:5]
	s_barrier
	s_setprio 0
	s_add_i32 s57, 0, 0x18000
	v_add_u32_e32 v151, s57, v146
	s_add_i32 s58, 0, 0x1c000
	ds_read_b128 v[152:155], v151
	ds_read_b128 v[156:159], v151 offset:1024
	ds_read_b128 v[160:163], v151 offset:2048
	ds_read_b128 v[164:167], v151 offset:3072
	v_add_u32_e32 v151, s58, v146
	ds_read_b128 v[168:171], v151
	ds_read_b128 v[172:175], v151 offset:1024
	ds_read_b128 v[178:181], v151 offset:2048
	ds_read_b128 v[182:185], v151 offset:3072
	s_add_u32 s2, s2, 0x40000
	s_addc_u32 s3, s3, 0
	s_mov_b32 m0, s41
	v_lshl_add_u64 v[224:225], s[2:3], 0, v[130:131]
	ds_read_b128 v[186:189], v150 offset:32768
	ds_read_b128 v[190:193], v150 offset:33792
	ds_read_b128 v[194:197], v150 offset:34816
	ds_read_b128 v[198:201], v150 offset:35840
	ds_read_b128 v[202:205], v150 offset:36864
	ds_read_b128 v[206:209], v150 offset:37888
	ds_read_b128 v[210:213], v150 offset:38912
	ds_read_b128 v[214:217], v150 offset:39936
	global_load_lds_dwordx4 v[224:225], off
	v_lshl_add_u64 v[224:225], s[2:3], 0, v[134:135]
	s_mov_b32 m0, s42
	s_nop 0
	global_load_lds_dwordx4 v[224:225], off
	s_waitcnt vmcnt(8)
	s_waitcnt lgkmcnt(0)
	s_setprio 1
	s_barrier
	v_mfma_f32_16x16x32_bf16 v[126:129], v[152:155], v[186:189], v[126:129]
	v_mfma_f32_16x16x32_bf16 v[122:125], v[160:163], v[186:189], v[122:125]
	v_mfma_f32_16x16x32_bf16 v[114:117], v[152:155], v[194:197], v[114:117]
	v_mfma_f32_16x16x32_bf16 v[106:109], v[160:163], v[194:197], v[106:109]
	v_mfma_f32_16x16x32_bf16 v[98:101], v[152:155], v[202:205], v[98:101]
	v_mfma_f32_16x16x32_bf16 v[90:93], v[160:163], v[202:205], v[90:93]
	v_mfma_f32_16x16x32_bf16 v[82:85], v[152:155], v[210:213], v[82:85]
	v_mfma_f32_16x16x32_bf16 v[74:77], v[160:163], v[210:213], v[74:77]
	v_mfma_f32_16x16x32_bf16 v[126:129], v[156:159], v[190:193], v[126:129]
	v_mfma_f32_16x16x32_bf16 v[122:125], v[164:167], v[190:193], v[122:125]
	v_mfma_f32_16x16x32_bf16 v[114:117], v[156:159], v[198:201], v[114:117]
	v_mfma_f32_16x16x32_bf16 v[106:109], v[164:167], v[198:201], v[106:109]
	v_mfma_f32_16x16x32_bf16 v[98:101], v[156:159], v[206:209], v[98:101]
	v_mfma_f32_16x16x32_bf16 v[90:93], v[164:167], v[206:209], v[90:93]
	v_mfma_f32_16x16x32_bf16 v[82:85], v[156:159], v[214:217], v[82:85]
	v_mfma_f32_16x16x32_bf16 v[74:77], v[164:167], v[214:217], v[74:77]
	s_setprio 0
	s_setprio 1
	v_mfma_f32_16x16x32_bf16 v[118:121], v[168:171], v[186:189], v[118:121]
	v_mfma_f32_16x16x32_bf16 v[110:113], v[178:181], v[186:189], v[110:113]
	v_mfma_f32_16x16x32_bf16 v[102:105], v[168:171], v[194:197], v[102:105]
	v_mfma_f32_16x16x32_bf16 v[94:97], v[178:181], v[194:197], v[94:97]
	v_mfma_f32_16x16x32_bf16 v[86:89], v[168:171], v[202:205], v[86:89]
	v_mfma_f32_16x16x32_bf16 v[78:81], v[178:181], v[202:205], v[78:81]
	v_mfma_f32_16x16x32_bf16 v[70:73], v[168:171], v[210:213], v[70:73]
	v_mfma_f32_16x16x32_bf16 v[66:69], v[178:181], v[210:213], v[66:69]
	v_mfma_f32_16x16x32_bf16 v[118:121], v[172:175], v[190:193], v[118:121]
	v_mfma_f32_16x16x32_bf16 v[110:113], v[182:185], v[190:193], v[110:113]
	v_mfma_f32_16x16x32_bf16 v[102:105], v[172:175], v[198:201], v[102:105]
	v_mfma_f32_16x16x32_bf16 v[94:97], v[182:185], v[198:201], v[94:97]
	v_mfma_f32_16x16x32_bf16 v[86:89], v[172:175], v[206:209], v[86:89]
	v_mfma_f32_16x16x32_bf16 v[78:81], v[182:185], v[206:209], v[78:81]
	v_mfma_f32_16x16x32_bf16 v[70:73], v[172:175], v[214:217], v[70:73]
	v_mfma_f32_16x16x32_bf16 v[66:69], v[182:185], v[214:217], v[66:69]
	s_barrier
	s_setprio 0
	s_add_i32 s2, s57, s39
	v_lshl_add_u64 v[144:145], v[144:145], 0, s[6:7]
	s_mov_b32 m0, s2
	ds_read_b128 v[186:189], v150 offset:49152
	ds_read_b128 v[190:193], v150 offset:50176
	ds_read_b128 v[194:197], v150 offset:51200
	ds_read_b128 v[198:201], v150 offset:52224
	ds_read_b128 v[202:205], v150 offset:53248
	ds_read_b128 v[206:209], v150 offset:54272
	ds_read_b128 v[210:213], v150 offset:55296
	ds_read_b128 v[214:217], v150 offset:56320
	global_load_lds_dwordx4 v[144:145], off
	s_add_i32 m0, s2, 0x2000
	s_add_u32 s2, s34, 0x40080
	v_lshl_add_u64 v[144:145], v[218:219], 0, s[6:7]
	s_addc_u32 s3, s35, 0
	s_add_i32 s34, s58, s39
	global_load_lds_dwordx4 v[144:145], off
	v_lshl_add_u64 v[144:145], s[2:3], 0, v[132:133]
	s_mov_b32 m0, s34
	s_nop 0
	global_load_lds_dwordx4 v[144:145], off
	v_lshl_add_u64 v[144:145], s[2:3], 0, v[136:137]
	s_add_i32 m0, s34, 0x2000
	s_nop 0
	global_load_lds_dwordx4 v[144:145], off
	v_lshl_add_u64 v[144:145], v[220:221], 0, s[6:7]
	s_mov_b32 m0, s44
	s_nop 0
	global_load_lds_dwordx4 v[144:145], off
	v_lshl_add_u64 v[144:145], v[222:223], 0, s[6:7]
	s_mov_b32 m0, s45
	s_nop 0
	global_load_lds_dwordx4 v[144:145], off
	s_waitcnt vmcnt(8)
	s_waitcnt lgkmcnt(0)
	s_setprio 1
	s_barrier
	v_mfma_f32_16x16x32_bf16 v[62:65], v[152:155], v[186:189], v[62:65]
	v_mfma_f32_16x16x32_bf16 v[58:61], v[160:163], v[186:189], v[58:61]
	v_mfma_f32_16x16x32_bf16 v[50:53], v[152:155], v[194:197], v[50:53]
	v_mfma_f32_16x16x32_bf16 v[42:45], v[160:163], v[194:197], v[42:45]
	v_mfma_f32_16x16x32_bf16 v[34:37], v[152:155], v[202:205], v[34:37]
	v_mfma_f32_16x16x32_bf16 v[26:29], v[160:163], v[202:205], v[26:29]
	v_mfma_f32_16x16x32_bf16 v[18:21], v[152:155], v[210:213], v[18:21]
	v_mfma_f32_16x16x32_bf16 v[10:13], v[160:163], v[210:213], v[10:13]
	v_mfma_f32_16x16x32_bf16 v[62:65], v[156:159], v[190:193], v[62:65]
	v_mfma_f32_16x16x32_bf16 v[58:61], v[164:167], v[190:193], v[58:61]
	v_mfma_f32_16x16x32_bf16 v[50:53], v[156:159], v[198:201], v[50:53]
	v_mfma_f32_16x16x32_bf16 v[42:45], v[164:167], v[198:201], v[42:45]
	v_mfma_f32_16x16x32_bf16 v[34:37], v[156:159], v[206:209], v[34:37]
	v_mfma_f32_16x16x32_bf16 v[26:29], v[164:167], v[206:209], v[26:29]
	v_mfma_f32_16x16x32_bf16 v[18:21], v[156:159], v[214:217], v[18:21]
	v_mfma_f32_16x16x32_bf16 v[10:13], v[164:167], v[214:217], v[10:13]
	s_setprio 0
	s_setprio 1
	v_mfma_f32_16x16x32_bf16 v[54:57], v[168:171], v[186:189], v[54:57]
	v_mfma_f32_16x16x32_bf16 v[46:49], v[178:181], v[186:189], v[46:49]
	v_mfma_f32_16x16x32_bf16 v[38:41], v[168:171], v[194:197], v[38:41]
	v_mfma_f32_16x16x32_bf16 v[30:33], v[178:181], v[194:197], v[30:33]
	v_mfma_f32_16x16x32_bf16 v[22:25], v[168:171], v[202:205], v[22:25]
	v_mfma_f32_16x16x32_bf16 v[14:17], v[178:181], v[202:205], v[14:17]
	v_mfma_f32_16x16x32_bf16 v[6:9], v[168:171], v[210:213], v[6:9]
	v_mfma_f32_16x16x32_bf16 v[2:5], v[178:181], v[210:213], v[2:5]
	v_mfma_f32_16x16x32_bf16 v[54:57], v[172:175], v[190:193], v[54:57]
	v_mfma_f32_16x16x32_bf16 v[46:49], v[182:185], v[190:193], v[46:49]
	v_mfma_f32_16x16x32_bf16 v[38:41], v[172:175], v[198:201], v[38:41]
	v_mfma_f32_16x16x32_bf16 v[30:33], v[182:185], v[198:201], v[30:33]
	v_mfma_f32_16x16x32_bf16 v[22:25], v[172:175], v[206:209], v[22:25]
	v_mfma_f32_16x16x32_bf16 v[14:17], v[182:185], v[206:209], v[14:17]
	v_mfma_f32_16x16x32_bf16 v[6:9], v[172:175], v[214:217], v[6:9]
	v_mfma_f32_16x16x32_bf16 v[2:5], v[182:185], v[214:217], v[2:5]
	s_barrier
	s_setprio 0
	s_add_i32 s56, s56, 2
	s_add_u32 s30, s30, 0x100
	s_addc_u32 s31, s31, 0
	s_add_u32 s54, s54, 0x100
	s_addc_u32 s55, s55, 0
	s_cmp_gt_u32 s56, 13
	s_cbranch_scc0 .LBB0_1098
	s_branch .Lpk1098_exit
.LBB0_1098:
	ds_read_b128 v[152:155], v148
	ds_read_b128 v[156:159], v148 offset:1024
	ds_read_b128 v[160:163], v148 offset:2048
	ds_read_b128 v[164:167], v148 offset:3072
	ds_read_b128 v[168:171], v149
	ds_read_b128 v[172:175], v149 offset:1024
	ds_read_b128 v[178:181], v149 offset:2048
	ds_read_b128 v[182:185], v149 offset:3072
	s_add_u32 s2, s30, 0xfffc0080
	s_addc_u32 s3, s31, -1
	s_cmp_eq_u32 s56, 12
	s_cselect_b32 s3, s15, s3
	s_cselect_b32 s2, s17, s2
	s_cselect_b32 s35, s52, s55
	s_cselect_b32 s34, s53, s54
	v_lshl_add_u64 v[144:145], s[30:31], 0, v[138:139]
	s_add_i32 m0, s40, 0xc000
	ds_read_b128 v[186:189], v150
	ds_read_b128 v[190:193], v150 offset:1024
	ds_read_b128 v[194:197], v150 offset:2048
	ds_read_b128 v[198:201], v150 offset:3072
	ds_read_b128 v[202:205], v150 offset:4096
	ds_read_b128 v[206:209], v150 offset:5120
	ds_read_b128 v[210:213], v150 offset:6144
	ds_read_b128 v[214:217], v150 offset:7168
	global_load_lds_dwordx4 v[144:145], off
	v_lshl_add_u64 v[144:145], s[30:31], 0, v[140:141]
	s_add_i32 m0, s40, 0xe000
	s_nop 0
	global_load_lds_dwordx4 v[144:145], off
	s_waitcnt vmcnt(8)
	s_waitcnt lgkmcnt(0)
	s_setprio 1
	s_barrier
	v_mfma_f32_16x16x32_bf16 v[126:129], v[152:155], v[186:189], v[126:129]
	v_mfma_f32_16x16x32_bf16 v[122:125], v[160:163], v[186:189], v[122:125]
	v_mfma_f32_16x16x32_bf16 v[114:117], v[152:155], v[194:197], v[114:117]
	v_mfma_f32_16x16x32_bf16 v[106:109], v[160:163], v[194:197], v[106:109]
	v_mfma_f32_16x16x32_bf16 v[98:101], v[152:155], v[202:205], v[98:101]
	v_mfma_f32_16x16x32_bf16 v[90:93], v[160:163], v[202:205], v[90:93]
	v_mfma_f32_16x16x32_bf16 v[82:85], v[152:155], v[210:213], v[82:85]
	v_mfma_f32_16x16x32_bf16 v[74:77], v[160:163], v[210:213], v[74:77]
	v_mfma_f32_16x16x32_bf16 v[126:129], v[156:159], v[190:193], v[126:129]
	v_mfma_f32_16x16x32_bf16 v[122:125], v[164:167], v[190:193], v[122:125]
	v_mfma_f32_16x16x32_bf16 v[114:117], v[156:159], v[198:201], v[114:117]
	v_mfma_f32_16x16x32_bf16 v[106:109], v[164:167], v[198:201], v[106:109]
	v_mfma_f32_16x16x32_bf16 v[98:101], v[156:159], v[206:209], v[98:101]
	v_mfma_f32_16x16x32_bf16 v[90:93], v[164:167], v[206:209], v[90:93]
	v_mfma_f32_16x16x32_bf16 v[82:85], v[156:159], v[214:217], v[82:85]
	v_mfma_f32_16x16x32_bf16 v[74:77], v[164:167], v[214:217], v[74:77]
	s_setprio 0
	s_setprio 1
	v_mfma_f32_16x16x32_bf16 v[118:121], v[168:171], v[186:189], v[118:121]
	v_mfma_f32_16x16x32_bf16 v[110:113], v[178:181], v[186:189], v[110:113]
	v_mfma_f32_16x16x32_bf16 v[102:105], v[168:171], v[194:197], v[102:105]
	v_mfma_f32_16x16x32_bf16 v[94:97], v[178:181], v[194:197], v[94:97]
	v_mfma_f32_16x16x32_bf16 v[86:89], v[168:171], v[202:205], v[86:89]
	v_mfma_f32_16x16x32_bf16 v[78:81], v[178:181], v[202:205], v[78:81]
	v_mfma_f32_16x16x32_bf16 v[70:73], v[168:171], v[210:213], v[70:73]
	v_mfma_f32_16x16x32_bf16 v[66:69], v[178:181], v[210:213], v[66:69]
	v_mfma_f32_16x16x32_bf16 v[118:121], v[172:175], v[190:193], v[118:121]
	v_mfma_f32_16x16x32_bf16 v[110:113], v[182:185], v[190:193], v[110:113]
	v_mfma_f32_16x16x32_bf16 v[102:105], v[172:175], v[198:201], v[102:105]
	v_mfma_f32_16x16x32_bf16 v[94:97], v[182:185], v[198:201], v[94:97]
	v_mfma_f32_16x16x32_bf16 v[86:89], v[172:175], v[206:209], v[86:89]
	v_mfma_f32_16x16x32_bf16 v[78:81], v[182:185], v[206:209], v[78:81]
	v_mfma_f32_16x16x32_bf16 v[70:73], v[172:175], v[214:217], v[70:73]
	v_mfma_f32_16x16x32_bf16 v[66:69], v[182:185], v[214:217], v[66:69]
	s_barrier
	s_setprio 0
	s_add_i32 s57, s47, s39
	v_lshl_add_u64 v[144:145], s[34:35], 0, v[132:133]
	s_mov_b32 m0, s57
	ds_read_b128 v[186:189], v150 offset:16384
	ds_read_b128 v[190:193], v150 offset:17408
	ds_read_b128 v[194:197], v150 offset:18432
	ds_read_b128 v[198:201], v150 offset:19456
	ds_read_b128 v[202:205], v150 offset:20480
	ds_read_b128 v[206:209], v150 offset:21504
	ds_read_b128 v[210:213], v150 offset:22528
	ds_read_b128 v[214:217], v150 offset:23552
	global_load_lds_dwordx4 v[144:145], off
	s_add_i32 m0, s57, 0x2000
	s_add_u32 s58, s34, 0x40000
	v_lshl_add_u64 v[218:219], s[34:35], 0, v[136:137]
	s_addc_u32 s59, s35, 0
	s_add_i32 s57, s48, s39
	global_load_lds_dwordx4 v[218:219], off
	v_lshl_add_u64 v[220:221], s[58:59], 0, v[132:133]
	s_mov_b32 m0, s57
	v_lshl_add_u64 v[222:223], s[2:3], 0, v[134:135]
	global_load_lds_dwordx4 v[220:221], off
	v_lshl_add_u64 v[220:221], s[58:59], 0, v[136:137]
	s_add_i32 m0, s57, 0x2000
	s_nop 0
	global_load_lds_dwordx4 v[220:221], off
	v_lshl_add_u64 v[220:221], s[2:3], 0, v[130:131]
	s_mov_b32 m0, s40
	s_nop 0
	global_load_lds_dwordx4 v[220:221], off
	s_mov_b32 m0, s29
	s_nop 0
	global_load_lds_dwordx4 v[222:223], off
	s_waitcnt vmcnt(8)
	s_waitcnt lgkmcnt(0)
	s_setprio 1
	s_barrier
	v_mfma_f32_16x16x32_bf16 v[62:65], v[152:155], v[186:189], v[62:65]
	v_mfma_f32_16x16x32_bf16 v[58:61], v[160:163], v[186:189], v[58:61]
	v_mfma_f32_16x16x32_bf16 v[50:53], v[152:155], v[194:197], v[50:53]
	v_mfma_f32_16x16x32_bf16 v[42:45], v[160:163], v[194:197], v[42:45]
	v_mfma_f32_16x16x32_bf16 v[34:37], v[152:155], v[202:205], v[34:37]
	v_mfma_f32_16x16x32_bf16 v[26:29], v[160:163], v[202:205], v[26:29]
	v_mfma_f32_16x16x32_bf16 v[18:21], v[152:155], v[210:213], v[18:21]
	v_mfma_f32_16x16x32_bf16 v[10:13], v[160:163], v[210:213], v[10:13]
	v_mfma_f32_16x16x32_bf16 v[62:65], v[156:159], v[190:193], v[62:65]
	v_mfma_f32_16x16x32_bf16 v[58:61], v[164:167], v[190:193], v[58:61]
	v_mfma_f32_16x16x32_bf16 v[50:53], v[156:159], v[198:201], v[50:53]
	v_mfma_f32_16x16x32_bf16 v[42:45], v[164:167], v[198:201], v[42:45]
	v_mfma_f32_16x16x32_bf16 v[34:37], v[156:159], v[206:209], v[34:37]
	v_mfma_f32_16x16x32_bf16 v[26:29], v[164:167], v[206:209], v[26:29]
	v_mfma_f32_16x16x32_bf16 v[18:21], v[156:159], v[214:217], v[18:21]
	v_mfma_f32_16x16x32_bf16 v[10:13], v[164:167], v[214:217], v[10:13]
	s_setprio 0
	s_setprio 1
	v_mfma_f32_16x16x32_bf16 v[54:57], v[168:171], v[186:189], v[54:57]
	v_mfma_f32_16x16x32_bf16 v[46:49], v[178:181], v[186:189], v[46:49]
	v_mfma_f32_16x16x32_bf16 v[38:41], v[168:171], v[194:197], v[38:41]
	v_mfma_f32_16x16x32_bf16 v[30:33], v[178:181], v[194:197], v[30:33]
	v_mfma_f32_16x16x32_bf16 v[22:25], v[168:171], v[202:205], v[22:25]
	v_mfma_f32_16x16x32_bf16 v[14:17], v[178:181], v[202:205], v[14:17]
	v_mfma_f32_16x16x32_bf16 v[6:9], v[168:171], v[210:213], v[6:9]
	v_mfma_f32_16x16x32_bf16 v[2:5], v[178:181], v[210:213], v[2:5]
	v_mfma_f32_16x16x32_bf16 v[54:57], v[172:175], v[190:193], v[54:57]
	v_mfma_f32_16x16x32_bf16 v[46:49], v[182:185], v[190:193], v[46:49]
	v_mfma_f32_16x16x32_bf16 v[38:41], v[172:175], v[198:201], v[38:41]
	v_mfma_f32_16x16x32_bf16 v[30:33], v[182:185], v[198:201], v[30:33]
	v_mfma_f32_16x16x32_bf16 v[22:25], v[172:175], v[206:209], v[22:25]
	v_mfma_f32_16x16x32_bf16 v[14:17], v[182:185], v[206:209], v[14:17]
	v_mfma_f32_16x16x32_bf16 v[6:9], v[172:175], v[214:217], v[6:9]
	v_mfma_f32_16x16x32_bf16 v[2:5], v[182:185], v[214:217], v[2:5]
	s_barrier
	s_setprio 0
	s_add_i32 s57, 0, 0x18000
	v_add_u32_e32 v151, s57, v146
	s_add_i32 s58, 0, 0x1c000
	ds_read_b128 v[152:155], v151
	ds_read_b128 v[156:159], v151 offset:1024
	ds_read_b128 v[160:163], v151 offset:2048
	ds_read_b128 v[164:167], v151 offset:3072
	v_add_u32_e32 v151, s58, v146
	ds_read_b128 v[168:171], v151
	ds_read_b128 v[172:175], v151 offset:1024
	ds_read_b128 v[178:181], v151 offset:2048
	ds_read_b128 v[182:185], v151 offset:3072
	s_add_u32 s2, s2, 0x40000
	s_addc_u32 s3, s3, 0
	s_mov_b32 m0, s41
	v_lshl_add_u64 v[224:225], s[2:3], 0, v[130:131]
	ds_read_b128 v[186:189], v150 offset:32768
	ds_read_b128 v[190:193], v150 offset:33792
	ds_read_b128 v[194:197], v150 offset:34816
	ds_read_b128 v[198:201], v150 offset:35840
	ds_read_b128 v[202:205], v150 offset:36864
	ds_read_b128 v[206:209], v150 offset:37888
	ds_read_b128 v[210:213], v150 offset:38912
	ds_read_b128 v[214:217], v150 offset:39936
	global_load_lds_dwordx4 v[224:225], off
	v_lshl_add_u64 v[224:225], s[2:3], 0, v[134:135]
	s_mov_b32 m0, s42
	s_nop 0
	global_load_lds_dwordx4 v[224:225], off
	s_waitcnt vmcnt(8)
	s_waitcnt lgkmcnt(0)
	s_setprio 1
	s_barrier
	v_mfma_f32_16x16x32_bf16 v[126:129], v[152:155], v[186:189], v[126:129]
	v_mfma_f32_16x16x32_bf16 v[122:125], v[160:163], v[186:189], v[122:125]
	v_mfma_f32_16x16x32_bf16 v[114:117], v[152:155], v[194:197], v[114:117]
	v_mfma_f32_16x16x32_bf16 v[106:109], v[160:163], v[194:197], v[106:109]
	v_mfma_f32_16x16x32_bf16 v[98:101], v[152:155], v[202:205], v[98:101]
	v_mfma_f32_16x16x32_bf16 v[90:93], v[160:163], v[202:205], v[90:93]
	v_mfma_f32_16x16x32_bf16 v[82:85], v[152:155], v[210:213], v[82:85]
	v_mfma_f32_16x16x32_bf16 v[74:77], v[160:163], v[210:213], v[74:77]
	v_mfma_f32_16x16x32_bf16 v[126:129], v[156:159], v[190:193], v[126:129]
	v_mfma_f32_16x16x32_bf16 v[122:125], v[164:167], v[190:193], v[122:125]
	v_mfma_f32_16x16x32_bf16 v[114:117], v[156:159], v[198:201], v[114:117]
	v_mfma_f32_16x16x32_bf16 v[106:109], v[164:167], v[198:201], v[106:109]
	v_mfma_f32_16x16x32_bf16 v[98:101], v[156:159], v[206:209], v[98:101]
	v_mfma_f32_16x16x32_bf16 v[90:93], v[164:167], v[206:209], v[90:93]
	v_mfma_f32_16x16x32_bf16 v[82:85], v[156:159], v[214:217], v[82:85]
	v_mfma_f32_16x16x32_bf16 v[74:77], v[164:167], v[214:217], v[74:77]
	s_setprio 0
	s_setprio 1
	v_mfma_f32_16x16x32_bf16 v[118:121], v[168:171], v[186:189], v[118:121]
	v_mfma_f32_16x16x32_bf16 v[110:113], v[178:181], v[186:189], v[110:113]
	v_mfma_f32_16x16x32_bf16 v[102:105], v[168:171], v[194:197], v[102:105]
	v_mfma_f32_16x16x32_bf16 v[94:97], v[178:181], v[194:197], v[94:97]
	v_mfma_f32_16x16x32_bf16 v[86:89], v[168:171], v[202:205], v[86:89]
	v_mfma_f32_16x16x32_bf16 v[78:81], v[178:181], v[202:205], v[78:81]
	v_mfma_f32_16x16x32_bf16 v[70:73], v[168:171], v[210:213], v[70:73]
	v_mfma_f32_16x16x32_bf16 v[66:69], v[178:181], v[210:213], v[66:69]
	v_mfma_f32_16x16x32_bf16 v[118:121], v[172:175], v[190:193], v[118:121]
	v_mfma_f32_16x16x32_bf16 v[110:113], v[182:185], v[190:193], v[110:113]
	v_mfma_f32_16x16x32_bf16 v[102:105], v[172:175], v[198:201], v[102:105]
	v_mfma_f32_16x16x32_bf16 v[94:97], v[182:185], v[198:201], v[94:97]
	v_mfma_f32_16x16x32_bf16 v[86:89], v[172:175], v[206:209], v[86:89]
	v_mfma_f32_16x16x32_bf16 v[78:81], v[182:185], v[206:209], v[78:81]
	v_mfma_f32_16x16x32_bf16 v[70:73], v[172:175], v[214:217], v[70:73]
	v_mfma_f32_16x16x32_bf16 v[66:69], v[182:185], v[214:217], v[66:69]
	s_barrier
	s_setprio 0
	s_add_i32 s2, s57, s39
	v_lshl_add_u64 v[144:145], v[144:145], 0, s[6:7]
	s_mov_b32 m0, s2
	ds_read_b128 v[186:189], v150 offset:49152
	ds_read_b128 v[190:193], v150 offset:50176
	ds_read_b128 v[194:197], v150 offset:51200
	ds_read_b128 v[198:201], v150 offset:52224
	ds_read_b128 v[202:205], v150 offset:53248
	ds_read_b128 v[206:209], v150 offset:54272
	ds_read_b128 v[210:213], v150 offset:55296
	ds_read_b128 v[214:217], v150 offset:56320
	global_load_lds_dwordx4 v[144:145], off
	s_add_i32 m0, s2, 0x2000
	s_add_u32 s2, s34, 0x40080
	v_lshl_add_u64 v[144:145], v[218:219], 0, s[6:7]
	s_addc_u32 s3, s35, 0
	s_add_i32 s34, s58, s39
	global_load_lds_dwordx4 v[144:145], off
	v_lshl_add_u64 v[144:145], s[2:3], 0, v[132:133]
	s_mov_b32 m0, s34
	s_nop 0
	global_load_lds_dwordx4 v[144:145], off
	v_lshl_add_u64 v[144:145], s[2:3], 0, v[136:137]
	s_add_i32 m0, s34, 0x2000
	s_nop 0
	global_load_lds_dwordx4 v[144:145], off
	v_lshl_add_u64 v[144:145], v[220:221], 0, s[6:7]
	s_mov_b32 m0, s44
	s_nop 0
	global_load_lds_dwordx4 v[144:145], off
	v_lshl_add_u64 v[144:145], v[222:223], 0, s[6:7]
	s_mov_b32 m0, s45
	s_nop 0
	global_load_lds_dwordx4 v[144:145], off
	s_waitcnt vmcnt(8)
	s_waitcnt lgkmcnt(0)
	s_setprio 1
	s_barrier
	v_mfma_f32_16x16x32_bf16 v[62:65], v[152:155], v[186:189], v[62:65]
	v_mfma_f32_16x16x32_bf16 v[58:61], v[160:163], v[186:189], v[58:61]
	v_mfma_f32_16x16x32_bf16 v[50:53], v[152:155], v[194:197], v[50:53]
	v_mfma_f32_16x16x32_bf16 v[42:45], v[160:163], v[194:197], v[42:45]
	v_mfma_f32_16x16x32_bf16 v[34:37], v[152:155], v[202:205], v[34:37]
	v_mfma_f32_16x16x32_bf16 v[26:29], v[160:163], v[202:205], v[26:29]
	v_mfma_f32_16x16x32_bf16 v[18:21], v[152:155], v[210:213], v[18:21]
	v_mfma_f32_16x16x32_bf16 v[10:13], v[160:163], v[210:213], v[10:13]
	v_mfma_f32_16x16x32_bf16 v[62:65], v[156:159], v[190:193], v[62:65]
	v_mfma_f32_16x16x32_bf16 v[58:61], v[164:167], v[190:193], v[58:61]
	v_mfma_f32_16x16x32_bf16 v[50:53], v[156:159], v[198:201], v[50:53]
	v_mfma_f32_16x16x32_bf16 v[42:45], v[164:167], v[198:201], v[42:45]
	v_mfma_f32_16x16x32_bf16 v[34:37], v[156:159], v[206:209], v[34:37]
	v_mfma_f32_16x16x32_bf16 v[26:29], v[164:167], v[206:209], v[26:29]
	v_mfma_f32_16x16x32_bf16 v[18:21], v[156:159], v[214:217], v[18:21]
	v_mfma_f32_16x16x32_bf16 v[10:13], v[164:167], v[214:217], v[10:13]
	s_setprio 0
	s_setprio 1
	v_mfma_f32_16x16x32_bf16 v[54:57], v[168:171], v[186:189], v[54:57]
	v_mfma_f32_16x16x32_bf16 v[46:49], v[178:181], v[186:189], v[46:49]
	v_mfma_f32_16x16x32_bf16 v[38:41], v[168:171], v[194:197], v[38:41]
	v_mfma_f32_16x16x32_bf16 v[30:33], v[178:181], v[194:197], v[30:33]
	v_mfma_f32_16x16x32_bf16 v[22:25], v[168:171], v[202:205], v[22:25]
	v_mfma_f32_16x16x32_bf16 v[14:17], v[178:181], v[202:205], v[14:17]
	v_mfma_f32_16x16x32_bf16 v[6:9], v[168:171], v[210:213], v[6:9]
	v_mfma_f32_16x16x32_bf16 v[2:5], v[178:181], v[210:213], v[2:5]
	v_mfma_f32_16x16x32_bf16 v[54:57], v[172:175], v[190:193], v[54:57]
	v_mfma_f32_16x16x32_bf16 v[46:49], v[182:185], v[190:193], v[46:49]
	v_mfma_f32_16x16x32_bf16 v[38:41], v[172:175], v[198:201], v[38:41]
	v_mfma_f32_16x16x32_bf16 v[30:33], v[182:185], v[198:201], v[30:33]
	v_mfma_f32_16x16x32_bf16 v[22:25], v[172:175], v[206:209], v[22:25]
	v_mfma_f32_16x16x32_bf16 v[14:17], v[182:185], v[206:209], v[14:17]
	v_mfma_f32_16x16x32_bf16 v[6:9], v[172:175], v[214:217], v[6:9]
	v_mfma_f32_16x16x32_bf16 v[2:5], v[182:185], v[214:217], v[2:5]
	s_barrier
	s_setprio 0
	s_add_i32 s56, s56, 2
	s_add_u32 s30, s30, 0x100
	s_addc_u32 s31, s31, 0
	s_add_u32 s54, s54, 0x100
	s_addc_u32 s55, s55, 0
	s_cmp_gt_u32 s56, 13
	s_cbranch_scc0 .LBB0_1098

.LBB0_1137:
	s_add_i32 s26, 0, 0x18000
	s_add_i32 s3, s26, s18
	s_mov_b64 s[24:25], 0x80
	v_lshl_add_u64 v[4:5], v[26:27], 0, s[24:25]
	s_mov_b32 m0, s3
	s_add_i32 s5, s3, 0x2000
	s_waitcnt vmcnt(2)
	s_barrier
	global_load_lds_dwordx4 v[4:5], off
	v_lshl_add_u64 v[6:7], v[28:29], 0, s[24:25]
	s_mov_b32 m0, s5
	s_add_i32 s4, s15, 0x8000
	global_load_lds_dwordx4 v[6:7], off
	v_lshl_add_u64 v[2:3], v[20:21], 0, s[24:25]
	s_mov_b32 m0, s4
	s_add_i32 s9, s15, 0xa000
	s_add_i32 s27, 0, 0x1c000
	global_load_lds_dwordx4 v[2:3], off
	v_lshl_add_u64 v[8:9], v[22:23], 0, s[24:25]
	s_mov_b32 m0, s9
	s_add_i32 s13, s27, s18
	global_load_lds_dwordx4 v[8:9], off
	v_lshl_add_u64 v[10:11], v[24:25], 0, s[24:25]
	s_mov_b32 m0, s13
	s_add_i32 s14, s13, 0x2000
	global_load_lds_dwordx4 v[10:11], off
	v_lshl_add_u64 v[12:13], v[18:19], 0, s[24:25]
	s_mov_b32 m0, s14
	v_and_b32_e32 v30, 15, v0
	global_load_lds_dwordx4 v[12:13], off
	v_lshlrev_b32_e32 v31, 1, v1
	v_lshlrev_b32_e32 v32, 2, v0
	v_lshl_or_b32 v130, s17, 6, v30
	v_lshl_or_b32 v30, v30, 6, v31
	s_lshl_b32 s2, s17, 13
	v_and_b32_e32 v32, 32, v32
	v_bitop3_b32 v62, v30, s2, v32 bitop3:0xde
	s_lshl_b32 s2, s19, 5
	s_and_b32 s2, s2, 0x60
	v_lshlrev_b32_e32 v30, 6, v0
	s_movk_i32 s17, 0x3c0
	v_and_or_b32 v30, v30, s17, v31
	s_lshl_b32 s17, s2, 7
	v_bitop3_b32 v63, s17, v30, v32 bitop3:0xf6
	s_add_i32 s29, 0, 0x10000
	s_add_i32 s28, 0, 0x14000
	v_add_u32_e32 v176, s29, v63
	s_waitcnt vmcnt(6)
	s_barrier
	v_add_u32_e32 v131, s28, v63
	ds_read_b128 v[30:33], v176
	ds_read_b128 v[34:37], v176 offset:1024
	ds_read_b128 v[38:41], v176 offset:2048
	ds_read_b128 v[42:45], v176 offset:3072
	ds_read_b128 v[46:49], v131
	ds_read_b128 v[50:53], v131 offset:1024
	ds_read_b128 v[54:57], v131 offset:2048
	ds_read_b128 v[58:61], v131 offset:3072
	s_add_i32 s20, s29, s18
	s_add_i32 s18, s28, s18
	s_add_i32 s22, s15, 0xc000
	s_add_i32 s21, s15, 0xe000
	s_add_i32 s19, s20, 0x2000
	s_add_i32 s17, s18, 0x2000
	s_cmpk_gt_u32 s23, 0xff
	v_add_u32_e32 v242, 0, v62
	v_add_u32_e32 v238, s27, v63
	v_add_u32_e32 v239, s26, v63
	s_mov_b32 m0, s22
	v_lshl_add_u64 v[94:95], v[14:15], 0, s[24:25]
	ds_read_b128 v[62:65], v242
	ds_read_b128 v[66:69], v242 offset:1024
	ds_read_b128 v[70:73], v242 offset:2048
	ds_read_b128 v[74:77], v242 offset:3072
	ds_read_b128 v[78:81], v242 offset:4096
	ds_read_b128 v[82:85], v242 offset:5120
	ds_read_b128 v[86:89], v242 offset:6144
	ds_read_b128 v[90:93], v242 offset:7168
	global_load_lds_dwordx4 v[94:95], off
	v_lshl_add_u64 v[94:95], v[16:17], 0, s[24:25]
	s_mov_b32 m0, s21
	s_nop 0
	global_load_lds_dwordx4 v[94:95], off
	s_waitcnt vmcnt(8)
	s_waitcnt lgkmcnt(0)
	s_setprio 1
	s_barrier
	v_mfma_f32_16x16x32_bf16 v[94:97], v[30:33], v[62:65], 0
	v_mfma_f32_16x16x32_bf16 v[98:101], v[38:41], v[62:65], 0
	v_mfma_f32_16x16x32_bf16 v[102:105], v[30:33], v[70:73], 0
	v_mfma_f32_16x16x32_bf16 v[106:109], v[38:41], v[70:73], 0
	v_mfma_f32_16x16x32_bf16 v[110:113], v[30:33], v[78:81], 0
	v_mfma_f32_16x16x32_bf16 v[114:117], v[38:41], v[78:81], 0
	v_mfma_f32_16x16x32_bf16 v[118:121], v[30:33], v[86:89], 0
	v_mfma_f32_16x16x32_bf16 v[122:125], v[38:41], v[86:89], 0
	v_mfma_f32_16x16x32_bf16 v[94:97], v[34:37], v[66:69], v[94:97]
	v_mfma_f32_16x16x32_bf16 v[98:101], v[42:45], v[66:69], v[98:101]
	v_mfma_f32_16x16x32_bf16 v[102:105], v[34:37], v[74:77], v[102:105]
	v_mfma_f32_16x16x32_bf16 v[106:109], v[42:45], v[74:77], v[106:109]
	v_mfma_f32_16x16x32_bf16 v[110:113], v[34:37], v[82:85], v[110:113]
	v_mfma_f32_16x16x32_bf16 v[114:117], v[42:45], v[82:85], v[114:117]
	v_mfma_f32_16x16x32_bf16 v[118:121], v[34:37], v[90:93], v[118:121]
	v_mfma_f32_16x16x32_bf16 v[122:125], v[42:45], v[90:93], v[122:125]
	s_setprio 0
	s_setprio 1
	v_mfma_f32_16x16x32_bf16 v[126:129], v[46:49], v[62:65], 0
	v_mfma_f32_16x16x32_bf16 v[62:65], v[54:57], v[62:65], 0
	v_mfma_f32_16x16x32_bf16 v[126:129], v[50:53], v[66:69], v[126:129]
	v_mfma_f32_16x16x32_bf16 v[62:65], v[58:61], v[66:69], v[62:65]
	v_mfma_f32_16x16x32_bf16 v[66:69], v[46:49], v[70:73], 0
	v_mfma_f32_16x16x32_bf16 v[70:73], v[54:57], v[70:73], 0
	v_mfma_f32_16x16x32_bf16 v[66:69], v[50:53], v[74:77], v[66:69]
	v_mfma_f32_16x16x32_bf16 v[70:73], v[58:61], v[74:77], v[70:73]
	v_mfma_f32_16x16x32_bf16 v[74:77], v[46:49], v[78:81], 0
	v_mfma_f32_16x16x32_bf16 v[78:81], v[54:57], v[78:81], 0
	v_mfma_f32_16x16x32_bf16 v[74:77], v[50:53], v[82:85], v[74:77]
	v_mfma_f32_16x16x32_bf16 v[78:81], v[58:61], v[82:85], v[78:81]
	v_mfma_f32_16x16x32_bf16 v[82:85], v[46:49], v[86:89], 0
	v_mfma_f32_16x16x32_bf16 v[86:89], v[54:57], v[86:89], 0
	v_mfma_f32_16x16x32_bf16 v[82:85], v[50:53], v[90:93], v[82:85]
	v_mfma_f32_16x16x32_bf16 v[86:89], v[58:61], v[90:93], v[86:89]
	s_barrier
	s_setprio 0
	s_mov_b64 s[24:25], 0x100
	s_mov_b32 m0, s20
	v_lshl_add_u64 v[160:161], v[26:27], 0, s[24:25]
	ds_read_b128 v[90:93], v242 offset:16384
	ds_read_b128 v[132:135], v242 offset:17408
	ds_read_b128 v[136:139], v242 offset:18432
	ds_read_b128 v[140:143], v242 offset:19456
	ds_read_b128 v[144:147], v242 offset:20480
	ds_read_b128 v[148:151], v242 offset:21504
	ds_read_b128 v[152:155], v242 offset:22528
	ds_read_b128 v[156:159], v242 offset:23552
	global_load_lds_dwordx4 v[160:161], off
	v_lshl_add_u64 v[160:161], v[28:29], 0, s[24:25]
	s_mov_b32 m0, s19
	s_nop 0
	global_load_lds_dwordx4 v[160:161], off
	v_lshl_add_u64 v[160:161], v[24:25], 0, s[24:25]
	s_mov_b32 m0, s18
	s_nop 0
	global_load_lds_dwordx4 v[160:161], off
	v_lshl_add_u64 v[160:161], v[18:19], 0, s[24:25]
	s_mov_b32 m0, s17
	s_nop 0
	global_load_lds_dwordx4 v[160:161], off
	v_lshl_add_u64 v[160:161], v[20:21], 0, s[24:25]
	s_mov_b32 m0, s15
	s_nop 0
	global_load_lds_dwordx4 v[160:161], off
	v_lshl_add_u64 v[160:161], v[22:23], 0, s[24:25]
	s_mov_b32 m0, s16
	s_nop 0
	global_load_lds_dwordx4 v[160:161], off
	s_waitcnt vmcnt(8)
	s_waitcnt lgkmcnt(0)
	s_setprio 1
	s_barrier
	v_mfma_f32_16x16x32_bf16 v[160:163], v[30:33], v[90:93], 0
	v_mfma_f32_16x16x32_bf16 v[168:171], v[30:33], v[136:139], 0
	v_mfma_f32_16x16x32_bf16 v[178:181], v[30:33], v[144:147], 0
	v_mfma_f32_16x16x32_bf16 v[30:33], v[30:33], v[152:155], 0
	v_mfma_f32_16x16x32_bf16 v[160:163], v[34:37], v[132:135], v[160:163]
	v_mfma_f32_16x16x32_bf16 v[168:171], v[34:37], v[140:143], v[168:171]
	v_mfma_f32_16x16x32_bf16 v[178:181], v[34:37], v[148:151], v[178:181]
	v_mfma_f32_16x16x32_bf16 v[30:33], v[34:37], v[156:159], v[30:33]
	v_mfma_f32_16x16x32_bf16 v[34:37], v[38:41], v[152:155], 0
	v_mfma_f32_16x16x32_bf16 v[164:167], v[38:41], v[90:93], 0
	v_mfma_f32_16x16x32_bf16 v[172:175], v[38:41], v[136:139], 0
	v_mfma_f32_16x16x32_bf16 v[182:185], v[38:41], v[144:147], 0
	v_mfma_f32_16x16x32_bf16 v[34:37], v[42:45], v[156:159], v[34:37]
	v_mfma_f32_16x16x32_bf16 v[164:167], v[42:45], v[132:135], v[164:167]
	v_mfma_f32_16x16x32_bf16 v[172:175], v[42:45], v[140:143], v[172:175]
	v_mfma_f32_16x16x32_bf16 v[182:185], v[42:45], v[148:151], v[182:185]
	s_setprio 0
	s_setprio 1
	v_mfma_f32_16x16x32_bf16 v[38:41], v[46:49], v[90:93], 0
	v_mfma_f32_16x16x32_bf16 v[42:45], v[54:57], v[90:93], 0
	v_mfma_f32_16x16x32_bf16 v[38:41], v[50:53], v[132:135], v[38:41]
	v_mfma_f32_16x16x32_bf16 v[42:45], v[58:61], v[132:135], v[42:45]
	v_mfma_f32_16x16x32_bf16 v[90:93], v[46:49], v[136:139], 0
	v_mfma_f32_16x16x32_bf16 v[132:135], v[54:57], v[136:139], 0
	v_mfma_f32_16x16x32_bf16 v[136:139], v[46:49], v[144:147], 0
	v_mfma_f32_16x16x32_bf16 v[46:49], v[46:49], v[152:155], 0
	v_mfma_f32_16x16x32_bf16 v[90:93], v[50:53], v[140:143], v[90:93]
	v_mfma_f32_16x16x32_bf16 v[136:139], v[50:53], v[148:151], v[136:139]
	v_mfma_f32_16x16x32_bf16 v[46:49], v[50:53], v[156:159], v[46:49]
	v_mfma_f32_16x16x32_bf16 v[50:53], v[54:57], v[152:155], 0
	v_mfma_f32_16x16x32_bf16 v[132:135], v[58:61], v[140:143], v[132:135]
	v_mfma_f32_16x16x32_bf16 v[140:143], v[54:57], v[144:147], 0
	v_mfma_f32_16x16x32_bf16 v[50:53], v[58:61], v[156:159], v[50:53]
	v_mfma_f32_16x16x32_bf16 v[140:143], v[58:61], v[148:151], v[140:143]
	s_barrier
	s_setprio 0
	ds_read_b128 v[54:57], v239
	ds_read_b128 v[58:61], v239 offset:1024
	ds_read_b128 v[144:147], v239 offset:2048
	ds_read_b128 v[148:151], v239 offset:3072
	ds_read_b128 v[152:155], v238
	ds_read_b128 v[156:159], v238 offset:1024
	ds_read_b128 v[186:189], v238 offset:2048
	ds_read_b128 v[190:193], v238 offset:3072
	s_mov_b32 m0, s11
	v_lshl_add_u64 v[226:227], v[14:15], 0, s[24:25]
	ds_read_b128 v[194:197], v242 offset:32768
	ds_read_b128 v[198:201], v242 offset:33792
	ds_read_b128 v[202:205], v242 offset:34816
	ds_read_b128 v[206:209], v242 offset:35840
	ds_read_b128 v[210:213], v242 offset:36864
	ds_read_b128 v[214:217], v242 offset:37888
	ds_read_b128 v[218:221], v242 offset:38912
	ds_read_b128 v[222:225], v242 offset:39936
	global_load_lds_dwordx4 v[226:227], off
	v_lshl_add_u64 v[226:227], v[16:17], 0, s[24:25]
	s_mov_b32 m0, s12
	s_nop 0
	global_load_lds_dwordx4 v[226:227], off
	s_waitcnt vmcnt(8)
	s_waitcnt lgkmcnt(0)
	s_setprio 1
	s_barrier
	v_mfma_f32_16x16x32_bf16 v[94:97], v[54:57], v[194:197], v[94:97]
	v_mfma_f32_16x16x32_bf16 v[98:101], v[144:147], v[194:197], v[98:101]
	v_mfma_f32_16x16x32_bf16 v[102:105], v[54:57], v[202:205], v[102:105]
	v_mfma_f32_16x16x32_bf16 v[106:109], v[144:147], v[202:205], v[106:109]
	v_mfma_f32_16x16x32_bf16 v[110:113], v[54:57], v[210:213], v[110:113]
	v_mfma_f32_16x16x32_bf16 v[114:117], v[144:147], v[210:213], v[114:117]
	v_mfma_f32_16x16x32_bf16 v[118:121], v[54:57], v[218:221], v[118:121]
	v_mfma_f32_16x16x32_bf16 v[122:125], v[144:147], v[218:221], v[122:125]
	v_mfma_f32_16x16x32_bf16 v[94:97], v[58:61], v[198:201], v[94:97]
	v_mfma_f32_16x16x32_bf16 v[98:101], v[148:151], v[198:201], v[98:101]
	v_mfma_f32_16x16x32_bf16 v[102:105], v[58:61], v[206:209], v[102:105]
	v_mfma_f32_16x16x32_bf16 v[106:109], v[148:151], v[206:209], v[106:109]
	v_mfma_f32_16x16x32_bf16 v[110:113], v[58:61], v[214:217], v[110:113]
	v_mfma_f32_16x16x32_bf16 v[114:117], v[148:151], v[214:217], v[114:117]
	v_mfma_f32_16x16x32_bf16 v[118:121], v[58:61], v[222:225], v[118:121]
	v_mfma_f32_16x16x32_bf16 v[122:125], v[148:151], v[222:225], v[122:125]
	s_setprio 0
	s_setprio 1
	v_mfma_f32_16x16x32_bf16 v[126:129], v[152:155], v[194:197], v[126:129]
	v_mfma_f32_16x16x32_bf16 v[62:65], v[186:189], v[194:197], v[62:65]
	v_mfma_f32_16x16x32_bf16 v[66:69], v[152:155], v[202:205], v[66:69]
	v_mfma_f32_16x16x32_bf16 v[70:73], v[186:189], v[202:205], v[70:73]
	v_mfma_f32_16x16x32_bf16 v[74:77], v[152:155], v[210:213], v[74:77]
	v_mfma_f32_16x16x32_bf16 v[78:81], v[186:189], v[210:213], v[78:81]
	v_mfma_f32_16x16x32_bf16 v[82:85], v[152:155], v[218:221], v[82:85]
	v_mfma_f32_16x16x32_bf16 v[86:89], v[186:189], v[218:221], v[86:89]
	v_mfma_f32_16x16x32_bf16 v[126:129], v[156:159], v[198:201], v[126:129]
	v_mfma_f32_16x16x32_bf16 v[62:65], v[190:193], v[198:201], v[62:65]
	v_mfma_f32_16x16x32_bf16 v[66:69], v[156:159], v[206:209], v[66:69]
	v_mfma_f32_16x16x32_bf16 v[70:73], v[190:193], v[206:209], v[70:73]
	v_mfma_f32_16x16x32_bf16 v[74:77], v[156:159], v[214:217], v[74:77]
	v_mfma_f32_16x16x32_bf16 v[78:81], v[190:193], v[214:217], v[78:81]
	v_mfma_f32_16x16x32_bf16 v[82:85], v[156:159], v[222:225], v[82:85]
	v_mfma_f32_16x16x32_bf16 v[86:89], v[190:193], v[222:225], v[86:89]
	s_barrier
	s_setprio 0
	s_mov_b64 s[24:25], 0x180
	s_mov_b32 m0, s3
	v_lshl_add_u64 v[226:227], v[26:27], 0, s[24:25]
	ds_read_b128 v[194:197], v242 offset:49152
	ds_read_b128 v[198:201], v242 offset:50176
	ds_read_b128 v[202:205], v242 offset:51200
	ds_read_b128 v[206:209], v242 offset:52224
	ds_read_b128 v[210:213], v242 offset:53248
	ds_read_b128 v[214:217], v242 offset:54272
	ds_read_b128 v[218:221], v242 offset:55296
	ds_read_b128 v[222:225], v242 offset:56320
	global_load_lds_dwordx4 v[226:227], off
	v_lshl_add_u64 v[226:227], v[28:29], 0, s[24:25]
	s_mov_b32 m0, s5
	s_nop 0
	global_load_lds_dwordx4 v[226:227], off
	v_lshl_add_u64 v[226:227], v[24:25], 0, s[24:25]
	s_mov_b32 m0, s13
	s_nop 0
	global_load_lds_dwordx4 v[226:227], off
	v_lshl_add_u64 v[226:227], v[18:19], 0, s[24:25]
	s_mov_b32 m0, s14
	s_nop 0
	global_load_lds_dwordx4 v[226:227], off
	v_lshl_add_u64 v[226:227], v[20:21], 0, s[24:25]
	s_mov_b32 m0, s4
	s_nop 0
	global_load_lds_dwordx4 v[226:227], off
	v_lshl_add_u64 v[226:227], v[22:23], 0, s[24:25]
	s_mov_b32 m0, s9
	s_nop 0
	global_load_lds_dwordx4 v[226:227], off
	s_waitcnt vmcnt(8)
	s_waitcnt lgkmcnt(0)
	s_setprio 1
	s_barrier
	v_mfma_f32_16x16x32_bf16 v[30:33], v[54:57], v[218:221], v[30:33]
	v_mfma_f32_16x16x32_bf16 v[34:37], v[144:147], v[218:221], v[34:37]
	v_mfma_f32_16x16x32_bf16 v[160:163], v[54:57], v[194:197], v[160:163]
	v_mfma_f32_16x16x32_bf16 v[164:167], v[144:147], v[194:197], v[164:167]
	v_mfma_f32_16x16x32_bf16 v[168:171], v[54:57], v[202:205], v[168:171]
	v_mfma_f32_16x16x32_bf16 v[172:175], v[144:147], v[202:205], v[172:175]
	v_mfma_f32_16x16x32_bf16 v[178:181], v[54:57], v[210:213], v[178:181]
	v_mfma_f32_16x16x32_bf16 v[182:185], v[144:147], v[210:213], v[182:185]
	v_mfma_f32_16x16x32_bf16 v[30:33], v[58:61], v[222:225], v[30:33]
	v_mfma_f32_16x16x32_bf16 v[34:37], v[148:151], v[222:225], v[34:37]
	v_mfma_f32_16x16x32_bf16 v[160:163], v[58:61], v[198:201], v[160:163]
	v_mfma_f32_16x16x32_bf16 v[164:167], v[148:151], v[198:201], v[164:167]
	v_mfma_f32_16x16x32_bf16 v[168:171], v[58:61], v[206:209], v[168:171]
	v_mfma_f32_16x16x32_bf16 v[172:175], v[148:151], v[206:209], v[172:175]
	v_mfma_f32_16x16x32_bf16 v[178:181], v[58:61], v[214:217], v[178:181]
	v_mfma_f32_16x16x32_bf16 v[182:185], v[148:151], v[214:217], v[182:185]
	s_setprio 0
	s_setprio 1
	v_mfma_f32_16x16x32_bf16 v[38:41], v[152:155], v[194:197], v[38:41]
	v_mfma_f32_16x16x32_bf16 v[42:45], v[186:189], v[194:197], v[42:45]
	v_mfma_f32_16x16x32_bf16 v[54:57], v[152:155], v[202:205], v[90:93]
	v_mfma_f32_16x16x32_bf16 v[58:61], v[186:189], v[202:205], v[132:135]
	v_mfma_f32_16x16x32_bf16 v[90:93], v[152:155], v[210:213], v[136:139]
	v_mfma_f32_16x16x32_bf16 v[46:49], v[152:155], v[218:221], v[46:49]
	v_mfma_f32_16x16x32_bf16 v[50:53], v[186:189], v[218:221], v[50:53]
	v_mfma_f32_16x16x32_bf16 v[38:41], v[156:159], v[198:201], v[38:41]
	v_mfma_f32_16x16x32_bf16 v[42:45], v[190:193], v[198:201], v[42:45]
	v_mfma_f32_16x16x32_bf16 v[54:57], v[156:159], v[206:209], v[54:57]
	v_mfma_f32_16x16x32_bf16 v[58:61], v[190:193], v[206:209], v[58:61]
	v_mfma_f32_16x16x32_bf16 v[90:93], v[156:159], v[214:217], v[90:93]
	v_mfma_f32_16x16x32_bf16 v[132:135], v[186:189], v[210:213], v[140:143]
	v_mfma_f32_16x16x32_bf16 v[46:49], v[156:159], v[222:225], v[46:49]
	v_mfma_f32_16x16x32_bf16 v[50:53], v[190:193], v[222:225], v[50:53]
	v_mfma_f32_16x16x32_bf16 v[132:135], v[190:193], v[214:217], v[132:135]
	s_barrier
	s_setprio 0
	ds_read_b128 v[136:139], v176
	ds_read_b128 v[140:143], v176 offset:1024
	ds_read_b128 v[144:147], v176 offset:2048
	ds_read_b128 v[148:151], v176 offset:3072
	ds_read_b128 v[152:155], v131
	ds_read_b128 v[156:159], v131 offset:1024
	ds_read_b128 v[186:189], v131 offset:2048
	ds_read_b128 v[190:193], v131 offset:3072
	s_mov_b32 m0, s22
	v_lshl_add_u64 v[226:227], v[14:15], 0, s[24:25]
	ds_read_b128 v[194:197], v242
	ds_read_b128 v[198:201], v242 offset:1024
	ds_read_b128 v[202:205], v242 offset:2048
	ds_read_b128 v[206:209], v242 offset:3072
	ds_read_b128 v[210:213], v242 offset:4096
	ds_read_b128 v[214:217], v242 offset:5120
	ds_read_b128 v[218:221], v242 offset:6144
	ds_read_b128 v[222:225], v242 offset:7168
	global_load_lds_dwordx4 v[226:227], off
	v_lshl_add_u64 v[226:227], v[16:17], 0, s[24:25]
	s_mov_b32 m0, s21
	s_nop 0
	global_load_lds_dwordx4 v[226:227], off
	s_waitcnt vmcnt(8)
	s_waitcnt lgkmcnt(0)
	s_setprio 1
	s_barrier
	v_mfma_f32_16x16x32_bf16 v[110:113], v[136:139], v[210:213], v[110:113]
	v_mfma_f32_16x16x32_bf16 v[226:229], v[140:143], v[214:217], v[110:113]
	v_mfma_f32_16x16x32_bf16 v[110:113], v[144:147], v[210:213], v[114:117]
	v_mfma_f32_16x16x32_bf16 v[94:97], v[136:139], v[194:197], v[94:97]
	v_mfma_f32_16x16x32_bf16 v[98:101], v[144:147], v[194:197], v[98:101]
	v_mfma_f32_16x16x32_bf16 v[102:105], v[136:139], v[202:205], v[102:105]
	v_mfma_f32_16x16x32_bf16 v[106:109], v[144:147], v[202:205], v[106:109]
	v_mfma_f32_16x16x32_bf16 v[114:117], v[148:151], v[214:217], v[110:113]
	v_mfma_f32_16x16x32_bf16 v[110:113], v[136:139], v[218:221], v[118:121]
	v_mfma_f32_16x16x32_bf16 v[94:97], v[140:143], v[198:201], v[94:97]
	v_mfma_f32_16x16x32_bf16 v[98:101], v[148:151], v[198:201], v[98:101]
	v_mfma_f32_16x16x32_bf16 v[102:105], v[140:143], v[206:209], v[102:105]
	v_mfma_f32_16x16x32_bf16 v[106:109], v[148:151], v[206:209], v[106:109]
	v_mfma_f32_16x16x32_bf16 v[118:121], v[140:143], v[222:225], v[110:113]
	v_mfma_f32_16x16x32_bf16 v[110:113], v[144:147], v[218:221], v[122:125]
	v_mfma_f32_16x16x32_bf16 v[230:233], v[148:151], v[222:225], v[110:113]
	s_setprio 0
	s_setprio 1
	v_mfma_f32_16x16x32_bf16 v[74:77], v[152:155], v[210:213], v[74:77]
	v_mfma_f32_16x16x32_bf16 v[110:113], v[152:155], v[194:197], v[126:129]
	v_mfma_f32_16x16x32_bf16 v[62:65], v[186:189], v[194:197], v[62:65]
	v_mfma_f32_16x16x32_bf16 v[194:197], v[156:159], v[214:217], v[74:77]
	v_mfma_f32_16x16x32_bf16 v[74:77], v[186:189], v[210:213], v[78:81]
	v_mfma_f32_16x16x32_bf16 v[234:237], v[156:159], v[198:201], v[110:113]
	v_mfma_f32_16x16x32_bf16 v[62:65], v[190:193], v[198:201], v[62:65]
	v_mfma_f32_16x16x32_bf16 v[66:69], v[152:155], v[202:205], v[66:69]
	v_mfma_f32_16x16x32_bf16 v[70:73], v[186:189], v[202:205], v[70:73]
	v_mfma_f32_16x16x32_bf16 v[198:201], v[190:193], v[214:217], v[74:77]
	v_mfma_f32_16x16x32_bf16 v[74:77], v[152:155], v[218:221], v[82:85]
	v_mfma_f32_16x16x32_bf16 v[66:69], v[156:159], v[206:209], v[66:69]
	v_mfma_f32_16x16x32_bf16 v[70:73], v[190:193], v[206:209], v[70:73]
	v_mfma_f32_16x16x32_bf16 v[202:205], v[156:159], v[222:225], v[74:77]
	v_mfma_f32_16x16x32_bf16 v[74:77], v[186:189], v[218:221], v[86:89]
	v_mfma_f32_16x16x32_bf16 v[206:209], v[190:193], v[222:225], v[74:77]
	s_barrier
	s_setprio 0
	s_mov_b32 m0, s20
	s_nop 3
	ds_read_b128 v[74:77], v242 offset:16384
	ds_read_b128 v[78:81], v242 offset:17408
	ds_read_b128 v[82:85], v242 offset:18432
	ds_read_b128 v[86:89], v242 offset:19456
	ds_read_b128 v[110:113], v242 offset:20480
	ds_read_b128 v[122:125], v242 offset:21504
	ds_read_b128 v[126:129], v242 offset:22528
	ds_read_b128 v[210:213], v242 offset:23552
	global_load_lds_dwordx4 v[26:27], off
	s_mov_b32 m0, s19
	s_nop 0
	global_load_lds_dwordx4 v[28:29], off
	s_mov_b32 m0, s18
	s_nop 0
	global_load_lds_dwordx4 v[24:25], off
	s_mov_b32 m0, s17
	s_nop 0
	global_load_lds_dwordx4 v[18:19], off
	s_mov_b32 m0, s15
	s_nop 0
	global_load_lds_dwordx4 v[20:21], off
	s_mov_b32 m0, s16
	s_nop 0
	global_load_lds_dwordx4 v[22:23], off
	s_waitcnt vmcnt(8)
	s_waitcnt lgkmcnt(0)
	s_setprio 1
	s_barrier
	v_mfma_f32_16x16x32_bf16 v[30:33], v[136:139], v[126:129], v[30:33]
	v_mfma_f32_16x16x32_bf16 v[18:21], v[136:139], v[74:77], v[160:163]
	v_mfma_f32_16x16x32_bf16 v[22:25], v[144:147], v[74:77], v[164:167]
	v_mfma_f32_16x16x32_bf16 v[26:29], v[136:139], v[82:85], v[168:171]
	v_mfma_f32_16x16x32_bf16 v[164:167], v[136:139], v[110:113], v[178:181]
	v_mfma_f32_16x16x32_bf16 v[136:139], v[140:143], v[210:213], v[30:33]
	v_mfma_f32_16x16x32_bf16 v[30:33], v[144:147], v[126:129], v[34:37]
	v_mfma_f32_16x16x32_bf16 v[18:21], v[140:143], v[78:81], v[18:21]
	v_mfma_f32_16x16x32_bf16 v[22:25], v[148:151], v[78:81], v[22:25]
	v_mfma_f32_16x16x32_bf16 v[26:29], v[140:143], v[86:89], v[26:29]
	v_mfma_f32_16x16x32_bf16 v[160:163], v[144:147], v[82:85], v[172:175]
	v_mfma_f32_16x16x32_bf16 v[168:171], v[144:147], v[110:113], v[182:185]
	v_mfma_f32_16x16x32_bf16 v[34:37], v[148:151], v[210:213], v[30:33]
	v_mfma_f32_16x16x32_bf16 v[160:163], v[148:151], v[86:89], v[160:163]
	v_mfma_f32_16x16x32_bf16 v[164:167], v[140:143], v[122:125], v[164:167]
	v_mfma_f32_16x16x32_bf16 v[168:171], v[148:151], v[122:125], v[168:171]
	s_setprio 0
	s_setprio 1
	v_mfma_f32_16x16x32_bf16 v[30:33], v[152:155], v[74:77], v[38:41]
	v_mfma_f32_16x16x32_bf16 v[38:41], v[156:159], v[78:81], v[30:33]
	v_mfma_f32_16x16x32_bf16 v[30:33], v[186:189], v[74:77], v[42:45]
	v_mfma_f32_16x16x32_bf16 v[140:143], v[190:193], v[78:81], v[30:33]
	v_mfma_f32_16x16x32_bf16 v[30:33], v[152:155], v[82:85], v[54:57]
	v_mfma_f32_16x16x32_bf16 v[144:147], v[156:159], v[86:89], v[30:33]
	v_mfma_f32_16x16x32_bf16 v[30:33], v[186:189], v[82:85], v[58:61]
	v_mfma_f32_16x16x32_bf16 v[148:151], v[190:193], v[86:89], v[30:33]
	v_mfma_f32_16x16x32_bf16 v[30:33], v[152:155], v[110:113], v[90:93]
	v_mfma_f32_16x16x32_bf16 v[172:175], v[156:159], v[122:125], v[30:33]
	v_mfma_f32_16x16x32_bf16 v[30:33], v[186:189], v[110:113], v[132:135]
	v_mfma_f32_16x16x32_bf16 v[132:135], v[190:193], v[122:125], v[30:33]
	v_mfma_f32_16x16x32_bf16 v[30:33], v[152:155], v[126:129], v[46:49]
	v_mfma_f32_16x16x32_bf16 v[152:155], v[156:159], v[210:213], v[30:33]
	v_mfma_f32_16x16x32_bf16 v[30:33], v[186:189], v[126:129], v[50:53]
	v_mfma_f32_16x16x32_bf16 v[156:159], v[190:193], v[210:213], v[30:33]
	s_barrier
	s_setprio 0
	ds_read_b128 v[50:53], v239
	ds_read_b128 v[54:57], v239 offset:1024
	ds_read_b128 v[178:181], v239 offset:2048
	ds_read_b128 v[182:185], v239 offset:3072
	ds_read_b128 v[186:189], v238
	ds_read_b128 v[190:193], v238 offset:1024
	ds_read_b128 v[210:213], v238 offset:2048
	ds_read_b128 v[214:217], v238 offset:3072
	s_mov_b32 m0, s11
	ds_read_b128 v[30:33], v242 offset:32768
	ds_read_b128 v[42:45], v242 offset:33792
	ds_read_b128 v[46:49], v242 offset:34816
	ds_read_b128 v[58:61], v242 offset:35840
	ds_read_b128 v[82:85], v242 offset:36864
	ds_read_b128 v[218:221], v242 offset:37888
	ds_read_b128 v[222:225], v242 offset:38912
	ds_read_b128 v[238:241], v242 offset:39936
	global_load_lds_dwordx4 v[14:15], off
	s_mov_b32 m0, s12
	s_nop 0
	global_load_lds_dwordx4 v[16:17], off
	s_waitcnt vmcnt(8)
	s_waitcnt lgkmcnt(0)
	s_setprio 1
	s_barrier
	v_mfma_f32_16x16x32_bf16 v[14:17], v[50:53], v[30:33], v[94:97]
	v_mfma_f32_16x16x32_bf16 v[126:129], v[54:57], v[42:45], v[14:17]
	v_mfma_f32_16x16x32_bf16 v[14:17], v[178:181], v[30:33], v[98:101]
	v_mfma_f32_16x16x32_bf16 v[122:125], v[182:185], v[42:45], v[14:17]
	v_mfma_f32_16x16x32_bf16 v[14:17], v[50:53], v[46:49], v[102:105]
	v_mfma_f32_16x16x32_bf16 v[110:113], v[54:57], v[58:61], v[14:17]
	v_mfma_f32_16x16x32_bf16 v[14:17], v[178:181], v[46:49], v[106:109]
	v_mfma_f32_16x16x32_bf16 v[106:109], v[182:185], v[58:61], v[14:17]
	v_mfma_f32_16x16x32_bf16 v[14:17], v[50:53], v[82:85], v[226:229]
	v_mfma_f32_16x16x32_bf16 v[94:97], v[54:57], v[218:221], v[14:17]
	v_mfma_f32_16x16x32_bf16 v[14:17], v[178:181], v[82:85], v[114:117]
	v_mfma_f32_16x16x32_bf16 v[90:93], v[182:185], v[218:221], v[14:17]
	v_mfma_f32_16x16x32_bf16 v[14:17], v[50:53], v[222:225], v[118:121]
	v_mfma_f32_16x16x32_bf16 v[78:81], v[54:57], v[238:241], v[14:17]
	v_mfma_f32_16x16x32_bf16 v[14:17], v[178:181], v[222:225], v[230:233]
	v_mfma_f32_16x16x32_bf16 v[74:77], v[182:185], v[238:241], v[14:17]
	s_setprio 0
	s_setprio 1
	v_mfma_f32_16x16x32_bf16 v[14:17], v[186:189], v[30:33], v[234:237]
	v_mfma_f32_16x16x32_bf16 v[118:121], v[190:193], v[42:45], v[14:17]
	v_mfma_f32_16x16x32_bf16 v[14:17], v[210:213], v[30:33], v[62:65]
	v_mfma_f32_16x16x32_bf16 v[114:117], v[214:217], v[42:45], v[14:17]
	v_mfma_f32_16x16x32_bf16 v[14:17], v[186:189], v[46:49], v[66:69]
	v_mfma_f32_16x16x32_bf16 v[102:105], v[190:193], v[58:61], v[14:17]
	v_mfma_f32_16x16x32_bf16 v[14:17], v[210:213], v[46:49], v[70:73]
	v_mfma_f32_16x16x32_bf16 v[98:101], v[214:217], v[58:61], v[14:17]
	v_mfma_f32_16x16x32_bf16 v[14:17], v[186:189], v[82:85], v[194:197]
	v_mfma_f32_16x16x32_bf16 v[86:89], v[190:193], v[218:221], v[14:17]
	v_mfma_f32_16x16x32_bf16 v[14:17], v[210:213], v[82:85], v[198:201]
	v_mfma_f32_16x16x32_bf16 v[82:85], v[214:217], v[218:221], v[14:17]
	v_mfma_f32_16x16x32_bf16 v[14:17], v[186:189], v[222:225], v[202:205]
	v_mfma_f32_16x16x32_bf16 v[66:69], v[190:193], v[238:241], v[14:17]
	v_mfma_f32_16x16x32_bf16 v[14:17], v[210:213], v[222:225], v[206:209]
	v_mfma_f32_16x16x32_bf16 v[58:61], v[214:217], v[238:241], v[14:17]
	s_barrier
	s_setprio 0
	s_mov_b32 m0, s3
	ds_read_b128 v[194:197], v242 offset:49152
	ds_read_b128 v[198:201], v242 offset:50176
	ds_read_b128 v[202:205], v242 offset:51200
	ds_read_b128 v[206:209], v242 offset:52224
	ds_read_b128 v[218:221], v242 offset:53248
	ds_read_b128 v[222:225], v242 offset:54272
	ds_read_b128 v[226:229], v242 offset:55296
	ds_read_b128 v[230:233], v242 offset:56320
	global_load_lds_dwordx4 v[4:5], off
	s_mov_b32 m0, s5
	s_nop 0
	global_load_lds_dwordx4 v[6:7], off
	s_mov_b32 m0, s13
	s_nop 0
	global_load_lds_dwordx4 v[10:11], off
	s_mov_b32 m0, s14
	s_nop 0
	global_load_lds_dwordx4 v[12:13], off
	s_mov_b32 m0, s4
	s_nop 0
	global_load_lds_dwordx4 v[2:3], off
	s_mov_b32 m0, s9
	s_nop 0
	global_load_lds_dwordx4 v[8:9], off
	s_waitcnt vmcnt(8)
	s_waitcnt lgkmcnt(0)
	s_setprio 1
	s_barrier
	v_mfma_f32_16x16x32_bf16 v[2:5], v[50:53], v[194:197], v[18:21]
	v_mfma_f32_16x16x32_bf16 v[70:73], v[54:57], v[198:201], v[2:5]
	v_mfma_f32_16x16x32_bf16 v[2:5], v[178:181], v[194:197], v[22:25]
	v_mfma_f32_16x16x32_bf16 v[62:65], v[182:185], v[198:201], v[2:5]
	v_mfma_f32_16x16x32_bf16 v[2:5], v[50:53], v[202:205], v[26:29]
	v_mfma_f32_16x16x32_bf16 v[46:49], v[54:57], v[206:209], v[2:5]
	v_mfma_f32_16x16x32_bf16 v[2:5], v[178:181], v[202:205], v[160:163]
	v_mfma_f32_16x16x32_bf16 v[42:45], v[182:185], v[206:209], v[2:5]
	v_mfma_f32_16x16x32_bf16 v[2:5], v[50:53], v[218:221], v[164:167]
	v_mfma_f32_16x16x32_bf16 v[30:33], v[54:57], v[222:225], v[2:5]
	v_mfma_f32_16x16x32_bf16 v[2:5], v[178:181], v[218:221], v[168:171]
	v_mfma_f32_16x16x32_bf16 v[26:29], v[182:185], v[222:225], v[2:5]
	v_mfma_f32_16x16x32_bf16 v[2:5], v[50:53], v[226:229], v[136:139]
	v_mfma_f32_16x16x32_bf16 v[14:17], v[54:57], v[230:233], v[2:5]
	v_mfma_f32_16x16x32_bf16 v[2:5], v[178:181], v[226:229], v[34:37]
	v_mfma_f32_16x16x32_bf16 v[10:13], v[182:185], v[230:233], v[2:5]
	s_setprio 0
	s_setprio 1
	v_mfma_f32_16x16x32_bf16 v[2:5], v[186:189], v[194:197], v[38:41]
	v_mfma_f32_16x16x32_bf16 v[54:57], v[190:193], v[198:201], v[2:5]
	v_mfma_f32_16x16x32_bf16 v[2:5], v[210:213], v[194:197], v[140:143]
	v_mfma_f32_16x16x32_bf16 v[50:53], v[214:217], v[198:201], v[2:5]
	v_mfma_f32_16x16x32_bf16 v[2:5], v[186:189], v[202:205], v[144:147]
	v_mfma_f32_16x16x32_bf16 v[38:41], v[190:193], v[206:209], v[2:5]
	v_mfma_f32_16x16x32_bf16 v[2:5], v[210:213], v[202:205], v[148:151]
	v_mfma_f32_16x16x32_bf16 v[34:37], v[214:217], v[206:209], v[2:5]
	v_mfma_f32_16x16x32_bf16 v[2:5], v[186:189], v[218:221], v[172:175]
	v_mfma_f32_16x16x32_bf16 v[22:25], v[190:193], v[222:225], v[2:5]
	v_mfma_f32_16x16x32_bf16 v[2:5], v[210:213], v[218:221], v[132:135]
	v_mfma_f32_16x16x32_bf16 v[18:21], v[214:217], v[222:225], v[2:5]
	v_mfma_f32_16x16x32_bf16 v[2:5], v[186:189], v[226:229], v[152:155]
	v_mfma_f32_16x16x32_bf16 v[6:9], v[190:193], v[230:233], v[2:5]
	v_mfma_f32_16x16x32_bf16 v[2:5], v[210:213], v[226:229], v[156:159]
	v_mfma_f32_16x16x32_bf16 v[2:5], v[214:217], v[230:233], v[2:5]
	s_barrier
	s_setprio 0
	s_cbranch_scc1 .LBB0_1139
	s_barrier

.Lpk1179_peel:
	ds_read_b128 v[144:147], v158
	ds_read_b128 v[164:167], v158 offset:1024
	ds_read_b128 v[168:171], v158 offset:2048
	ds_read_b128 v[172:175], v158 offset:3072
	ds_read_b128 v[178:181], v159
	ds_read_b128 v[182:185], v159 offset:1024
	ds_read_b128 v[186:189], v159 offset:2048
	ds_read_b128 v[190:193], v159 offset:3072
	s_add_u32 s2, s36, 0xfffc0080
	s_addc_u32 s3, s37, -1
	s_cmp_eq_u32 s61, 12
	s_cselect_b32 s3, s19, s3
	s_cselect_b32 s2, s21, s2
	s_cselect_b32 s39, s57, s60
	s_cselect_b32 s38, s58, s59
	v_lshl_add_u64 v[226:227], s[36:37], 0, v[138:139]
	s_add_i32 m0, s42, 0xc000
	ds_read_b128 v[194:197], v160
	ds_read_b128 v[198:201], v160 offset:1024
	ds_read_b128 v[202:205], v160 offset:2048
	ds_read_b128 v[206:209], v160 offset:3072
	ds_read_b128 v[210:213], v160 offset:4096
	ds_read_b128 v[214:217], v160 offset:5120
	ds_read_b128 v[218:221], v160 offset:6144
	ds_read_b128 v[222:225], v160 offset:7168
	global_load_lds_dwordx4 v[226:227], off
	v_lshl_add_u64 v[226:227], s[36:37], 0, v[140:141]
	s_add_i32 m0, s42, 0xe000
	s_nop 0
	global_load_lds_dwordx4 v[226:227], off
	s_waitcnt vmcnt(8)
	s_waitcnt lgkmcnt(0)
	s_setprio 1
	s_barrier
	v_mfma_f32_16x16x32_bf16 v[126:129], v[144:147], v[194:197], 0
	v_mfma_f32_16x16x32_bf16 v[122:125], v[168:171], v[194:197], 0
	v_mfma_f32_16x16x32_bf16 v[114:117], v[144:147], v[202:205], 0
	v_mfma_f32_16x16x32_bf16 v[106:109], v[168:171], v[202:205], 0
	v_mfma_f32_16x16x32_bf16 v[98:101], v[144:147], v[210:213], 0
	v_mfma_f32_16x16x32_bf16 v[90:93], v[168:171], v[210:213], 0
	v_mfma_f32_16x16x32_bf16 v[82:85], v[144:147], v[218:221], 0
	v_mfma_f32_16x16x32_bf16 v[74:77], v[168:171], v[218:221], 0
	v_mfma_f32_16x16x32_bf16 v[126:129], v[164:167], v[198:201], v[126:129]
	v_mfma_f32_16x16x32_bf16 v[122:125], v[172:175], v[198:201], v[122:125]
	v_mfma_f32_16x16x32_bf16 v[114:117], v[164:167], v[206:209], v[114:117]
	v_mfma_f32_16x16x32_bf16 v[106:109], v[172:175], v[206:209], v[106:109]
	v_mfma_f32_16x16x32_bf16 v[98:101], v[164:167], v[214:217], v[98:101]
	v_mfma_f32_16x16x32_bf16 v[90:93], v[172:175], v[214:217], v[90:93]
	v_mfma_f32_16x16x32_bf16 v[82:85], v[164:167], v[222:225], v[82:85]
	v_mfma_f32_16x16x32_bf16 v[74:77], v[172:175], v[222:225], v[74:77]
	s_setprio 0
	s_setprio 1
	v_mfma_f32_16x16x32_bf16 v[118:121], v[178:181], v[194:197], 0
	v_mfma_f32_16x16x32_bf16 v[110:113], v[186:189], v[194:197], 0
	v_mfma_f32_16x16x32_bf16 v[102:105], v[178:181], v[202:205], 0
	v_mfma_f32_16x16x32_bf16 v[94:97], v[186:189], v[202:205], 0
	v_mfma_f32_16x16x32_bf16 v[86:89], v[178:181], v[210:213], 0
	v_mfma_f32_16x16x32_bf16 v[78:81], v[186:189], v[210:213], 0
	v_mfma_f32_16x16x32_bf16 v[70:73], v[178:181], v[218:221], 0
	v_mfma_f32_16x16x32_bf16 v[66:69], v[186:189], v[218:221], 0
	v_mfma_f32_16x16x32_bf16 v[118:121], v[182:185], v[198:201], v[118:121]
	v_mfma_f32_16x16x32_bf16 v[110:113], v[190:193], v[198:201], v[110:113]
	v_mfma_f32_16x16x32_bf16 v[102:105], v[182:185], v[206:209], v[102:105]
	v_mfma_f32_16x16x32_bf16 v[94:97], v[190:193], v[206:209], v[94:97]
	v_mfma_f32_16x16x32_bf16 v[86:89], v[182:185], v[214:217], v[86:89]
	v_mfma_f32_16x16x32_bf16 v[78:81], v[190:193], v[214:217], v[78:81]
	v_mfma_f32_16x16x32_bf16 v[70:73], v[182:185], v[222:225], v[70:73]
	v_mfma_f32_16x16x32_bf16 v[66:69], v[190:193], v[222:225], v[66:69]
	s_barrier
	s_setprio 0
	s_add_i32 s62, s51, s41
	v_lshl_add_u64 v[226:227], s[38:39], 0, v[132:133]
	s_mov_b32 m0, s62
	ds_read_b128 v[194:197], v160 offset:16384
	ds_read_b128 v[198:201], v160 offset:17408
	ds_read_b128 v[202:205], v160 offset:18432
	ds_read_b128 v[206:209], v160 offset:19456
	ds_read_b128 v[210:213], v160 offset:20480
	ds_read_b128 v[214:217], v160 offset:21504
	ds_read_b128 v[218:221], v160 offset:22528
	ds_read_b128 v[222:225], v160 offset:23552
	global_load_lds_dwordx4 v[226:227], off
	s_add_i32 m0, s62, 0x2000
	s_add_u32 s62, s38, 0x40000
	v_lshl_add_u64 v[228:229], s[38:39], 0, v[136:137]
	s_addc_u32 s63, s39, 0
	s_add_i32 s64, s52, s41
	global_load_lds_dwordx4 v[228:229], off
	v_lshl_add_u64 v[230:231], s[62:63], 0, v[132:133]
	s_mov_b32 m0, s64
	v_lshl_add_u64 v[232:233], s[2:3], 0, v[134:135]
	global_load_lds_dwordx4 v[230:231], off
	v_lshl_add_u64 v[230:231], s[62:63], 0, v[136:137]
	s_add_i32 m0, s64, 0x2000
	s_nop 0
	global_load_lds_dwordx4 v[230:231], off
	v_lshl_add_u64 v[230:231], s[2:3], 0, v[130:131]
	s_mov_b32 m0, s42
	s_nop 0
	global_load_lds_dwordx4 v[230:231], off
	s_mov_b32 m0, s43
	s_nop 0
	global_load_lds_dwordx4 v[232:233], off
	s_waitcnt vmcnt(8)
	s_waitcnt lgkmcnt(0)
	s_setprio 1
	s_barrier
	v_mfma_f32_16x16x32_bf16 v[62:65], v[144:147], v[194:197], 0
	v_mfma_f32_16x16x32_bf16 v[58:61], v[168:171], v[194:197], 0
	v_mfma_f32_16x16x32_bf16 v[50:53], v[144:147], v[202:205], 0
	v_mfma_f32_16x16x32_bf16 v[42:45], v[168:171], v[202:205], 0
	v_mfma_f32_16x16x32_bf16 v[34:37], v[144:147], v[210:213], 0
	v_mfma_f32_16x16x32_bf16 v[26:29], v[168:171], v[210:213], 0
	v_mfma_f32_16x16x32_bf16 v[18:21], v[144:147], v[218:221], 0
	v_mfma_f32_16x16x32_bf16 v[10:13], v[168:171], v[218:221], 0
	v_mfma_f32_16x16x32_bf16 v[62:65], v[164:167], v[198:201], v[62:65]
	v_mfma_f32_16x16x32_bf16 v[58:61], v[172:175], v[198:201], v[58:61]
	v_mfma_f32_16x16x32_bf16 v[50:53], v[164:167], v[206:209], v[50:53]
	v_mfma_f32_16x16x32_bf16 v[42:45], v[172:175], v[206:209], v[42:45]
	v_mfma_f32_16x16x32_bf16 v[34:37], v[164:167], v[214:217], v[34:37]
	v_mfma_f32_16x16x32_bf16 v[26:29], v[172:175], v[214:217], v[26:29]
	v_mfma_f32_16x16x32_bf16 v[18:21], v[164:167], v[222:225], v[18:21]
	v_mfma_f32_16x16x32_bf16 v[10:13], v[172:175], v[222:225], v[10:13]
	s_setprio 0
	s_setprio 1
	v_mfma_f32_16x16x32_bf16 v[54:57], v[178:181], v[194:197], 0
	v_mfma_f32_16x16x32_bf16 v[46:49], v[186:189], v[194:197], 0
	v_mfma_f32_16x16x32_bf16 v[38:41], v[178:181], v[202:205], 0
	v_mfma_f32_16x16x32_bf16 v[30:33], v[186:189], v[202:205], 0
	v_mfma_f32_16x16x32_bf16 v[22:25], v[178:181], v[210:213], 0
	v_mfma_f32_16x16x32_bf16 v[14:17], v[186:189], v[210:213], 0
	v_mfma_f32_16x16x32_bf16 v[6:9], v[178:181], v[218:221], 0
	v_mfma_f32_16x16x32_bf16 v[2:5], v[186:189], v[218:221], 0
	v_mfma_f32_16x16x32_bf16 v[54:57], v[182:185], v[198:201], v[54:57]
	v_mfma_f32_16x16x32_bf16 v[46:49], v[190:193], v[198:201], v[46:49]
	v_mfma_f32_16x16x32_bf16 v[38:41], v[182:185], v[206:209], v[38:41]
	v_mfma_f32_16x16x32_bf16 v[30:33], v[190:193], v[206:209], v[30:33]
	v_mfma_f32_16x16x32_bf16 v[22:25], v[182:185], v[214:217], v[22:25]
	v_mfma_f32_16x16x32_bf16 v[14:17], v[190:193], v[214:217], v[14:17]
	v_mfma_f32_16x16x32_bf16 v[6:9], v[182:185], v[222:225], v[6:9]
	v_mfma_f32_16x16x32_bf16 v[2:5], v[190:193], v[222:225], v[2:5]
	s_barrier
	s_setprio 0
	s_add_i32 s62, 0, 0x18000
	v_add_u32_e32 v163, s62, v148
	s_add_i32 s63, 0, 0x1c000
	ds_read_b128 v[144:147], v163
	ds_read_b128 v[164:167], v163 offset:1024
	ds_read_b128 v[168:171], v163 offset:2048
	ds_read_b128 v[172:175], v163 offset:3072
	v_add_u32_e32 v163, s63, v148
	ds_read_b128 v[178:181], v163
	ds_read_b128 v[182:185], v163 offset:1024
	ds_read_b128 v[186:189], v163 offset:2048
	ds_read_b128 v[190:193], v163 offset:3072
	s_add_u32 s2, s2, 0x40000
	s_addc_u32 s3, s3, 0
	s_mov_b32 m0, s44
	v_lshl_add_u64 v[234:235], s[2:3], 0, v[130:131]
	ds_read_b128 v[194:197], v160 offset:32768
	ds_read_b128 v[198:201], v160 offset:33792
	ds_read_b128 v[202:205], v160 offset:34816
	ds_read_b128 v[206:209], v160 offset:35840
	ds_read_b128 v[210:213], v160 offset:36864
	ds_read_b128 v[214:217], v160 offset:37888
	ds_read_b128 v[218:221], v160 offset:38912
	ds_read_b128 v[222:225], v160 offset:39936
	global_load_lds_dwordx4 v[234:235], off
	v_lshl_add_u64 v[234:235], s[2:3], 0, v[134:135]
	s_mov_b32 m0, s45
	s_nop 0
	global_load_lds_dwordx4 v[234:235], off
	s_waitcnt vmcnt(8)
	s_waitcnt lgkmcnt(0)
	s_setprio 1
	s_barrier
	v_mfma_f32_16x16x32_bf16 v[126:129], v[144:147], v[194:197], v[126:129]
	v_mfma_f32_16x16x32_bf16 v[122:125], v[168:171], v[194:197], v[122:125]
	v_mfma_f32_16x16x32_bf16 v[114:117], v[144:147], v[202:205], v[114:117]
	v_mfma_f32_16x16x32_bf16 v[106:109], v[168:171], v[202:205], v[106:109]
	v_mfma_f32_16x16x32_bf16 v[98:101], v[144:147], v[210:213], v[98:101]
	v_mfma_f32_16x16x32_bf16 v[90:93], v[168:171], v[210:213], v[90:93]
	v_mfma_f32_16x16x32_bf16 v[82:85], v[144:147], v[218:221], v[82:85]
	v_mfma_f32_16x16x32_bf16 v[74:77], v[168:171], v[218:221], v[74:77]
	v_mfma_f32_16x16x32_bf16 v[126:129], v[164:167], v[198:201], v[126:129]
	v_mfma_f32_16x16x32_bf16 v[122:125], v[172:175], v[198:201], v[122:125]
	v_mfma_f32_16x16x32_bf16 v[114:117], v[164:167], v[206:209], v[114:117]
	v_mfma_f32_16x16x32_bf16 v[106:109], v[172:175], v[206:209], v[106:109]
	v_mfma_f32_16x16x32_bf16 v[98:101], v[164:167], v[214:217], v[98:101]
	v_mfma_f32_16x16x32_bf16 v[90:93], v[172:175], v[214:217], v[90:93]
	v_mfma_f32_16x16x32_bf16 v[82:85], v[164:167], v[222:225], v[82:85]
	v_mfma_f32_16x16x32_bf16 v[74:77], v[172:175], v[222:225], v[74:77]
	s_setprio 0
	s_setprio 1
	v_mfma_f32_16x16x32_bf16 v[118:121], v[178:181], v[194:197], v[118:121]
	v_mfma_f32_16x16x32_bf16 v[110:113], v[186:189], v[194:197], v[110:113]
	v_mfma_f32_16x16x32_bf16 v[102:105], v[178:181], v[202:205], v[102:105]
	v_mfma_f32_16x16x32_bf16 v[94:97], v[186:189], v[202:205], v[94:97]
	v_mfma_f32_16x16x32_bf16 v[86:89], v[178:181], v[210:213], v[86:89]
	v_mfma_f32_16x16x32_bf16 v[78:81], v[186:189], v[210:213], v[78:81]
	v_mfma_f32_16x16x32_bf16 v[70:73], v[178:181], v[218:221], v[70:73]
	v_mfma_f32_16x16x32_bf16 v[66:69], v[186:189], v[218:221], v[66:69]
	v_mfma_f32_16x16x32_bf16 v[118:121], v[182:185], v[198:201], v[118:121]
	v_mfma_f32_16x16x32_bf16 v[110:113], v[190:193], v[198:201], v[110:113]
	v_mfma_f32_16x16x32_bf16 v[102:105], v[182:185], v[206:209], v[102:105]
	v_mfma_f32_16x16x32_bf16 v[94:97], v[190:193], v[206:209], v[94:97]
	v_mfma_f32_16x16x32_bf16 v[86:89], v[182:185], v[214:217], v[86:89]
	v_mfma_f32_16x16x32_bf16 v[78:81], v[190:193], v[214:217], v[78:81]
	v_mfma_f32_16x16x32_bf16 v[70:73], v[182:185], v[222:225], v[70:73]
	v_mfma_f32_16x16x32_bf16 v[66:69], v[190:193], v[222:225], v[66:69]
	s_barrier
	s_setprio 0
	s_add_i32 s2, s62, s41
	v_lshl_add_u64 v[226:227], v[226:227], 0, s[10:11]
	s_mov_b32 m0, s2
	ds_read_b128 v[194:197], v160 offset:49152
	ds_read_b128 v[198:201], v160 offset:50176
	ds_read_b128 v[202:205], v160 offset:51200
	ds_read_b128 v[206:209], v160 offset:52224
	ds_read_b128 v[210:213], v160 offset:53248
	ds_read_b128 v[214:217], v160 offset:54272
	ds_read_b128 v[218:221], v160 offset:55296
	ds_read_b128 v[222:225], v160 offset:56320
	global_load_lds_dwordx4 v[226:227], off
	s_add_i32 m0, s2, 0x2000
	s_add_u32 s2, s38, 0x40080
	v_lshl_add_u64 v[226:227], v[228:229], 0, s[10:11]
	s_addc_u32 s3, s39, 0
	s_add_i32 s38, s63, s41
	global_load_lds_dwordx4 v[226:227], off
	v_lshl_add_u64 v[226:227], s[2:3], 0, v[132:133]
	s_mov_b32 m0, s38
	s_nop 0
	global_load_lds_dwordx4 v[226:227], off
	v_lshl_add_u64 v[226:227], s[2:3], 0, v[136:137]
	s_add_i32 m0, s38, 0x2000
	s_nop 0
	global_load_lds_dwordx4 v[226:227], off
	v_lshl_add_u64 v[226:227], v[230:231], 0, s[10:11]
	s_mov_b32 m0, s47
	s_nop 0
	global_load_lds_dwordx4 v[226:227], off
	v_lshl_add_u64 v[226:227], v[232:233], 0, s[10:11]
	s_mov_b32 m0, s48
	s_nop 0
	global_load_lds_dwordx4 v[226:227], off
	s_waitcnt vmcnt(8)
	s_waitcnt lgkmcnt(0)
	s_setprio 1
	s_barrier
	v_mfma_f32_16x16x32_bf16 v[62:65], v[144:147], v[194:197], v[62:65]
	v_mfma_f32_16x16x32_bf16 v[58:61], v[168:171], v[194:197], v[58:61]
	v_mfma_f32_16x16x32_bf16 v[50:53], v[144:147], v[202:205], v[50:53]
	v_mfma_f32_16x16x32_bf16 v[42:45], v[168:171], v[202:205], v[42:45]
	v_mfma_f32_16x16x32_bf16 v[34:37], v[144:147], v[210:213], v[34:37]
	v_mfma_f32_16x16x32_bf16 v[26:29], v[168:171], v[210:213], v[26:29]
	v_mfma_f32_16x16x32_bf16 v[18:21], v[144:147], v[218:221], v[18:21]
	v_mfma_f32_16x16x32_bf16 v[10:13], v[168:171], v[218:221], v[10:13]
	v_mfma_f32_16x16x32_bf16 v[62:65], v[164:167], v[198:201], v[62:65]
	v_mfma_f32_16x16x32_bf16 v[58:61], v[172:175], v[198:201], v[58:61]
	v_mfma_f32_16x16x32_bf16 v[50:53], v[164:167], v[206:209], v[50:53]
	v_mfma_f32_16x16x32_bf16 v[42:45], v[172:175], v[206:209], v[42:45]
	v_mfma_f32_16x16x32_bf16 v[34:37], v[164:167], v[214:217], v[34:37]
	v_mfma_f32_16x16x32_bf16 v[26:29], v[172:175], v[214:217], v[26:29]
	v_mfma_f32_16x16x32_bf16 v[18:21], v[164:167], v[222:225], v[18:21]
	v_mfma_f32_16x16x32_bf16 v[10:13], v[172:175], v[222:225], v[10:13]
	s_setprio 0
	s_setprio 1
	v_mfma_f32_16x16x32_bf16 v[54:57], v[178:181], v[194:197], v[54:57]
	v_mfma_f32_16x16x32_bf16 v[46:49], v[186:189], v[194:197], v[46:49]
	v_mfma_f32_16x16x32_bf16 v[38:41], v[178:181], v[202:205], v[38:41]
	v_mfma_f32_16x16x32_bf16 v[30:33], v[186:189], v[202:205], v[30:33]
	v_mfma_f32_16x16x32_bf16 v[22:25], v[178:181], v[210:213], v[22:25]
	v_mfma_f32_16x16x32_bf16 v[14:17], v[186:189], v[210:213], v[14:17]
	v_mfma_f32_16x16x32_bf16 v[6:9], v[178:181], v[218:221], v[6:9]
	v_mfma_f32_16x16x32_bf16 v[2:5], v[186:189], v[218:221], v[2:5]
	v_mfma_f32_16x16x32_bf16 v[54:57], v[182:185], v[198:201], v[54:57]
	v_mfma_f32_16x16x32_bf16 v[46:49], v[190:193], v[198:201], v[46:49]
	v_mfma_f32_16x16x32_bf16 v[38:41], v[182:185], v[206:209], v[38:41]
	v_mfma_f32_16x16x32_bf16 v[30:33], v[190:193], v[206:209], v[30:33]
	v_mfma_f32_16x16x32_bf16 v[22:25], v[182:185], v[214:217], v[22:25]
	v_mfma_f32_16x16x32_bf16 v[14:17], v[190:193], v[214:217], v[14:17]
	v_mfma_f32_16x16x32_bf16 v[6:9], v[182:185], v[222:225], v[6:9]
	v_mfma_f32_16x16x32_bf16 v[2:5], v[190:193], v[222:225], v[2:5]
	s_barrier
	s_setprio 0
	s_add_i32 s61, s61, 2
	s_add_u32 s36, s36, 0x100
	s_addc_u32 s37, s37, 0
	s_add_u32 s59, s59, 0x100
	s_addc_u32 s60, s60, 0
	s_cmp_gt_u32 s61, 13
	s_cbranch_scc0 .LBB0_1179
	s_branch .Lpk1179_exit
.LBB0_1179:
	ds_read_b128 v[144:147], v158
	ds_read_b128 v[164:167], v158 offset:1024
	ds_read_b128 v[168:171], v158 offset:2048
	ds_read_b128 v[172:175], v158 offset:3072
	ds_read_b128 v[178:181], v159
	ds_read_b128 v[182:185], v159 offset:1024
	ds_read_b128 v[186:189], v159 offset:2048
	ds_read_b128 v[190:193], v159 offset:3072
	s_add_u32 s2, s36, 0xfffc0080
	s_addc_u32 s3, s37, -1
	s_cmp_eq_u32 s61, 12
	s_cselect_b32 s3, s19, s3
	s_cselect_b32 s2, s21, s2
	s_cselect_b32 s39, s57, s60
	s_cselect_b32 s38, s58, s59
	v_lshl_add_u64 v[226:227], s[36:37], 0, v[138:139]
	s_add_i32 m0, s42, 0xc000
	ds_read_b128 v[194:197], v160
	ds_read_b128 v[198:201], v160 offset:1024
	ds_read_b128 v[202:205], v160 offset:2048
	ds_read_b128 v[206:209], v160 offset:3072
	ds_read_b128 v[210:213], v160 offset:4096
	ds_read_b128 v[214:217], v160 offset:5120
	ds_read_b128 v[218:221], v160 offset:6144
	ds_read_b128 v[222:225], v160 offset:7168
	global_load_lds_dwordx4 v[226:227], off
	v_lshl_add_u64 v[226:227], s[36:37], 0, v[140:141]
	s_add_i32 m0, s42, 0xe000
	s_nop 0
	global_load_lds_dwordx4 v[226:227], off
	s_waitcnt vmcnt(8)
	s_waitcnt lgkmcnt(0)
	s_setprio 1
	s_barrier
	v_mfma_f32_16x16x32_bf16 v[126:129], v[144:147], v[194:197], v[126:129]
	v_mfma_f32_16x16x32_bf16 v[122:125], v[168:171], v[194:197], v[122:125]
	v_mfma_f32_16x16x32_bf16 v[114:117], v[144:147], v[202:205], v[114:117]
	v_mfma_f32_16x16x32_bf16 v[106:109], v[168:171], v[202:205], v[106:109]
	v_mfma_f32_16x16x32_bf16 v[98:101], v[144:147], v[210:213], v[98:101]
	v_mfma_f32_16x16x32_bf16 v[90:93], v[168:171], v[210:213], v[90:93]
	v_mfma_f32_16x16x32_bf16 v[82:85], v[144:147], v[218:221], v[82:85]
	v_mfma_f32_16x16x32_bf16 v[74:77], v[168:171], v[218:221], v[74:77]
	v_mfma_f32_16x16x32_bf16 v[126:129], v[164:167], v[198:201], v[126:129]
	v_mfma_f32_16x16x32_bf16 v[122:125], v[172:175], v[198:201], v[122:125]
	v_mfma_f32_16x16x32_bf16 v[114:117], v[164:167], v[206:209], v[114:117]
	v_mfma_f32_16x16x32_bf16 v[106:109], v[172:175], v[206:209], v[106:109]
	v_mfma_f32_16x16x32_bf16 v[98:101], v[164:167], v[214:217], v[98:101]
	v_mfma_f32_16x16x32_bf16 v[90:93], v[172:175], v[214:217], v[90:93]
	v_mfma_f32_16x16x32_bf16 v[82:85], v[164:167], v[222:225], v[82:85]
	v_mfma_f32_16x16x32_bf16 v[74:77], v[172:175], v[222:225], v[74:77]
	s_setprio 0
	s_setprio 1
	v_mfma_f32_16x16x32_bf16 v[118:121], v[178:181], v[194:197], v[118:121]
	v_mfma_f32_16x16x32_bf16 v[110:113], v[186:189], v[194:197], v[110:113]
	v_mfma_f32_16x16x32_bf16 v[102:105], v[178:181], v[202:205], v[102:105]
	v_mfma_f32_16x16x32_bf16 v[94:97], v[186:189], v[202:205], v[94:97]
	v_mfma_f32_16x16x32_bf16 v[86:89], v[178:181], v[210:213], v[86:89]
	v_mfma_f32_16x16x32_bf16 v[78:81], v[186:189], v[210:213], v[78:81]
	v_mfma_f32_16x16x32_bf16 v[70:73], v[178:181], v[218:221], v[70:73]
	v_mfma_f32_16x16x32_bf16 v[66:69], v[186:189], v[218:221], v[66:69]
	v_mfma_f32_16x16x32_bf16 v[118:121], v[182:185], v[198:201], v[118:121]
	v_mfma_f32_16x16x32_bf16 v[110:113], v[190:193], v[198:201], v[110:113]
	v_mfma_f32_16x16x32_bf16 v[102:105], v[182:185], v[206:209], v[102:105]
	v_mfma_f32_16x16x32_bf16 v[94:97], v[190:193], v[206:209], v[94:97]
	v_mfma_f32_16x16x32_bf16 v[86:89], v[182:185], v[214:217], v[86:89]
	v_mfma_f32_16x16x32_bf16 v[78:81], v[190:193], v[214:217], v[78:81]
	v_mfma_f32_16x16x32_bf16 v[70:73], v[182:185], v[222:225], v[70:73]
	v_mfma_f32_16x16x32_bf16 v[66:69], v[190:193], v[222:225], v[66:69]
	s_barrier
	s_setprio 0
	s_add_i32 s62, s51, s41
	v_lshl_add_u64 v[226:227], s[38:39], 0, v[132:133]
	s_mov_b32 m0, s62
	ds_read_b128 v[194:197], v160 offset:16384
	ds_read_b128 v[198:201], v160 offset:17408
	ds_read_b128 v[202:205], v160 offset:18432
	ds_read_b128 v[206:209], v160 offset:19456
	ds_read_b128 v[210:213], v160 offset:20480
	ds_read_b128 v[214:217], v160 offset:21504
	ds_read_b128 v[218:221], v160 offset:22528
	ds_read_b128 v[222:225], v160 offset:23552
	global_load_lds_dwordx4 v[226:227], off
	s_add_i32 m0, s62, 0x2000
	s_add_u32 s62, s38, 0x40000
	v_lshl_add_u64 v[228:229], s[38:39], 0, v[136:137]
	s_addc_u32 s63, s39, 0
	s_add_i32 s64, s52, s41
	global_load_lds_dwordx4 v[228:229], off
	v_lshl_add_u64 v[230:231], s[62:63], 0, v[132:133]
	s_mov_b32 m0, s64
	v_lshl_add_u64 v[232:233], s[2:3], 0, v[134:135]
	global_load_lds_dwordx4 v[230:231], off
	v_lshl_add_u64 v[230:231], s[62:63], 0, v[136:137]
	s_add_i32 m0, s64, 0x2000
	s_nop 0
	global_load_lds_dwordx4 v[230:231], off
	v_lshl_add_u64 v[230:231], s[2:3], 0, v[130:131]
	s_mov_b32 m0, s42
	s_nop 0
	global_load_lds_dwordx4 v[230:231], off
	s_mov_b32 m0, s43
	s_nop 0
	global_load_lds_dwordx4 v[232:233], off
	s_waitcnt vmcnt(8)
	s_waitcnt lgkmcnt(0)
	s_setprio 1
	s_barrier
	v_mfma_f32_16x16x32_bf16 v[62:65], v[144:147], v[194:197], v[62:65]
	v_mfma_f32_16x16x32_bf16 v[58:61], v[168:171], v[194:197], v[58:61]
	v_mfma_f32_16x16x32_bf16 v[50:53], v[144:147], v[202:205], v[50:53]
	v_mfma_f32_16x16x32_bf16 v[42:45], v[168:171], v[202:205], v[42:45]
	v_mfma_f32_16x16x32_bf16 v[34:37], v[144:147], v[210:213], v[34:37]
	v_mfma_f32_16x16x32_bf16 v[26:29], v[168:171], v[210:213], v[26:29]
	v_mfma_f32_16x16x32_bf16 v[18:21], v[144:147], v[218:221], v[18:21]
	v_mfma_f32_16x16x32_bf16 v[10:13], v[168:171], v[218:221], v[10:13]
	v_mfma_f32_16x16x32_bf16 v[62:65], v[164:167], v[198:201], v[62:65]
	v_mfma_f32_16x16x32_bf16 v[58:61], v[172:175], v[198:201], v[58:61]
	v_mfma_f32_16x16x32_bf16 v[50:53], v[164:167], v[206:209], v[50:53]
	v_mfma_f32_16x16x32_bf16 v[42:45], v[172:175], v[206:209], v[42:45]
	v_mfma_f32_16x16x32_bf16 v[34:37], v[164:167], v[214:217], v[34:37]
	v_mfma_f32_16x16x32_bf16 v[26:29], v[172:175], v[214:217], v[26:29]
	v_mfma_f32_16x16x32_bf16 v[18:21], v[164:167], v[222:225], v[18:21]
	v_mfma_f32_16x16x32_bf16 v[10:13], v[172:175], v[222:225], v[10:13]
	s_setprio 0
	s_setprio 1
	v_mfma_f32_16x16x32_bf16 v[54:57], v[178:181], v[194:197], v[54:57]
	v_mfma_f32_16x16x32_bf16 v[46:49], v[186:189], v[194:197], v[46:49]
	v_mfma_f32_16x16x32_bf16 v[38:41], v[178:181], v[202:205], v[38:41]
	v_mfma_f32_16x16x32_bf16 v[30:33], v[186:189], v[202:205], v[30:33]
	v_mfma_f32_16x16x32_bf16 v[22:25], v[178:181], v[210:213], v[22:25]
	v_mfma_f32_16x16x32_bf16 v[14:17], v[186:189], v[210:213], v[14:17]
	v_mfma_f32_16x16x32_bf16 v[6:9], v[178:181], v[218:221], v[6:9]
	v_mfma_f32_16x16x32_bf16 v[2:5], v[186:189], v[218:221], v[2:5]
	v_mfma_f32_16x16x32_bf16 v[54:57], v[182:185], v[198:201], v[54:57]
	v_mfma_f32_16x16x32_bf16 v[46:49], v[190:193], v[198:201], v[46:49]
	v_mfma_f32_16x16x32_bf16 v[38:41], v[182:185], v[206:209], v[38:41]
	v_mfma_f32_16x16x32_bf16 v[30:33], v[190:193], v[206:209], v[30:33]
	v_mfma_f32_16x16x32_bf16 v[22:25], v[182:185], v[214:217], v[22:25]
	v_mfma_f32_16x16x32_bf16 v[14:17], v[190:193], v[214:217], v[14:17]
	v_mfma_f32_16x16x32_bf16 v[6:9], v[182:185], v[222:225], v[6:9]
	v_mfma_f32_16x16x32_bf16 v[2:5], v[190:193], v[222:225], v[2:5]
	s_barrier
	s_setprio 0
	s_add_i32 s62, 0, 0x18000
	v_add_u32_e32 v163, s62, v148
	s_add_i32 s63, 0, 0x1c000
	ds_read_b128 v[144:147], v163
	ds_read_b128 v[164:167], v163 offset:1024
	ds_read_b128 v[168:171], v163 offset:2048
	ds_read_b128 v[172:175], v163 offset:3072
	v_add_u32_e32 v163, s63, v148
	ds_read_b128 v[178:181], v163
	ds_read_b128 v[182:185], v163 offset:1024
	ds_read_b128 v[186:189], v163 offset:2048
	ds_read_b128 v[190:193], v163 offset:3072
	s_add_u32 s2, s2, 0x40000
	s_addc_u32 s3, s3, 0
	s_mov_b32 m0, s44
	v_lshl_add_u64 v[234:235], s[2:3], 0, v[130:131]
	ds_read_b128 v[194:197], v160 offset:32768
	ds_read_b128 v[198:201], v160 offset:33792
	ds_read_b128 v[202:205], v160 offset:34816
	ds_read_b128 v[206:209], v160 offset:35840
	ds_read_b128 v[210:213], v160 offset:36864
	ds_read_b128 v[214:217], v160 offset:37888
	ds_read_b128 v[218:221], v160 offset:38912
	ds_read_b128 v[222:225], v160 offset:39936
	global_load_lds_dwordx4 v[234:235], off
	v_lshl_add_u64 v[234:235], s[2:3], 0, v[134:135]
	s_mov_b32 m0, s45
	s_nop 0
	global_load_lds_dwordx4 v[234:235], off
	s_waitcnt vmcnt(8)
	s_waitcnt lgkmcnt(0)
	s_setprio 1
	s_barrier
	v_mfma_f32_16x16x32_bf16 v[126:129], v[144:147], v[194:197], v[126:129]
	v_mfma_f32_16x16x32_bf16 v[122:125], v[168:171], v[194:197], v[122:125]
	v_mfma_f32_16x16x32_bf16 v[114:117], v[144:147], v[202:205], v[114:117]
	v_mfma_f32_16x16x32_bf16 v[106:109], v[168:171], v[202:205], v[106:109]
	v_mfma_f32_16x16x32_bf16 v[98:101], v[144:147], v[210:213], v[98:101]
	v_mfma_f32_16x16x32_bf16 v[90:93], v[168:171], v[210:213], v[90:93]
	v_mfma_f32_16x16x32_bf16 v[82:85], v[144:147], v[218:221], v[82:85]
	v_mfma_f32_16x16x32_bf16 v[74:77], v[168:171], v[218:221], v[74:77]
	v_mfma_f32_16x16x32_bf16 v[126:129], v[164:167], v[198:201], v[126:129]
	v_mfma_f32_16x16x32_bf16 v[122:125], v[172:175], v[198:201], v[122:125]
	v_mfma_f32_16x16x32_bf16 v[114:117], v[164:167], v[206:209], v[114:117]
	v_mfma_f32_16x16x32_bf16 v[106:109], v[172:175], v[206:209], v[106:109]
	v_mfma_f32_16x16x32_bf16 v[98:101], v[164:167], v[214:217], v[98:101]
	v_mfma_f32_16x16x32_bf16 v[90:93], v[172:175], v[214:217], v[90:93]
	v_mfma_f32_16x16x32_bf16 v[82:85], v[164:167], v[222:225], v[82:85]
	v_mfma_f32_16x16x32_bf16 v[74:77], v[172:175], v[222:225], v[74:77]
	s_setprio 0
	s_setprio 1
	v_mfma_f32_16x16x32_bf16 v[118:121], v[178:181], v[194:197], v[118:121]
	v_mfma_f32_16x16x32_bf16 v[110:113], v[186:189], v[194:197], v[110:113]
	v_mfma_f32_16x16x32_bf16 v[102:105], v[178:181], v[202:205], v[102:105]
	v_mfma_f32_16x16x32_bf16 v[94:97], v[186:189], v[202:205], v[94:97]
	v_mfma_f32_16x16x32_bf16 v[86:89], v[178:181], v[210:213], v[86:89]
	v_mfma_f32_16x16x32_bf16 v[78:81], v[186:189], v[210:213], v[78:81]
	v_mfma_f32_16x16x32_bf16 v[70:73], v[178:181], v[218:221], v[70:73]
	v_mfma_f32_16x16x32_bf16 v[66:69], v[186:189], v[218:221], v[66:69]
	v_mfma_f32_16x16x32_bf16 v[118:121], v[182:185], v[198:201], v[118:121]
	v_mfma_f32_16x16x32_bf16 v[110:113], v[190:193], v[198:201], v[110:113]
	v_mfma_f32_16x16x32_bf16 v[102:105], v[182:185], v[206:209], v[102:105]
	v_mfma_f32_16x16x32_bf16 v[94:97], v[190:193], v[206:209], v[94:97]
	v_mfma_f32_16x16x32_bf16 v[86:89], v[182:185], v[214:217], v[86:89]
	v_mfma_f32_16x16x32_bf16 v[78:81], v[190:193], v[214:217], v[78:81]
	v_mfma_f32_16x16x32_bf16 v[70:73], v[182:185], v[222:225], v[70:73]
	v_mfma_f32_16x16x32_bf16 v[66:69], v[190:193], v[222:225], v[66:69]
	s_barrier
	s_setprio 0
	s_add_i32 s2, s62, s41
	v_lshl_add_u64 v[226:227], v[226:227], 0, s[10:11]
	s_mov_b32 m0, s2
	ds_read_b128 v[194:197], v160 offset:49152
	ds_read_b128 v[198:201], v160 offset:50176
	ds_read_b128 v[202:205], v160 offset:51200
	ds_read_b128 v[206:209], v160 offset:52224
	ds_read_b128 v[210:213], v160 offset:53248
	ds_read_b128 v[214:217], v160 offset:54272
	ds_read_b128 v[218:221], v160 offset:55296
	ds_read_b128 v[222:225], v160 offset:56320
	global_load_lds_dwordx4 v[226:227], off
	s_add_i32 m0, s2, 0x2000
	s_add_u32 s2, s38, 0x40080
	v_lshl_add_u64 v[226:227], v[228:229], 0, s[10:11]
	s_addc_u32 s3, s39, 0
	s_add_i32 s38, s63, s41
	global_load_lds_dwordx4 v[226:227], off
	v_lshl_add_u64 v[226:227], s[2:3], 0, v[132:133]
	s_mov_b32 m0, s38
	s_nop 0
	global_load_lds_dwordx4 v[226:227], off
	v_lshl_add_u64 v[226:227], s[2:3], 0, v[136:137]
	s_add_i32 m0, s38, 0x2000
	s_nop 0
	global_load_lds_dwordx4 v[226:227], off
	v_lshl_add_u64 v[226:227], v[230:231], 0, s[10:11]
	s_mov_b32 m0, s47
	s_nop 0
	global_load_lds_dwordx4 v[226:227], off
	v_lshl_add_u64 v[226:227], v[232:233], 0, s[10:11]
	s_mov_b32 m0, s48
	s_nop 0
	global_load_lds_dwordx4 v[226:227], off
	s_waitcnt vmcnt(8)
	s_waitcnt lgkmcnt(0)
	s_setprio 1
	s_barrier
	v_mfma_f32_16x16x32_bf16 v[62:65], v[144:147], v[194:197], v[62:65]
	v_mfma_f32_16x16x32_bf16 v[58:61], v[168:171], v[194:197], v[58:61]
	v_mfma_f32_16x16x32_bf16 v[50:53], v[144:147], v[202:205], v[50:53]
	v_mfma_f32_16x16x32_bf16 v[42:45], v[168:171], v[202:205], v[42:45]
	v_mfma_f32_16x16x32_bf16 v[34:37], v[144:147], v[210:213], v[34:37]
	v_mfma_f32_16x16x32_bf16 v[26:29], v[168:171], v[210:213], v[26:29]
	v_mfma_f32_16x16x32_bf16 v[18:21], v[144:147], v[218:221], v[18:21]
	v_mfma_f32_16x16x32_bf16 v[10:13], v[168:171], v[218:221], v[10:13]
	v_mfma_f32_16x16x32_bf16 v[62:65], v[164:167], v[198:201], v[62:65]
	v_mfma_f32_16x16x32_bf16 v[58:61], v[172:175], v[198:201], v[58:61]
	v_mfma_f32_16x16x32_bf16 v[50:53], v[164:167], v[206:209], v[50:53]
	v_mfma_f32_16x16x32_bf16 v[42:45], v[172:175], v[206:209], v[42:45]
	v_mfma_f32_16x16x32_bf16 v[34:37], v[164:167], v[214:217], v[34:37]
	v_mfma_f32_16x16x32_bf16 v[26:29], v[172:175], v[214:217], v[26:29]
	v_mfma_f32_16x16x32_bf16 v[18:21], v[164:167], v[222:225], v[18:21]
	v_mfma_f32_16x16x32_bf16 v[10:13], v[172:175], v[222:225], v[10:13]
	s_setprio 0
	s_setprio 1
	v_mfma_f32_16x16x32_bf16 v[54:57], v[178:181], v[194:197], v[54:57]
	v_mfma_f32_16x16x32_bf16 v[46:49], v[186:189], v[194:197], v[46:49]
	v_mfma_f32_16x16x32_bf16 v[38:41], v[178:181], v[202:205], v[38:41]
	v_mfma_f32_16x16x32_bf16 v[30:33], v[186:189], v[202:205], v[30:33]
	v_mfma_f32_16x16x32_bf16 v[22:25], v[178:181], v[210:213], v[22:25]
	v_mfma_f32_16x16x32_bf16 v[14:17], v[186:189], v[210:213], v[14:17]
	v_mfma_f32_16x16x32_bf16 v[6:9], v[178:181], v[218:221], v[6:9]
	v_mfma_f32_16x16x32_bf16 v[2:5], v[186:189], v[218:221], v[2:5]
	v_mfma_f32_16x16x32_bf16 v[54:57], v[182:185], v[198:201], v[54:57]
	v_mfma_f32_16x16x32_bf16 v[46:49], v[190:193], v[198:201], v[46:49]
	v_mfma_f32_16x16x32_bf16 v[38:41], v[182:185], v[206:209], v[38:41]
	v_mfma_f32_16x16x32_bf16 v[30:33], v[190:193], v[206:209], v[30:33]
	v_mfma_f32_16x16x32_bf16 v[22:25], v[182:185], v[214:217], v[22:25]
	v_mfma_f32_16x16x32_bf16 v[14:17], v[190:193], v[214:217], v[14:17]
	v_mfma_f32_16x16x32_bf16 v[6:9], v[182:185], v[222:225], v[6:9]
	v_mfma_f32_16x16x32_bf16 v[2:5], v[190:193], v[222:225], v[2:5]
	s_barrier
	s_setprio 0
	s_add_i32 s61, s61, 2
	s_add_u32 s36, s36, 0x100
	s_addc_u32 s37, s37, 0
	s_add_u32 s59, s59, 0x100
	s_addc_u32 s60, s60, 0
	s_cmp_gt_u32 s61, 13
	s_cbranch_scc0 .LBB0_1179

.Lpk1239_peel:
	ds_read_b128 v[152:155], v148
	ds_read_b128 v[156:159], v148 offset:1024
	ds_read_b128 v[160:163], v148 offset:2048
	ds_read_b128 v[164:167], v148 offset:3072
	ds_read_b128 v[168:171], v149
	ds_read_b128 v[172:175], v149 offset:1024
	ds_read_b128 v[178:181], v149 offset:2048
	ds_read_b128 v[182:185], v149 offset:3072
	s_add_u32 s2, s36, 0xfffc0080
	s_addc_u32 s3, s37, -1
	s_cmp_eq_u32 s62, 12
	s_cselect_b32 s3, s19, s3
	s_cselect_b32 s2, s21, s2
	s_cselect_b32 s39, s58, s61
	s_cselect_b32 s38, s59, s60
	v_lshl_add_u64 v[144:145], s[36:37], 0, v[138:139]
	s_add_i32 m0, s44, 0xc000
	ds_read_b128 v[186:189], v150
	ds_read_b128 v[190:193], v150 offset:1024
	ds_read_b128 v[194:197], v150 offset:2048
	ds_read_b128 v[198:201], v150 offset:3072
	ds_read_b128 v[202:205], v150 offset:4096
	ds_read_b128 v[206:209], v150 offset:5120
	ds_read_b128 v[210:213], v150 offset:6144
	ds_read_b128 v[214:217], v150 offset:7168
	global_load_lds_dwordx4 v[144:145], off
	v_lshl_add_u64 v[144:145], s[36:37], 0, v[140:141]
	s_add_i32 m0, s44, 0xe000
	s_nop 0
	global_load_lds_dwordx4 v[144:145], off
	s_waitcnt vmcnt(8)
	s_waitcnt lgkmcnt(0)
	s_setprio 1
	s_barrier
	v_mfma_f32_16x16x32_bf16 v[126:129], v[152:155], v[186:189], 0
	v_mfma_f32_16x16x32_bf16 v[122:125], v[160:163], v[186:189], 0
	v_mfma_f32_16x16x32_bf16 v[114:117], v[152:155], v[194:197], 0
	v_mfma_f32_16x16x32_bf16 v[106:109], v[160:163], v[194:197], 0
	v_mfma_f32_16x16x32_bf16 v[98:101], v[152:155], v[202:205], 0
	v_mfma_f32_16x16x32_bf16 v[90:93], v[160:163], v[202:205], 0
	v_mfma_f32_16x16x32_bf16 v[82:85], v[152:155], v[210:213], 0
	v_mfma_f32_16x16x32_bf16 v[74:77], v[160:163], v[210:213], 0
	v_mfma_f32_16x16x32_bf16 v[126:129], v[156:159], v[190:193], v[126:129]
	v_mfma_f32_16x16x32_bf16 v[122:125], v[164:167], v[190:193], v[122:125]
	v_mfma_f32_16x16x32_bf16 v[114:117], v[156:159], v[198:201], v[114:117]
	v_mfma_f32_16x16x32_bf16 v[106:109], v[164:167], v[198:201], v[106:109]
	v_mfma_f32_16x16x32_bf16 v[98:101], v[156:159], v[206:209], v[98:101]
	v_mfma_f32_16x16x32_bf16 v[90:93], v[164:167], v[206:209], v[90:93]
	v_mfma_f32_16x16x32_bf16 v[82:85], v[156:159], v[214:217], v[82:85]
	v_mfma_f32_16x16x32_bf16 v[74:77], v[164:167], v[214:217], v[74:77]
	s_setprio 0
	s_setprio 1
	v_mfma_f32_16x16x32_bf16 v[118:121], v[168:171], v[186:189], 0
	v_mfma_f32_16x16x32_bf16 v[110:113], v[178:181], v[186:189], 0
	v_mfma_f32_16x16x32_bf16 v[102:105], v[168:171], v[194:197], 0
	v_mfma_f32_16x16x32_bf16 v[94:97], v[178:181], v[194:197], 0
	v_mfma_f32_16x16x32_bf16 v[86:89], v[168:171], v[202:205], 0
	v_mfma_f32_16x16x32_bf16 v[78:81], v[178:181], v[202:205], 0
	v_mfma_f32_16x16x32_bf16 v[70:73], v[168:171], v[210:213], 0
	v_mfma_f32_16x16x32_bf16 v[66:69], v[178:181], v[210:213], 0
	v_mfma_f32_16x16x32_bf16 v[118:121], v[172:175], v[190:193], v[118:121]
	v_mfma_f32_16x16x32_bf16 v[110:113], v[182:185], v[190:193], v[110:113]
	v_mfma_f32_16x16x32_bf16 v[102:105], v[172:175], v[198:201], v[102:105]
	v_mfma_f32_16x16x32_bf16 v[94:97], v[182:185], v[198:201], v[94:97]
	v_mfma_f32_16x16x32_bf16 v[86:89], v[172:175], v[206:209], v[86:89]
	v_mfma_f32_16x16x32_bf16 v[78:81], v[182:185], v[206:209], v[78:81]
	v_mfma_f32_16x16x32_bf16 v[70:73], v[172:175], v[214:217], v[70:73]
	v_mfma_f32_16x16x32_bf16 v[66:69], v[182:185], v[214:217], v[66:69]
	s_barrier
	s_setprio 0
	s_add_i32 s63, s51, s43
	v_lshl_add_u64 v[144:145], s[38:39], 0, v[132:133]
	s_mov_b32 m0, s63
	ds_read_b128 v[186:189], v150 offset:16384
	ds_read_b128 v[190:193], v150 offset:17408
	ds_read_b128 v[194:197], v150 offset:18432
	ds_read_b128 v[198:201], v150 offset:19456
	ds_read_b128 v[202:205], v150 offset:20480
	ds_read_b128 v[206:209], v150 offset:21504
	ds_read_b128 v[210:213], v150 offset:22528
	ds_read_b128 v[214:217], v150 offset:23552
	global_load_lds_dwordx4 v[144:145], off
	s_add_i32 m0, s63, 0x2000
	s_add_u32 s64, s38, 0x40000
	v_lshl_add_u64 v[218:219], s[38:39], 0, v[136:137]
	s_addc_u32 s65, s39, 0
	s_add_i32 s63, s52, s43
	global_load_lds_dwordx4 v[218:219], off
	v_lshl_add_u64 v[220:221], s[64:65], 0, v[132:133]
	s_mov_b32 m0, s63
	v_lshl_add_u64 v[222:223], s[2:3], 0, v[134:135]
	global_load_lds_dwordx4 v[220:221], off
	v_lshl_add_u64 v[220:221], s[64:65], 0, v[136:137]
	s_add_i32 m0, s63, 0x2000
	s_nop 0
	global_load_lds_dwordx4 v[220:221], off
	v_lshl_add_u64 v[220:221], s[2:3], 0, v[130:131]
	s_mov_b32 m0, s44
	s_nop 0
	global_load_lds_dwordx4 v[220:221], off
	s_mov_b32 m0, s35
	s_nop 0
	global_load_lds_dwordx4 v[222:223], off
	s_waitcnt vmcnt(8)
	s_waitcnt lgkmcnt(0)
	s_setprio 1
	s_barrier
	v_mfma_f32_16x16x32_bf16 v[62:65], v[152:155], v[186:189], 0
	v_mfma_f32_16x16x32_bf16 v[58:61], v[160:163], v[186:189], 0
	v_mfma_f32_16x16x32_bf16 v[50:53], v[152:155], v[194:197], 0
	v_mfma_f32_16x16x32_bf16 v[42:45], v[160:163], v[194:197], 0
	v_mfma_f32_16x16x32_bf16 v[34:37], v[152:155], v[202:205], 0
	v_mfma_f32_16x16x32_bf16 v[26:29], v[160:163], v[202:205], 0
	v_mfma_f32_16x16x32_bf16 v[18:21], v[152:155], v[210:213], 0
	v_mfma_f32_16x16x32_bf16 v[10:13], v[160:163], v[210:213], 0
	v_mfma_f32_16x16x32_bf16 v[62:65], v[156:159], v[190:193], v[62:65]
	v_mfma_f32_16x16x32_bf16 v[58:61], v[164:167], v[190:193], v[58:61]
	v_mfma_f32_16x16x32_bf16 v[50:53], v[156:159], v[198:201], v[50:53]
	v_mfma_f32_16x16x32_bf16 v[42:45], v[164:167], v[198:201], v[42:45]
	v_mfma_f32_16x16x32_bf16 v[34:37], v[156:159], v[206:209], v[34:37]
	v_mfma_f32_16x16x32_bf16 v[26:29], v[164:167], v[206:209], v[26:29]
	v_mfma_f32_16x16x32_bf16 v[18:21], v[156:159], v[214:217], v[18:21]
	v_mfma_f32_16x16x32_bf16 v[10:13], v[164:167], v[214:217], v[10:13]
	s_setprio 0
	s_setprio 1
	v_mfma_f32_16x16x32_bf16 v[54:57], v[168:171], v[186:189], 0
	v_mfma_f32_16x16x32_bf16 v[46:49], v[178:181], v[186:189], 0
	v_mfma_f32_16x16x32_bf16 v[38:41], v[168:171], v[194:197], 0
	v_mfma_f32_16x16x32_bf16 v[30:33], v[178:181], v[194:197], 0
	v_mfma_f32_16x16x32_bf16 v[22:25], v[168:171], v[202:205], 0
	v_mfma_f32_16x16x32_bf16 v[14:17], v[178:181], v[202:205], 0
	v_mfma_f32_16x16x32_bf16 v[6:9], v[168:171], v[210:213], 0
	v_mfma_f32_16x16x32_bf16 v[2:5], v[178:181], v[210:213], 0
	v_mfma_f32_16x16x32_bf16 v[54:57], v[172:175], v[190:193], v[54:57]
	v_mfma_f32_16x16x32_bf16 v[46:49], v[182:185], v[190:193], v[46:49]
	v_mfma_f32_16x16x32_bf16 v[38:41], v[172:175], v[198:201], v[38:41]
	v_mfma_f32_16x16x32_bf16 v[30:33], v[182:185], v[198:201], v[30:33]
	v_mfma_f32_16x16x32_bf16 v[22:25], v[172:175], v[206:209], v[22:25]
	v_mfma_f32_16x16x32_bf16 v[14:17], v[182:185], v[206:209], v[14:17]
	v_mfma_f32_16x16x32_bf16 v[6:9], v[172:175], v[214:217], v[6:9]
	v_mfma_f32_16x16x32_bf16 v[2:5], v[182:185], v[214:217], v[2:5]
	s_barrier
	s_setprio 0
	s_add_i32 s63, 0, 0x18000
	v_add_u32_e32 v151, s63, v146
	s_add_i32 s64, 0, 0x1c000
	ds_read_b128 v[152:155], v151
	ds_read_b128 v[156:159], v151 offset:1024
	ds_read_b128 v[160:163], v151 offset:2048
	ds_read_b128 v[164:167], v151 offset:3072
	v_add_u32_e32 v151, s64, v146
	ds_read_b128 v[168:171], v151
	ds_read_b128 v[172:175], v151 offset:1024
	ds_read_b128 v[178:181], v151 offset:2048
	ds_read_b128 v[182:185], v151 offset:3072
	s_add_u32 s2, s2, 0x40000
	s_addc_u32 s3, s3, 0
	s_mov_b32 m0, s45
	v_lshl_add_u64 v[224:225], s[2:3], 0, v[130:131]
	ds_read_b128 v[186:189], v150 offset:32768
	ds_read_b128 v[190:193], v150 offset:33792
	ds_read_b128 v[194:197], v150 offset:34816
	ds_read_b128 v[198:201], v150 offset:35840
	ds_read_b128 v[202:205], v150 offset:36864
	ds_read_b128 v[206:209], v150 offset:37888
	ds_read_b128 v[210:213], v150 offset:38912
	ds_read_b128 v[214:217], v150 offset:39936
	global_load_lds_dwordx4 v[224:225], off
	v_lshl_add_u64 v[224:225], s[2:3], 0, v[134:135]
	s_mov_b32 m0, s46
	s_nop 0
	global_load_lds_dwordx4 v[224:225], off
	s_waitcnt vmcnt(8)
	s_waitcnt lgkmcnt(0)
	s_setprio 1
	s_barrier
	v_mfma_f32_16x16x32_bf16 v[126:129], v[152:155], v[186:189], v[126:129]
	v_mfma_f32_16x16x32_bf16 v[122:125], v[160:163], v[186:189], v[122:125]
	v_mfma_f32_16x16x32_bf16 v[114:117], v[152:155], v[194:197], v[114:117]
	v_mfma_f32_16x16x32_bf16 v[106:109], v[160:163], v[194:197], v[106:109]
	v_mfma_f32_16x16x32_bf16 v[98:101], v[152:155], v[202:205], v[98:101]
	v_mfma_f32_16x16x32_bf16 v[90:93], v[160:163], v[202:205], v[90:93]
	v_mfma_f32_16x16x32_bf16 v[82:85], v[152:155], v[210:213], v[82:85]
	v_mfma_f32_16x16x32_bf16 v[74:77], v[160:163], v[210:213], v[74:77]
	v_mfma_f32_16x16x32_bf16 v[126:129], v[156:159], v[190:193], v[126:129]
	v_mfma_f32_16x16x32_bf16 v[122:125], v[164:167], v[190:193], v[122:125]
	v_mfma_f32_16x16x32_bf16 v[114:117], v[156:159], v[198:201], v[114:117]
	v_mfma_f32_16x16x32_bf16 v[106:109], v[164:167], v[198:201], v[106:109]
	v_mfma_f32_16x16x32_bf16 v[98:101], v[156:159], v[206:209], v[98:101]
	v_mfma_f32_16x16x32_bf16 v[90:93], v[164:167], v[206:209], v[90:93]
	v_mfma_f32_16x16x32_bf16 v[82:85], v[156:159], v[214:217], v[82:85]
	v_mfma_f32_16x16x32_bf16 v[74:77], v[164:167], v[214:217], v[74:77]
	s_setprio 0
	s_setprio 1
	v_mfma_f32_16x16x32_bf16 v[118:121], v[168:171], v[186:189], v[118:121]
	v_mfma_f32_16x16x32_bf16 v[110:113], v[178:181], v[186:189], v[110:113]
	v_mfma_f32_16x16x32_bf16 v[102:105], v[168:171], v[194:197], v[102:105]
	v_mfma_f32_16x16x32_bf16 v[94:97], v[178:181], v[194:197], v[94:97]
	v_mfma_f32_16x16x32_bf16 v[86:89], v[168:171], v[202:205], v[86:89]
	v_mfma_f32_16x16x32_bf16 v[78:81], v[178:181], v[202:205], v[78:81]
	v_mfma_f32_16x16x32_bf16 v[70:73], v[168:171], v[210:213], v[70:73]
	v_mfma_f32_16x16x32_bf16 v[66:69], v[178:181], v[210:213], v[66:69]
	v_mfma_f32_16x16x32_bf16 v[118:121], v[172:175], v[190:193], v[118:121]
	v_mfma_f32_16x16x32_bf16 v[110:113], v[182:185], v[190:193], v[110:113]
	v_mfma_f32_16x16x32_bf16 v[102:105], v[172:175], v[198:201], v[102:105]
	v_mfma_f32_16x16x32_bf16 v[94:97], v[182:185], v[198:201], v[94:97]
	v_mfma_f32_16x16x32_bf16 v[86:89], v[172:175], v[206:209], v[86:89]
	v_mfma_f32_16x16x32_bf16 v[78:81], v[182:185], v[206:209], v[78:81]
	v_mfma_f32_16x16x32_bf16 v[70:73], v[172:175], v[214:217], v[70:73]
	v_mfma_f32_16x16x32_bf16 v[66:69], v[182:185], v[214:217], v[66:69]
	s_barrier
	s_setprio 0
	s_add_i32 s2, s63, s43
	v_lshl_add_u64 v[144:145], v[144:145], 0, s[8:9]
	s_mov_b32 m0, s2
	ds_read_b128 v[186:189], v150 offset:49152
	ds_read_b128 v[190:193], v150 offset:50176
	ds_read_b128 v[194:197], v150 offset:51200
	ds_read_b128 v[198:201], v150 offset:52224
	ds_read_b128 v[202:205], v150 offset:53248
	ds_read_b128 v[206:209], v150 offset:54272
	ds_read_b128 v[210:213], v150 offset:55296
	ds_read_b128 v[214:217], v150 offset:56320
	global_load_lds_dwordx4 v[144:145], off
	s_add_i32 m0, s2, 0x2000
	s_add_u32 s2, s38, 0x40080
	v_lshl_add_u64 v[144:145], v[218:219], 0, s[8:9]
	s_addc_u32 s3, s39, 0
	s_add_i32 s38, s64, s43
	global_load_lds_dwordx4 v[144:145], off
	v_lshl_add_u64 v[144:145], s[2:3], 0, v[132:133]
	s_mov_b32 m0, s38
	s_nop 0
	global_load_lds_dwordx4 v[144:145], off
	v_lshl_add_u64 v[144:145], s[2:3], 0, v[136:137]
	s_add_i32 m0, s38, 0x2000
	s_nop 0
	global_load_lds_dwordx4 v[144:145], off
	v_lshl_add_u64 v[144:145], v[220:221], 0, s[8:9]
	s_mov_b32 m0, s48
	s_nop 0
	global_load_lds_dwordx4 v[144:145], off
	v_lshl_add_u64 v[144:145], v[222:223], 0, s[8:9]
	s_mov_b32 m0, s49
	s_nop 0
	global_load_lds_dwordx4 v[144:145], off
	s_waitcnt vmcnt(8)
	s_waitcnt lgkmcnt(0)
	s_setprio 1
	s_barrier
	v_mfma_f32_16x16x32_bf16 v[62:65], v[152:155], v[186:189], v[62:65]
	v_mfma_f32_16x16x32_bf16 v[58:61], v[160:163], v[186:189], v[58:61]
	v_mfma_f32_16x16x32_bf16 v[50:53], v[152:155], v[194:197], v[50:53]
	v_mfma_f32_16x16x32_bf16 v[42:45], v[160:163], v[194:197], v[42:45]
	v_mfma_f32_16x16x32_bf16 v[34:37], v[152:155], v[202:205], v[34:37]
	v_mfma_f32_16x16x32_bf16 v[26:29], v[160:163], v[202:205], v[26:29]
	v_mfma_f32_16x16x32_bf16 v[18:21], v[152:155], v[210:213], v[18:21]
	v_mfma_f32_16x16x32_bf16 v[10:13], v[160:163], v[210:213], v[10:13]
	v_mfma_f32_16x16x32_bf16 v[62:65], v[156:159], v[190:193], v[62:65]
	v_mfma_f32_16x16x32_bf16 v[58:61], v[164:167], v[190:193], v[58:61]
	v_mfma_f32_16x16x32_bf16 v[50:53], v[156:159], v[198:201], v[50:53]
	v_mfma_f32_16x16x32_bf16 v[42:45], v[164:167], v[198:201], v[42:45]
	v_mfma_f32_16x16x32_bf16 v[34:37], v[156:159], v[206:209], v[34:37]
	v_mfma_f32_16x16x32_bf16 v[26:29], v[164:167], v[206:209], v[26:29]
	v_mfma_f32_16x16x32_bf16 v[18:21], v[156:159], v[214:217], v[18:21]
	v_mfma_f32_16x16x32_bf16 v[10:13], v[164:167], v[214:217], v[10:13]
	s_setprio 0
	s_setprio 1
	v_mfma_f32_16x16x32_bf16 v[54:57], v[168:171], v[186:189], v[54:57]
	v_mfma_f32_16x16x32_bf16 v[46:49], v[178:181], v[186:189], v[46:49]
	v_mfma_f32_16x16x32_bf16 v[38:41], v[168:171], v[194:197], v[38:41]
	v_mfma_f32_16x16x32_bf16 v[30:33], v[178:181], v[194:197], v[30:33]
	v_mfma_f32_16x16x32_bf16 v[22:25], v[168:171], v[202:205], v[22:25]
	v_mfma_f32_16x16x32_bf16 v[14:17], v[178:181], v[202:205], v[14:17]
	v_mfma_f32_16x16x32_bf16 v[6:9], v[168:171], v[210:213], v[6:9]
	v_mfma_f32_16x16x32_bf16 v[2:5], v[178:181], v[210:213], v[2:5]
	v_mfma_f32_16x16x32_bf16 v[54:57], v[172:175], v[190:193], v[54:57]
	v_mfma_f32_16x16x32_bf16 v[46:49], v[182:185], v[190:193], v[46:49]
	v_mfma_f32_16x16x32_bf16 v[38:41], v[172:175], v[198:201], v[38:41]
	v_mfma_f32_16x16x32_bf16 v[30:33], v[182:185], v[198:201], v[30:33]
	v_mfma_f32_16x16x32_bf16 v[22:25], v[172:175], v[206:209], v[22:25]
	v_mfma_f32_16x16x32_bf16 v[14:17], v[182:185], v[206:209], v[14:17]
	v_mfma_f32_16x16x32_bf16 v[6:9], v[172:175], v[214:217], v[6:9]
	v_mfma_f32_16x16x32_bf16 v[2:5], v[182:185], v[214:217], v[2:5]
	s_barrier
	s_setprio 0
	s_add_i32 s62, s62, 2
	s_add_u32 s36, s36, 0x100
	s_addc_u32 s37, s37, 0
	s_add_u32 s60, s60, 0x100
	s_addc_u32 s61, s61, 0
	s_cmp_gt_u32 s62, 13
	s_cbranch_scc0 .LBB0_1239
	s_branch .Lpk1239_exit
.LBB0_1239:
	ds_read_b128 v[152:155], v148
	ds_read_b128 v[156:159], v148 offset:1024
	ds_read_b128 v[160:163], v148 offset:2048
	ds_read_b128 v[164:167], v148 offset:3072
	ds_read_b128 v[168:171], v149
	ds_read_b128 v[172:175], v149 offset:1024
	ds_read_b128 v[178:181], v149 offset:2048
	ds_read_b128 v[182:185], v149 offset:3072
	s_add_u32 s2, s36, 0xfffc0080
	s_addc_u32 s3, s37, -1
	s_cmp_eq_u32 s62, 12
	s_cselect_b32 s3, s19, s3
	s_cselect_b32 s2, s21, s2
	s_cselect_b32 s39, s58, s61
	s_cselect_b32 s38, s59, s60
	v_lshl_add_u64 v[144:145], s[36:37], 0, v[138:139]
	s_add_i32 m0, s44, 0xc000
	ds_read_b128 v[186:189], v150
	ds_read_b128 v[190:193], v150 offset:1024
	ds_read_b128 v[194:197], v150 offset:2048
	ds_read_b128 v[198:201], v150 offset:3072
	ds_read_b128 v[202:205], v150 offset:4096
	ds_read_b128 v[206:209], v150 offset:5120
	ds_read_b128 v[210:213], v150 offset:6144
	ds_read_b128 v[214:217], v150 offset:7168
	global_load_lds_dwordx4 v[144:145], off
	v_lshl_add_u64 v[144:145], s[36:37], 0, v[140:141]
	s_add_i32 m0, s44, 0xe000
	s_nop 0
	global_load_lds_dwordx4 v[144:145], off
	s_waitcnt vmcnt(8)
	s_waitcnt lgkmcnt(0)
	s_setprio 1
	s_barrier
	v_mfma_f32_16x16x32_bf16 v[126:129], v[152:155], v[186:189], v[126:129]
	v_mfma_f32_16x16x32_bf16 v[122:125], v[160:163], v[186:189], v[122:125]
	v_mfma_f32_16x16x32_bf16 v[114:117], v[152:155], v[194:197], v[114:117]
	v_mfma_f32_16x16x32_bf16 v[106:109], v[160:163], v[194:197], v[106:109]
	v_mfma_f32_16x16x32_bf16 v[98:101], v[152:155], v[202:205], v[98:101]
	v_mfma_f32_16x16x32_bf16 v[90:93], v[160:163], v[202:205], v[90:93]
	v_mfma_f32_16x16x32_bf16 v[82:85], v[152:155], v[210:213], v[82:85]
	v_mfma_f32_16x16x32_bf16 v[74:77], v[160:163], v[210:213], v[74:77]
	v_mfma_f32_16x16x32_bf16 v[126:129], v[156:159], v[190:193], v[126:129]
	v_mfma_f32_16x16x32_bf16 v[122:125], v[164:167], v[190:193], v[122:125]
	v_mfma_f32_16x16x32_bf16 v[114:117], v[156:159], v[198:201], v[114:117]
	v_mfma_f32_16x16x32_bf16 v[106:109], v[164:167], v[198:201], v[106:109]
	v_mfma_f32_16x16x32_bf16 v[98:101], v[156:159], v[206:209], v[98:101]
	v_mfma_f32_16x16x32_bf16 v[90:93], v[164:167], v[206:209], v[90:93]
	v_mfma_f32_16x16x32_bf16 v[82:85], v[156:159], v[214:217], v[82:85]
	v_mfma_f32_16x16x32_bf16 v[74:77], v[164:167], v[214:217], v[74:77]
	s_setprio 0
	s_setprio 1
	v_mfma_f32_16x16x32_bf16 v[118:121], v[168:171], v[186:189], v[118:121]
	v_mfma_f32_16x16x32_bf16 v[110:113], v[178:181], v[186:189], v[110:113]
	v_mfma_f32_16x16x32_bf16 v[102:105], v[168:171], v[194:197], v[102:105]
	v_mfma_f32_16x16x32_bf16 v[94:97], v[178:181], v[194:197], v[94:97]
	v_mfma_f32_16x16x32_bf16 v[86:89], v[168:171], v[202:205], v[86:89]
	v_mfma_f32_16x16x32_bf16 v[78:81], v[178:181], v[202:205], v[78:81]
	v_mfma_f32_16x16x32_bf16 v[70:73], v[168:171], v[210:213], v[70:73]
	v_mfma_f32_16x16x32_bf16 v[66:69], v[178:181], v[210:213], v[66:69]
	v_mfma_f32_16x16x32_bf16 v[118:121], v[172:175], v[190:193], v[118:121]
	v_mfma_f32_16x16x32_bf16 v[110:113], v[182:185], v[190:193], v[110:113]
	v_mfma_f32_16x16x32_bf16 v[102:105], v[172:175], v[198:201], v[102:105]
	v_mfma_f32_16x16x32_bf16 v[94:97], v[182:185], v[198:201], v[94:97]
	v_mfma_f32_16x16x32_bf16 v[86:89], v[172:175], v[206:209], v[86:89]
	v_mfma_f32_16x16x32_bf16 v[78:81], v[182:185], v[206:209], v[78:81]
	v_mfma_f32_16x16x32_bf16 v[70:73], v[172:175], v[214:217], v[70:73]
	v_mfma_f32_16x16x32_bf16 v[66:69], v[182:185], v[214:217], v[66:69]
	s_barrier
	s_setprio 0
	s_add_i32 s63, s51, s43
	v_lshl_add_u64 v[144:145], s[38:39], 0, v[132:133]
	s_mov_b32 m0, s63
	ds_read_b128 v[186:189], v150 offset:16384
	ds_read_b128 v[190:193], v150 offset:17408
	ds_read_b128 v[194:197], v150 offset:18432
	ds_read_b128 v[198:201], v150 offset:19456
	ds_read_b128 v[202:205], v150 offset:20480
	ds_read_b128 v[206:209], v150 offset:21504
	ds_read_b128 v[210:213], v150 offset:22528
	ds_read_b128 v[214:217], v150 offset:23552
	global_load_lds_dwordx4 v[144:145], off
	s_add_i32 m0, s63, 0x2000
	s_add_u32 s64, s38, 0x40000
	v_lshl_add_u64 v[218:219], s[38:39], 0, v[136:137]
	s_addc_u32 s65, s39, 0
	s_add_i32 s63, s52, s43
	global_load_lds_dwordx4 v[218:219], off
	v_lshl_add_u64 v[220:221], s[64:65], 0, v[132:133]
	s_mov_b32 m0, s63
	v_lshl_add_u64 v[222:223], s[2:3], 0, v[134:135]
	global_load_lds_dwordx4 v[220:221], off
	v_lshl_add_u64 v[220:221], s[64:65], 0, v[136:137]
	s_add_i32 m0, s63, 0x2000
	s_nop 0
	global_load_lds_dwordx4 v[220:221], off
	v_lshl_add_u64 v[220:221], s[2:3], 0, v[130:131]
	s_mov_b32 m0, s44
	s_nop 0
	global_load_lds_dwordx4 v[220:221], off
	s_mov_b32 m0, s35
	s_nop 0
	global_load_lds_dwordx4 v[222:223], off
	s_waitcnt vmcnt(8)
	s_waitcnt lgkmcnt(0)
	s_setprio 1
	s_barrier
	v_mfma_f32_16x16x32_bf16 v[62:65], v[152:155], v[186:189], v[62:65]
	v_mfma_f32_16x16x32_bf16 v[58:61], v[160:163], v[186:189], v[58:61]
	v_mfma_f32_16x16x32_bf16 v[50:53], v[152:155], v[194:197], v[50:53]
	v_mfma_f32_16x16x32_bf16 v[42:45], v[160:163], v[194:197], v[42:45]
	v_mfma_f32_16x16x32_bf16 v[34:37], v[152:155], v[202:205], v[34:37]
	v_mfma_f32_16x16x32_bf16 v[26:29], v[160:163], v[202:205], v[26:29]
	v_mfma_f32_16x16x32_bf16 v[18:21], v[152:155], v[210:213], v[18:21]
	v_mfma_f32_16x16x32_bf16 v[10:13], v[160:163], v[210:213], v[10:13]
	v_mfma_f32_16x16x32_bf16 v[62:65], v[156:159], v[190:193], v[62:65]
	v_mfma_f32_16x16x32_bf16 v[58:61], v[164:167], v[190:193], v[58:61]
	v_mfma_f32_16x16x32_bf16 v[50:53], v[156:159], v[198:201], v[50:53]
	v_mfma_f32_16x16x32_bf16 v[42:45], v[164:167], v[198:201], v[42:45]
	v_mfma_f32_16x16x32_bf16 v[34:37], v[156:159], v[206:209], v[34:37]
	v_mfma_f32_16x16x32_bf16 v[26:29], v[164:167], v[206:209], v[26:29]
	v_mfma_f32_16x16x32_bf16 v[18:21], v[156:159], v[214:217], v[18:21]
	v_mfma_f32_16x16x32_bf16 v[10:13], v[164:167], v[214:217], v[10:13]
	s_setprio 0
	s_setprio 1
	v_mfma_f32_16x16x32_bf16 v[54:57], v[168:171], v[186:189], v[54:57]
	v_mfma_f32_16x16x32_bf16 v[46:49], v[178:181], v[186:189], v[46:49]
	v_mfma_f32_16x16x32_bf16 v[38:41], v[168:171], v[194:197], v[38:41]
	v_mfma_f32_16x16x32_bf16 v[30:33], v[178:181], v[194:197], v[30:33]
	v_mfma_f32_16x16x32_bf16 v[22:25], v[168:171], v[202:205], v[22:25]
	v_mfma_f32_16x16x32_bf16 v[14:17], v[178:181], v[202:205], v[14:17]
	v_mfma_f32_16x16x32_bf16 v[6:9], v[168:171], v[210:213], v[6:9]
	v_mfma_f32_16x16x32_bf16 v[2:5], v[178:181], v[210:213], v[2:5]
	v_mfma_f32_16x16x32_bf16 v[54:57], v[172:175], v[190:193], v[54:57]
	v_mfma_f32_16x16x32_bf16 v[46:49], v[182:185], v[190:193], v[46:49]
	v_mfma_f32_16x16x32_bf16 v[38:41], v[172:175], v[198:201], v[38:41]
	v_mfma_f32_16x16x32_bf16 v[30:33], v[182:185], v[198:201], v[30:33]
	v_mfma_f32_16x16x32_bf16 v[22:25], v[172:175], v[206:209], v[22:25]
	v_mfma_f32_16x16x32_bf16 v[14:17], v[182:185], v[206:209], v[14:17]
	v_mfma_f32_16x16x32_bf16 v[6:9], v[172:175], v[214:217], v[6:9]
	v_mfma_f32_16x16x32_bf16 v[2:5], v[182:185], v[214:217], v[2:5]
	s_barrier
	s_setprio 0
	s_add_i32 s63, 0, 0x18000
	v_add_u32_e32 v151, s63, v146
	s_add_i32 s64, 0, 0x1c000
	ds_read_b128 v[152:155], v151
	ds_read_b128 v[156:159], v151 offset:1024
	ds_read_b128 v[160:163], v151 offset:2048
	ds_read_b128 v[164:167], v151 offset:3072
	v_add_u32_e32 v151, s64, v146
	ds_read_b128 v[168:171], v151
	ds_read_b128 v[172:175], v151 offset:1024
	ds_read_b128 v[178:181], v151 offset:2048
	ds_read_b128 v[182:185], v151 offset:3072
	s_add_u32 s2, s2, 0x40000
	s_addc_u32 s3, s3, 0
	s_mov_b32 m0, s45
	v_lshl_add_u64 v[224:225], s[2:3], 0, v[130:131]
	ds_read_b128 v[186:189], v150 offset:32768
	ds_read_b128 v[190:193], v150 offset:33792
	ds_read_b128 v[194:197], v150 offset:34816
	ds_read_b128 v[198:201], v150 offset:35840
	ds_read_b128 v[202:205], v150 offset:36864
	ds_read_b128 v[206:209], v150 offset:37888
	ds_read_b128 v[210:213], v150 offset:38912
	ds_read_b128 v[214:217], v150 offset:39936
	global_load_lds_dwordx4 v[224:225], off
	v_lshl_add_u64 v[224:225], s[2:3], 0, v[134:135]
	s_mov_b32 m0, s46
	s_nop 0
	global_load_lds_dwordx4 v[224:225], off
	s_waitcnt vmcnt(8)
	s_waitcnt lgkmcnt(0)
	s_setprio 1
	s_barrier
	v_mfma_f32_16x16x32_bf16 v[126:129], v[152:155], v[186:189], v[126:129]
	v_mfma_f32_16x16x32_bf16 v[122:125], v[160:163], v[186:189], v[122:125]
	v_mfma_f32_16x16x32_bf16 v[114:117], v[152:155], v[194:197], v[114:117]
	v_mfma_f32_16x16x32_bf16 v[106:109], v[160:163], v[194:197], v[106:109]
	v_mfma_f32_16x16x32_bf16 v[98:101], v[152:155], v[202:205], v[98:101]
	v_mfma_f32_16x16x32_bf16 v[90:93], v[160:163], v[202:205], v[90:93]
	v_mfma_f32_16x16x32_bf16 v[82:85], v[152:155], v[210:213], v[82:85]
	v_mfma_f32_16x16x32_bf16 v[74:77], v[160:163], v[210:213], v[74:77]
	v_mfma_f32_16x16x32_bf16 v[126:129], v[156:159], v[190:193], v[126:129]
	v_mfma_f32_16x16x32_bf16 v[122:125], v[164:167], v[190:193], v[122:125]
	v_mfma_f32_16x16x32_bf16 v[114:117], v[156:159], v[198:201], v[114:117]
	v_mfma_f32_16x16x32_bf16 v[106:109], v[164:167], v[198:201], v[106:109]
	v_mfma_f32_16x16x32_bf16 v[98:101], v[156:159], v[206:209], v[98:101]
	v_mfma_f32_16x16x32_bf16 v[90:93], v[164:167], v[206:209], v[90:93]
	v_mfma_f32_16x16x32_bf16 v[82:85], v[156:159], v[214:217], v[82:85]
	v_mfma_f32_16x16x32_bf16 v[74:77], v[164:167], v[214:217], v[74:77]
	s_setprio 0
	s_setprio 1
	v_mfma_f32_16x16x32_bf16 v[118:121], v[168:171], v[186:189], v[118:121]
	v_mfma_f32_16x16x32_bf16 v[110:113], v[178:181], v[186:189], v[110:113]
	v_mfma_f32_16x16x32_bf16 v[102:105], v[168:171], v[194:197], v[102:105]
	v_mfma_f32_16x16x32_bf16 v[94:97], v[178:181], v[194:197], v[94:97]
	v_mfma_f32_16x16x32_bf16 v[86:89], v[168:171], v[202:205], v[86:89]
	v_mfma_f32_16x16x32_bf16 v[78:81], v[178:181], v[202:205], v[78:81]
	v_mfma_f32_16x16x32_bf16 v[70:73], v[168:171], v[210:213], v[70:73]
	v_mfma_f32_16x16x32_bf16 v[66:69], v[178:181], v[210:213], v[66:69]
	v_mfma_f32_16x16x32_bf16 v[118:121], v[172:175], v[190:193], v[118:121]
	v_mfma_f32_16x16x32_bf16 v[110:113], v[182:185], v[190:193], v[110:113]
	v_mfma_f32_16x16x32_bf16 v[102:105], v[172:175], v[198:201], v[102:105]
	v_mfma_f32_16x16x32_bf16 v[94:97], v[182:185], v[198:201], v[94:97]
	v_mfma_f32_16x16x32_bf16 v[86:89], v[172:175], v[206:209], v[86:89]
	v_mfma_f32_16x16x32_bf16 v[78:81], v[182:185], v[206:209], v[78:81]
	v_mfma_f32_16x16x32_bf16 v[70:73], v[172:175], v[214:217], v[70:73]
	v_mfma_f32_16x16x32_bf16 v[66:69], v[182:185], v[214:217], v[66:69]
	s_barrier
	s_setprio 0
	s_add_i32 s2, s63, s43
	v_lshl_add_u64 v[144:145], v[144:145], 0, s[8:9]
	s_mov_b32 m0, s2
	ds_read_b128 v[186:189], v150 offset:49152
	ds_read_b128 v[190:193], v150 offset:50176
	ds_read_b128 v[194:197], v150 offset:51200
	ds_read_b128 v[198:201], v150 offset:52224
	ds_read_b128 v[202:205], v150 offset:53248
	ds_read_b128 v[206:209], v150 offset:54272
	ds_read_b128 v[210:213], v150 offset:55296
	ds_read_b128 v[214:217], v150 offset:56320
	global_load_lds_dwordx4 v[144:145], off
	s_add_i32 m0, s2, 0x2000
	s_add_u32 s2, s38, 0x40080
	v_lshl_add_u64 v[144:145], v[218:219], 0, s[8:9]
	s_addc_u32 s3, s39, 0
	s_add_i32 s38, s64, s43
	global_load_lds_dwordx4 v[144:145], off
	v_lshl_add_u64 v[144:145], s[2:3], 0, v[132:133]
	s_mov_b32 m0, s38
	s_nop 0
	global_load_lds_dwordx4 v[144:145], off
	v_lshl_add_u64 v[144:145], s[2:3], 0, v[136:137]
	s_add_i32 m0, s38, 0x2000
	s_nop 0
	global_load_lds_dwordx4 v[144:145], off
	v_lshl_add_u64 v[144:145], v[220:221], 0, s[8:9]
	s_mov_b32 m0, s48
	s_nop 0
	global_load_lds_dwordx4 v[144:145], off
	v_lshl_add_u64 v[144:145], v[222:223], 0, s[8:9]
	s_mov_b32 m0, s49
	s_nop 0
	global_load_lds_dwordx4 v[144:145], off
	s_waitcnt vmcnt(8)
	s_waitcnt lgkmcnt(0)
	s_setprio 1
	s_barrier
	v_mfma_f32_16x16x32_bf16 v[62:65], v[152:155], v[186:189], v[62:65]
	v_mfma_f32_16x16x32_bf16 v[58:61], v[160:163], v[186:189], v[58:61]
	v_mfma_f32_16x16x32_bf16 v[50:53], v[152:155], v[194:197], v[50:53]
	v_mfma_f32_16x16x32_bf16 v[42:45], v[160:163], v[194:197], v[42:45]
	v_mfma_f32_16x16x32_bf16 v[34:37], v[152:155], v[202:205], v[34:37]
	v_mfma_f32_16x16x32_bf16 v[26:29], v[160:163], v[202:205], v[26:29]
	v_mfma_f32_16x16x32_bf16 v[18:21], v[152:155], v[210:213], v[18:21]
	v_mfma_f32_16x16x32_bf16 v[10:13], v[160:163], v[210:213], v[10:13]
	v_mfma_f32_16x16x32_bf16 v[62:65], v[156:159], v[190:193], v[62:65]
	v_mfma_f32_16x16x32_bf16 v[58:61], v[164:167], v[190:193], v[58:61]
	v_mfma_f32_16x16x32_bf16 v[50:53], v[156:159], v[198:201], v[50:53]
	v_mfma_f32_16x16x32_bf16 v[42:45], v[164:167], v[198:201], v[42:45]
	v_mfma_f32_16x16x32_bf16 v[34:37], v[156:159], v[206:209], v[34:37]
	v_mfma_f32_16x16x32_bf16 v[26:29], v[164:167], v[206:209], v[26:29]
	v_mfma_f32_16x16x32_bf16 v[18:21], v[156:159], v[214:217], v[18:21]
	v_mfma_f32_16x16x32_bf16 v[10:13], v[164:167], v[214:217], v[10:13]
	s_setprio 0
	s_setprio 1
	v_mfma_f32_16x16x32_bf16 v[54:57], v[168:171], v[186:189], v[54:57]
	v_mfma_f32_16x16x32_bf16 v[46:49], v[178:181], v[186:189], v[46:49]
	v_mfma_f32_16x16x32_bf16 v[38:41], v[168:171], v[194:197], v[38:41]
	v_mfma_f32_16x16x32_bf16 v[30:33], v[178:181], v[194:197], v[30:33]
	v_mfma_f32_16x16x32_bf16 v[22:25], v[168:171], v[202:205], v[22:25]
	v_mfma_f32_16x16x32_bf16 v[14:17], v[178:181], v[202:205], v[14:17]
	v_mfma_f32_16x16x32_bf16 v[6:9], v[168:171], v[210:213], v[6:9]
	v_mfma_f32_16x16x32_bf16 v[2:5], v[178:181], v[210:213], v[2:5]
	v_mfma_f32_16x16x32_bf16 v[54:57], v[172:175], v[190:193], v[54:57]
	v_mfma_f32_16x16x32_bf16 v[46:49], v[182:185], v[190:193], v[46:49]
	v_mfma_f32_16x16x32_bf16 v[38:41], v[172:175], v[198:201], v[38:41]
	v_mfma_f32_16x16x32_bf16 v[30:33], v[182:185], v[198:201], v[30:33]
	v_mfma_f32_16x16x32_bf16 v[22:25], v[172:175], v[206:209], v[22:25]
	v_mfma_f32_16x16x32_bf16 v[14:17], v[182:185], v[206:209], v[14:17]
	v_mfma_f32_16x16x32_bf16 v[6:9], v[172:175], v[214:217], v[6:9]
	v_mfma_f32_16x16x32_bf16 v[2:5], v[182:185], v[214:217], v[2:5]
	s_barrier
	s_setprio 0
	s_add_i32 s62, s62, 2
	s_add_u32 s36, s36, 0x100
	s_addc_u32 s37, s37, 0
	s_add_u32 s60, s60, 0x100
	s_addc_u32 s61, s61, 0
	s_cmp_gt_u32 s62, 13
	s_cbranch_scc0 .LBB0_1239

.Lpk1303_peel:
	ds_read_b128 v[166:169], v139
	ds_read_b128 v[170:173], v139 offset:1024
	ds_read_b128 v[178:181], v139 offset:2048
	ds_read_b128 v[182:185], v139 offset:3072
	ds_read_b128 v[186:189], v163
	ds_read_b128 v[190:193], v163 offset:1024
	ds_read_b128 v[194:197], v163 offset:2048
	ds_read_b128 v[198:201], v163 offset:3072
	s_add_u32 s2, s26, 0xfffc0080
	s_addc_u32 s3, s27, -1
	s_cmp_eq_u32 s55, 12
	s_cselect_b32 s3, s11, s3
	s_cselect_b32 s2, s13, s2
	s_cselect_b32 s29, s47, s54
	s_cselect_b32 s28, s52, s53
	v_lshl_add_u64 v[148:149], s[26:27], 0, v[142:143]
	s_add_i32 m0, s34, 0xc000
	ds_read_b128 v[202:205], v164
	ds_read_b128 v[206:209], v164 offset:1024
	ds_read_b128 v[210:213], v164 offset:2048
	ds_read_b128 v[214:217], v164 offset:3072
	ds_read_b128 v[218:221], v164 offset:4096
	ds_read_b128 v[222:225], v164 offset:5120
	ds_read_b128 v[226:229], v164 offset:6144
	ds_read_b128 v[230:233], v164 offset:7168
	global_load_lds_dwordx4 v[148:149], off
	v_lshl_add_u64 v[148:149], s[26:27], 0, v[144:145]
	s_add_i32 m0, s34, 0xe000
	s_nop 0
	global_load_lds_dwordx4 v[148:149], off
	s_waitcnt vmcnt(8)
	s_waitcnt lgkmcnt(0)
	s_setprio 1
	s_barrier
	v_mfma_f32_16x16x32_bf16 v[126:129], v[166:169], v[202:205], 0
	v_mfma_f32_16x16x32_bf16 v[122:125], v[178:181], v[202:205], 0
	v_mfma_f32_16x16x32_bf16 v[110:113], v[166:169], v[210:213], 0
	v_mfma_f32_16x16x32_bf16 v[106:109], v[178:181], v[210:213], 0
	v_mfma_f32_16x16x32_bf16 v[94:97], v[166:169], v[218:221], 0
	v_mfma_f32_16x16x32_bf16 v[90:93], v[178:181], v[218:221], 0
	v_mfma_f32_16x16x32_bf16 v[78:81], v[166:169], v[226:229], 0
	v_mfma_f32_16x16x32_bf16 v[74:77], v[178:181], v[226:229], 0
	v_mfma_f32_16x16x32_bf16 v[126:129], v[170:173], v[206:209], v[126:129]
	v_mfma_f32_16x16x32_bf16 v[122:125], v[182:185], v[206:209], v[122:125]
	v_mfma_f32_16x16x32_bf16 v[110:113], v[170:173], v[214:217], v[110:113]
	v_mfma_f32_16x16x32_bf16 v[106:109], v[182:185], v[214:217], v[106:109]
	v_mfma_f32_16x16x32_bf16 v[94:97], v[170:173], v[222:225], v[94:97]
	v_mfma_f32_16x16x32_bf16 v[90:93], v[182:185], v[222:225], v[90:93]
	v_mfma_f32_16x16x32_bf16 v[78:81], v[170:173], v[230:233], v[78:81]
	v_mfma_f32_16x16x32_bf16 v[74:77], v[182:185], v[230:233], v[74:77]
	s_setprio 0
	s_setprio 1
	v_mfma_f32_16x16x32_bf16 v[118:121], v[186:189], v[202:205], 0
	v_mfma_f32_16x16x32_bf16 v[114:117], v[194:197], v[202:205], 0
	v_mfma_f32_16x16x32_bf16 v[102:105], v[186:189], v[210:213], 0
	v_mfma_f32_16x16x32_bf16 v[98:101], v[194:197], v[210:213], 0
	v_mfma_f32_16x16x32_bf16 v[86:89], v[186:189], v[218:221], 0
	v_mfma_f32_16x16x32_bf16 v[82:85], v[194:197], v[218:221], 0
	v_mfma_f32_16x16x32_bf16 v[70:73], v[186:189], v[226:229], 0
	v_mfma_f32_16x16x32_bf16 v[66:69], v[194:197], v[226:229], 0
	v_mfma_f32_16x16x32_bf16 v[118:121], v[190:193], v[206:209], v[118:121]
	v_mfma_f32_16x16x32_bf16 v[114:117], v[198:201], v[206:209], v[114:117]
	v_mfma_f32_16x16x32_bf16 v[102:105], v[190:193], v[214:217], v[102:105]
	v_mfma_f32_16x16x32_bf16 v[98:101], v[198:201], v[214:217], v[98:101]
	v_mfma_f32_16x16x32_bf16 v[86:89], v[190:193], v[222:225], v[86:89]
	v_mfma_f32_16x16x32_bf16 v[82:85], v[198:201], v[222:225], v[82:85]
	v_mfma_f32_16x16x32_bf16 v[70:73], v[190:193], v[230:233], v[70:73]
	v_mfma_f32_16x16x32_bf16 v[66:69], v[198:201], v[230:233], v[66:69]
	s_barrier
	s_setprio 0
	s_add_i32 s56, s42, s30
	v_lshl_add_u64 v[148:149], s[28:29], 0, v[132:133]
	s_mov_b32 m0, s56
	ds_read_b128 v[202:205], v164 offset:16384
	ds_read_b128 v[206:209], v164 offset:17408
	ds_read_b128 v[210:213], v164 offset:18432
	ds_read_b128 v[214:217], v164 offset:19456
	ds_read_b128 v[218:221], v164 offset:20480
	ds_read_b128 v[222:225], v164 offset:21504
	ds_read_b128 v[226:229], v164 offset:22528
	ds_read_b128 v[230:233], v164 offset:23552
	global_load_lds_dwordx4 v[148:149], off
	s_add_i32 m0, s56, 0x2000
	s_add_u32 s56, s28, 0x40000
	v_lshl_add_u64 v[174:175], s[28:29], 0, v[136:137]
	s_addc_u32 s57, s29, 0
	s_add_i32 s58, s43, s30
	global_load_lds_dwordx4 v[174:175], off
	v_lshl_add_u64 v[234:235], s[56:57], 0, v[132:133]
	s_mov_b32 m0, s58
	v_lshl_add_u64 v[236:237], s[2:3], 0, v[134:135]
	global_load_lds_dwordx4 v[234:235], off
	v_lshl_add_u64 v[234:235], s[56:57], 0, v[136:137]
	s_add_i32 m0, s58, 0x2000
	s_nop 0
	global_load_lds_dwordx4 v[234:235], off
	v_lshl_add_u64 v[234:235], s[2:3], 0, v[130:131]
	s_mov_b32 m0, s34
	s_nop 0
	global_load_lds_dwordx4 v[234:235], off
	s_mov_b32 m0, s25
	s_nop 0
	global_load_lds_dwordx4 v[236:237], off
	s_waitcnt vmcnt(8)
	s_waitcnt lgkmcnt(0)
	s_setprio 1
	s_barrier
	v_mfma_f32_16x16x32_bf16 v[62:65], v[166:169], v[202:205], 0
	v_mfma_f32_16x16x32_bf16 v[58:61], v[178:181], v[202:205], 0
	v_mfma_f32_16x16x32_bf16 v[46:49], v[166:169], v[210:213], 0
	v_mfma_f32_16x16x32_bf16 v[42:45], v[178:181], v[210:213], 0
	v_mfma_f32_16x16x32_bf16 v[30:33], v[166:169], v[218:221], 0
	v_mfma_f32_16x16x32_bf16 v[26:29], v[178:181], v[218:221], 0
	v_mfma_f32_16x16x32_bf16 v[14:17], v[166:169], v[226:229], 0
	v_mfma_f32_16x16x32_bf16 v[10:13], v[178:181], v[226:229], 0
	v_mfma_f32_16x16x32_bf16 v[62:65], v[170:173], v[206:209], v[62:65]
	v_mfma_f32_16x16x32_bf16 v[58:61], v[182:185], v[206:209], v[58:61]
	v_mfma_f32_16x16x32_bf16 v[46:49], v[170:173], v[214:217], v[46:49]
	v_mfma_f32_16x16x32_bf16 v[42:45], v[182:185], v[214:217], v[42:45]
	v_mfma_f32_16x16x32_bf16 v[30:33], v[170:173], v[222:225], v[30:33]
	v_mfma_f32_16x16x32_bf16 v[26:29], v[182:185], v[222:225], v[26:29]
	v_mfma_f32_16x16x32_bf16 v[14:17], v[170:173], v[230:233], v[14:17]
	v_mfma_f32_16x16x32_bf16 v[10:13], v[182:185], v[230:233], v[10:13]
	s_setprio 0
	s_setprio 1
	v_mfma_f32_16x16x32_bf16 v[54:57], v[186:189], v[202:205], 0
	v_mfma_f32_16x16x32_bf16 v[50:53], v[194:197], v[202:205], 0
	v_mfma_f32_16x16x32_bf16 v[38:41], v[186:189], v[210:213], 0
	v_mfma_f32_16x16x32_bf16 v[34:37], v[194:197], v[210:213], 0
	v_mfma_f32_16x16x32_bf16 v[22:25], v[186:189], v[218:221], 0
	v_mfma_f32_16x16x32_bf16 v[18:21], v[194:197], v[218:221], 0
	v_mfma_f32_16x16x32_bf16 v[6:9], v[186:189], v[226:229], 0
	v_mfma_f32_16x16x32_bf16 v[2:5], v[194:197], v[226:229], 0
	v_mfma_f32_16x16x32_bf16 v[54:57], v[190:193], v[206:209], v[54:57]
	v_mfma_f32_16x16x32_bf16 v[50:53], v[198:201], v[206:209], v[50:53]
	v_mfma_f32_16x16x32_bf16 v[38:41], v[190:193], v[214:217], v[38:41]
	v_mfma_f32_16x16x32_bf16 v[34:37], v[198:201], v[214:217], v[34:37]
	v_mfma_f32_16x16x32_bf16 v[22:25], v[190:193], v[222:225], v[22:25]
	v_mfma_f32_16x16x32_bf16 v[18:21], v[198:201], v[222:225], v[18:21]
	v_mfma_f32_16x16x32_bf16 v[6:9], v[190:193], v[230:233], v[6:9]
	v_mfma_f32_16x16x32_bf16 v[2:5], v[198:201], v[230:233], v[2:5]
	s_barrier
	s_setprio 0
	s_add_i32 s56, 0, 0x18000
	v_add_u32_e32 v165, s56, v162
	s_add_i32 s57, 0, 0x1c000
	ds_read_b128 v[166:169], v165
	ds_read_b128 v[170:173], v165 offset:1024
	ds_read_b128 v[178:181], v165 offset:2048
	ds_read_b128 v[182:185], v165 offset:3072
	v_add_u32_e32 v165, s57, v162
	ds_read_b128 v[186:189], v165
	ds_read_b128 v[190:193], v165 offset:1024
	ds_read_b128 v[194:197], v165 offset:2048
	ds_read_b128 v[198:201], v165 offset:3072
	s_add_u32 s2, s2, 0x40000
	s_addc_u32 s3, s3, 0
	s_mov_b32 m0, s35
	v_lshl_add_u64 v[238:239], s[2:3], 0, v[130:131]
	ds_read_b128 v[202:205], v164 offset:32768
	ds_read_b128 v[206:209], v164 offset:33792
	ds_read_b128 v[210:213], v164 offset:34816
	ds_read_b128 v[214:217], v164 offset:35840
	ds_read_b128 v[218:221], v164 offset:36864
	ds_read_b128 v[222:225], v164 offset:37888
	ds_read_b128 v[226:229], v164 offset:38912
	ds_read_b128 v[230:233], v164 offset:39936
	global_load_lds_dwordx4 v[238:239], off
	v_lshl_add_u64 v[238:239], s[2:3], 0, v[134:135]
	s_mov_b32 m0, s36
	s_nop 0
	global_load_lds_dwordx4 v[238:239], off
	s_waitcnt vmcnt(8)
	s_waitcnt lgkmcnt(0)
	s_setprio 1
	s_barrier
	v_mfma_f32_16x16x32_bf16 v[126:129], v[166:169], v[202:205], v[126:129]
	v_mfma_f32_16x16x32_bf16 v[122:125], v[178:181], v[202:205], v[122:125]
	v_mfma_f32_16x16x32_bf16 v[110:113], v[166:169], v[210:213], v[110:113]
	v_mfma_f32_16x16x32_bf16 v[106:109], v[178:181], v[210:213], v[106:109]
	v_mfma_f32_16x16x32_bf16 v[94:97], v[166:169], v[218:221], v[94:97]
	v_mfma_f32_16x16x32_bf16 v[90:93], v[178:181], v[218:221], v[90:93]
	v_mfma_f32_16x16x32_bf16 v[78:81], v[166:169], v[226:229], v[78:81]
	v_mfma_f32_16x16x32_bf16 v[74:77], v[178:181], v[226:229], v[74:77]
	v_mfma_f32_16x16x32_bf16 v[126:129], v[170:173], v[206:209], v[126:129]
	v_mfma_f32_16x16x32_bf16 v[122:125], v[182:185], v[206:209], v[122:125]
	v_mfma_f32_16x16x32_bf16 v[110:113], v[170:173], v[214:217], v[110:113]
	v_mfma_f32_16x16x32_bf16 v[106:109], v[182:185], v[214:217], v[106:109]
	v_mfma_f32_16x16x32_bf16 v[94:97], v[170:173], v[222:225], v[94:97]
	v_mfma_f32_16x16x32_bf16 v[90:93], v[182:185], v[222:225], v[90:93]
	v_mfma_f32_16x16x32_bf16 v[78:81], v[170:173], v[230:233], v[78:81]
	v_mfma_f32_16x16x32_bf16 v[74:77], v[182:185], v[230:233], v[74:77]
	s_setprio 0
	s_setprio 1
	v_mfma_f32_16x16x32_bf16 v[118:121], v[186:189], v[202:205], v[118:121]
	v_mfma_f32_16x16x32_bf16 v[114:117], v[194:197], v[202:205], v[114:117]
	v_mfma_f32_16x16x32_bf16 v[102:105], v[186:189], v[210:213], v[102:105]
	v_mfma_f32_16x16x32_bf16 v[98:101], v[194:197], v[210:213], v[98:101]
	v_mfma_f32_16x16x32_bf16 v[86:89], v[186:189], v[218:221], v[86:89]
	v_mfma_f32_16x16x32_bf16 v[82:85], v[194:197], v[218:221], v[82:85]
	v_mfma_f32_16x16x32_bf16 v[70:73], v[186:189], v[226:229], v[70:73]
	v_mfma_f32_16x16x32_bf16 v[66:69], v[194:197], v[226:229], v[66:69]
	v_mfma_f32_16x16x32_bf16 v[118:121], v[190:193], v[206:209], v[118:121]
	v_mfma_f32_16x16x32_bf16 v[114:117], v[198:201], v[206:209], v[114:117]
	v_mfma_f32_16x16x32_bf16 v[102:105], v[190:193], v[214:217], v[102:105]
	v_mfma_f32_16x16x32_bf16 v[98:101], v[198:201], v[214:217], v[98:101]
	v_mfma_f32_16x16x32_bf16 v[86:89], v[190:193], v[222:225], v[86:89]
	v_mfma_f32_16x16x32_bf16 v[82:85], v[198:201], v[222:225], v[82:85]
	v_mfma_f32_16x16x32_bf16 v[70:73], v[190:193], v[230:233], v[70:73]
	v_mfma_f32_16x16x32_bf16 v[66:69], v[198:201], v[230:233], v[66:69]
	s_barrier
	s_setprio 0
	s_add_i32 s2, s56, s30
	v_lshl_add_u64 v[148:149], v[148:149], 0, s[6:7]
	s_mov_b32 m0, s2
	ds_read_b128 v[202:205], v164 offset:49152
	ds_read_b128 v[206:209], v164 offset:50176
	ds_read_b128 v[210:213], v164 offset:51200
	ds_read_b128 v[214:217], v164 offset:52224
	ds_read_b128 v[218:221], v164 offset:53248
	ds_read_b128 v[222:225], v164 offset:54272
	ds_read_b128 v[226:229], v164 offset:55296
	ds_read_b128 v[230:233], v164 offset:56320
	global_load_lds_dwordx4 v[148:149], off
	s_add_i32 m0, s2, 0x2000
	s_add_u32 s2, s28, 0x40080
	v_lshl_add_u64 v[148:149], v[174:175], 0, s[6:7]
	s_addc_u32 s3, s29, 0
	s_add_i32 s28, s57, s30
	global_load_lds_dwordx4 v[148:149], off
	v_lshl_add_u64 v[148:149], s[2:3], 0, v[132:133]
	s_mov_b32 m0, s28
	s_nop 0
	global_load_lds_dwordx4 v[148:149], off
	v_lshl_add_u64 v[148:149], s[2:3], 0, v[136:137]
	s_add_i32 m0, s28, 0x2000
	s_nop 0
	global_load_lds_dwordx4 v[148:149], off
	v_lshl_add_u64 v[148:149], v[234:235], 0, s[6:7]
	s_mov_b32 m0, s39
	s_nop 0
	global_load_lds_dwordx4 v[148:149], off
	v_lshl_add_u64 v[148:149], v[236:237], 0, s[6:7]
	s_mov_b32 m0, s40
	s_nop 0
	global_load_lds_dwordx4 v[148:149], off
	s_waitcnt vmcnt(8)
	s_waitcnt lgkmcnt(0)
	s_setprio 1
	s_barrier
	v_mfma_f32_16x16x32_bf16 v[62:65], v[166:169], v[202:205], v[62:65]
	v_mfma_f32_16x16x32_bf16 v[58:61], v[178:181], v[202:205], v[58:61]
	v_mfma_f32_16x16x32_bf16 v[46:49], v[166:169], v[210:213], v[46:49]
	v_mfma_f32_16x16x32_bf16 v[42:45], v[178:181], v[210:213], v[42:45]
	v_mfma_f32_16x16x32_bf16 v[30:33], v[166:169], v[218:221], v[30:33]
	v_mfma_f32_16x16x32_bf16 v[26:29], v[178:181], v[218:221], v[26:29]
	v_mfma_f32_16x16x32_bf16 v[14:17], v[166:169], v[226:229], v[14:17]
	v_mfma_f32_16x16x32_bf16 v[10:13], v[178:181], v[226:229], v[10:13]
	v_mfma_f32_16x16x32_bf16 v[62:65], v[170:173], v[206:209], v[62:65]
	v_mfma_f32_16x16x32_bf16 v[58:61], v[182:185], v[206:209], v[58:61]
	v_mfma_f32_16x16x32_bf16 v[46:49], v[170:173], v[214:217], v[46:49]
	v_mfma_f32_16x16x32_bf16 v[42:45], v[182:185], v[214:217], v[42:45]
	v_mfma_f32_16x16x32_bf16 v[30:33], v[170:173], v[222:225], v[30:33]
	v_mfma_f32_16x16x32_bf16 v[26:29], v[182:185], v[222:225], v[26:29]
	v_mfma_f32_16x16x32_bf16 v[14:17], v[170:173], v[230:233], v[14:17]
	v_mfma_f32_16x16x32_bf16 v[10:13], v[182:185], v[230:233], v[10:13]
	s_setprio 0
	s_setprio 1
	v_mfma_f32_16x16x32_bf16 v[54:57], v[186:189], v[202:205], v[54:57]
	v_mfma_f32_16x16x32_bf16 v[50:53], v[194:197], v[202:205], v[50:53]
	v_mfma_f32_16x16x32_bf16 v[38:41], v[186:189], v[210:213], v[38:41]
	v_mfma_f32_16x16x32_bf16 v[34:37], v[194:197], v[210:213], v[34:37]
	v_mfma_f32_16x16x32_bf16 v[22:25], v[186:189], v[218:221], v[22:25]
	v_mfma_f32_16x16x32_bf16 v[18:21], v[194:197], v[218:221], v[18:21]
	v_mfma_f32_16x16x32_bf16 v[6:9], v[186:189], v[226:229], v[6:9]
	v_mfma_f32_16x16x32_bf16 v[2:5], v[194:197], v[226:229], v[2:5]
	v_mfma_f32_16x16x32_bf16 v[54:57], v[190:193], v[206:209], v[54:57]
	v_mfma_f32_16x16x32_bf16 v[50:53], v[198:201], v[206:209], v[50:53]
	v_mfma_f32_16x16x32_bf16 v[38:41], v[190:193], v[214:217], v[38:41]
	v_mfma_f32_16x16x32_bf16 v[34:37], v[198:201], v[214:217], v[34:37]
	v_mfma_f32_16x16x32_bf16 v[22:25], v[190:193], v[222:225], v[22:25]
	v_mfma_f32_16x16x32_bf16 v[18:21], v[198:201], v[222:225], v[18:21]
	v_mfma_f32_16x16x32_bf16 v[6:9], v[190:193], v[230:233], v[6:9]
	v_mfma_f32_16x16x32_bf16 v[2:5], v[198:201], v[230:233], v[2:5]
	s_barrier
	s_setprio 0
	s_add_i32 s55, s55, 2
	s_add_u32 s26, s26, 0x100
	s_addc_u32 s27, s27, 0
	s_add_u32 s53, s53, 0x100
	s_addc_u32 s54, s54, 0
	s_cmp_gt_u32 s55, 13
	s_cbranch_scc0 .LBB0_1303
	s_branch .Lpk1303_exit
.LBB0_1303:
	ds_read_b128 v[166:169], v139
	ds_read_b128 v[170:173], v139 offset:1024
	ds_read_b128 v[178:181], v139 offset:2048
	ds_read_b128 v[182:185], v139 offset:3072
	ds_read_b128 v[186:189], v163
	ds_read_b128 v[190:193], v163 offset:1024
	ds_read_b128 v[194:197], v163 offset:2048
	ds_read_b128 v[198:201], v163 offset:3072
	s_add_u32 s2, s26, 0xfffc0080
	s_addc_u32 s3, s27, -1
	s_cmp_eq_u32 s55, 12
	s_cselect_b32 s3, s11, s3
	s_cselect_b32 s2, s13, s2
	s_cselect_b32 s29, s47, s54
	s_cselect_b32 s28, s52, s53
	v_lshl_add_u64 v[148:149], s[26:27], 0, v[142:143]
	s_add_i32 m0, s34, 0xc000
	ds_read_b128 v[202:205], v164
	ds_read_b128 v[206:209], v164 offset:1024
	ds_read_b128 v[210:213], v164 offset:2048
	ds_read_b128 v[214:217], v164 offset:3072
	ds_read_b128 v[218:221], v164 offset:4096
	ds_read_b128 v[222:225], v164 offset:5120
	ds_read_b128 v[226:229], v164 offset:6144
	ds_read_b128 v[230:233], v164 offset:7168
	global_load_lds_dwordx4 v[148:149], off
	v_lshl_add_u64 v[148:149], s[26:27], 0, v[144:145]
	s_add_i32 m0, s34, 0xe000
	s_nop 0
	global_load_lds_dwordx4 v[148:149], off
	s_waitcnt vmcnt(8)
	s_waitcnt lgkmcnt(0)
	s_setprio 1
	s_barrier
	v_mfma_f32_16x16x32_bf16 v[126:129], v[166:169], v[202:205], v[126:129]
	v_mfma_f32_16x16x32_bf16 v[122:125], v[178:181], v[202:205], v[122:125]
	v_mfma_f32_16x16x32_bf16 v[110:113], v[166:169], v[210:213], v[110:113]
	v_mfma_f32_16x16x32_bf16 v[106:109], v[178:181], v[210:213], v[106:109]
	v_mfma_f32_16x16x32_bf16 v[94:97], v[166:169], v[218:221], v[94:97]
	v_mfma_f32_16x16x32_bf16 v[90:93], v[178:181], v[218:221], v[90:93]
	v_mfma_f32_16x16x32_bf16 v[78:81], v[166:169], v[226:229], v[78:81]
	v_mfma_f32_16x16x32_bf16 v[74:77], v[178:181], v[226:229], v[74:77]
	v_mfma_f32_16x16x32_bf16 v[126:129], v[170:173], v[206:209], v[126:129]
	v_mfma_f32_16x16x32_bf16 v[122:125], v[182:185], v[206:209], v[122:125]
	v_mfma_f32_16x16x32_bf16 v[110:113], v[170:173], v[214:217], v[110:113]
	v_mfma_f32_16x16x32_bf16 v[106:109], v[182:185], v[214:217], v[106:109]
	v_mfma_f32_16x16x32_bf16 v[94:97], v[170:173], v[222:225], v[94:97]
	v_mfma_f32_16x16x32_bf16 v[90:93], v[182:185], v[222:225], v[90:93]
	v_mfma_f32_16x16x32_bf16 v[78:81], v[170:173], v[230:233], v[78:81]
	v_mfma_f32_16x16x32_bf16 v[74:77], v[182:185], v[230:233], v[74:77]
	s_setprio 0
	s_setprio 1
	v_mfma_f32_16x16x32_bf16 v[118:121], v[186:189], v[202:205], v[118:121]
	v_mfma_f32_16x16x32_bf16 v[114:117], v[194:197], v[202:205], v[114:117]
	v_mfma_f32_16x16x32_bf16 v[102:105], v[186:189], v[210:213], v[102:105]
	v_mfma_f32_16x16x32_bf16 v[98:101], v[194:197], v[210:213], v[98:101]
	v_mfma_f32_16x16x32_bf16 v[86:89], v[186:189], v[218:221], v[86:89]
	v_mfma_f32_16x16x32_bf16 v[82:85], v[194:197], v[218:221], v[82:85]
	v_mfma_f32_16x16x32_bf16 v[70:73], v[186:189], v[226:229], v[70:73]
	v_mfma_f32_16x16x32_bf16 v[66:69], v[194:197], v[226:229], v[66:69]
	v_mfma_f32_16x16x32_bf16 v[118:121], v[190:193], v[206:209], v[118:121]
	v_mfma_f32_16x16x32_bf16 v[114:117], v[198:201], v[206:209], v[114:117]
	v_mfma_f32_16x16x32_bf16 v[102:105], v[190:193], v[214:217], v[102:105]
	v_mfma_f32_16x16x32_bf16 v[98:101], v[198:201], v[214:217], v[98:101]
	v_mfma_f32_16x16x32_bf16 v[86:89], v[190:193], v[222:225], v[86:89]
	v_mfma_f32_16x16x32_bf16 v[82:85], v[198:201], v[222:225], v[82:85]
	v_mfma_f32_16x16x32_bf16 v[70:73], v[190:193], v[230:233], v[70:73]
	v_mfma_f32_16x16x32_bf16 v[66:69], v[198:201], v[230:233], v[66:69]
	s_barrier
	s_setprio 0
	s_add_i32 s56, s42, s30
	v_lshl_add_u64 v[148:149], s[28:29], 0, v[132:133]
	s_mov_b32 m0, s56
	ds_read_b128 v[202:205], v164 offset:16384
	ds_read_b128 v[206:209], v164 offset:17408
	ds_read_b128 v[210:213], v164 offset:18432
	ds_read_b128 v[214:217], v164 offset:19456
	ds_read_b128 v[218:221], v164 offset:20480
	ds_read_b128 v[222:225], v164 offset:21504
	ds_read_b128 v[226:229], v164 offset:22528
	ds_read_b128 v[230:233], v164 offset:23552
	global_load_lds_dwordx4 v[148:149], off
	s_add_i32 m0, s56, 0x2000
	s_add_u32 s56, s28, 0x40000
	v_lshl_add_u64 v[174:175], s[28:29], 0, v[136:137]
	s_addc_u32 s57, s29, 0
	s_add_i32 s58, s43, s30
	global_load_lds_dwordx4 v[174:175], off
	v_lshl_add_u64 v[234:235], s[56:57], 0, v[132:133]
	s_mov_b32 m0, s58
	v_lshl_add_u64 v[236:237], s[2:3], 0, v[134:135]
	global_load_lds_dwordx4 v[234:235], off
	v_lshl_add_u64 v[234:235], s[56:57], 0, v[136:137]
	s_add_i32 m0, s58, 0x2000
	s_nop 0
	global_load_lds_dwordx4 v[234:235], off
	v_lshl_add_u64 v[234:235], s[2:3], 0, v[130:131]
	s_mov_b32 m0, s34
	s_nop 0
	global_load_lds_dwordx4 v[234:235], off
	s_mov_b32 m0, s25
	s_nop 0
	global_load_lds_dwordx4 v[236:237], off
	s_waitcnt vmcnt(8)
	s_waitcnt lgkmcnt(0)
	s_setprio 1
	s_barrier
	v_mfma_f32_16x16x32_bf16 v[62:65], v[166:169], v[202:205], v[62:65]
	v_mfma_f32_16x16x32_bf16 v[58:61], v[178:181], v[202:205], v[58:61]
	v_mfma_f32_16x16x32_bf16 v[46:49], v[166:169], v[210:213], v[46:49]
	v_mfma_f32_16x16x32_bf16 v[42:45], v[178:181], v[210:213], v[42:45]
	v_mfma_f32_16x16x32_bf16 v[30:33], v[166:169], v[218:221], v[30:33]
	v_mfma_f32_16x16x32_bf16 v[26:29], v[178:181], v[218:221], v[26:29]
	v_mfma_f32_16x16x32_bf16 v[14:17], v[166:169], v[226:229], v[14:17]
	v_mfma_f32_16x16x32_bf16 v[10:13], v[178:181], v[226:229], v[10:13]
	v_mfma_f32_16x16x32_bf16 v[62:65], v[170:173], v[206:209], v[62:65]
	v_mfma_f32_16x16x32_bf16 v[58:61], v[182:185], v[206:209], v[58:61]
	v_mfma_f32_16x16x32_bf16 v[46:49], v[170:173], v[214:217], v[46:49]
	v_mfma_f32_16x16x32_bf16 v[42:45], v[182:185], v[214:217], v[42:45]
	v_mfma_f32_16x16x32_bf16 v[30:33], v[170:173], v[222:225], v[30:33]
	v_mfma_f32_16x16x32_bf16 v[26:29], v[182:185], v[222:225], v[26:29]
	v_mfma_f32_16x16x32_bf16 v[14:17], v[170:173], v[230:233], v[14:17]
	v_mfma_f32_16x16x32_bf16 v[10:13], v[182:185], v[230:233], v[10:13]
	s_setprio 0
	s_setprio 1
	v_mfma_f32_16x16x32_bf16 v[54:57], v[186:189], v[202:205], v[54:57]
	v_mfma_f32_16x16x32_bf16 v[50:53], v[194:197], v[202:205], v[50:53]
	v_mfma_f32_16x16x32_bf16 v[38:41], v[186:189], v[210:213], v[38:41]
	v_mfma_f32_16x16x32_bf16 v[34:37], v[194:197], v[210:213], v[34:37]
	v_mfma_f32_16x16x32_bf16 v[22:25], v[186:189], v[218:221], v[22:25]
	v_mfma_f32_16x16x32_bf16 v[18:21], v[194:197], v[218:221], v[18:21]
	v_mfma_f32_16x16x32_bf16 v[6:9], v[186:189], v[226:229], v[6:9]
	v_mfma_f32_16x16x32_bf16 v[2:5], v[194:197], v[226:229], v[2:5]
	v_mfma_f32_16x16x32_bf16 v[54:57], v[190:193], v[206:209], v[54:57]
	v_mfma_f32_16x16x32_bf16 v[50:53], v[198:201], v[206:209], v[50:53]
	v_mfma_f32_16x16x32_bf16 v[38:41], v[190:193], v[214:217], v[38:41]
	v_mfma_f32_16x16x32_bf16 v[34:37], v[198:201], v[214:217], v[34:37]
	v_mfma_f32_16x16x32_bf16 v[22:25], v[190:193], v[222:225], v[22:25]
	v_mfma_f32_16x16x32_bf16 v[18:21], v[198:201], v[222:225], v[18:21]
	v_mfma_f32_16x16x32_bf16 v[6:9], v[190:193], v[230:233], v[6:9]
	v_mfma_f32_16x16x32_bf16 v[2:5], v[198:201], v[230:233], v[2:5]
	s_barrier
	s_setprio 0
	s_add_i32 s56, 0, 0x18000
	v_add_u32_e32 v165, s56, v162
	s_add_i32 s57, 0, 0x1c000
	ds_read_b128 v[166:169], v165
	ds_read_b128 v[170:173], v165 offset:1024
	ds_read_b128 v[178:181], v165 offset:2048
	ds_read_b128 v[182:185], v165 offset:3072
	v_add_u32_e32 v165, s57, v162
	ds_read_b128 v[186:189], v165
	ds_read_b128 v[190:193], v165 offset:1024
	ds_read_b128 v[194:197], v165 offset:2048
	ds_read_b128 v[198:201], v165 offset:3072
	s_add_u32 s2, s2, 0x40000
	s_addc_u32 s3, s3, 0
	s_mov_b32 m0, s35
	v_lshl_add_u64 v[238:239], s[2:3], 0, v[130:131]
	ds_read_b128 v[202:205], v164 offset:32768
	ds_read_b128 v[206:209], v164 offset:33792
	ds_read_b128 v[210:213], v164 offset:34816
	ds_read_b128 v[214:217], v164 offset:35840
	ds_read_b128 v[218:221], v164 offset:36864
	ds_read_b128 v[222:225], v164 offset:37888
	ds_read_b128 v[226:229], v164 offset:38912
	ds_read_b128 v[230:233], v164 offset:39936
	global_load_lds_dwordx4 v[238:239], off
	v_lshl_add_u64 v[238:239], s[2:3], 0, v[134:135]
	s_mov_b32 m0, s36
	s_nop 0
	global_load_lds_dwordx4 v[238:239], off
	s_waitcnt vmcnt(8)
	s_waitcnt lgkmcnt(0)
	s_setprio 1
	s_barrier
	v_mfma_f32_16x16x32_bf16 v[126:129], v[166:169], v[202:205], v[126:129]
	v_mfma_f32_16x16x32_bf16 v[122:125], v[178:181], v[202:205], v[122:125]
	v_mfma_f32_16x16x32_bf16 v[110:113], v[166:169], v[210:213], v[110:113]
	v_mfma_f32_16x16x32_bf16 v[106:109], v[178:181], v[210:213], v[106:109]
	v_mfma_f32_16x16x32_bf16 v[94:97], v[166:169], v[218:221], v[94:97]
	v_mfma_f32_16x16x32_bf16 v[90:93], v[178:181], v[218:221], v[90:93]
	v_mfma_f32_16x16x32_bf16 v[78:81], v[166:169], v[226:229], v[78:81]
	v_mfma_f32_16x16x32_bf16 v[74:77], v[178:181], v[226:229], v[74:77]
	v_mfma_f32_16x16x32_bf16 v[126:129], v[170:173], v[206:209], v[126:129]
	v_mfma_f32_16x16x32_bf16 v[122:125], v[182:185], v[206:209], v[122:125]
	v_mfma_f32_16x16x32_bf16 v[110:113], v[170:173], v[214:217], v[110:113]
	v_mfma_f32_16x16x32_bf16 v[106:109], v[182:185], v[214:217], v[106:109]
	v_mfma_f32_16x16x32_bf16 v[94:97], v[170:173], v[222:225], v[94:97]
	v_mfma_f32_16x16x32_bf16 v[90:93], v[182:185], v[222:225], v[90:93]
	v_mfma_f32_16x16x32_bf16 v[78:81], v[170:173], v[230:233], v[78:81]
	v_mfma_f32_16x16x32_bf16 v[74:77], v[182:185], v[230:233], v[74:77]
	s_setprio 0
	s_setprio 1
	v_mfma_f32_16x16x32_bf16 v[118:121], v[186:189], v[202:205], v[118:121]
	v_mfma_f32_16x16x32_bf16 v[114:117], v[194:197], v[202:205], v[114:117]
	v_mfma_f32_16x16x32_bf16 v[102:105], v[186:189], v[210:213], v[102:105]
	v_mfma_f32_16x16x32_bf16 v[98:101], v[194:197], v[210:213], v[98:101]
	v_mfma_f32_16x16x32_bf16 v[86:89], v[186:189], v[218:221], v[86:89]
	v_mfma_f32_16x16x32_bf16 v[82:85], v[194:197], v[218:221], v[82:85]
	v_mfma_f32_16x16x32_bf16 v[70:73], v[186:189], v[226:229], v[70:73]
	v_mfma_f32_16x16x32_bf16 v[66:69], v[194:197], v[226:229], v[66:69]
	v_mfma_f32_16x16x32_bf16 v[118:121], v[190:193], v[206:209], v[118:121]
	v_mfma_f32_16x16x32_bf16 v[114:117], v[198:201], v[206:209], v[114:117]
	v_mfma_f32_16x16x32_bf16 v[102:105], v[190:193], v[214:217], v[102:105]
	v_mfma_f32_16x16x32_bf16 v[98:101], v[198:201], v[214:217], v[98:101]
	v_mfma_f32_16x16x32_bf16 v[86:89], v[190:193], v[222:225], v[86:89]
	v_mfma_f32_16x16x32_bf16 v[82:85], v[198:201], v[222:225], v[82:85]
	v_mfma_f32_16x16x32_bf16 v[70:73], v[190:193], v[230:233], v[70:73]
	v_mfma_f32_16x16x32_bf16 v[66:69], v[198:201], v[230:233], v[66:69]
	s_barrier
	s_setprio 0
	s_add_i32 s2, s56, s30
	v_lshl_add_u64 v[148:149], v[148:149], 0, s[6:7]
	s_mov_b32 m0, s2
	ds_read_b128 v[202:205], v164 offset:49152
	ds_read_b128 v[206:209], v164 offset:50176
	ds_read_b128 v[210:213], v164 offset:51200
	ds_read_b128 v[214:217], v164 offset:52224
	ds_read_b128 v[218:221], v164 offset:53248
	ds_read_b128 v[222:225], v164 offset:54272
	ds_read_b128 v[226:229], v164 offset:55296
	ds_read_b128 v[230:233], v164 offset:56320
	global_load_lds_dwordx4 v[148:149], off
	s_add_i32 m0, s2, 0x2000
	s_add_u32 s2, s28, 0x40080
	v_lshl_add_u64 v[148:149], v[174:175], 0, s[6:7]
	s_addc_u32 s3, s29, 0
	s_add_i32 s28, s57, s30
	global_load_lds_dwordx4 v[148:149], off
	v_lshl_add_u64 v[148:149], s[2:3], 0, v[132:133]
	s_mov_b32 m0, s28
	s_nop 0
	global_load_lds_dwordx4 v[148:149], off
	v_lshl_add_u64 v[148:149], s[2:3], 0, v[136:137]
	s_add_i32 m0, s28, 0x2000
	s_nop 0
	global_load_lds_dwordx4 v[148:149], off
	v_lshl_add_u64 v[148:149], v[234:235], 0, s[6:7]
	s_mov_b32 m0, s39
	s_nop 0
	global_load_lds_dwordx4 v[148:149], off
	v_lshl_add_u64 v[148:149], v[236:237], 0, s[6:7]
	s_mov_b32 m0, s40
	s_nop 0
	global_load_lds_dwordx4 v[148:149], off
	s_waitcnt vmcnt(8)
	s_waitcnt lgkmcnt(0)
	s_setprio 1
	s_barrier
	v_mfma_f32_16x16x32_bf16 v[62:65], v[166:169], v[202:205], v[62:65]
	v_mfma_f32_16x16x32_bf16 v[58:61], v[178:181], v[202:205], v[58:61]
	v_mfma_f32_16x16x32_bf16 v[46:49], v[166:169], v[210:213], v[46:49]
	v_mfma_f32_16x16x32_bf16 v[42:45], v[178:181], v[210:213], v[42:45]
	v_mfma_f32_16x16x32_bf16 v[30:33], v[166:169], v[218:221], v[30:33]
	v_mfma_f32_16x16x32_bf16 v[26:29], v[178:181], v[218:221], v[26:29]
	v_mfma_f32_16x16x32_bf16 v[14:17], v[166:169], v[226:229], v[14:17]
	v_mfma_f32_16x16x32_bf16 v[10:13], v[178:181], v[226:229], v[10:13]
	v_mfma_f32_16x16x32_bf16 v[62:65], v[170:173], v[206:209], v[62:65]
	v_mfma_f32_16x16x32_bf16 v[58:61], v[182:185], v[206:209], v[58:61]
	v_mfma_f32_16x16x32_bf16 v[46:49], v[170:173], v[214:217], v[46:49]
	v_mfma_f32_16x16x32_bf16 v[42:45], v[182:185], v[214:217], v[42:45]
	v_mfma_f32_16x16x32_bf16 v[30:33], v[170:173], v[222:225], v[30:33]
	v_mfma_f32_16x16x32_bf16 v[26:29], v[182:185], v[222:225], v[26:29]
	v_mfma_f32_16x16x32_bf16 v[14:17], v[170:173], v[230:233], v[14:17]
	v_mfma_f32_16x16x32_bf16 v[10:13], v[182:185], v[230:233], v[10:13]
	s_setprio 0
	s_setprio 1
	v_mfma_f32_16x16x32_bf16 v[54:57], v[186:189], v[202:205], v[54:57]
	v_mfma_f32_16x16x32_bf16 v[50:53], v[194:197], v[202:205], v[50:53]
	v_mfma_f32_16x16x32_bf16 v[38:41], v[186:189], v[210:213], v[38:41]
	v_mfma_f32_16x16x32_bf16 v[34:37], v[194:197], v[210:213], v[34:37]
	v_mfma_f32_16x16x32_bf16 v[22:25], v[186:189], v[218:221], v[22:25]
	v_mfma_f32_16x16x32_bf16 v[18:21], v[194:197], v[218:221], v[18:21]
	v_mfma_f32_16x16x32_bf16 v[6:9], v[186:189], v[226:229], v[6:9]
	v_mfma_f32_16x16x32_bf16 v[2:5], v[194:197], v[226:229], v[2:5]
	v_mfma_f32_16x16x32_bf16 v[54:57], v[190:193], v[206:209], v[54:57]
	v_mfma_f32_16x16x32_bf16 v[50:53], v[198:201], v[206:209], v[50:53]
	v_mfma_f32_16x16x32_bf16 v[38:41], v[190:193], v[214:217], v[38:41]
	v_mfma_f32_16x16x32_bf16 v[34:37], v[198:201], v[214:217], v[34:37]
	v_mfma_f32_16x16x32_bf16 v[22:25], v[190:193], v[222:225], v[22:25]
	v_mfma_f32_16x16x32_bf16 v[18:21], v[198:201], v[222:225], v[18:21]
	v_mfma_f32_16x16x32_bf16 v[6:9], v[190:193], v[230:233], v[6:9]
	v_mfma_f32_16x16x32_bf16 v[2:5], v[198:201], v[230:233], v[2:5]
	s_barrier
	s_setprio 0
	s_add_i32 s55, s55, 2
	s_add_u32 s26, s26, 0x100
	s_addc_u32 s27, s27, 0
	s_add_u32 s53, s53, 0x100
	s_addc_u32 s54, s54, 0
	s_cmp_gt_u32 s55, 13
	s_cbranch_scc0 .LBB0_1303

.LBB0_1386:
	ds_read_b128 v[160:163], v133
	ds_read_b128 v[164:167], v133 offset:1024
	ds_read_b128 v[168:171], v133 offset:2048
	ds_read_b128 v[172:175], v133 offset:3072
	ds_read_b128 v[178:181], v135
	ds_read_b128 v[182:185], v135 offset:1024
	ds_read_b128 v[186:189], v135 offset:2048
	ds_read_b128 v[190:193], v135 offset:3072
	s_cmp_lg_u32 s8, 0x160000
	s_cselect_b32 s13, s8, 0
	s_cselect_b32 s12, s9, 0
	s_add_u32 s2, s6, s13
	s_addc_u32 s3, s7, s12
	s_add_u32 s14, s0, s13
	s_addc_u32 s15, s1, s12
	s_add_u32 s12, s2, 0x8000
	s_addc_u32 s13, s3, 0
	v_lshl_add_u64 v[226:227], v[148:149], 0, s[8:9]
	s_mov_b32 m0, s27
	v_lshl_add_u64 v[226:227], v[226:227], 0, s[10:11]
	ds_read_b128 v[194:197], v137
	ds_read_b128 v[198:201], v137 offset:1024
	ds_read_b128 v[202:205], v137 offset:2048
	ds_read_b128 v[206:209], v137 offset:3072
	ds_read_b128 v[210:213], v137 offset:4096
	ds_read_b128 v[214:217], v137 offset:5120
	ds_read_b128 v[218:221], v137 offset:6144
	ds_read_b128 v[222:225], v137 offset:7168
	global_load_lds_dwordx4 v[226:227], off
	v_lshl_add_u64 v[226:227], v[150:151], 0, s[8:9]
	v_lshl_add_u64 v[226:227], v[226:227], 0, s[10:11]
	s_mov_b32 m0, s28
	s_nop 0
	global_load_lds_dwordx4 v[226:227], off
	s_waitcnt vmcnt(8)
	s_waitcnt lgkmcnt(0)
	s_setprio 1
	s_barrier
	v_mfma_f32_16x16x32_bf16 v[126:129], v[160:163], v[194:197], v[126:129]
	v_mfma_f32_16x16x32_bf16 v[122:125], v[168:171], v[194:197], v[122:125]
	v_mfma_f32_16x16x32_bf16 v[114:117], v[160:163], v[202:205], v[114:117]
	v_mfma_f32_16x16x32_bf16 v[106:109], v[168:171], v[202:205], v[106:109]
	v_mfma_f32_16x16x32_bf16 v[98:101], v[160:163], v[210:213], v[98:101]
	v_mfma_f32_16x16x32_bf16 v[90:93], v[168:171], v[210:213], v[90:93]
	v_mfma_f32_16x16x32_bf16 v[82:85], v[160:163], v[218:221], v[82:85]
	v_mfma_f32_16x16x32_bf16 v[74:77], v[168:171], v[218:221], v[74:77]
	v_mfma_f32_16x16x32_bf16 v[126:129], v[164:167], v[198:201], v[126:129]
	v_mfma_f32_16x16x32_bf16 v[122:125], v[172:175], v[198:201], v[122:125]
	v_mfma_f32_16x16x32_bf16 v[114:117], v[164:167], v[206:209], v[114:117]
	v_mfma_f32_16x16x32_bf16 v[106:109], v[172:175], v[206:209], v[106:109]
	v_mfma_f32_16x16x32_bf16 v[98:101], v[164:167], v[214:217], v[98:101]
	v_mfma_f32_16x16x32_bf16 v[90:93], v[172:175], v[214:217], v[90:93]
	v_mfma_f32_16x16x32_bf16 v[82:85], v[164:167], v[222:225], v[82:85]
	v_mfma_f32_16x16x32_bf16 v[74:77], v[172:175], v[222:225], v[74:77]
	s_setprio 0
	s_setprio 1
	v_mfma_f32_16x16x32_bf16 v[118:121], v[178:181], v[194:197], v[118:121]
	v_mfma_f32_16x16x32_bf16 v[110:113], v[186:189], v[194:197], v[110:113]
	v_mfma_f32_16x16x32_bf16 v[102:105], v[178:181], v[202:205], v[102:105]
	v_mfma_f32_16x16x32_bf16 v[94:97], v[186:189], v[202:205], v[94:97]
	v_mfma_f32_16x16x32_bf16 v[86:89], v[178:181], v[210:213], v[86:89]
	v_mfma_f32_16x16x32_bf16 v[78:81], v[186:189], v[210:213], v[78:81]
	v_mfma_f32_16x16x32_bf16 v[70:73], v[178:181], v[218:221], v[70:73]
	v_mfma_f32_16x16x32_bf16 v[66:69], v[186:189], v[218:221], v[66:69]
	v_mfma_f32_16x16x32_bf16 v[118:121], v[182:185], v[198:201], v[118:121]
	v_mfma_f32_16x16x32_bf16 v[110:113], v[190:193], v[198:201], v[110:113]
	v_mfma_f32_16x16x32_bf16 v[102:105], v[182:185], v[206:209], v[102:105]
	v_mfma_f32_16x16x32_bf16 v[94:97], v[190:193], v[206:209], v[94:97]
	v_mfma_f32_16x16x32_bf16 v[86:89], v[182:185], v[214:217], v[86:89]
	v_mfma_f32_16x16x32_bf16 v[78:81], v[190:193], v[214:217], v[78:81]
	v_mfma_f32_16x16x32_bf16 v[70:73], v[182:185], v[222:225], v[70:73]
	v_mfma_f32_16x16x32_bf16 v[66:69], v[190:193], v[222:225], v[66:69]
	s_barrier
	s_setprio 0
	s_mov_b32 m0, s29
	v_lshl_add_u64 v[226:227], s[14:15], 0, v[142:143]
	s_add_u32 s40, s14, 0x4000
	ds_read_b128 v[194:197], v137 offset:16384
	ds_read_b128 v[198:201], v137 offset:17408
	ds_read_b128 v[202:205], v137 offset:18432
	ds_read_b128 v[206:209], v137 offset:19456
	ds_read_b128 v[210:213], v137 offset:20480
	ds_read_b128 v[214:217], v137 offset:21504
	ds_read_b128 v[218:221], v137 offset:22528
	ds_read_b128 v[222:225], v137 offset:23552
	global_load_lds_dwordx4 v[226:227], off
	v_lshl_add_u64 v[226:227], s[14:15], 0, v[146:147]
	s_mov_b32 m0, s30
	s_addc_u32 s41, s15, 0
	global_load_lds_dwordx4 v[226:227], off
	v_lshl_add_u64 v[226:227], s[40:41], 0, v[142:143]
	s_mov_b32 m0, s31
	s_nop 0
	global_load_lds_dwordx4 v[226:227], off
	v_lshl_add_u64 v[226:227], s[40:41], 0, v[146:147]
	s_mov_b32 m0, s34
	s_nop 0
	global_load_lds_dwordx4 v[226:227], off
	v_lshl_add_u64 v[226:227], s[2:3], 0, v[140:141]
	s_mov_b32 m0, s19
	s_nop 0
	global_load_lds_dwordx4 v[226:227], off
	v_lshl_add_u64 v[226:227], s[2:3], 0, v[144:145]
	s_mov_b32 m0, s20
	s_nop 0
	global_load_lds_dwordx4 v[226:227], off
	s_waitcnt vmcnt(8)
	s_waitcnt lgkmcnt(0)
	s_setprio 1
	s_barrier
	v_mfma_f32_16x16x32_bf16 v[62:65], v[160:163], v[194:197], v[62:65]
	v_mfma_f32_16x16x32_bf16 v[58:61], v[168:171], v[194:197], v[58:61]
	v_mfma_f32_16x16x32_bf16 v[50:53], v[160:163], v[202:205], v[50:53]
	v_mfma_f32_16x16x32_bf16 v[42:45], v[168:171], v[202:205], v[42:45]
	v_mfma_f32_16x16x32_bf16 v[34:37], v[160:163], v[210:213], v[34:37]
	v_mfma_f32_16x16x32_bf16 v[26:29], v[168:171], v[210:213], v[26:29]
	v_mfma_f32_16x16x32_bf16 v[18:21], v[160:163], v[218:221], v[18:21]
	v_mfma_f32_16x16x32_bf16 v[10:13], v[168:171], v[218:221], v[10:13]
	v_mfma_f32_16x16x32_bf16 v[62:65], v[164:167], v[198:201], v[62:65]
	v_mfma_f32_16x16x32_bf16 v[58:61], v[172:175], v[198:201], v[58:61]
	v_mfma_f32_16x16x32_bf16 v[50:53], v[164:167], v[206:209], v[50:53]
	v_mfma_f32_16x16x32_bf16 v[42:45], v[172:175], v[206:209], v[42:45]
	v_mfma_f32_16x16x32_bf16 v[34:37], v[164:167], v[214:217], v[34:37]
	v_mfma_f32_16x16x32_bf16 v[26:29], v[172:175], v[214:217], v[26:29]
	v_mfma_f32_16x16x32_bf16 v[18:21], v[164:167], v[222:225], v[18:21]
	v_mfma_f32_16x16x32_bf16 v[10:13], v[172:175], v[222:225], v[10:13]
	s_setprio 0
	s_setprio 1
	v_mfma_f32_16x16x32_bf16 v[54:57], v[178:181], v[194:197], v[54:57]
	v_mfma_f32_16x16x32_bf16 v[46:49], v[186:189], v[194:197], v[46:49]
	v_mfma_f32_16x16x32_bf16 v[38:41], v[178:181], v[202:205], v[38:41]
	v_mfma_f32_16x16x32_bf16 v[30:33], v[186:189], v[202:205], v[30:33]
	v_mfma_f32_16x16x32_bf16 v[22:25], v[178:181], v[210:213], v[22:25]
	v_mfma_f32_16x16x32_bf16 v[14:17], v[186:189], v[210:213], v[14:17]
	v_mfma_f32_16x16x32_bf16 v[6:9], v[178:181], v[218:221], v[6:9]
	v_mfma_f32_16x16x32_bf16 v[2:5], v[186:189], v[218:221], v[2:5]
	v_mfma_f32_16x16x32_bf16 v[54:57], v[182:185], v[198:201], v[54:57]
	v_mfma_f32_16x16x32_bf16 v[46:49], v[190:193], v[198:201], v[46:49]
	v_mfma_f32_16x16x32_bf16 v[38:41], v[182:185], v[206:209], v[38:41]
	v_mfma_f32_16x16x32_bf16 v[30:33], v[190:193], v[206:209], v[30:33]
	v_mfma_f32_16x16x32_bf16 v[22:25], v[182:185], v[214:217], v[22:25]
	v_mfma_f32_16x16x32_bf16 v[14:17], v[190:193], v[214:217], v[14:17]
	v_mfma_f32_16x16x32_bf16 v[6:9], v[182:185], v[222:225], v[6:9]
	v_mfma_f32_16x16x32_bf16 v[2:5], v[190:193], v[222:225], v[2:5]
	s_barrier
	s_setprio 0
	ds_read_b128 v[160:163], v139
	ds_read_b128 v[164:167], v139 offset:1024
	ds_read_b128 v[168:171], v139 offset:2048
	ds_read_b128 v[172:175], v139 offset:3072
	ds_read_b128 v[178:181], v158
	ds_read_b128 v[182:185], v158 offset:1024
	ds_read_b128 v[186:189], v158 offset:2048
	ds_read_b128 v[190:193], v158 offset:3072
	s_add_u32 s2, s2, 0x4000
	s_addc_u32 s3, s3, 0
	s_mov_b32 m0, s21
	v_lshl_add_u64 v[226:227], s[2:3], 0, v[140:141]
	ds_read_b128 v[194:197], v137 offset:32768
	ds_read_b128 v[198:201], v137 offset:33792
	ds_read_b128 v[202:205], v137 offset:34816
	ds_read_b128 v[206:209], v137 offset:35840
	ds_read_b128 v[210:213], v137 offset:36864
	ds_read_b128 v[214:217], v137 offset:37888
	ds_read_b128 v[218:221], v137 offset:38912
	ds_read_b128 v[222:225], v137 offset:39936
	global_load_lds_dwordx4 v[226:227], off
	v_lshl_add_u64 v[226:227], s[2:3], 0, v[144:145]
	s_mov_b32 m0, s22
	s_nop 0
	global_load_lds_dwordx4 v[226:227], off
	s_waitcnt vmcnt(8)
	s_waitcnt lgkmcnt(0)
	s_setprio 1
	s_barrier
	v_mfma_f32_16x16x32_bf16 v[126:129], v[160:163], v[194:197], v[126:129]
	v_mfma_f32_16x16x32_bf16 v[122:125], v[168:171], v[194:197], v[122:125]
	v_mfma_f32_16x16x32_bf16 v[114:117], v[160:163], v[202:205], v[114:117]
	v_mfma_f32_16x16x32_bf16 v[106:109], v[168:171], v[202:205], v[106:109]
	v_mfma_f32_16x16x32_bf16 v[98:101], v[160:163], v[210:213], v[98:101]
	v_mfma_f32_16x16x32_bf16 v[90:93], v[168:171], v[210:213], v[90:93]
	v_mfma_f32_16x16x32_bf16 v[82:85], v[160:163], v[218:221], v[82:85]
	v_mfma_f32_16x16x32_bf16 v[74:77], v[168:171], v[218:221], v[74:77]
	v_mfma_f32_16x16x32_bf16 v[126:129], v[164:167], v[198:201], v[126:129]
	v_mfma_f32_16x16x32_bf16 v[122:125], v[172:175], v[198:201], v[122:125]
	v_mfma_f32_16x16x32_bf16 v[114:117], v[164:167], v[206:209], v[114:117]
	v_mfma_f32_16x16x32_bf16 v[106:109], v[172:175], v[206:209], v[106:109]
	v_mfma_f32_16x16x32_bf16 v[98:101], v[164:167], v[214:217], v[98:101]
	v_mfma_f32_16x16x32_bf16 v[90:93], v[172:175], v[214:217], v[90:93]
	v_mfma_f32_16x16x32_bf16 v[82:85], v[164:167], v[222:225], v[82:85]
	v_mfma_f32_16x16x32_bf16 v[74:77], v[172:175], v[222:225], v[74:77]
	s_setprio 0
	s_setprio 1
	v_mfma_f32_16x16x32_bf16 v[118:121], v[178:181], v[194:197], v[118:121]
	v_mfma_f32_16x16x32_bf16 v[110:113], v[186:189], v[194:197], v[110:113]
	v_mfma_f32_16x16x32_bf16 v[102:105], v[178:181], v[202:205], v[102:105]
	v_mfma_f32_16x16x32_bf16 v[94:97], v[186:189], v[202:205], v[94:97]
	v_mfma_f32_16x16x32_bf16 v[86:89], v[178:181], v[210:213], v[86:89]
	v_mfma_f32_16x16x32_bf16 v[78:81], v[186:189], v[210:213], v[78:81]
	v_mfma_f32_16x16x32_bf16 v[70:73], v[178:181], v[218:221], v[70:73]
	v_mfma_f32_16x16x32_bf16 v[66:69], v[186:189], v[218:221], v[66:69]
	v_mfma_f32_16x16x32_bf16 v[118:121], v[182:185], v[198:201], v[118:121]
	v_mfma_f32_16x16x32_bf16 v[110:113], v[190:193], v[198:201], v[110:113]
	v_mfma_f32_16x16x32_bf16 v[102:105], v[182:185], v[206:209], v[102:105]
	v_mfma_f32_16x16x32_bf16 v[94:97], v[190:193], v[206:209], v[94:97]
	v_mfma_f32_16x16x32_bf16 v[86:89], v[182:185], v[214:217], v[86:89]
	v_mfma_f32_16x16x32_bf16 v[78:81], v[190:193], v[214:217], v[78:81]
	v_mfma_f32_16x16x32_bf16 v[70:73], v[182:185], v[222:225], v[70:73]
	v_mfma_f32_16x16x32_bf16 v[66:69], v[190:193], v[222:225], v[66:69]
	s_barrier
	s_setprio 0
	s_add_u32 s2, s14, 0x8000
	s_addc_u32 s3, s15, 0
	s_mov_b32 m0, s35
	v_lshl_add_u64 v[226:227], s[2:3], 0, v[142:143]
	ds_read_b128 v[194:197], v137 offset:49152
	ds_read_b128 v[198:201], v137 offset:50176
	ds_read_b128 v[202:205], v137 offset:51200
	ds_read_b128 v[206:209], v137 offset:52224
	ds_read_b128 v[210:213], v137 offset:53248
	ds_read_b128 v[214:217], v137 offset:54272
	ds_read_b128 v[218:221], v137 offset:55296
	ds_read_b128 v[222:225], v137 offset:56320
	global_load_lds_dwordx4 v[226:227], off
	v_lshl_add_u64 v[226:227], s[2:3], 0, v[146:147]
	s_add_u32 s2, s14, 0xc000
	s_mov_b32 m0, s36
	s_addc_u32 s3, s15, 0
	global_load_lds_dwordx4 v[226:227], off
	v_lshl_add_u64 v[226:227], s[2:3], 0, v[142:143]
	s_mov_b32 m0, s37
	s_nop 0
	global_load_lds_dwordx4 v[226:227], off
	v_lshl_add_u64 v[226:227], s[2:3], 0, v[146:147]
	s_mov_b32 m0, s38
	s_nop 0
	global_load_lds_dwordx4 v[226:227], off
	v_lshl_add_u64 v[226:227], s[12:13], 0, v[140:141]
	s_mov_b32 m0, s24
	s_nop 0
	global_load_lds_dwordx4 v[226:227], off
	v_lshl_add_u64 v[226:227], s[12:13], 0, v[144:145]
	s_mov_b32 m0, s25
	s_nop 0
	global_load_lds_dwordx4 v[226:227], off
	s_waitcnt vmcnt(8)
	s_waitcnt lgkmcnt(0)
	s_setprio 1
	s_barrier
	v_mfma_f32_16x16x32_bf16 v[62:65], v[160:163], v[194:197], v[62:65]
	v_mfma_f32_16x16x32_bf16 v[58:61], v[168:171], v[194:197], v[58:61]
	v_mfma_f32_16x16x32_bf16 v[50:53], v[160:163], v[202:205], v[50:53]
	v_mfma_f32_16x16x32_bf16 v[42:45], v[168:171], v[202:205], v[42:45]
	v_mfma_f32_16x16x32_bf16 v[34:37], v[160:163], v[210:213], v[34:37]
	v_mfma_f32_16x16x32_bf16 v[26:29], v[168:171], v[210:213], v[26:29]
	v_mfma_f32_16x16x32_bf16 v[18:21], v[160:163], v[218:221], v[18:21]
	v_mfma_f32_16x16x32_bf16 v[10:13], v[168:171], v[218:221], v[10:13]
	v_mfma_f32_16x16x32_bf16 v[62:65], v[164:167], v[198:201], v[62:65]
	v_mfma_f32_16x16x32_bf16 v[58:61], v[172:175], v[198:201], v[58:61]
	v_mfma_f32_16x16x32_bf16 v[50:53], v[164:167], v[206:209], v[50:53]
	v_mfma_f32_16x16x32_bf16 v[42:45], v[172:175], v[206:209], v[42:45]
	v_mfma_f32_16x16x32_bf16 v[34:37], v[164:167], v[214:217], v[34:37]
	v_mfma_f32_16x16x32_bf16 v[26:29], v[172:175], v[214:217], v[26:29]
	v_mfma_f32_16x16x32_bf16 v[18:21], v[164:167], v[222:225], v[18:21]
	v_mfma_f32_16x16x32_bf16 v[10:13], v[172:175], v[222:225], v[10:13]
	s_setprio 0
	s_setprio 1
	v_mfma_f32_16x16x32_bf16 v[54:57], v[178:181], v[194:197], v[54:57]
	v_mfma_f32_16x16x32_bf16 v[46:49], v[186:189], v[194:197], v[46:49]
	v_mfma_f32_16x16x32_bf16 v[38:41], v[178:181], v[202:205], v[38:41]
	v_mfma_f32_16x16x32_bf16 v[30:33], v[186:189], v[202:205], v[30:33]
	v_mfma_f32_16x16x32_bf16 v[22:25], v[178:181], v[210:213], v[22:25]
	v_mfma_f32_16x16x32_bf16 v[14:17], v[186:189], v[210:213], v[14:17]
	v_mfma_f32_16x16x32_bf16 v[6:9], v[178:181], v[218:221], v[6:9]
	v_mfma_f32_16x16x32_bf16 v[2:5], v[186:189], v[218:221], v[2:5]
	v_mfma_f32_16x16x32_bf16 v[54:57], v[182:185], v[198:201], v[54:57]
	v_mfma_f32_16x16x32_bf16 v[46:49], v[190:193], v[198:201], v[46:49]
	v_mfma_f32_16x16x32_bf16 v[38:41], v[182:185], v[206:209], v[38:41]
	v_mfma_f32_16x16x32_bf16 v[30:33], v[190:193], v[206:209], v[30:33]
	v_mfma_f32_16x16x32_bf16 v[22:25], v[182:185], v[214:217], v[22:25]
	v_mfma_f32_16x16x32_bf16 v[14:17], v[190:193], v[214:217], v[14:17]
	v_mfma_f32_16x16x32_bf16 v[6:9], v[182:185], v[222:225], v[6:9]
	v_mfma_f32_16x16x32_bf16 v[2:5], v[190:193], v[222:225], v[2:5]
	s_barrier
	s_setprio 0
	s_add_i32 s26, s26, 2
	s_add_u32 s8, s8, 0x10000
	s_addc_u32 s9, s9, 0
	s_cmp_gt_u32 s26, 41
	s_cbranch_scc0 .LBB0_1386
	s_cmpk_lt_u32 s16, 0x100
	s_cbranch_scc0 .LBB0_1389
	s_barrier

.Lpk1400_peel:
	ds_read_b128 v[152:155], v1
	ds_read_b128 v[156:159], v1 offset:1024
	ds_read_b128 v[160:163], v1 offset:2048
	ds_read_b128 v[164:167], v1 offset:3072
	ds_read_b128 v[168:171], v149
	ds_read_b128 v[172:175], v149 offset:1024
	ds_read_b128 v[178:181], v149 offset:2048
	ds_read_b128 v[182:185], v149 offset:3072
	s_add_u32 s2, s28, 0xfffc0080
	s_addc_u32 s3, s29, -1
	s_cmp_eq_u32 s55, 12
	s_cselect_b32 s3, s11, s3
	s_cselect_b32 s2, s13, s2
	s_cselect_b32 s31, s47, s54
	s_cselect_b32 s30, s52, s53
	v_lshl_add_u64 v[146:147], s[28:29], 0, v[140:141]
	s_add_i32 m0, s25, 0xc000
	ds_read_b128 v[186:189], v150
	ds_read_b128 v[190:193], v150 offset:1024
	ds_read_b128 v[194:197], v150 offset:2048
	ds_read_b128 v[198:201], v150 offset:3072
	ds_read_b128 v[202:205], v150 offset:4096
	ds_read_b128 v[206:209], v150 offset:5120
	ds_read_b128 v[210:213], v150 offset:6144
	ds_read_b128 v[214:217], v150 offset:7168
	global_load_lds_dwordx4 v[146:147], off
	v_lshl_add_u64 v[146:147], s[28:29], 0, v[142:143]
	s_add_i32 m0, s25, 0xe000
	s_nop 0
	global_load_lds_dwordx4 v[146:147], off
	s_waitcnt vmcnt(8)
	s_waitcnt lgkmcnt(0)
	s_setprio 1
	s_barrier
	v_mfma_f32_16x16x32_bf16 v[126:129], v[152:155], v[186:189], 0
	v_mfma_f32_16x16x32_bf16 v[122:125], v[160:163], v[186:189], 0
	v_mfma_f32_16x16x32_bf16 v[110:113], v[152:155], v[194:197], 0
	v_mfma_f32_16x16x32_bf16 v[106:109], v[160:163], v[194:197], 0
	v_mfma_f32_16x16x32_bf16 v[94:97], v[152:155], v[202:205], 0
	v_mfma_f32_16x16x32_bf16 v[90:93], v[160:163], v[202:205], 0
	v_mfma_f32_16x16x32_bf16 v[78:81], v[152:155], v[210:213], 0
	v_mfma_f32_16x16x32_bf16 v[74:77], v[160:163], v[210:213], 0
	v_mfma_f32_16x16x32_bf16 v[126:129], v[156:159], v[190:193], v[126:129]
	v_mfma_f32_16x16x32_bf16 v[122:125], v[164:167], v[190:193], v[122:125]
	v_mfma_f32_16x16x32_bf16 v[110:113], v[156:159], v[198:201], v[110:113]
	v_mfma_f32_16x16x32_bf16 v[106:109], v[164:167], v[198:201], v[106:109]
	v_mfma_f32_16x16x32_bf16 v[94:97], v[156:159], v[206:209], v[94:97]
	v_mfma_f32_16x16x32_bf16 v[90:93], v[164:167], v[206:209], v[90:93]
	v_mfma_f32_16x16x32_bf16 v[78:81], v[156:159], v[214:217], v[78:81]
	v_mfma_f32_16x16x32_bf16 v[74:77], v[164:167], v[214:217], v[74:77]
	s_setprio 0
	s_setprio 1
	v_mfma_f32_16x16x32_bf16 v[118:121], v[168:171], v[186:189], 0
	v_mfma_f32_16x16x32_bf16 v[114:117], v[178:181], v[186:189], 0
	v_mfma_f32_16x16x32_bf16 v[102:105], v[168:171], v[194:197], 0
	v_mfma_f32_16x16x32_bf16 v[98:101], v[178:181], v[194:197], 0
	v_mfma_f32_16x16x32_bf16 v[86:89], v[168:171], v[202:205], 0
	v_mfma_f32_16x16x32_bf16 v[82:85], v[178:181], v[202:205], 0
	v_mfma_f32_16x16x32_bf16 v[70:73], v[168:171], v[210:213], 0
	v_mfma_f32_16x16x32_bf16 v[66:69], v[178:181], v[210:213], 0
	v_mfma_f32_16x16x32_bf16 v[118:121], v[172:175], v[190:193], v[118:121]
	v_mfma_f32_16x16x32_bf16 v[114:117], v[182:185], v[190:193], v[114:117]
	v_mfma_f32_16x16x32_bf16 v[102:105], v[172:175], v[198:201], v[102:105]
	v_mfma_f32_16x16x32_bf16 v[98:101], v[182:185], v[198:201], v[98:101]
	v_mfma_f32_16x16x32_bf16 v[86:89], v[172:175], v[206:209], v[86:89]
	v_mfma_f32_16x16x32_bf16 v[82:85], v[182:185], v[206:209], v[82:85]
	v_mfma_f32_16x16x32_bf16 v[70:73], v[172:175], v[214:217], v[70:73]
	v_mfma_f32_16x16x32_bf16 v[66:69], v[182:185], v[214:217], v[66:69]
	s_barrier
	s_setprio 0
	s_add_i32 s56, s43, s34
	v_lshl_add_u64 v[146:147], s[30:31], 0, v[132:133]
	s_mov_b32 m0, s56
	ds_read_b128 v[186:189], v150 offset:16384
	ds_read_b128 v[190:193], v150 offset:17408
	ds_read_b128 v[194:197], v150 offset:18432
	ds_read_b128 v[198:201], v150 offset:19456
	ds_read_b128 v[202:205], v150 offset:20480
	ds_read_b128 v[206:209], v150 offset:21504
	ds_read_b128 v[210:213], v150 offset:22528
	ds_read_b128 v[214:217], v150 offset:23552
	global_load_lds_dwordx4 v[146:147], off
	s_add_i32 m0, s56, 0x2000
	s_add_u32 s56, s30, 0x40000
	v_lshl_add_u64 v[218:219], s[30:31], 0, v[136:137]
	s_addc_u32 s57, s31, 0
	s_add_i32 s58, s44, s34
	global_load_lds_dwordx4 v[218:219], off
	v_lshl_add_u64 v[220:221], s[56:57], 0, v[132:133]
	s_mov_b32 m0, s58
	v_lshl_add_u64 v[222:223], s[2:3], 0, v[134:135]
	global_load_lds_dwordx4 v[220:221], off
	v_lshl_add_u64 v[220:221], s[56:57], 0, v[136:137]
	s_add_i32 m0, s58, 0x2000
	s_nop 0
	global_load_lds_dwordx4 v[220:221], off
	v_lshl_add_u64 v[220:221], s[2:3], 0, v[130:131]
	s_mov_b32 m0, s25
	s_nop 0
	global_load_lds_dwordx4 v[220:221], off
	s_mov_b32 m0, s27
	s_nop 0
	global_load_lds_dwordx4 v[222:223], off
	s_waitcnt vmcnt(8)
	s_waitcnt lgkmcnt(0)
	s_setprio 1
	s_barrier
	v_mfma_f32_16x16x32_bf16 v[62:65], v[152:155], v[186:189], 0
	v_mfma_f32_16x16x32_bf16 v[58:61], v[160:163], v[186:189], 0
	v_mfma_f32_16x16x32_bf16 v[46:49], v[152:155], v[194:197], 0
	v_mfma_f32_16x16x32_bf16 v[42:45], v[160:163], v[194:197], 0
	v_mfma_f32_16x16x32_bf16 v[30:33], v[152:155], v[202:205], 0
	v_mfma_f32_16x16x32_bf16 v[26:29], v[160:163], v[202:205], 0
	v_mfma_f32_16x16x32_bf16 v[14:17], v[152:155], v[210:213], 0
	v_mfma_f32_16x16x32_bf16 v[10:13], v[160:163], v[210:213], 0
	v_mfma_f32_16x16x32_bf16 v[62:65], v[156:159], v[190:193], v[62:65]
	v_mfma_f32_16x16x32_bf16 v[58:61], v[164:167], v[190:193], v[58:61]
	v_mfma_f32_16x16x32_bf16 v[46:49], v[156:159], v[198:201], v[46:49]
	v_mfma_f32_16x16x32_bf16 v[42:45], v[164:167], v[198:201], v[42:45]
	v_mfma_f32_16x16x32_bf16 v[30:33], v[156:159], v[206:209], v[30:33]
	v_mfma_f32_16x16x32_bf16 v[26:29], v[164:167], v[206:209], v[26:29]
	v_mfma_f32_16x16x32_bf16 v[14:17], v[156:159], v[214:217], v[14:17]
	v_mfma_f32_16x16x32_bf16 v[10:13], v[164:167], v[214:217], v[10:13]
	s_setprio 0
	s_setprio 1
	v_mfma_f32_16x16x32_bf16 v[54:57], v[168:171], v[186:189], 0
	v_mfma_f32_16x16x32_bf16 v[50:53], v[178:181], v[186:189], 0
	v_mfma_f32_16x16x32_bf16 v[38:41], v[168:171], v[194:197], 0
	v_mfma_f32_16x16x32_bf16 v[34:37], v[178:181], v[194:197], 0
	v_mfma_f32_16x16x32_bf16 v[22:25], v[168:171], v[202:205], 0
	v_mfma_f32_16x16x32_bf16 v[18:21], v[178:181], v[202:205], 0
	v_mfma_f32_16x16x32_bf16 v[6:9], v[168:171], v[210:213], 0
	v_mfma_f32_16x16x32_bf16 v[2:5], v[178:181], v[210:213], 0
	v_mfma_f32_16x16x32_bf16 v[54:57], v[172:175], v[190:193], v[54:57]
	v_mfma_f32_16x16x32_bf16 v[50:53], v[182:185], v[190:193], v[50:53]
	v_mfma_f32_16x16x32_bf16 v[38:41], v[172:175], v[198:201], v[38:41]
	v_mfma_f32_16x16x32_bf16 v[34:37], v[182:185], v[198:201], v[34:37]
	v_mfma_f32_16x16x32_bf16 v[22:25], v[172:175], v[206:209], v[22:25]
	v_mfma_f32_16x16x32_bf16 v[18:21], v[182:185], v[206:209], v[18:21]
	v_mfma_f32_16x16x32_bf16 v[6:9], v[172:175], v[214:217], v[6:9]
	v_mfma_f32_16x16x32_bf16 v[2:5], v[182:185], v[214:217], v[2:5]
	s_barrier
	s_setprio 0
	s_add_i32 s56, 0, 0x18000
	v_add_u32_e32 v151, s56, v148
	s_add_i32 s57, 0, 0x1c000
	ds_read_b128 v[152:155], v151
	ds_read_b128 v[156:159], v151 offset:1024
	ds_read_b128 v[160:163], v151 offset:2048
	ds_read_b128 v[164:167], v151 offset:3072
	v_add_u32_e32 v151, s57, v148
	ds_read_b128 v[168:171], v151
	ds_read_b128 v[172:175], v151 offset:1024
	ds_read_b128 v[178:181], v151 offset:2048
	ds_read_b128 v[182:185], v151 offset:3072
	s_add_u32 s2, s2, 0x40000
	s_addc_u32 s3, s3, 0
	s_mov_b32 m0, s36
	v_lshl_add_u64 v[224:225], s[2:3], 0, v[130:131]
	ds_read_b128 v[186:189], v150 offset:32768
	ds_read_b128 v[190:193], v150 offset:33792
	ds_read_b128 v[194:197], v150 offset:34816
	ds_read_b128 v[198:201], v150 offset:35840
	ds_read_b128 v[202:205], v150 offset:36864
	ds_read_b128 v[206:209], v150 offset:37888
	ds_read_b128 v[210:213], v150 offset:38912
	ds_read_b128 v[214:217], v150 offset:39936
	global_load_lds_dwordx4 v[224:225], off
	v_lshl_add_u64 v[224:225], s[2:3], 0, v[134:135]
	s_mov_b32 m0, s37
	s_nop 0
	global_load_lds_dwordx4 v[224:225], off
	s_waitcnt vmcnt(8)
	s_waitcnt lgkmcnt(0)
	s_setprio 1
	s_barrier
	v_mfma_f32_16x16x32_bf16 v[126:129], v[152:155], v[186:189], v[126:129]
	v_mfma_f32_16x16x32_bf16 v[122:125], v[160:163], v[186:189], v[122:125]
	v_mfma_f32_16x16x32_bf16 v[110:113], v[152:155], v[194:197], v[110:113]
	v_mfma_f32_16x16x32_bf16 v[106:109], v[160:163], v[194:197], v[106:109]
	v_mfma_f32_16x16x32_bf16 v[94:97], v[152:155], v[202:205], v[94:97]
	v_mfma_f32_16x16x32_bf16 v[90:93], v[160:163], v[202:205], v[90:93]
	v_mfma_f32_16x16x32_bf16 v[78:81], v[152:155], v[210:213], v[78:81]
	v_mfma_f32_16x16x32_bf16 v[74:77], v[160:163], v[210:213], v[74:77]
	v_mfma_f32_16x16x32_bf16 v[126:129], v[156:159], v[190:193], v[126:129]
	v_mfma_f32_16x16x32_bf16 v[122:125], v[164:167], v[190:193], v[122:125]
	v_mfma_f32_16x16x32_bf16 v[110:113], v[156:159], v[198:201], v[110:113]
	v_mfma_f32_16x16x32_bf16 v[106:109], v[164:167], v[198:201], v[106:109]
	v_mfma_f32_16x16x32_bf16 v[94:97], v[156:159], v[206:209], v[94:97]
	v_mfma_f32_16x16x32_bf16 v[90:93], v[164:167], v[206:209], v[90:93]
	v_mfma_f32_16x16x32_bf16 v[78:81], v[156:159], v[214:217], v[78:81]
	v_mfma_f32_16x16x32_bf16 v[74:77], v[164:167], v[214:217], v[74:77]
	s_setprio 0
	s_setprio 1
	v_mfma_f32_16x16x32_bf16 v[118:121], v[168:171], v[186:189], v[118:121]
	v_mfma_f32_16x16x32_bf16 v[114:117], v[178:181], v[186:189], v[114:117]
	v_mfma_f32_16x16x32_bf16 v[102:105], v[168:171], v[194:197], v[102:105]
	v_mfma_f32_16x16x32_bf16 v[98:101], v[178:181], v[194:197], v[98:101]
	v_mfma_f32_16x16x32_bf16 v[86:89], v[168:171], v[202:205], v[86:89]
	v_mfma_f32_16x16x32_bf16 v[82:85], v[178:181], v[202:205], v[82:85]
	v_mfma_f32_16x16x32_bf16 v[70:73], v[168:171], v[210:213], v[70:73]
	v_mfma_f32_16x16x32_bf16 v[66:69], v[178:181], v[210:213], v[66:69]
	v_mfma_f32_16x16x32_bf16 v[118:121], v[172:175], v[190:193], v[118:121]
	v_mfma_f32_16x16x32_bf16 v[114:117], v[182:185], v[190:193], v[114:117]
	v_mfma_f32_16x16x32_bf16 v[102:105], v[172:175], v[198:201], v[102:105]
	v_mfma_f32_16x16x32_bf16 v[98:101], v[182:185], v[198:201], v[98:101]
	v_mfma_f32_16x16x32_bf16 v[86:89], v[172:175], v[206:209], v[86:89]
	v_mfma_f32_16x16x32_bf16 v[82:85], v[182:185], v[206:209], v[82:85]
	v_mfma_f32_16x16x32_bf16 v[70:73], v[172:175], v[214:217], v[70:73]
	v_mfma_f32_16x16x32_bf16 v[66:69], v[182:185], v[214:217], v[66:69]
	s_barrier
	s_setprio 0
	s_add_i32 s2, s56, s34
	v_lshl_add_u64 v[146:147], v[146:147], 0, s[6:7]
	s_mov_b32 m0, s2
	ds_read_b128 v[186:189], v150 offset:49152
	ds_read_b128 v[190:193], v150 offset:50176
	ds_read_b128 v[194:197], v150 offset:51200
	ds_read_b128 v[198:201], v150 offset:52224
	ds_read_b128 v[202:205], v150 offset:53248
	ds_read_b128 v[206:209], v150 offset:54272
	ds_read_b128 v[210:213], v150 offset:55296
	ds_read_b128 v[214:217], v150 offset:56320
	global_load_lds_dwordx4 v[146:147], off
	s_add_i32 m0, s2, 0x2000
	s_add_u32 s2, s30, 0x40080
	v_lshl_add_u64 v[146:147], v[218:219], 0, s[6:7]
	s_addc_u32 s3, s31, 0
	s_add_i32 s30, s57, s34
	global_load_lds_dwordx4 v[146:147], off
	v_lshl_add_u64 v[146:147], s[2:3], 0, v[132:133]
	s_mov_b32 m0, s30
	s_nop 0
	global_load_lds_dwordx4 v[146:147], off
	v_lshl_add_u64 v[146:147], s[2:3], 0, v[136:137]
	s_add_i32 m0, s30, 0x2000
	s_nop 0
	global_load_lds_dwordx4 v[146:147], off
	v_lshl_add_u64 v[146:147], v[220:221], 0, s[6:7]
	s_mov_b32 m0, s40
	s_nop 0
	global_load_lds_dwordx4 v[146:147], off
	v_lshl_add_u64 v[146:147], v[222:223], 0, s[6:7]
	s_mov_b32 m0, s41
	s_nop 0
	global_load_lds_dwordx4 v[146:147], off
	s_waitcnt vmcnt(8)
	s_waitcnt lgkmcnt(0)
	s_setprio 1
	s_barrier
	v_mfma_f32_16x16x32_bf16 v[62:65], v[152:155], v[186:189], v[62:65]
	v_mfma_f32_16x16x32_bf16 v[58:61], v[160:163], v[186:189], v[58:61]
	v_mfma_f32_16x16x32_bf16 v[46:49], v[152:155], v[194:197], v[46:49]
	v_mfma_f32_16x16x32_bf16 v[42:45], v[160:163], v[194:197], v[42:45]
	v_mfma_f32_16x16x32_bf16 v[30:33], v[152:155], v[202:205], v[30:33]
	v_mfma_f32_16x16x32_bf16 v[26:29], v[160:163], v[202:205], v[26:29]
	v_mfma_f32_16x16x32_bf16 v[14:17], v[152:155], v[210:213], v[14:17]
	v_mfma_f32_16x16x32_bf16 v[10:13], v[160:163], v[210:213], v[10:13]
	v_mfma_f32_16x16x32_bf16 v[62:65], v[156:159], v[190:193], v[62:65]
	v_mfma_f32_16x16x32_bf16 v[58:61], v[164:167], v[190:193], v[58:61]
	v_mfma_f32_16x16x32_bf16 v[46:49], v[156:159], v[198:201], v[46:49]
	v_mfma_f32_16x16x32_bf16 v[42:45], v[164:167], v[198:201], v[42:45]
	v_mfma_f32_16x16x32_bf16 v[30:33], v[156:159], v[206:209], v[30:33]
	v_mfma_f32_16x16x32_bf16 v[26:29], v[164:167], v[206:209], v[26:29]
	v_mfma_f32_16x16x32_bf16 v[14:17], v[156:159], v[214:217], v[14:17]
	v_mfma_f32_16x16x32_bf16 v[10:13], v[164:167], v[214:217], v[10:13]
	s_setprio 0
	s_setprio 1
	v_mfma_f32_16x16x32_bf16 v[54:57], v[168:171], v[186:189], v[54:57]
	v_mfma_f32_16x16x32_bf16 v[50:53], v[178:181], v[186:189], v[50:53]
	v_mfma_f32_16x16x32_bf16 v[38:41], v[168:171], v[194:197], v[38:41]
	v_mfma_f32_16x16x32_bf16 v[34:37], v[178:181], v[194:197], v[34:37]
	v_mfma_f32_16x16x32_bf16 v[22:25], v[168:171], v[202:205], v[22:25]
	v_mfma_f32_16x16x32_bf16 v[18:21], v[178:181], v[202:205], v[18:21]
	v_mfma_f32_16x16x32_bf16 v[6:9], v[168:171], v[210:213], v[6:9]
	v_mfma_f32_16x16x32_bf16 v[2:5], v[178:181], v[210:213], v[2:5]
	v_mfma_f32_16x16x32_bf16 v[54:57], v[172:175], v[190:193], v[54:57]
	v_mfma_f32_16x16x32_bf16 v[50:53], v[182:185], v[190:193], v[50:53]
	v_mfma_f32_16x16x32_bf16 v[38:41], v[172:175], v[198:201], v[38:41]
	v_mfma_f32_16x16x32_bf16 v[34:37], v[182:185], v[198:201], v[34:37]
	v_mfma_f32_16x16x32_bf16 v[22:25], v[172:175], v[206:209], v[22:25]
	v_mfma_f32_16x16x32_bf16 v[18:21], v[182:185], v[206:209], v[18:21]
	v_mfma_f32_16x16x32_bf16 v[6:9], v[172:175], v[214:217], v[6:9]
	v_mfma_f32_16x16x32_bf16 v[2:5], v[182:185], v[214:217], v[2:5]
	s_barrier
	s_setprio 0
	s_add_i32 s55, s55, 2
	s_add_u32 s28, s28, 0x100
	s_addc_u32 s29, s29, 0
	s_add_u32 s53, s53, 0x100
	s_addc_u32 s54, s54, 0
	s_cmp_gt_u32 s55, 13
	s_cbranch_scc0 .LBB0_1400
	s_branch .Lpk1400_exit
.LBB0_1400:
	ds_read_b128 v[152:155], v1
	ds_read_b128 v[156:159], v1 offset:1024
	ds_read_b128 v[160:163], v1 offset:2048
	ds_read_b128 v[164:167], v1 offset:3072
	ds_read_b128 v[168:171], v149
	ds_read_b128 v[172:175], v149 offset:1024
	ds_read_b128 v[178:181], v149 offset:2048
	ds_read_b128 v[182:185], v149 offset:3072
	s_add_u32 s2, s28, 0xfffc0080
	s_addc_u32 s3, s29, -1
	s_cmp_eq_u32 s55, 12
	s_cselect_b32 s3, s11, s3
	s_cselect_b32 s2, s13, s2
	s_cselect_b32 s31, s47, s54
	s_cselect_b32 s30, s52, s53
	v_lshl_add_u64 v[146:147], s[28:29], 0, v[140:141]
	s_add_i32 m0, s25, 0xc000
	ds_read_b128 v[186:189], v150
	ds_read_b128 v[190:193], v150 offset:1024
	ds_read_b128 v[194:197], v150 offset:2048
	ds_read_b128 v[198:201], v150 offset:3072
	ds_read_b128 v[202:205], v150 offset:4096
	ds_read_b128 v[206:209], v150 offset:5120
	ds_read_b128 v[210:213], v150 offset:6144
	ds_read_b128 v[214:217], v150 offset:7168
	global_load_lds_dwordx4 v[146:147], off
	v_lshl_add_u64 v[146:147], s[28:29], 0, v[142:143]
	s_add_i32 m0, s25, 0xe000
	s_nop 0
	global_load_lds_dwordx4 v[146:147], off
	s_waitcnt vmcnt(8)
	s_waitcnt lgkmcnt(0)
	s_setprio 1
	s_barrier
	v_mfma_f32_16x16x32_bf16 v[126:129], v[152:155], v[186:189], v[126:129]
	v_mfma_f32_16x16x32_bf16 v[122:125], v[160:163], v[186:189], v[122:125]
	v_mfma_f32_16x16x32_bf16 v[110:113], v[152:155], v[194:197], v[110:113]
	v_mfma_f32_16x16x32_bf16 v[106:109], v[160:163], v[194:197], v[106:109]
	v_mfma_f32_16x16x32_bf16 v[94:97], v[152:155], v[202:205], v[94:97]
	v_mfma_f32_16x16x32_bf16 v[90:93], v[160:163], v[202:205], v[90:93]
	v_mfma_f32_16x16x32_bf16 v[78:81], v[152:155], v[210:213], v[78:81]
	v_mfma_f32_16x16x32_bf16 v[74:77], v[160:163], v[210:213], v[74:77]
	v_mfma_f32_16x16x32_bf16 v[126:129], v[156:159], v[190:193], v[126:129]
	v_mfma_f32_16x16x32_bf16 v[122:125], v[164:167], v[190:193], v[122:125]
	v_mfma_f32_16x16x32_bf16 v[110:113], v[156:159], v[198:201], v[110:113]
	v_mfma_f32_16x16x32_bf16 v[106:109], v[164:167], v[198:201], v[106:109]
	v_mfma_f32_16x16x32_bf16 v[94:97], v[156:159], v[206:209], v[94:97]
	v_mfma_f32_16x16x32_bf16 v[90:93], v[164:167], v[206:209], v[90:93]
	v_mfma_f32_16x16x32_bf16 v[78:81], v[156:159], v[214:217], v[78:81]
	v_mfma_f32_16x16x32_bf16 v[74:77], v[164:167], v[214:217], v[74:77]
	s_setprio 0
	s_setprio 1
	v_mfma_f32_16x16x32_bf16 v[118:121], v[168:171], v[186:189], v[118:121]
	v_mfma_f32_16x16x32_bf16 v[114:117], v[178:181], v[186:189], v[114:117]
	v_mfma_f32_16x16x32_bf16 v[102:105], v[168:171], v[194:197], v[102:105]
	v_mfma_f32_16x16x32_bf16 v[98:101], v[178:181], v[194:197], v[98:101]
	v_mfma_f32_16x16x32_bf16 v[86:89], v[168:171], v[202:205], v[86:89]
	v_mfma_f32_16x16x32_bf16 v[82:85], v[178:181], v[202:205], v[82:85]
	v_mfma_f32_16x16x32_bf16 v[70:73], v[168:171], v[210:213], v[70:73]
	v_mfma_f32_16x16x32_bf16 v[66:69], v[178:181], v[210:213], v[66:69]
	v_mfma_f32_16x16x32_bf16 v[118:121], v[172:175], v[190:193], v[118:121]
	v_mfma_f32_16x16x32_bf16 v[114:117], v[182:185], v[190:193], v[114:117]
	v_mfma_f32_16x16x32_bf16 v[102:105], v[172:175], v[198:201], v[102:105]
	v_mfma_f32_16x16x32_bf16 v[98:101], v[182:185], v[198:201], v[98:101]
	v_mfma_f32_16x16x32_bf16 v[86:89], v[172:175], v[206:209], v[86:89]
	v_mfma_f32_16x16x32_bf16 v[82:85], v[182:185], v[206:209], v[82:85]
	v_mfma_f32_16x16x32_bf16 v[70:73], v[172:175], v[214:217], v[70:73]
	v_mfma_f32_16x16x32_bf16 v[66:69], v[182:185], v[214:217], v[66:69]
	s_barrier
	s_setprio 0
	s_add_i32 s56, s43, s34
	v_lshl_add_u64 v[146:147], s[30:31], 0, v[132:133]
	s_mov_b32 m0, s56
	ds_read_b128 v[186:189], v150 offset:16384
	ds_read_b128 v[190:193], v150 offset:17408
	ds_read_b128 v[194:197], v150 offset:18432
	ds_read_b128 v[198:201], v150 offset:19456
	ds_read_b128 v[202:205], v150 offset:20480
	ds_read_b128 v[206:209], v150 offset:21504
	ds_read_b128 v[210:213], v150 offset:22528
	ds_read_b128 v[214:217], v150 offset:23552
	global_load_lds_dwordx4 v[146:147], off
	s_add_i32 m0, s56, 0x2000
	s_add_u32 s56, s30, 0x40000
	v_lshl_add_u64 v[218:219], s[30:31], 0, v[136:137]
	s_addc_u32 s57, s31, 0
	s_add_i32 s58, s44, s34
	global_load_lds_dwordx4 v[218:219], off
	v_lshl_add_u64 v[220:221], s[56:57], 0, v[132:133]
	s_mov_b32 m0, s58
	v_lshl_add_u64 v[222:223], s[2:3], 0, v[134:135]
	global_load_lds_dwordx4 v[220:221], off
	v_lshl_add_u64 v[220:221], s[56:57], 0, v[136:137]
	s_add_i32 m0, s58, 0x2000
	s_nop 0
	global_load_lds_dwordx4 v[220:221], off
	v_lshl_add_u64 v[220:221], s[2:3], 0, v[130:131]
	s_mov_b32 m0, s25
	s_nop 0
	global_load_lds_dwordx4 v[220:221], off
	s_mov_b32 m0, s27
	s_nop 0
	global_load_lds_dwordx4 v[222:223], off
	s_waitcnt vmcnt(8)
	s_waitcnt lgkmcnt(0)
	s_setprio 1
	s_barrier
	v_mfma_f32_16x16x32_bf16 v[62:65], v[152:155], v[186:189], v[62:65]
	v_mfma_f32_16x16x32_bf16 v[58:61], v[160:163], v[186:189], v[58:61]
	v_mfma_f32_16x16x32_bf16 v[46:49], v[152:155], v[194:197], v[46:49]
	v_mfma_f32_16x16x32_bf16 v[42:45], v[160:163], v[194:197], v[42:45]
	v_mfma_f32_16x16x32_bf16 v[30:33], v[152:155], v[202:205], v[30:33]
	v_mfma_f32_16x16x32_bf16 v[26:29], v[160:163], v[202:205], v[26:29]
	v_mfma_f32_16x16x32_bf16 v[14:17], v[152:155], v[210:213], v[14:17]
	v_mfma_f32_16x16x32_bf16 v[10:13], v[160:163], v[210:213], v[10:13]
	v_mfma_f32_16x16x32_bf16 v[62:65], v[156:159], v[190:193], v[62:65]
	v_mfma_f32_16x16x32_bf16 v[58:61], v[164:167], v[190:193], v[58:61]
	v_mfma_f32_16x16x32_bf16 v[46:49], v[156:159], v[198:201], v[46:49]
	v_mfma_f32_16x16x32_bf16 v[42:45], v[164:167], v[198:201], v[42:45]
	v_mfma_f32_16x16x32_bf16 v[30:33], v[156:159], v[206:209], v[30:33]
	v_mfma_f32_16x16x32_bf16 v[26:29], v[164:167], v[206:209], v[26:29]
	v_mfma_f32_16x16x32_bf16 v[14:17], v[156:159], v[214:217], v[14:17]
	v_mfma_f32_16x16x32_bf16 v[10:13], v[164:167], v[214:217], v[10:13]
	s_setprio 0
	s_setprio 1
	v_mfma_f32_16x16x32_bf16 v[54:57], v[168:171], v[186:189], v[54:57]
	v_mfma_f32_16x16x32_bf16 v[50:53], v[178:181], v[186:189], v[50:53]
	v_mfma_f32_16x16x32_bf16 v[38:41], v[168:171], v[194:197], v[38:41]
	v_mfma_f32_16x16x32_bf16 v[34:37], v[178:181], v[194:197], v[34:37]
	v_mfma_f32_16x16x32_bf16 v[22:25], v[168:171], v[202:205], v[22:25]
	v_mfma_f32_16x16x32_bf16 v[18:21], v[178:181], v[202:205], v[18:21]
	v_mfma_f32_16x16x32_bf16 v[6:9], v[168:171], v[210:213], v[6:9]
	v_mfma_f32_16x16x32_bf16 v[2:5], v[178:181], v[210:213], v[2:5]
	v_mfma_f32_16x16x32_bf16 v[54:57], v[172:175], v[190:193], v[54:57]
	v_mfma_f32_16x16x32_bf16 v[50:53], v[182:185], v[190:193], v[50:53]
	v_mfma_f32_16x16x32_bf16 v[38:41], v[172:175], v[198:201], v[38:41]
	v_mfma_f32_16x16x32_bf16 v[34:37], v[182:185], v[198:201], v[34:37]
	v_mfma_f32_16x16x32_bf16 v[22:25], v[172:175], v[206:209], v[22:25]
	v_mfma_f32_16x16x32_bf16 v[18:21], v[182:185], v[206:209], v[18:21]
	v_mfma_f32_16x16x32_bf16 v[6:9], v[172:175], v[214:217], v[6:9]
	v_mfma_f32_16x16x32_bf16 v[2:5], v[182:185], v[214:217], v[2:5]
	s_barrier
	s_setprio 0
	s_add_i32 s56, 0, 0x18000
	v_add_u32_e32 v151, s56, v148
	s_add_i32 s57, 0, 0x1c000
	ds_read_b128 v[152:155], v151
	ds_read_b128 v[156:159], v151 offset:1024
	ds_read_b128 v[160:163], v151 offset:2048
	ds_read_b128 v[164:167], v151 offset:3072
	v_add_u32_e32 v151, s57, v148
	ds_read_b128 v[168:171], v151
	ds_read_b128 v[172:175], v151 offset:1024
	ds_read_b128 v[178:181], v151 offset:2048
	ds_read_b128 v[182:185], v151 offset:3072
	s_add_u32 s2, s2, 0x40000
	s_addc_u32 s3, s3, 0
	s_mov_b32 m0, s36
	v_lshl_add_u64 v[224:225], s[2:3], 0, v[130:131]
	ds_read_b128 v[186:189], v150 offset:32768
	ds_read_b128 v[190:193], v150 offset:33792
	ds_read_b128 v[194:197], v150 offset:34816
	ds_read_b128 v[198:201], v150 offset:35840
	ds_read_b128 v[202:205], v150 offset:36864
	ds_read_b128 v[206:209], v150 offset:37888
	ds_read_b128 v[210:213], v150 offset:38912
	ds_read_b128 v[214:217], v150 offset:39936
	global_load_lds_dwordx4 v[224:225], off
	v_lshl_add_u64 v[224:225], s[2:3], 0, v[134:135]
	s_mov_b32 m0, s37
	s_nop 0
	global_load_lds_dwordx4 v[224:225], off
	s_waitcnt vmcnt(8)
	s_waitcnt lgkmcnt(0)
	s_setprio 1
	s_barrier
	v_mfma_f32_16x16x32_bf16 v[126:129], v[152:155], v[186:189], v[126:129]
	v_mfma_f32_16x16x32_bf16 v[122:125], v[160:163], v[186:189], v[122:125]
	v_mfma_f32_16x16x32_bf16 v[110:113], v[152:155], v[194:197], v[110:113]
	v_mfma_f32_16x16x32_bf16 v[106:109], v[160:163], v[194:197], v[106:109]
	v_mfma_f32_16x16x32_bf16 v[94:97], v[152:155], v[202:205], v[94:97]
	v_mfma_f32_16x16x32_bf16 v[90:93], v[160:163], v[202:205], v[90:93]
	v_mfma_f32_16x16x32_bf16 v[78:81], v[152:155], v[210:213], v[78:81]
	v_mfma_f32_16x16x32_bf16 v[74:77], v[160:163], v[210:213], v[74:77]
	v_mfma_f32_16x16x32_bf16 v[126:129], v[156:159], v[190:193], v[126:129]
	v_mfma_f32_16x16x32_bf16 v[122:125], v[164:167], v[190:193], v[122:125]
	v_mfma_f32_16x16x32_bf16 v[110:113], v[156:159], v[198:201], v[110:113]
	v_mfma_f32_16x16x32_bf16 v[106:109], v[164:167], v[198:201], v[106:109]
	v_mfma_f32_16x16x32_bf16 v[94:97], v[156:159], v[206:209], v[94:97]
	v_mfma_f32_16x16x32_bf16 v[90:93], v[164:167], v[206:209], v[90:93]
	v_mfma_f32_16x16x32_bf16 v[78:81], v[156:159], v[214:217], v[78:81]
	v_mfma_f32_16x16x32_bf16 v[74:77], v[164:167], v[214:217], v[74:77]
	s_setprio 0
	s_setprio 1
	v_mfma_f32_16x16x32_bf16 v[118:121], v[168:171], v[186:189], v[118:121]
	v_mfma_f32_16x16x32_bf16 v[114:117], v[178:181], v[186:189], v[114:117]
	v_mfma_f32_16x16x32_bf16 v[102:105], v[168:171], v[194:197], v[102:105]
	v_mfma_f32_16x16x32_bf16 v[98:101], v[178:181], v[194:197], v[98:101]
	v_mfma_f32_16x16x32_bf16 v[86:89], v[168:171], v[202:205], v[86:89]
	v_mfma_f32_16x16x32_bf16 v[82:85], v[178:181], v[202:205], v[82:85]
	v_mfma_f32_16x16x32_bf16 v[70:73], v[168:171], v[210:213], v[70:73]
	v_mfma_f32_16x16x32_bf16 v[66:69], v[178:181], v[210:213], v[66:69]
	v_mfma_f32_16x16x32_bf16 v[118:121], v[172:175], v[190:193], v[118:121]
	v_mfma_f32_16x16x32_bf16 v[114:117], v[182:185], v[190:193], v[114:117]
	v_mfma_f32_16x16x32_bf16 v[102:105], v[172:175], v[198:201], v[102:105]
	v_mfma_f32_16x16x32_bf16 v[98:101], v[182:185], v[198:201], v[98:101]
	v_mfma_f32_16x16x32_bf16 v[86:89], v[172:175], v[206:209], v[86:89]
	v_mfma_f32_16x16x32_bf16 v[82:85], v[182:185], v[206:209], v[82:85]
	v_mfma_f32_16x16x32_bf16 v[70:73], v[172:175], v[214:217], v[70:73]
	v_mfma_f32_16x16x32_bf16 v[66:69], v[182:185], v[214:217], v[66:69]
	s_barrier
	s_setprio 0
	s_add_i32 s2, s56, s34
	v_lshl_add_u64 v[146:147], v[146:147], 0, s[6:7]
	s_mov_b32 m0, s2
	ds_read_b128 v[186:189], v150 offset:49152
	ds_read_b128 v[190:193], v150 offset:50176
	ds_read_b128 v[194:197], v150 offset:51200
	ds_read_b128 v[198:201], v150 offset:52224
	ds_read_b128 v[202:205], v150 offset:53248
	ds_read_b128 v[206:209], v150 offset:54272
	ds_read_b128 v[210:213], v150 offset:55296
	ds_read_b128 v[214:217], v150 offset:56320
	global_load_lds_dwordx4 v[146:147], off
	s_add_i32 m0, s2, 0x2000
	s_add_u32 s2, s30, 0x40080
	v_lshl_add_u64 v[146:147], v[218:219], 0, s[6:7]
	s_addc_u32 s3, s31, 0
	s_add_i32 s30, s57, s34
	global_load_lds_dwordx4 v[146:147], off
	v_lshl_add_u64 v[146:147], s[2:3], 0, v[132:133]
	s_mov_b32 m0, s30
	s_nop 0
	global_load_lds_dwordx4 v[146:147], off
	v_lshl_add_u64 v[146:147], s[2:3], 0, v[136:137]
	s_add_i32 m0, s30, 0x2000
	s_nop 0
	global_load_lds_dwordx4 v[146:147], off
	v_lshl_add_u64 v[146:147], v[220:221], 0, s[6:7]
	s_mov_b32 m0, s40
	s_nop 0
	global_load_lds_dwordx4 v[146:147], off
	v_lshl_add_u64 v[146:147], v[222:223], 0, s[6:7]
	s_mov_b32 m0, s41
	s_nop 0
	global_load_lds_dwordx4 v[146:147], off
	s_waitcnt vmcnt(8)
	s_waitcnt lgkmcnt(0)
	s_setprio 1
	s_barrier
	v_mfma_f32_16x16x32_bf16 v[62:65], v[152:155], v[186:189], v[62:65]
	v_mfma_f32_16x16x32_bf16 v[58:61], v[160:163], v[186:189], v[58:61]
	v_mfma_f32_16x16x32_bf16 v[46:49], v[152:155], v[194:197], v[46:49]
	v_mfma_f32_16x16x32_bf16 v[42:45], v[160:163], v[194:197], v[42:45]
	v_mfma_f32_16x16x32_bf16 v[30:33], v[152:155], v[202:205], v[30:33]
	v_mfma_f32_16x16x32_bf16 v[26:29], v[160:163], v[202:205], v[26:29]
	v_mfma_f32_16x16x32_bf16 v[14:17], v[152:155], v[210:213], v[14:17]
	v_mfma_f32_16x16x32_bf16 v[10:13], v[160:163], v[210:213], v[10:13]
	v_mfma_f32_16x16x32_bf16 v[62:65], v[156:159], v[190:193], v[62:65]
	v_mfma_f32_16x16x32_bf16 v[58:61], v[164:167], v[190:193], v[58:61]
	v_mfma_f32_16x16x32_bf16 v[46:49], v[156:159], v[198:201], v[46:49]
	v_mfma_f32_16x16x32_bf16 v[42:45], v[164:167], v[198:201], v[42:45]
	v_mfma_f32_16x16x32_bf16 v[30:33], v[156:159], v[206:209], v[30:33]
	v_mfma_f32_16x16x32_bf16 v[26:29], v[164:167], v[206:209], v[26:29]
	v_mfma_f32_16x16x32_bf16 v[14:17], v[156:159], v[214:217], v[14:17]
	v_mfma_f32_16x16x32_bf16 v[10:13], v[164:167], v[214:217], v[10:13]
	s_setprio 0
	s_setprio 1
	v_mfma_f32_16x16x32_bf16 v[54:57], v[168:171], v[186:189], v[54:57]
	v_mfma_f32_16x16x32_bf16 v[50:53], v[178:181], v[186:189], v[50:53]
	v_mfma_f32_16x16x32_bf16 v[38:41], v[168:171], v[194:197], v[38:41]
	v_mfma_f32_16x16x32_bf16 v[34:37], v[178:181], v[194:197], v[34:37]
	v_mfma_f32_16x16x32_bf16 v[22:25], v[168:171], v[202:205], v[22:25]
	v_mfma_f32_16x16x32_bf16 v[18:21], v[178:181], v[202:205], v[18:21]
	v_mfma_f32_16x16x32_bf16 v[6:9], v[168:171], v[210:213], v[6:9]
	v_mfma_f32_16x16x32_bf16 v[2:5], v[178:181], v[210:213], v[2:5]
	v_mfma_f32_16x16x32_bf16 v[54:57], v[172:175], v[190:193], v[54:57]
	v_mfma_f32_16x16x32_bf16 v[50:53], v[182:185], v[190:193], v[50:53]
	v_mfma_f32_16x16x32_bf16 v[38:41], v[172:175], v[198:201], v[38:41]
	v_mfma_f32_16x16x32_bf16 v[34:37], v[182:185], v[198:201], v[34:37]
	v_mfma_f32_16x16x32_bf16 v[22:25], v[172:175], v[206:209], v[22:25]
	v_mfma_f32_16x16x32_bf16 v[18:21], v[182:185], v[206:209], v[18:21]
	v_mfma_f32_16x16x32_bf16 v[6:9], v[172:175], v[214:217], v[6:9]
	v_mfma_f32_16x16x32_bf16 v[2:5], v[182:185], v[214:217], v[2:5]
	s_barrier
	s_setprio 0
	s_add_i32 s55, s55, 2
	s_add_u32 s28, s28, 0x100
	s_addc_u32 s29, s29, 0
	s_add_u32 s53, s53, 0x100
	s_addc_u32 s54, s54, 0
	s_cmp_gt_u32 s55, 13
	s_cbranch_scc0 .LBB0_1400

.Lpk1444_peel:
	ds_read_b128 v[152:155], v148
	ds_read_b128 v[156:159], v148 offset:1024
	ds_read_b128 v[160:163], v148 offset:2048
	ds_read_b128 v[164:167], v148 offset:3072
	ds_read_b128 v[168:171], v149
	ds_read_b128 v[172:175], v149 offset:1024
	ds_read_b128 v[178:181], v149 offset:2048
	ds_read_b128 v[182:185], v149 offset:3072
	s_add_u32 s2, s26, 0x4000
	s_addc_u32 s3, s27, 0
	s_cmp_eq_u32 s62, 40
	s_cselect_b32 s2, s57, s2
	s_cselect_b32 s3, s56, s3
	s_cselect_b32 s31, s58, s61
	s_cselect_b32 s30, s59, s60
	s_add_u32 s28, s2, 0x8000
	s_addc_u32 s29, s3, 0
	v_lshl_add_u64 v[144:145], s[26:27], 0, v[138:139]
	s_add_i32 m0, s39, 0xc000
	ds_read_b128 v[186:189], v150
	ds_read_b128 v[190:193], v150 offset:1024
	ds_read_b128 v[194:197], v150 offset:2048
	ds_read_b128 v[198:201], v150 offset:3072
	ds_read_b128 v[202:205], v150 offset:4096
	ds_read_b128 v[206:209], v150 offset:5120
	ds_read_b128 v[210:213], v150 offset:6144
	ds_read_b128 v[214:217], v150 offset:7168
	global_load_lds_dwordx4 v[144:145], off
	v_lshl_add_u64 v[144:145], s[26:27], 0, v[140:141]
	s_add_i32 m0, s39, 0xe000
	s_nop 0
	global_load_lds_dwordx4 v[144:145], off
	s_waitcnt vmcnt(8)
	s_waitcnt lgkmcnt(0)
	s_setprio 1
	s_barrier
	v_mfma_f32_16x16x32_bf16 v[126:129], v[152:155], v[186:189], 0
	v_mfma_f32_16x16x32_bf16 v[122:125], v[160:163], v[186:189], 0
	v_mfma_f32_16x16x32_bf16 v[114:117], v[152:155], v[194:197], 0
	v_mfma_f32_16x16x32_bf16 v[106:109], v[160:163], v[194:197], 0
	v_mfma_f32_16x16x32_bf16 v[98:101], v[152:155], v[202:205], 0
	v_mfma_f32_16x16x32_bf16 v[90:93], v[160:163], v[202:205], 0
	v_mfma_f32_16x16x32_bf16 v[82:85], v[152:155], v[210:213], 0
	v_mfma_f32_16x16x32_bf16 v[74:77], v[160:163], v[210:213], 0
	v_mfma_f32_16x16x32_bf16 v[126:129], v[156:159], v[190:193], v[126:129]
	v_mfma_f32_16x16x32_bf16 v[122:125], v[164:167], v[190:193], v[122:125]
	v_mfma_f32_16x16x32_bf16 v[114:117], v[156:159], v[198:201], v[114:117]
	v_mfma_f32_16x16x32_bf16 v[106:109], v[164:167], v[198:201], v[106:109]
	v_mfma_f32_16x16x32_bf16 v[98:101], v[156:159], v[206:209], v[98:101]
	v_mfma_f32_16x16x32_bf16 v[90:93], v[164:167], v[206:209], v[90:93]
	v_mfma_f32_16x16x32_bf16 v[82:85], v[156:159], v[214:217], v[82:85]
	v_mfma_f32_16x16x32_bf16 v[74:77], v[164:167], v[214:217], v[74:77]
	s_setprio 0
	s_setprio 1
	v_mfma_f32_16x16x32_bf16 v[118:121], v[168:171], v[186:189], 0
	v_mfma_f32_16x16x32_bf16 v[110:113], v[178:181], v[186:189], 0
	v_mfma_f32_16x16x32_bf16 v[102:105], v[168:171], v[194:197], 0
	v_mfma_f32_16x16x32_bf16 v[94:97], v[178:181], v[194:197], 0
	v_mfma_f32_16x16x32_bf16 v[86:89], v[168:171], v[202:205], 0
	v_mfma_f32_16x16x32_bf16 v[78:81], v[178:181], v[202:205], 0
	v_mfma_f32_16x16x32_bf16 v[70:73], v[168:171], v[210:213], 0
	v_mfma_f32_16x16x32_bf16 v[66:69], v[178:181], v[210:213], 0
	v_mfma_f32_16x16x32_bf16 v[118:121], v[172:175], v[190:193], v[118:121]
	v_mfma_f32_16x16x32_bf16 v[110:113], v[182:185], v[190:193], v[110:113]
	v_mfma_f32_16x16x32_bf16 v[102:105], v[172:175], v[198:201], v[102:105]
	v_mfma_f32_16x16x32_bf16 v[94:97], v[182:185], v[198:201], v[94:97]
	v_mfma_f32_16x16x32_bf16 v[86:89], v[172:175], v[206:209], v[86:89]
	v_mfma_f32_16x16x32_bf16 v[78:81], v[182:185], v[206:209], v[78:81]
	v_mfma_f32_16x16x32_bf16 v[70:73], v[172:175], v[214:217], v[70:73]
	v_mfma_f32_16x16x32_bf16 v[66:69], v[182:185], v[214:217], v[66:69]
	s_barrier
	s_setprio 0
	s_add_i32 s63, s46, s38
	v_lshl_add_u64 v[144:145], s[30:31], 0, v[132:133]
	s_mov_b32 m0, s63
	ds_read_b128 v[186:189], v150 offset:16384
	ds_read_b128 v[190:193], v150 offset:17408
	ds_read_b128 v[194:197], v150 offset:18432
	ds_read_b128 v[198:201], v150 offset:19456
	ds_read_b128 v[202:205], v150 offset:20480
	ds_read_b128 v[206:209], v150 offset:21504
	ds_read_b128 v[210:213], v150 offset:22528
	ds_read_b128 v[214:217], v150 offset:23552
	global_load_lds_dwordx4 v[144:145], off
	s_add_i32 m0, s63, 0x2000
	s_add_u32 s64, s30, 0x4000
	v_lshl_add_u64 v[144:145], s[30:31], 0, v[136:137]
	s_addc_u32 s65, s31, 0
	s_add_i32 s63, s47, s38
	global_load_lds_dwordx4 v[144:145], off
	v_lshl_add_u64 v[144:145], s[64:65], 0, v[132:133]
	s_mov_b32 m0, s63
	s_nop 0
	global_load_lds_dwordx4 v[144:145], off
	v_lshl_add_u64 v[144:145], s[64:65], 0, v[136:137]
	s_add_i32 m0, s63, 0x2000
	s_nop 0
	global_load_lds_dwordx4 v[144:145], off
	v_lshl_add_u64 v[144:145], s[2:3], 0, v[130:131]
	s_mov_b32 m0, s39
	s_nop 0
	global_load_lds_dwordx4 v[144:145], off
	v_lshl_add_u64 v[144:145], s[2:3], 0, v[134:135]
	s_mov_b32 m0, s40
	s_nop 0
	global_load_lds_dwordx4 v[144:145], off
	s_waitcnt vmcnt(8)
	s_waitcnt lgkmcnt(0)
	s_setprio 1
	s_barrier
	v_mfma_f32_16x16x32_bf16 v[62:65], v[152:155], v[186:189], 0
	v_mfma_f32_16x16x32_bf16 v[58:61], v[160:163], v[186:189], 0
	v_mfma_f32_16x16x32_bf16 v[50:53], v[152:155], v[194:197], 0
	v_mfma_f32_16x16x32_bf16 v[42:45], v[160:163], v[194:197], 0
	v_mfma_f32_16x16x32_bf16 v[34:37], v[152:155], v[202:205], 0
	v_mfma_f32_16x16x32_bf16 v[26:29], v[160:163], v[202:205], 0
	v_mfma_f32_16x16x32_bf16 v[18:21], v[152:155], v[210:213], 0
	v_mfma_f32_16x16x32_bf16 v[10:13], v[160:163], v[210:213], 0
	v_mfma_f32_16x16x32_bf16 v[62:65], v[156:159], v[190:193], v[62:65]
	v_mfma_f32_16x16x32_bf16 v[58:61], v[164:167], v[190:193], v[58:61]
	v_mfma_f32_16x16x32_bf16 v[50:53], v[156:159], v[198:201], v[50:53]
	v_mfma_f32_16x16x32_bf16 v[42:45], v[164:167], v[198:201], v[42:45]
	v_mfma_f32_16x16x32_bf16 v[34:37], v[156:159], v[206:209], v[34:37]
	v_mfma_f32_16x16x32_bf16 v[26:29], v[164:167], v[206:209], v[26:29]
	v_mfma_f32_16x16x32_bf16 v[18:21], v[156:159], v[214:217], v[18:21]
	v_mfma_f32_16x16x32_bf16 v[10:13], v[164:167], v[214:217], v[10:13]
	s_setprio 0
	s_setprio 1
	v_mfma_f32_16x16x32_bf16 v[54:57], v[168:171], v[186:189], 0
	v_mfma_f32_16x16x32_bf16 v[46:49], v[178:181], v[186:189], 0
	v_mfma_f32_16x16x32_bf16 v[38:41], v[168:171], v[194:197], 0
	v_mfma_f32_16x16x32_bf16 v[30:33], v[178:181], v[194:197], 0
	v_mfma_f32_16x16x32_bf16 v[22:25], v[168:171], v[202:205], 0
	v_mfma_f32_16x16x32_bf16 v[14:17], v[178:181], v[202:205], 0
	v_mfma_f32_16x16x32_bf16 v[6:9], v[168:171], v[210:213], 0
	v_mfma_f32_16x16x32_bf16 v[2:5], v[178:181], v[210:213], 0
	v_mfma_f32_16x16x32_bf16 v[54:57], v[172:175], v[190:193], v[54:57]
	v_mfma_f32_16x16x32_bf16 v[46:49], v[182:185], v[190:193], v[46:49]
	v_mfma_f32_16x16x32_bf16 v[38:41], v[172:175], v[198:201], v[38:41]
	v_mfma_f32_16x16x32_bf16 v[30:33], v[182:185], v[198:201], v[30:33]
	v_mfma_f32_16x16x32_bf16 v[22:25], v[172:175], v[206:209], v[22:25]
	v_mfma_f32_16x16x32_bf16 v[14:17], v[182:185], v[206:209], v[14:17]
	v_mfma_f32_16x16x32_bf16 v[6:9], v[172:175], v[214:217], v[6:9]
	v_mfma_f32_16x16x32_bf16 v[2:5], v[182:185], v[214:217], v[2:5]
	s_barrier
	s_setprio 0
	s_add_i32 s63, 0, 0x18000
	v_add_u32_e32 v144, s63, v146
	s_add_i32 s64, 0, 0x1c000
	ds_read_b128 v[152:155], v144
	ds_read_b128 v[156:159], v144 offset:1024
	ds_read_b128 v[160:163], v144 offset:2048
	ds_read_b128 v[164:167], v144 offset:3072
	v_add_u32_e32 v144, s64, v146
	ds_read_b128 v[168:171], v144
	ds_read_b128 v[172:175], v144 offset:1024
	ds_read_b128 v[178:181], v144 offset:2048
	ds_read_b128 v[182:185], v144 offset:3072
	s_add_u32 s2, s2, 0x4000
	s_addc_u32 s3, s3, 0
	s_mov_b32 m0, s41
	v_lshl_add_u64 v[144:145], s[2:3], 0, v[130:131]
	ds_read_b128 v[186:189], v150 offset:32768
	ds_read_b128 v[190:193], v150 offset:33792
	ds_read_b128 v[194:197], v150 offset:34816
	ds_read_b128 v[198:201], v150 offset:35840
	ds_read_b128 v[202:205], v150 offset:36864
	ds_read_b128 v[206:209], v150 offset:37888
	ds_read_b128 v[210:213], v150 offset:38912
	ds_read_b128 v[214:217], v150 offset:39936
	global_load_lds_dwordx4 v[144:145], off
	v_lshl_add_u64 v[144:145], s[2:3], 0, v[134:135]
	s_mov_b32 m0, s42
	s_nop 0
	global_load_lds_dwordx4 v[144:145], off
	s_waitcnt vmcnt(8)
	s_waitcnt lgkmcnt(0)
	s_setprio 1
	s_barrier
	v_mfma_f32_16x16x32_bf16 v[126:129], v[152:155], v[186:189], v[126:129]
	v_mfma_f32_16x16x32_bf16 v[122:125], v[160:163], v[186:189], v[122:125]
	v_mfma_f32_16x16x32_bf16 v[114:117], v[152:155], v[194:197], v[114:117]
	v_mfma_f32_16x16x32_bf16 v[106:109], v[160:163], v[194:197], v[106:109]
	v_mfma_f32_16x16x32_bf16 v[98:101], v[152:155], v[202:205], v[98:101]
	v_mfma_f32_16x16x32_bf16 v[90:93], v[160:163], v[202:205], v[90:93]
	v_mfma_f32_16x16x32_bf16 v[82:85], v[152:155], v[210:213], v[82:85]
	v_mfma_f32_16x16x32_bf16 v[74:77], v[160:163], v[210:213], v[74:77]
	v_mfma_f32_16x16x32_bf16 v[126:129], v[156:159], v[190:193], v[126:129]
	v_mfma_f32_16x16x32_bf16 v[122:125], v[164:167], v[190:193], v[122:125]
	v_mfma_f32_16x16x32_bf16 v[114:117], v[156:159], v[198:201], v[114:117]
	v_mfma_f32_16x16x32_bf16 v[106:109], v[164:167], v[198:201], v[106:109]
	v_mfma_f32_16x16x32_bf16 v[98:101], v[156:159], v[206:209], v[98:101]
	v_mfma_f32_16x16x32_bf16 v[90:93], v[164:167], v[206:209], v[90:93]
	v_mfma_f32_16x16x32_bf16 v[82:85], v[156:159], v[214:217], v[82:85]
	v_mfma_f32_16x16x32_bf16 v[74:77], v[164:167], v[214:217], v[74:77]
	s_setprio 0
	s_setprio 1
	v_mfma_f32_16x16x32_bf16 v[118:121], v[168:171], v[186:189], v[118:121]
	v_mfma_f32_16x16x32_bf16 v[110:113], v[178:181], v[186:189], v[110:113]
	v_mfma_f32_16x16x32_bf16 v[102:105], v[168:171], v[194:197], v[102:105]
	v_mfma_f32_16x16x32_bf16 v[94:97], v[178:181], v[194:197], v[94:97]
	v_mfma_f32_16x16x32_bf16 v[86:89], v[168:171], v[202:205], v[86:89]
	v_mfma_f32_16x16x32_bf16 v[78:81], v[178:181], v[202:205], v[78:81]
	v_mfma_f32_16x16x32_bf16 v[70:73], v[168:171], v[210:213], v[70:73]
	v_mfma_f32_16x16x32_bf16 v[66:69], v[178:181], v[210:213], v[66:69]
	v_mfma_f32_16x16x32_bf16 v[118:121], v[172:175], v[190:193], v[118:121]
	v_mfma_f32_16x16x32_bf16 v[110:113], v[182:185], v[190:193], v[110:113]
	v_mfma_f32_16x16x32_bf16 v[102:105], v[172:175], v[198:201], v[102:105]
	v_mfma_f32_16x16x32_bf16 v[94:97], v[182:185], v[198:201], v[94:97]
	v_mfma_f32_16x16x32_bf16 v[86:89], v[172:175], v[206:209], v[86:89]
	v_mfma_f32_16x16x32_bf16 v[78:81], v[182:185], v[206:209], v[78:81]
	v_mfma_f32_16x16x32_bf16 v[70:73], v[172:175], v[214:217], v[70:73]
	v_mfma_f32_16x16x32_bf16 v[66:69], v[182:185], v[214:217], v[66:69]
	s_barrier
	s_setprio 0
	s_add_u32 s2, s30, 0x8000
	s_addc_u32 s3, s31, 0
	s_add_i32 s63, s63, s38
	v_lshl_add_u64 v[144:145], s[2:3], 0, v[132:133]
	s_mov_b32 m0, s63
	ds_read_b128 v[186:189], v150 offset:49152
	ds_read_b128 v[190:193], v150 offset:50176
	ds_read_b128 v[194:197], v150 offset:51200
	ds_read_b128 v[198:201], v150 offset:52224
	ds_read_b128 v[202:205], v150 offset:53248
	ds_read_b128 v[206:209], v150 offset:54272
	ds_read_b128 v[210:213], v150 offset:55296
	ds_read_b128 v[214:217], v150 offset:56320
	global_load_lds_dwordx4 v[144:145], off
	s_add_i32 m0, s63, 0x2000
	v_lshl_add_u64 v[144:145], s[2:3], 0, v[136:137]
	s_add_u32 s2, s30, 0xc000
	s_addc_u32 s3, s31, 0
	s_add_i32 s30, s64, s38
	global_load_lds_dwordx4 v[144:145], off
	v_lshl_add_u64 v[144:145], s[2:3], 0, v[132:133]
	s_mov_b32 m0, s30
	s_nop 0
	global_load_lds_dwordx4 v[144:145], off
	v_lshl_add_u64 v[144:145], s[2:3], 0, v[136:137]
	s_add_i32 m0, s30, 0x2000
	s_nop 0
	global_load_lds_dwordx4 v[144:145], off
	v_lshl_add_u64 v[144:145], s[28:29], 0, v[130:131]
	s_mov_b32 m0, s44
	s_nop 0
	global_load_lds_dwordx4 v[144:145], off
	v_lshl_add_u64 v[144:145], s[28:29], 0, v[134:135]
	s_mov_b32 m0, s45
	s_nop 0
	global_load_lds_dwordx4 v[144:145], off
	s_waitcnt vmcnt(8)
	s_waitcnt lgkmcnt(0)
	s_setprio 1
	s_barrier
	v_mfma_f32_16x16x32_bf16 v[62:65], v[152:155], v[186:189], v[62:65]
	v_mfma_f32_16x16x32_bf16 v[58:61], v[160:163], v[186:189], v[58:61]
	v_mfma_f32_16x16x32_bf16 v[50:53], v[152:155], v[194:197], v[50:53]
	v_mfma_f32_16x16x32_bf16 v[42:45], v[160:163], v[194:197], v[42:45]
	v_mfma_f32_16x16x32_bf16 v[34:37], v[152:155], v[202:205], v[34:37]
	v_mfma_f32_16x16x32_bf16 v[26:29], v[160:163], v[202:205], v[26:29]
	v_mfma_f32_16x16x32_bf16 v[18:21], v[152:155], v[210:213], v[18:21]
	v_mfma_f32_16x16x32_bf16 v[10:13], v[160:163], v[210:213], v[10:13]
	v_mfma_f32_16x16x32_bf16 v[62:65], v[156:159], v[190:193], v[62:65]
	v_mfma_f32_16x16x32_bf16 v[58:61], v[164:167], v[190:193], v[58:61]
	v_mfma_f32_16x16x32_bf16 v[50:53], v[156:159], v[198:201], v[50:53]
	v_mfma_f32_16x16x32_bf16 v[42:45], v[164:167], v[198:201], v[42:45]
	v_mfma_f32_16x16x32_bf16 v[34:37], v[156:159], v[206:209], v[34:37]
	v_mfma_f32_16x16x32_bf16 v[26:29], v[164:167], v[206:209], v[26:29]
	v_mfma_f32_16x16x32_bf16 v[18:21], v[156:159], v[214:217], v[18:21]
	v_mfma_f32_16x16x32_bf16 v[10:13], v[164:167], v[214:217], v[10:13]
	s_setprio 0
	s_setprio 1
	v_mfma_f32_16x16x32_bf16 v[54:57], v[168:171], v[186:189], v[54:57]
	v_mfma_f32_16x16x32_bf16 v[46:49], v[178:181], v[186:189], v[46:49]
	v_mfma_f32_16x16x32_bf16 v[38:41], v[168:171], v[194:197], v[38:41]
	v_mfma_f32_16x16x32_bf16 v[30:33], v[178:181], v[194:197], v[30:33]
	v_mfma_f32_16x16x32_bf16 v[22:25], v[168:171], v[202:205], v[22:25]
	v_mfma_f32_16x16x32_bf16 v[14:17], v[178:181], v[202:205], v[14:17]
	v_mfma_f32_16x16x32_bf16 v[6:9], v[168:171], v[210:213], v[6:9]
	v_mfma_f32_16x16x32_bf16 v[2:5], v[178:181], v[210:213], v[2:5]
	v_mfma_f32_16x16x32_bf16 v[54:57], v[172:175], v[190:193], v[54:57]
	v_mfma_f32_16x16x32_bf16 v[46:49], v[182:185], v[190:193], v[46:49]
	v_mfma_f32_16x16x32_bf16 v[38:41], v[172:175], v[198:201], v[38:41]
	v_mfma_f32_16x16x32_bf16 v[30:33], v[182:185], v[198:201], v[30:33]
	v_mfma_f32_16x16x32_bf16 v[22:25], v[172:175], v[206:209], v[22:25]
	v_mfma_f32_16x16x32_bf16 v[14:17], v[182:185], v[206:209], v[14:17]
	v_mfma_f32_16x16x32_bf16 v[6:9], v[172:175], v[214:217], v[6:9]
	v_mfma_f32_16x16x32_bf16 v[2:5], v[182:185], v[214:217], v[2:5]
	s_barrier
	s_setprio 0
	s_add_i32 s62, s62, 2
	s_add_u32 s26, s26, 0x10000
	s_addc_u32 s27, s27, 0
	s_add_u32 s60, s60, 0x10000
	s_addc_u32 s61, s61, 0
	s_cmp_gt_u32 s62, 41
	s_cbranch_scc0 .LBB0_1444
	s_branch .Lpk1444_exit
.LBB0_1444:
	ds_read_b128 v[152:155], v148
	ds_read_b128 v[156:159], v148 offset:1024
	ds_read_b128 v[160:163], v148 offset:2048
	ds_read_b128 v[164:167], v148 offset:3072
	ds_read_b128 v[168:171], v149
	ds_read_b128 v[172:175], v149 offset:1024
	ds_read_b128 v[178:181], v149 offset:2048
	ds_read_b128 v[182:185], v149 offset:3072
	s_add_u32 s2, s26, 0x4000
	s_addc_u32 s3, s27, 0
	s_cmp_eq_u32 s62, 40
	s_cselect_b32 s2, s57, s2
	s_cselect_b32 s3, s56, s3
	s_cselect_b32 s31, s58, s61
	s_cselect_b32 s30, s59, s60
	s_add_u32 s28, s2, 0x8000
	s_addc_u32 s29, s3, 0
	v_lshl_add_u64 v[144:145], s[26:27], 0, v[138:139]
	s_add_i32 m0, s39, 0xc000
	ds_read_b128 v[186:189], v150
	ds_read_b128 v[190:193], v150 offset:1024
	ds_read_b128 v[194:197], v150 offset:2048
	ds_read_b128 v[198:201], v150 offset:3072
	ds_read_b128 v[202:205], v150 offset:4096
	ds_read_b128 v[206:209], v150 offset:5120
	ds_read_b128 v[210:213], v150 offset:6144
	ds_read_b128 v[214:217], v150 offset:7168
	global_load_lds_dwordx4 v[144:145], off
	v_lshl_add_u64 v[144:145], s[26:27], 0, v[140:141]
	s_add_i32 m0, s39, 0xe000
	s_nop 0
	global_load_lds_dwordx4 v[144:145], off
	s_waitcnt vmcnt(8)
	s_waitcnt lgkmcnt(0)
	s_setprio 1
	s_barrier
	v_mfma_f32_16x16x32_bf16 v[126:129], v[152:155], v[186:189], v[126:129]
	v_mfma_f32_16x16x32_bf16 v[122:125], v[160:163], v[186:189], v[122:125]
	v_mfma_f32_16x16x32_bf16 v[114:117], v[152:155], v[194:197], v[114:117]
	v_mfma_f32_16x16x32_bf16 v[106:109], v[160:163], v[194:197], v[106:109]
	v_mfma_f32_16x16x32_bf16 v[98:101], v[152:155], v[202:205], v[98:101]
	v_mfma_f32_16x16x32_bf16 v[90:93], v[160:163], v[202:205], v[90:93]
	v_mfma_f32_16x16x32_bf16 v[82:85], v[152:155], v[210:213], v[82:85]
	v_mfma_f32_16x16x32_bf16 v[74:77], v[160:163], v[210:213], v[74:77]
	v_mfma_f32_16x16x32_bf16 v[126:129], v[156:159], v[190:193], v[126:129]
	v_mfma_f32_16x16x32_bf16 v[122:125], v[164:167], v[190:193], v[122:125]
	v_mfma_f32_16x16x32_bf16 v[114:117], v[156:159], v[198:201], v[114:117]
	v_mfma_f32_16x16x32_bf16 v[106:109], v[164:167], v[198:201], v[106:109]
	v_mfma_f32_16x16x32_bf16 v[98:101], v[156:159], v[206:209], v[98:101]
	v_mfma_f32_16x16x32_bf16 v[90:93], v[164:167], v[206:209], v[90:93]
	v_mfma_f32_16x16x32_bf16 v[82:85], v[156:159], v[214:217], v[82:85]
	v_mfma_f32_16x16x32_bf16 v[74:77], v[164:167], v[214:217], v[74:77]
	s_setprio 0
	s_setprio 1
	v_mfma_f32_16x16x32_bf16 v[118:121], v[168:171], v[186:189], v[118:121]
	v_mfma_f32_16x16x32_bf16 v[110:113], v[178:181], v[186:189], v[110:113]
	v_mfma_f32_16x16x32_bf16 v[102:105], v[168:171], v[194:197], v[102:105]
	v_mfma_f32_16x16x32_bf16 v[94:97], v[178:181], v[194:197], v[94:97]
	v_mfma_f32_16x16x32_bf16 v[86:89], v[168:171], v[202:205], v[86:89]
	v_mfma_f32_16x16x32_bf16 v[78:81], v[178:181], v[202:205], v[78:81]
	v_mfma_f32_16x16x32_bf16 v[70:73], v[168:171], v[210:213], v[70:73]
	v_mfma_f32_16x16x32_bf16 v[66:69], v[178:181], v[210:213], v[66:69]
	v_mfma_f32_16x16x32_bf16 v[118:121], v[172:175], v[190:193], v[118:121]
	v_mfma_f32_16x16x32_bf16 v[110:113], v[182:185], v[190:193], v[110:113]
	v_mfma_f32_16x16x32_bf16 v[102:105], v[172:175], v[198:201], v[102:105]
	v_mfma_f32_16x16x32_bf16 v[94:97], v[182:185], v[198:201], v[94:97]
	v_mfma_f32_16x16x32_bf16 v[86:89], v[172:175], v[206:209], v[86:89]
	v_mfma_f32_16x16x32_bf16 v[78:81], v[182:185], v[206:209], v[78:81]
	v_mfma_f32_16x16x32_bf16 v[70:73], v[172:175], v[214:217], v[70:73]
	v_mfma_f32_16x16x32_bf16 v[66:69], v[182:185], v[214:217], v[66:69]
	s_barrier
	s_setprio 0
	s_add_i32 s63, s46, s38
	v_lshl_add_u64 v[144:145], s[30:31], 0, v[132:133]
	s_mov_b32 m0, s63
	ds_read_b128 v[186:189], v150 offset:16384
	ds_read_b128 v[190:193], v150 offset:17408
	ds_read_b128 v[194:197], v150 offset:18432
	ds_read_b128 v[198:201], v150 offset:19456
	ds_read_b128 v[202:205], v150 offset:20480
	ds_read_b128 v[206:209], v150 offset:21504
	ds_read_b128 v[210:213], v150 offset:22528
	ds_read_b128 v[214:217], v150 offset:23552
	global_load_lds_dwordx4 v[144:145], off
	s_add_i32 m0, s63, 0x2000
	s_add_u32 s64, s30, 0x4000
	v_lshl_add_u64 v[144:145], s[30:31], 0, v[136:137]
	s_addc_u32 s65, s31, 0
	s_add_i32 s63, s47, s38
	global_load_lds_dwordx4 v[144:145], off
	v_lshl_add_u64 v[144:145], s[64:65], 0, v[132:133]
	s_mov_b32 m0, s63
	s_nop 0
	global_load_lds_dwordx4 v[144:145], off
	v_lshl_add_u64 v[144:145], s[64:65], 0, v[136:137]
	s_add_i32 m0, s63, 0x2000
	s_nop 0
	global_load_lds_dwordx4 v[144:145], off
	v_lshl_add_u64 v[144:145], s[2:3], 0, v[130:131]
	s_mov_b32 m0, s39
	s_nop 0
	global_load_lds_dwordx4 v[144:145], off
	v_lshl_add_u64 v[144:145], s[2:3], 0, v[134:135]
	s_mov_b32 m0, s40
	s_nop 0
	global_load_lds_dwordx4 v[144:145], off
	s_waitcnt vmcnt(8)
	s_waitcnt lgkmcnt(0)
	s_setprio 1
	s_barrier
	v_mfma_f32_16x16x32_bf16 v[62:65], v[152:155], v[186:189], v[62:65]
	v_mfma_f32_16x16x32_bf16 v[58:61], v[160:163], v[186:189], v[58:61]
	v_mfma_f32_16x16x32_bf16 v[50:53], v[152:155], v[194:197], v[50:53]
	v_mfma_f32_16x16x32_bf16 v[42:45], v[160:163], v[194:197], v[42:45]
	v_mfma_f32_16x16x32_bf16 v[34:37], v[152:155], v[202:205], v[34:37]
	v_mfma_f32_16x16x32_bf16 v[26:29], v[160:163], v[202:205], v[26:29]
	v_mfma_f32_16x16x32_bf16 v[18:21], v[152:155], v[210:213], v[18:21]
	v_mfma_f32_16x16x32_bf16 v[10:13], v[160:163], v[210:213], v[10:13]
	v_mfma_f32_16x16x32_bf16 v[62:65], v[156:159], v[190:193], v[62:65]
	v_mfma_f32_16x16x32_bf16 v[58:61], v[164:167], v[190:193], v[58:61]
	v_mfma_f32_16x16x32_bf16 v[50:53], v[156:159], v[198:201], v[50:53]
	v_mfma_f32_16x16x32_bf16 v[42:45], v[164:167], v[198:201], v[42:45]
	v_mfma_f32_16x16x32_bf16 v[34:37], v[156:159], v[206:209], v[34:37]
	v_mfma_f32_16x16x32_bf16 v[26:29], v[164:167], v[206:209], v[26:29]
	v_mfma_f32_16x16x32_bf16 v[18:21], v[156:159], v[214:217], v[18:21]
	v_mfma_f32_16x16x32_bf16 v[10:13], v[164:167], v[214:217], v[10:13]
	s_setprio 0
	s_setprio 1
	v_mfma_f32_16x16x32_bf16 v[54:57], v[168:171], v[186:189], v[54:57]
	v_mfma_f32_16x16x32_bf16 v[46:49], v[178:181], v[186:189], v[46:49]
	v_mfma_f32_16x16x32_bf16 v[38:41], v[168:171], v[194:197], v[38:41]
	v_mfma_f32_16x16x32_bf16 v[30:33], v[178:181], v[194:197], v[30:33]
	v_mfma_f32_16x16x32_bf16 v[22:25], v[168:171], v[202:205], v[22:25]
	v_mfma_f32_16x16x32_bf16 v[14:17], v[178:181], v[202:205], v[14:17]
	v_mfma_f32_16x16x32_bf16 v[6:9], v[168:171], v[210:213], v[6:9]
	v_mfma_f32_16x16x32_bf16 v[2:5], v[178:181], v[210:213], v[2:5]
	v_mfma_f32_16x16x32_bf16 v[54:57], v[172:175], v[190:193], v[54:57]
	v_mfma_f32_16x16x32_bf16 v[46:49], v[182:185], v[190:193], v[46:49]
	v_mfma_f32_16x16x32_bf16 v[38:41], v[172:175], v[198:201], v[38:41]
	v_mfma_f32_16x16x32_bf16 v[30:33], v[182:185], v[198:201], v[30:33]
	v_mfma_f32_16x16x32_bf16 v[22:25], v[172:175], v[206:209], v[22:25]
	v_mfma_f32_16x16x32_bf16 v[14:17], v[182:185], v[206:209], v[14:17]
	v_mfma_f32_16x16x32_bf16 v[6:9], v[172:175], v[214:217], v[6:9]
	v_mfma_f32_16x16x32_bf16 v[2:5], v[182:185], v[214:217], v[2:5]
	s_barrier
	s_setprio 0
	s_add_i32 s63, 0, 0x18000
	v_add_u32_e32 v144, s63, v146
	s_add_i32 s64, 0, 0x1c000
	ds_read_b128 v[152:155], v144
	ds_read_b128 v[156:159], v144 offset:1024
	ds_read_b128 v[160:163], v144 offset:2048
	ds_read_b128 v[164:167], v144 offset:3072
	v_add_u32_e32 v144, s64, v146
	ds_read_b128 v[168:171], v144
	ds_read_b128 v[172:175], v144 offset:1024
	ds_read_b128 v[178:181], v144 offset:2048
	ds_read_b128 v[182:185], v144 offset:3072
	s_add_u32 s2, s2, 0x4000
	s_addc_u32 s3, s3, 0
	s_mov_b32 m0, s41
	v_lshl_add_u64 v[144:145], s[2:3], 0, v[130:131]
	ds_read_b128 v[186:189], v150 offset:32768
	ds_read_b128 v[190:193], v150 offset:33792
	ds_read_b128 v[194:197], v150 offset:34816
	ds_read_b128 v[198:201], v150 offset:35840
	ds_read_b128 v[202:205], v150 offset:36864
	ds_read_b128 v[206:209], v150 offset:37888
	ds_read_b128 v[210:213], v150 offset:38912
	ds_read_b128 v[214:217], v150 offset:39936
	global_load_lds_dwordx4 v[144:145], off
	v_lshl_add_u64 v[144:145], s[2:3], 0, v[134:135]
	s_mov_b32 m0, s42
	s_nop 0
	global_load_lds_dwordx4 v[144:145], off
	s_waitcnt vmcnt(8)
	s_waitcnt lgkmcnt(0)
	s_setprio 1
	s_barrier
	v_mfma_f32_16x16x32_bf16 v[126:129], v[152:155], v[186:189], v[126:129]
	v_mfma_f32_16x16x32_bf16 v[122:125], v[160:163], v[186:189], v[122:125]
	v_mfma_f32_16x16x32_bf16 v[114:117], v[152:155], v[194:197], v[114:117]
	v_mfma_f32_16x16x32_bf16 v[106:109], v[160:163], v[194:197], v[106:109]
	v_mfma_f32_16x16x32_bf16 v[98:101], v[152:155], v[202:205], v[98:101]
	v_mfma_f32_16x16x32_bf16 v[90:93], v[160:163], v[202:205], v[90:93]
	v_mfma_f32_16x16x32_bf16 v[82:85], v[152:155], v[210:213], v[82:85]
	v_mfma_f32_16x16x32_bf16 v[74:77], v[160:163], v[210:213], v[74:77]
	v_mfma_f32_16x16x32_bf16 v[126:129], v[156:159], v[190:193], v[126:129]
	v_mfma_f32_16x16x32_bf16 v[122:125], v[164:167], v[190:193], v[122:125]
	v_mfma_f32_16x16x32_bf16 v[114:117], v[156:159], v[198:201], v[114:117]
	v_mfma_f32_16x16x32_bf16 v[106:109], v[164:167], v[198:201], v[106:109]
	v_mfma_f32_16x16x32_bf16 v[98:101], v[156:159], v[206:209], v[98:101]
	v_mfma_f32_16x16x32_bf16 v[90:93], v[164:167], v[206:209], v[90:93]
	v_mfma_f32_16x16x32_bf16 v[82:85], v[156:159], v[214:217], v[82:85]
	v_mfma_f32_16x16x32_bf16 v[74:77], v[164:167], v[214:217], v[74:77]
	s_setprio 0
	s_setprio 1
	v_mfma_f32_16x16x32_bf16 v[118:121], v[168:171], v[186:189], v[118:121]
	v_mfma_f32_16x16x32_bf16 v[110:113], v[178:181], v[186:189], v[110:113]
	v_mfma_f32_16x16x32_bf16 v[102:105], v[168:171], v[194:197], v[102:105]
	v_mfma_f32_16x16x32_bf16 v[94:97], v[178:181], v[194:197], v[94:97]
	v_mfma_f32_16x16x32_bf16 v[86:89], v[168:171], v[202:205], v[86:89]
	v_mfma_f32_16x16x32_bf16 v[78:81], v[178:181], v[202:205], v[78:81]
	v_mfma_f32_16x16x32_bf16 v[70:73], v[168:171], v[210:213], v[70:73]
	v_mfma_f32_16x16x32_bf16 v[66:69], v[178:181], v[210:213], v[66:69]
	v_mfma_f32_16x16x32_bf16 v[118:121], v[172:175], v[190:193], v[118:121]
	v_mfma_f32_16x16x32_bf16 v[110:113], v[182:185], v[190:193], v[110:113]
	v_mfma_f32_16x16x32_bf16 v[102:105], v[172:175], v[198:201], v[102:105]
	v_mfma_f32_16x16x32_bf16 v[94:97], v[182:185], v[198:201], v[94:97]
	v_mfma_f32_16x16x32_bf16 v[86:89], v[172:175], v[206:209], v[86:89]
	v_mfma_f32_16x16x32_bf16 v[78:81], v[182:185], v[206:209], v[78:81]
	v_mfma_f32_16x16x32_bf16 v[70:73], v[172:175], v[214:217], v[70:73]
	v_mfma_f32_16x16x32_bf16 v[66:69], v[182:185], v[214:217], v[66:69]
	s_barrier
	s_setprio 0
	s_add_u32 s2, s30, 0x8000
	s_addc_u32 s3, s31, 0
	s_add_i32 s63, s63, s38
	v_lshl_add_u64 v[144:145], s[2:3], 0, v[132:133]
	s_mov_b32 m0, s63
	ds_read_b128 v[186:189], v150 offset:49152
	ds_read_b128 v[190:193], v150 offset:50176
	ds_read_b128 v[194:197], v150 offset:51200
	ds_read_b128 v[198:201], v150 offset:52224
	ds_read_b128 v[202:205], v150 offset:53248
	ds_read_b128 v[206:209], v150 offset:54272
	ds_read_b128 v[210:213], v150 offset:55296
	ds_read_b128 v[214:217], v150 offset:56320
	global_load_lds_dwordx4 v[144:145], off
	s_add_i32 m0, s63, 0x2000
	v_lshl_add_u64 v[144:145], s[2:3], 0, v[136:137]
	s_add_u32 s2, s30, 0xc000
	s_addc_u32 s3, s31, 0
	s_add_i32 s30, s64, s38
	global_load_lds_dwordx4 v[144:145], off
	v_lshl_add_u64 v[144:145], s[2:3], 0, v[132:133]
	s_mov_b32 m0, s30
	s_nop 0
	global_load_lds_dwordx4 v[144:145], off
	v_lshl_add_u64 v[144:145], s[2:3], 0, v[136:137]
	s_add_i32 m0, s30, 0x2000
	s_nop 0
	global_load_lds_dwordx4 v[144:145], off
	v_lshl_add_u64 v[144:145], s[28:29], 0, v[130:131]
	s_mov_b32 m0, s44
	s_nop 0
	global_load_lds_dwordx4 v[144:145], off
	v_lshl_add_u64 v[144:145], s[28:29], 0, v[134:135]
	s_mov_b32 m0, s45
	s_nop 0
	global_load_lds_dwordx4 v[144:145], off
	s_waitcnt vmcnt(8)
	s_waitcnt lgkmcnt(0)
	s_setprio 1
	s_barrier
	v_mfma_f32_16x16x32_bf16 v[62:65], v[152:155], v[186:189], v[62:65]
	v_mfma_f32_16x16x32_bf16 v[58:61], v[160:163], v[186:189], v[58:61]
	v_mfma_f32_16x16x32_bf16 v[50:53], v[152:155], v[194:197], v[50:53]
	v_mfma_f32_16x16x32_bf16 v[42:45], v[160:163], v[194:197], v[42:45]
	v_mfma_f32_16x16x32_bf16 v[34:37], v[152:155], v[202:205], v[34:37]
	v_mfma_f32_16x16x32_bf16 v[26:29], v[160:163], v[202:205], v[26:29]
	v_mfma_f32_16x16x32_bf16 v[18:21], v[152:155], v[210:213], v[18:21]
	v_mfma_f32_16x16x32_bf16 v[10:13], v[160:163], v[210:213], v[10:13]
	v_mfma_f32_16x16x32_bf16 v[62:65], v[156:159], v[190:193], v[62:65]
	v_mfma_f32_16x16x32_bf16 v[58:61], v[164:167], v[190:193], v[58:61]
	v_mfma_f32_16x16x32_bf16 v[50:53], v[156:159], v[198:201], v[50:53]
	v_mfma_f32_16x16x32_bf16 v[42:45], v[164:167], v[198:201], v[42:45]
	v_mfma_f32_16x16x32_bf16 v[34:37], v[156:159], v[206:209], v[34:37]
	v_mfma_f32_16x16x32_bf16 v[26:29], v[164:167], v[206:209], v[26:29]
	v_mfma_f32_16x16x32_bf16 v[18:21], v[156:159], v[214:217], v[18:21]
	v_mfma_f32_16x16x32_bf16 v[10:13], v[164:167], v[214:217], v[10:13]
	s_setprio 0
	s_setprio 1
	v_mfma_f32_16x16x32_bf16 v[54:57], v[168:171], v[186:189], v[54:57]
	v_mfma_f32_16x16x32_bf16 v[46:49], v[178:181], v[186:189], v[46:49]
	v_mfma_f32_16x16x32_bf16 v[38:41], v[168:171], v[194:197], v[38:41]
	v_mfma_f32_16x16x32_bf16 v[30:33], v[178:181], v[194:197], v[30:33]
	v_mfma_f32_16x16x32_bf16 v[22:25], v[168:171], v[202:205], v[22:25]
	v_mfma_f32_16x16x32_bf16 v[14:17], v[178:181], v[202:205], v[14:17]
	v_mfma_f32_16x16x32_bf16 v[6:9], v[168:171], v[210:213], v[6:9]
	v_mfma_f32_16x16x32_bf16 v[2:5], v[178:181], v[210:213], v[2:5]
	v_mfma_f32_16x16x32_bf16 v[54:57], v[172:175], v[190:193], v[54:57]
	v_mfma_f32_16x16x32_bf16 v[46:49], v[182:185], v[190:193], v[46:49]
	v_mfma_f32_16x16x32_bf16 v[38:41], v[172:175], v[198:201], v[38:41]
	v_mfma_f32_16x16x32_bf16 v[30:33], v[182:185], v[198:201], v[30:33]
	v_mfma_f32_16x16x32_bf16 v[22:25], v[172:175], v[206:209], v[22:25]
	v_mfma_f32_16x16x32_bf16 v[14:17], v[182:185], v[206:209], v[14:17]
	v_mfma_f32_16x16x32_bf16 v[6:9], v[172:175], v[214:217], v[6:9]
	v_mfma_f32_16x16x32_bf16 v[2:5], v[182:185], v[214:217], v[2:5]
	s_barrier
	s_setprio 0
	s_add_i32 s62, s62, 2
	s_add_u32 s26, s26, 0x10000
	s_addc_u32 s27, s27, 0
	s_add_u32 s60, s60, 0x10000
	s_addc_u32 s61, s61, 0
	s_cmp_gt_u32 s62, 41
	s_cbranch_scc0 .LBB0_1444
